# non-temporal (nt) hint on the read-once f32 weight and x loads of the conversion loops (P0 and FFN-in tails) to stop them evicting GEMM operands from L2
# speedup vs baseline: 1.0370x; 1.0101x over previous
; #define LAS __attribute__((address_space(3)))
; __device__ __forceinline__ void transpose_tile(const float* W, const float* gain, int K, int N, int k0, int n0, bf16* WT, int drow0, LAS float* scr, int lane) {
;     f32x4 v[8]; float gv[8];
;     const int r0 = lane >> 3, c4 = lane & 7;
; #pragma unroll
;     for (int i = 0; i < 8; ++i) { v[i] = *(const f32x4*)(W + (size_t)(k0 + r0 + 8 * i) * N + n0 + 4 * c4); gv[i] = gain ? gain[k0 + r0 + 8 * i] : 1.0f; }
; template <bool SWIGLU> __device__ __forceinline__ void transpose_item(const float* W, const float* gain, int K, int N, bf16* WT, LAS float* scr, int item, int lane) {
;     const int nblk = N / 32, kb = item / nblk, nb = item % nblk, n0 = 32 * nb;
;     int drow0 = n0;
;     if (SWIGLU) { const int up = n0 >= FF, f = up ? n0 - FF : n0; drow0 = 256 * (f >> 7) + (up ? 128 : 0) + (f & 127); }
;     transpose_tile(W, gain, K, N, 64 * kb, n0, WT, drow0, scr, lane);
.LBB0_8:
	s_mov_b32 s2, 2
	s_ashr_i32 s3, s2, 31
	s_lshl_b64 s[2:3], s[2:3], 3
	s_add_u32 s2, s0, s2
	s_addc_u32 s3, s1, s3
	s_mov_b32 s6, 1
	s_load_dwordx2 s[2:3], s[2:3], 0x0
	s_ashr_i32 s7, s6, 31
	s_lshl_b64 s[6:7], s[6:7], 3
	s_add_u32 s10, s0, s6
	s_mul_hi_i32 s6, s18, 0x2e8ba2e9
	s_addc_u32 s11, s1, s7
	s_lshr_b32 s7, s6, 31
	s_ashr_i32 s6, s6, 5
	s_add_i32 s7, s6, s7
	s_mul_i32 s6, s7, 0xffffea00
	s_add_i32 s8, s15, s6
	s_ashr_i32 s9, s8, 31
	s_lshl_b32 s6, s7, 6
	s_lshl_b64 s[20:21], s[8:9], 2
	s_waitcnt lgkmcnt(0)
	s_add_u32 s2, s2, s20
	s_addc_u32 s3, s3, s21
	v_add_u32_e32 v30, s6, v39
	v_lshl_add_u64 v[32:33], s[2:3], 0, v[34:35]
	v_mad_i64_i32 v[2:3], s[2:3], v30, s17, v[32:33]
	global_load_dwordx4 v[2:5], v[2:3], off nt
	s_load_dwordx2 s[2:3], s[10:11], 0x0
	v_ashrrev_i32_e32 v31, 31, v30
	v_mov_b32_e32 v38, 1.0
	v_mov_b32_e32 v42, 1.0
	s_waitcnt lgkmcnt(0)
	s_cmp_lg_u64 s[2:3], 0
	s_cselect_b64 s[10:11], -1, 0
	s_cmp_eq_u64 s[2:3], 0
	v_lshl_add_u64 v[50:51], v[30:31], 2, s[2:3]
	s_cbranch_scc1 .LBB0_10
	global_load_dword v42, v[50:51], off nt
.LBB0_10:
	v_add_u32_e32 v6, 8, v30
	v_mad_i64_i32 v[6:7], s[2:3], v6, s17, v[32:33]
	global_load_dwordx4 v[6:9], v[6:7], off nt
	v_cndmask_b32_e64 v10, 0, 1, s[10:11]
	v_cmp_ne_u32_e64 s[2:3], 1, v10
	s_andn2_b64 vcc, exec, s[10:11]
	s_cbranch_vccnz .LBB0_12
	global_load_dword v38, v[50:51], off offset:32 nt
.LBB0_12:
	v_add_u32_e32 v10, 16, v30
	v_mad_i64_i32 v[10:11], s[10:11], v10, s17, v[32:33]
	global_load_dwordx4 v[10:13], v[10:11], off nt
	v_mov_b32_e32 v40, 1.0
	s_and_b64 vcc, exec, s[2:3]
	v_mov_b32_e32 v46, 1.0
	s_cbranch_vccnz .LBB0_14
	global_load_dword v46, v[50:51], off offset:64 nt
.LBB0_14:
	v_add_u32_e32 v14, 24, v30
	v_mad_i64_i32 v[14:15], s[10:11], v14, s17, v[32:33]
	global_load_dwordx4 v[14:17], v[14:15], off nt
	s_and_b64 vcc, exec, s[2:3]
	s_cbranch_vccnz .LBB0_16
	global_load_dword v40, v[50:51], off offset:96 nt
.LBB0_16:
	v_add_u32_e32 v18, 32, v30
	v_mad_i64_i32 v[18:19], s[10:11], v18, s17, v[32:33]
	global_load_dwordx4 v[18:21], v[18:19], off nt
	v_mov_b32_e32 v44, 1.0
	s_and_b64 vcc, exec, s[2:3]
	v_mov_b32_e32 v52, 1.0
	s_cbranch_vccnz .LBB0_18
	global_load_dword v52, v[50:51], off offset:128 nt
.LBB0_18:
	v_add_u32_e32 v22, 40, v30
	v_mad_i64_i32 v[22:23], s[10:11], v22, s17, v[32:33]
	global_load_dwordx4 v[22:25], v[22:23], off nt
	s_and_b64 vcc, exec, s[2:3]
	s_cbranch_vccnz .LBB0_20
	global_load_dword v44, v[50:51], off offset:160 nt
.LBB0_20:
	v_add_u32_e32 v26, 48, v30
	v_mad_i64_i32 v[26:27], s[10:11], v26, s17, v[32:33]
	global_load_dwordx4 v[26:29], v[26:27], off nt
	v_mov_b32_e32 v48, 1.0
	s_and_b64 vcc, exec, s[2:3]
	v_mov_b32_e32 v54, 1.0
	s_cbranch_vccnz .LBB0_22
	global_load_dword v54, v[50:51], off offset:192 nt
.LBB0_22:
	v_add_u32_e32 v30, 56, v30
	v_mad_i64_i32 v[30:31], s[10:11], v30, s17, v[32:33]
	global_load_dwordx4 v[30:33], v[30:31], off nt
	s_and_b64 vcc, exec, s[2:3]
	s_cbranch_vccnz .LBB0_7
	global_load_dword v48, v[50:51], off offset:224 nt
	s_branch .LBB0_7

; __device__ __forceinline__ unsigned pk_bf16(float lo, float hi) { typedef __bf16 b2_t __attribute__((ext_vector_type(2))); f32x2 v = {lo, hi}; b2_t b = __builtin_convertvector(v, b2_t); return __builtin_bit_cast(unsigned, b); }
; __device__ __forceinline__ void cvt_phase(const float* x, bf16* xn, float* ssq, int gw, int ngw, int lane) {
;     for (int m = gw; m < M; m += ngw) {
;         const f32x4* xr = (const f32x4*)(x + (size_t)m * D) + lane;
;         f32x4 v[4]; float s = 0.f;
; #pragma unroll
;         for (int j = 0; j < 4; ++j) { v[j] = xr[64 * j]; s += (v[j].x * v[j].x + v[j].y * v[j].y) + (v[j].z * v[j].z + v[j].w * v[j].w); }
;         s = wave_sum(s);
;         if (lane == 0) ssq[m] = s;
;         v2u* o = (v2u*)(xn + (size_t)m * D) + lane;
; #pragma unroll
;         for (int j = 0; j < 4; ++j) { v2u w; w.x = pk_bf16(v[j].x, v[j].y); w.y = pk_bf16(v[j].z, v[j].w); o[64 * j] = w; }
;     }
.LBB0_27:
	global_load_dwordx4 v[6:9], v[22:23], off offset:-3072 nt
	global_load_dwordx4 v[2:5], v[22:23], off offset:-2048 nt
	global_load_dwordx4 v[10:13], v[22:23], off offset:-1024 nt
	global_load_dwordx4 v[14:17], v[22:23], off nt
	s_waitcnt vmcnt(3)
	v_mul_f32_e32 v20, v7, v7
	v_mul_f32_e32 v30, v9, v9
	s_waitcnt vmcnt(2)
	v_mul_f32_e32 v31, v3, v3
	v_mul_f32_e32 v32, v5, v5
	s_waitcnt vmcnt(1)
	v_mul_f32_e32 v33, v11, v11
	v_mul_f32_e32 v34, v13, v13
	v_fmac_f32_e32 v20, v6, v6
	v_fmac_f32_e32 v30, v8, v8
	v_fmac_f32_e32 v31, v2, v2
	v_fmac_f32_e32 v32, v4, v4
	s_waitcnt vmcnt(0)
	v_mul_f32_e32 v35, v15, v15
	v_mul_f32_e32 v36, v17, v17
	v_fmac_f32_e32 v33, v10, v10
	v_fmac_f32_e32 v34, v12, v12
	v_add_f32_e32 v20, v20, v30
	v_add_f32_e32 v30, v31, v32
	v_fmac_f32_e32 v35, v14, v14
	v_fmac_f32_e32 v36, v16, v16
	v_add_f32_e32 v31, v33, v34
	v_add_f32_e32 v20, v20, v30
	v_add_f32_e32 v20, v20, v31
	v_add_f32_e32 v30, v35, v36
	v_add_f32_e32 v20, v20, v30
	ds_bpermute_b32 v30, v24, v20
	s_waitcnt lgkmcnt(0)
	v_add_f32_e32 v20, v20, v30
	ds_bpermute_b32 v30, v25, v20
	s_waitcnt lgkmcnt(0)
	v_add_f32_e32 v20, v20, v30
	ds_bpermute_b32 v30, v26, v20
	s_waitcnt lgkmcnt(0)
	v_add_f32_e32 v20, v20, v30
	ds_bpermute_b32 v30, v27, v20
	s_waitcnt lgkmcnt(0)
	v_add_f32_e32 v20, v20, v30
	ds_bpermute_b32 v30, v28, v20
	s_waitcnt lgkmcnt(0)
	v_add_f32_e32 v20, v20, v30
	ds_bpermute_b32 v30, v29, v20
	s_and_saveexec_b64 s[12:13], s[2:3]
	s_cbranch_execz .LBB0_26
	s_add_u32 s20, s44, s16
	s_waitcnt lgkmcnt(0)
	v_add_f32_e32 v20, v20, v30
	s_addc_u32 s21, s45, s17
	global_store_dword v21, v20, s[20:21]
	s_branch .LBB0_26

; #define SEAM() xcd_barrier(xbar, wave)
; __global__ void __launch_bounds__(512, 2) fwd_megakernel(Args a) {
;     ...
;         for (int i = bid * 512 + tid; i < 2 * BATCH * NCH * D; i += G * 512) ((unsigned long long*)(ws + WS_SUM))[i] = 0ull;
;     }
;     ...
;     if (a.ws == nullptr) grid.sync();
;     SEAM();
.LBB0_32:
	s_or_b64 exec, exec, s[2:3]
	s_ashr_i32 s37, s14, 31
	s_ashr_i32 s80, s46, 31
	s_mov_b32 s84, s33
	s_cmp_eq_u64 s[44:45], 0
	s_cbranch_scc0 .LBB0_44
	v_lshrrev_b32_e32 v2, 20, v0
	v_lshrrev_b32_e32 v0, 10, v0
	v_or_b32_e32 v0, v0, v2
	s_movk_i32 s2, 0x3ff
	v_and_or_b32 v0, v0, s2, v1
	v_cmp_eq_u32_e32 vcc, 0, v0
	s_barrier
	s_and_saveexec_b64 s[2:3], vcc
	s_cbranch_execz .LBB0_43
	buffer_wbl2 sc1
	s_waitcnt vmcnt(0)
	s_load_dwordx2 s[4:5], s[4:5], 0x58
	v_mov_b32_e32 v2, 0
	s_mov_b64 s[6:7], exec
	v_mbcnt_lo_u32_b32 v1, s6, 0
	v_mbcnt_hi_u32_b32 v1, s7, v1
	s_waitcnt lgkmcnt(0)
	global_load_dword v0, v2, s[4:5] offset:40 nt
	v_cmp_eq_u32_e32 vcc, 0, v1
	s_and_saveexec_b64 s[8:9], vcc
	s_cbranch_execz .LBB0_36
	s_bcnt1_i32_b64 s6, s[6:7]
	v_mov_b32_e32 v3, s6
	global_atomic_add v3, v2, v3, s[4:5] offset:32 sc0

; #define LAS __attribute__((address_space(3)))
; __device__ __forceinline__ void transpose_tile(const float* W, const float* gain, int K, int N, int k0, int n0, bf16* WT, int drow0, LAS float* scr, int lane) {
;     f32x4 v[8]; float gv[8];
;     const int r0 = lane >> 3, c4 = lane & 7;
; #pragma unroll
;     for (int i = 0; i < 8; ++i) { v[i] = *(const f32x4*)(W + (size_t)(k0 + r0 + 8 * i) * N + n0 + 4 * c4); gv[i] = gain ? gain[k0 + r0 + 8 * i] : 1.0f; }
.LBB0_119:
	s_cmpk_gt_i32 s14, 0xaff
	s_mov_b64 s[2:3], -1
	s_cbranch_scc0 .LBB0_165
	s_cmpk_gt_u32 s14, 0x107f
	s_cbranch_scc0 .LBB0_162
	s_cmpk_gt_u32 s14, 0x167f
	s_cbranch_scc0 .LBB0_143
	s_cmpk_gt_u32 s14, 0x187f
	s_cbranch_scc0 .LBB0_140
	s_mov_b32 s2, 10
	s_ashr_i32 s3, s2, 31
	s_lshl_b64 s[2:3], s[2:3], 3
	s_add_u32 s2, s0, s2
	s_addc_u32 s3, s1, s3
	s_mov_b32 s8, 9
	s_load_dwordx2 s[2:3], s[2:3], 0x0
	s_ashr_i32 s9, s8, 31
	s_lshl_b64 s[8:9], s[8:9], 3
	s_add_u32 s8, s0, s8
	s_addc_u32 s9, s1, s9
	s_add_i32 s6, s14, 0xe780
	s_and_b32 s10, s6, 0xffff
	s_mul_i32 s10, s10, 0xba2f
	s_lshr_b32 s11, s10, 23
	s_mul_i32 s10, s11, 0xb0
	s_sub_i32 s10, s6, s10
	s_lshl_b32 s6, s11, 6
	s_lshl_b32 s11, s10, 7
	s_and_b32 s11, s11, 0x3ff80
	s_waitcnt lgkmcnt(0)
	s_add_u32 s2, s2, s11
	s_addc_u32 s3, s3, 0
	v_add_u32_e32 v28, s6, v45
	v_lshl_add_u64 v[30:31], s[2:3], 0, v[32:33]
	v_mad_i64_i32 v[0:1], s[2:3], v28, s19, v[30:31]
	global_load_dwordx4 v[0:3], v[0:1], off nt
	s_load_dwordx2 s[2:3], s[8:9], 0x0
	v_ashrrev_i32_e32 v29, 31, v28
	v_mov_b32_e32 v44, 1.0
	v_mov_b32_e32 v46, 1.0
	s_waitcnt lgkmcnt(0)
	s_cmp_lg_u64 s[2:3], 0
	s_cselect_b64 s[8:9], -1, 0
	s_cmp_eq_u64 s[2:3], 0
	v_lshl_add_u64 v[56:57], v[28:29], 2, s[2:3]
	s_cbranch_scc1 .LBB0_125
	global_load_dword v46, v[56:57], off nt
.LBB0_125:
	v_add_u32_e32 v4, 8, v28
	v_mad_i64_i32 v[4:5], s[2:3], v4, s19, v[30:31]
	global_load_dwordx4 v[4:7], v[4:5], off nt
	v_cndmask_b32_e64 v8, 0, 1, s[8:9]
	v_cmp_ne_u32_e64 s[2:3], 1, v8
	s_andn2_b64 vcc, exec, s[8:9]
	s_cbranch_vccnz .LBB0_127
	global_load_dword v44, v[56:57], off offset:32 nt
.LBB0_127:
	v_add_u32_e32 v8, 16, v28
	v_mad_i64_i32 v[8:9], s[8:9], v8, s19, v[30:31]
	global_load_dwordx4 v[8:11], v[8:9], off nt
	v_mov_b32_e32 v48, 1.0
	s_and_b64 vcc, exec, s[2:3]
	v_mov_b32_e32 v52, 1.0
	s_cbranch_vccnz .LBB0_129
	global_load_dword v52, v[56:57], off offset:64 nt
.LBB0_129:
	v_add_u32_e32 v12, 24, v28
	v_mad_i64_i32 v[12:13], s[8:9], v12, s19, v[30:31]
	global_load_dwordx4 v[12:15], v[12:13], off nt
	s_and_b64 vcc, exec, s[2:3]
	s_cbranch_vccnz .LBB0_131
	global_load_dword v48, v[56:57], off offset:96 nt
.LBB0_131:
	v_add_u32_e32 v16, 32, v28
	v_mad_i64_i32 v[16:17], s[8:9], v16, s19, v[30:31]
	global_load_dwordx4 v[16:19], v[16:17], off nt
	v_mov_b32_e32 v50, 1.0
	s_and_b64 vcc, exec, s[2:3]
	v_mov_b32_e32 v58, 1.0
	s_cbranch_vccnz .LBB0_133
	global_load_dword v58, v[56:57], off offset:128 nt
.LBB0_133:
	v_add_u32_e32 v20, 40, v28
	v_mad_i64_i32 v[20:21], s[8:9], v20, s19, v[30:31]
	global_load_dwordx4 v[20:23], v[20:21], off nt
	s_and_b64 vcc, exec, s[2:3]
	s_cbranch_vccnz .LBB0_135
	global_load_dword v50, v[56:57], off offset:160 nt
.LBB0_135:
	v_add_u32_e32 v24, 48, v28
	v_mad_i64_i32 v[24:25], s[8:9], v24, s19, v[30:31]
	global_load_dwordx4 v[24:27], v[24:25], off nt
	v_mov_b32_e32 v54, 1.0
	s_and_b64 vcc, exec, s[2:3]
	v_mov_b32_e32 v60, 1.0
	s_cbranch_vccnz .LBB0_137
	global_load_dword v60, v[56:57], off offset:192 nt
.LBB0_137:
	v_add_u32_e32 v28, 56, v28
	v_mad_i64_i32 v[28:29], s[8:9], v28, s19, v[30:31]
	global_load_dwordx4 v[28:31], v[28:29], off nt
	s_and_b64 vcc, exec, s[2:3]
	s_lshl_b32 s2, s10, 5
	s_cbranch_vccnz .LBB0_139
	global_load_dword v54, v[56:57], off offset:224 nt

; __device__ __forceinline__ unsigned pk_bf16(float lo, float hi) { typedef __bf16 b2_t __attribute__((ext_vector_type(2))); f32x2 v = {lo, hi}; b2_t b = __builtin_convertvector(v, b2_t); return __builtin_bit_cast(unsigned, b); }
; #define LAS __attribute__((address_space(3)))
; __device__ __forceinline__ void transpose_tile(const float* W, const float* gain, int K, int N, int k0, int n0, bf16* WT, int drow0, LAS float* scr, int lane) {
;     f32x4 v[8]; float gv[8];
;     const int r0 = lane >> 3, c4 = lane & 7;
; #pragma unroll
;     for (int i = 0; i < 8; ++i) { v[i] = *(const f32x4*)(W + (size_t)(k0 + r0 + 8 * i) * N + n0 + 4 * c4); gv[i] = gain ? gain[k0 + r0 + 8 * i] : 1.0f; }
; #pragma unroll
;     for (int i = 0; i < 8; ++i) { LAS float* d = scr + (r0 + 8 * i) * 33 + 4 * c4; d[0] = v[i][0] * gv[i]; d[1] = v[i][1] * gv[i]; d[2] = v[i][2] * gv[i]; d[3] = v[i][3] * gv[i]; }
;     asm volatile("s_waitcnt lgkmcnt(0)" ::: "memory");
;     const int c = lane & 7;
; #pragma unroll
;     for (int j = 0; j < 4; ++j) { const int n = (lane >> 3) + 8 * j; const LAS float* s = scr + (8 * c) * 33 + n;
;         v4u o; o.x = pk_bf16(s[0 * 33], s[1 * 33]); o.y = pk_bf16(s[2 * 33], s[3 * 33]); o.z = pk_bf16(s[4 * 33], s[5 * 33]); o.w = pk_bf16(s[6 * 33], s[7 * 33]);
;         *(v4u*)(WT + (size_t)(drow0 + n) * K + k0 + 8 * c) = o; }
;     asm volatile("s_waitcnt lgkmcnt(0)" ::: "memory");
; }
.LBB0_140:
	s_and_b64 vcc, exec, s[2:3]
	s_cbranch_vccz .LBB0_142
	s_mov_b32 s2, 8
	s_ashr_i32 s3, s2, 31
	s_lshl_b64 s[2:3], s[2:3], 3
	s_add_u32 s2, s0, s2
	s_addc_u32 s3, s1, s3
	s_load_dwordx2 s[2:3], s[2:3], 0x0
	s_lshl_b32 s6, s14, 5
	s_and_b32 s8, s6, 0x3e0
	s_and_b32 s6, s17, 0x1ffc0
	s_lshl_b32 s9, s8, 2
	v_add_u32_e32 v0, s6, v45
	s_waitcnt lgkmcnt(0)
	s_add_u32 s2, s2, s9
	s_addc_u32 s3, s3, 0
	v_ashrrev_i32_e32 v1, 31, v0
	v_lshl_add_u64 v[2:3], s[2:3], 0, v[32:33]
	v_lshlrev_b64 v[0:1], 12, v[0:1]
	v_lshl_add_u64 v[28:29], v[2:3], 0, v[0:1]
	v_add_co_u32_e32 v4, vcc, s20, v28
	v_add_u32_e32 v44, v47, v49
	s_nop 0
	v_addc_co_u32_e32 v5, vcc, 0, v29, vcc
	v_add_co_u32_e32 v8, vcc, s21, v28
	global_load_dwordx4 v[0:3], v[28:29], off nt
	s_nop 0
	global_load_dwordx4 v[4:7], v[4:5], off nt
	v_addc_co_u32_e32 v9, vcc, 0, v29, vcc
	v_add_co_u32_e32 v12, vcc, s22, v28
	v_add_u32_e32 v46, 0x420, v44
	s_nop 0
	v_addc_co_u32_e32 v13, vcc, 0, v29, vcc
	v_add_co_u32_e32 v16, vcc, s23, v28
	global_load_dwordx4 v[8:11], v[8:9], off nt
	s_nop 0
	global_load_dwordx4 v[12:15], v[12:13], off nt
	v_addc_co_u32_e32 v17, vcc, 0, v29, vcc
	v_add_co_u32_e32 v20, vcc, s24, v28
	v_add_u32_e32 v48, 0x428, v44
	s_nop 0
	v_addc_co_u32_e32 v21, vcc, 0, v29, vcc
	global_load_dwordx4 v[16:19], v[16:17], off nt
	s_nop 0
	global_load_dwordx4 v[20:23], v[20:21], off nt
	v_add_co_u32_e32 v24, vcc, s25, v28
	v_add_u32_e32 v50, 0x840, v44
	s_nop 0
	v_addc_co_u32_e32 v25, vcc, 0, v29, vcc
	global_load_dwordx4 v[24:27], v[24:25], off nt
	v_add_co_u32_e32 v28, vcc, s26, v28
	v_add_u32_e32 v54, 0x848, v44
	s_nop 0
	v_addc_co_u32_e32 v29, vcc, 0, v29, vcc
	global_load_dwordx4 v[28:31], v[28:29], off nt
	v_add_u32_e32 v58, 0xc60, v44
	v_add_u32_e32 v60, 0xc68, v44
	v_add_u32_e32 v62, 0x1080, v44
	v_add_u32_e32 v63, 0x1088, v44
	v_add_u32_e32 v64, 0x14a0, v44
	v_add_u32_e32 v65, 0x14a8, v44
	v_add_u32_e32 v66, 0x18c0, v44
	v_add_u32_e32 v67, 0x18c8, v44
	v_add_u32_e32 v68, 0x1ce0, v44
	v_add_u32_e32 v69, 0x1ce8, v44
	v_add_u32_e32 v52, s8, v45
	v_ashrrev_i32_e32 v53, 31, v52
	s_lshl_b32 s6, s6, 1
	v_lshlrev_b64 v[52:53], 11, v[52:53]
	v_lshl_add_u64 v[56:57], v[36:37], 0, s[6:7]
	s_waitcnt vmcnt(0)
	ds_write2_b32 v44, v0, v1 offset1:1
	ds_write2_b32 v44, v2, v3 offset0:2 offset1:3
	ds_write2_b32 v46, v4, v5 offset1:1
	ds_write2_b32 v48, v6, v7 offset1:1
	ds_write2_b32 v50, v8, v9 offset1:1
	ds_write2_b32 v54, v10, v11 offset1:1
	ds_write2_b32 v58, v12, v13 offset1:1
	ds_write2_b32 v60, v14, v15 offset1:1
	ds_write2_b32 v62, v16, v17 offset1:1
	ds_write2_b32 v63, v18, v19 offset1:1
	ds_write2_b32 v64, v20, v21 offset1:1
	ds_write2_b32 v65, v22, v23 offset1:1
	ds_write2_b32 v66, v24, v25 offset1:1
	ds_write2_b32 v67, v26, v27 offset1:1
	ds_write2_b32 v68, v28, v29 offset1:1
	ds_write2_b32 v69, v30, v31 offset1:1
	s_waitcnt lgkmcnt(0)
	ds_read2_b32 v[4:5], v61 offset0:33 offset1:41
	ds_read2_b32 v[6:7], v61 offset1:8
	ds_read2_b32 v[8:9], v61 offset0:66 offset1:74
	ds_read2_b32 v[10:11], v61 offset0:99 offset1:107
	ds_read2_b32 v[12:13], v61 offset0:132 offset1:140
	ds_read2_b32 v[14:15], v61 offset0:165 offset1:173
	ds_read2_b32 v[16:17], v61 offset0:198 offset1:206
	ds_read2_b32 v[18:19], v61 offset0:231 offset1:239
	v_lshl_add_u64 v[20:21], v[56:57], 0, v[52:53]
	s_waitcnt lgkmcnt(6)
	v_cvt_pk_bf16_f32 v0, v6, v4
	s_waitcnt lgkmcnt(4)
	v_cvt_pk_bf16_f32 v1, v8, v10
	s_waitcnt lgkmcnt(2)
	v_cvt_pk_bf16_f32 v2, v12, v14
	s_waitcnt lgkmcnt(0)
	v_cvt_pk_bf16_f32 v3, v16, v18
	v_add_u32_e32 v4, s8, v51
	global_store_dwordx4 v[20:21], v[0:3], off sc1
	s_nop 1
	v_cvt_pk_bf16_f32 v0, v7, v5
	v_ashrrev_i32_e32 v5, 31, v4
	v_cvt_pk_bf16_f32 v1, v9, v11
	v_cvt_pk_bf16_f32 v2, v13, v15
	v_cvt_pk_bf16_f32 v3, v17, v19
	v_lshlrev_b64 v[4:5], 11, v[4:5]
	ds_read2_b32 v[6:7], v61 offset0:49 offset1:57
	ds_read2_b32 v[8:9], v61 offset0:16 offset1:24
	ds_read2_b32 v[10:11], v61 offset0:82 offset1:90
	ds_read2_b32 v[12:13], v61 offset0:115 offset1:123
	ds_read2_b32 v[14:15], v61 offset0:148 offset1:156
	ds_read2_b32 v[16:17], v61 offset0:181 offset1:189
	ds_read2_b32 v[18:19], v61 offset0:214 offset1:222
	ds_read2_b32 v[20:21], v61 offset0:247 offset1:255
	v_lshl_add_u64 v[4:5], v[56:57], 0, v[4:5]
	global_store_dwordx4 v[4:5], v[0:3], off sc1
	v_add_u32_e32 v4, s8, v55
	v_ashrrev_i32_e32 v5, 31, v4
	v_lshlrev_b64 v[4:5], 11, v[4:5]
	s_waitcnt lgkmcnt(6)
	v_cvt_pk_bf16_f32 v0, v8, v6
	s_waitcnt lgkmcnt(4)
	v_cvt_pk_bf16_f32 v1, v10, v12
	s_waitcnt lgkmcnt(2)
	v_cvt_pk_bf16_f32 v2, v14, v16
	s_waitcnt lgkmcnt(0)
	v_cvt_pk_bf16_f32 v3, v18, v20
	v_lshl_add_u64 v[4:5], v[56:57], 0, v[4:5]
	global_store_dwordx4 v[4:5], v[0:3], off sc1
	v_add_u32_e32 v4, s8, v59
	v_ashrrev_i32_e32 v5, 31, v4
	v_lshlrev_b64 v[4:5], 11, v[4:5]
	v_cvt_pk_bf16_f32 v0, v9, v7
	v_cvt_pk_bf16_f32 v1, v11, v13
	v_cvt_pk_bf16_f32 v2, v15, v17
	v_cvt_pk_bf16_f32 v3, v19, v21
	v_lshl_add_u64 v[4:5], v[56:57], 0, v[4:5]
	global_store_dwordx4 v[4:5], v[0:3], off sc1
	s_waitcnt lgkmcnt(0)

; #define LAS __attribute__((address_space(3)))
; __device__ __forceinline__ void transpose_tile(const float* W, const float* gain, int K, int N, int k0, int n0, bf16* WT, int drow0, LAS float* scr, int lane) {
;     f32x4 v[8]; float gv[8];
;     const int r0 = lane >> 3, c4 = lane & 7;
; #pragma unroll
;     for (int i = 0; i < 8; ++i) { v[i] = *(const f32x4*)(W + (size_t)(k0 + r0 + 8 * i) * N + n0 + 4 * c4); gv[i] = gain ? gain[k0 + r0 + 8 * i] : 1.0f; }
; template <bool SWIGLU> __device__ __forceinline__ void transpose_item(const float* W, const float* gain, int K, int N, bf16* WT, LAS float* scr, int item, int lane) {
;     const int nblk = N / 32, kb = item / nblk, nb = item % nblk, n0 = 32 * nb;
;     int drow0 = n0;
;     if (SWIGLU) { const int up = n0 >= FF, f = up ? n0 - FF : n0; drow0 = 256 * (f >> 7) + (up ? 128 : 0) + (f & 127); }
;     transpose_tile(W, gain, K, N, 64 * kb, n0, WT, drow0, scr, lane);
.LBB0_143:
	s_andn2_b64 vcc, exec, s[2:3]
	s_cbranch_vccnz .LBB0_161
	s_mov_b32 s2, 5
	s_ashr_i32 s3, s2, 31
	s_lshl_b64 s[2:3], s[2:3], 3
	s_add_u32 s2, s0, s2
	s_addc_u32 s3, s1, s3
	s_mov_b32 s8, 4
	s_load_dwordx2 s[2:3], s[2:3], 0x0
	s_ashr_i32 s9, s8, 31
	s_lshl_b64 s[8:9], s[8:9], 3
	s_add_u32 s8, s0, s8
	s_addc_u32 s9, s1, s9
	s_add_i32 s6, s14, 0xef80
	s_and_b32 s10, s6, 0xffff
	s_mul_i32 s10, s10, 0xaaab
	s_lshr_b32 s11, s10, 16
	s_lshr_b32 s10, s10, 22
	s_mulk_i32 s10, 0x60
	s_sub_i32 s10, s6, s10
	s_and_b32 s6, s11, 0xffc0
	s_lshl_b32 s11, s10, 7
	s_and_b32 s11, s11, 0x3ff80
	s_waitcnt lgkmcnt(0)
	s_add_u32 s2, s2, s11
	s_addc_u32 s3, s3, 0
	v_add_u32_e32 v28, s6, v45
	v_lshl_add_u64 v[30:31], s[2:3], 0, v[32:33]
	v_mad_i64_i32 v[0:1], s[2:3], v28, s27, v[30:31]
	global_load_dwordx4 v[0:3], v[0:1], off nt
	s_load_dwordx2 s[2:3], s[8:9], 0x0
	v_ashrrev_i32_e32 v29, 31, v28
	v_mov_b32_e32 v44, 1.0
	v_mov_b32_e32 v46, 1.0
	s_waitcnt lgkmcnt(0)
	s_cmp_lg_u64 s[2:3], 0
	s_cselect_b64 s[8:9], -1, 0
	s_cmp_eq_u64 s[2:3], 0
	v_lshl_add_u64 v[52:53], v[28:29], 2, s[2:3]
	s_cbranch_scc1 .LBB0_146
	global_load_dword v46, v[52:53], off nt
.LBB0_146:
	v_add_u32_e32 v4, 8, v28
	v_mad_i64_i32 v[4:5], s[2:3], v4, s27, v[30:31]
	global_load_dwordx4 v[4:7], v[4:5], off nt
	v_cndmask_b32_e64 v8, 0, 1, s[8:9]
	v_cmp_ne_u32_e64 s[2:3], 1, v8
	s_andn2_b64 vcc, exec, s[8:9]
	s_cbranch_vccnz .LBB0_148
	global_load_dword v44, v[52:53], off offset:32 nt
.LBB0_148:
	v_add_u32_e32 v8, 16, v28
	v_mad_i64_i32 v[8:9], s[8:9], v8, s27, v[30:31]
	global_load_dwordx4 v[8:11], v[8:9], off nt
	v_mov_b32_e32 v48, 1.0
	s_and_b64 vcc, exec, s[2:3]
	v_mov_b32_e32 v54, 1.0
	s_cbranch_vccnz .LBB0_150
	global_load_dword v54, v[52:53], off offset:64 nt
.LBB0_150:
	v_add_u32_e32 v12, 24, v28
	v_mad_i64_i32 v[12:13], s[8:9], v12, s27, v[30:31]
	global_load_dwordx4 v[12:15], v[12:13], off nt
	s_and_b64 vcc, exec, s[2:3]
	s_cbranch_vccnz .LBB0_152
	global_load_dword v48, v[52:53], off offset:96 nt
.LBB0_152:
	v_add_u32_e32 v16, 32, v28
	v_mad_i64_i32 v[16:17], s[8:9], v16, s27, v[30:31]
	global_load_dwordx4 v[16:19], v[16:17], off nt
	v_mov_b32_e32 v50, 1.0
	s_and_b64 vcc, exec, s[2:3]
	v_mov_b32_e32 v58, 1.0
	s_cbranch_vccnz .LBB0_154
	global_load_dword v58, v[52:53], off offset:128 nt
.LBB0_154:
	v_add_u32_e32 v20, 40, v28
	v_mad_i64_i32 v[20:21], s[8:9], v20, s27, v[30:31]
	global_load_dwordx4 v[20:23], v[20:21], off nt
	s_and_b64 vcc, exec, s[2:3]
	s_cbranch_vccnz .LBB0_156
	global_load_dword v50, v[52:53], off offset:160 nt
.LBB0_156:
	v_add_u32_e32 v24, 48, v28
	v_mad_i64_i32 v[24:25], s[8:9], v24, s27, v[30:31]
	global_load_dwordx4 v[24:27], v[24:25], off nt
	v_mov_b32_e32 v56, 1.0
	s_and_b64 vcc, exec, s[2:3]
	v_mov_b32_e32 v60, 1.0
	s_cbranch_vccnz .LBB0_158
	global_load_dword v60, v[52:53], off offset:192 nt
.LBB0_158:
	v_add_u32_e32 v28, 56, v28
	v_mad_i64_i32 v[28:29], s[8:9], v28, s27, v[30:31]
	global_load_dwordx4 v[28:31], v[28:29], off nt
	s_and_b64 vcc, exec, s[2:3]
	s_cbranch_vccnz .LBB0_160
	global_load_dword v56, v[52:53], off offset:224 nt

; __device__ __forceinline__ unsigned pk_bf16(float lo, float hi) { typedef __bf16 b2_t __attribute__((ext_vector_type(2))); f32x2 v = {lo, hi}; b2_t b = __builtin_convertvector(v, b2_t); return __builtin_bit_cast(unsigned, b); }
; #define LAS __attribute__((address_space(3)))
; __device__ __forceinline__ void transpose_tile(const float* W, const float* gain, int K, int N, int k0, int n0, bf16* WT, int drow0, LAS float* scr, int lane) {
;     f32x4 v[8]; float gv[8];
;     const int r0 = lane >> 3, c4 = lane & 7;
; #pragma unroll
;     for (int i = 0; i < 8; ++i) { v[i] = *(const f32x4*)(W + (size_t)(k0 + r0 + 8 * i) * N + n0 + 4 * c4); gv[i] = gain ? gain[k0 + r0 + 8 * i] : 1.0f; }
; #pragma unroll
;     for (int i = 0; i < 8; ++i) { LAS float* d = scr + (r0 + 8 * i) * 33 + 4 * c4; d[0] = v[i][0] * gv[i]; d[1] = v[i][1] * gv[i]; d[2] = v[i][2] * gv[i]; d[3] = v[i][3] * gv[i]; }
;     asm volatile("s_waitcnt lgkmcnt(0)" ::: "memory");
;     const int c = lane & 7;
; #pragma unroll
;     for (int j = 0; j < 4; ++j) { const int n = (lane >> 3) + 8 * j; const LAS float* s = scr + (8 * c) * 33 + n;
;         v4u o; o.x = pk_bf16(s[0 * 33], s[1 * 33]); o.y = pk_bf16(s[2 * 33], s[3 * 33]); o.z = pk_bf16(s[4 * 33], s[5 * 33]); o.w = pk_bf16(s[6 * 33], s[7 * 33]);
;         *(v4u*)(WT + (size_t)(drow0 + n) * K + k0 + 8 * c) = o; }
;     asm volatile("s_waitcnt lgkmcnt(0)" ::: "memory");
; }
.LBB0_162:
	s_andn2_b64 vcc, exec, s[2:3]
	s_cbranch_vccnz .LBB0_164
	s_mov_b32 s2, 3
	s_ashr_i32 s3, s2, 31
	s_lshl_b64 s[2:3], s[2:3], 3
	s_add_u32 s2, s0, s2
	s_addc_u32 s3, s1, s3
	s_load_dwordx2 s[2:3], s[2:3], 0x0
	s_lshl_b32 s6, s14, 5
	s_and_b32 s8, s6, 0x3e0
	s_add_i32 s6, s17, 0x1700
	s_and_b32 s6, s6, 0x1ffc0
	s_lshl_b32 s9, s8, 2
	v_add_u32_e32 v0, s6, v45
	s_waitcnt lgkmcnt(0)
	s_add_u32 s2, s2, s9
	s_addc_u32 s3, s3, 0
	v_ashrrev_i32_e32 v1, 31, v0
	v_lshl_add_u64 v[2:3], s[2:3], 0, v[32:33]
	v_lshlrev_b64 v[0:1], 12, v[0:1]
	v_lshl_add_u64 v[28:29], v[2:3], 0, v[0:1]
	v_add_co_u32_e32 v4, vcc, s20, v28
	v_add_u32_e32 v44, v47, v49
	s_nop 0
	v_addc_co_u32_e32 v5, vcc, 0, v29, vcc
	v_add_co_u32_e32 v8, vcc, s21, v28
	global_load_dwordx4 v[0:3], v[28:29], off nt
	s_nop 0
	global_load_dwordx4 v[4:7], v[4:5], off nt
	v_addc_co_u32_e32 v9, vcc, 0, v29, vcc
	v_add_co_u32_e32 v12, vcc, s22, v28
	v_add_u32_e32 v46, 0x420, v44
	s_nop 0
	v_addc_co_u32_e32 v13, vcc, 0, v29, vcc
	v_add_co_u32_e32 v16, vcc, s23, v28
	global_load_dwordx4 v[8:11], v[8:9], off nt
	s_nop 0
	global_load_dwordx4 v[12:15], v[12:13], off nt
	v_addc_co_u32_e32 v17, vcc, 0, v29, vcc
	v_add_co_u32_e32 v20, vcc, s24, v28
	v_add_u32_e32 v48, 0x428, v44
	s_nop 0
	v_addc_co_u32_e32 v21, vcc, 0, v29, vcc
	global_load_dwordx4 v[16:19], v[16:17], off nt
	s_nop 0
	global_load_dwordx4 v[20:23], v[20:21], off nt
	v_add_co_u32_e32 v24, vcc, s25, v28
	v_add_u32_e32 v50, 0x840, v44
	s_nop 0
	v_addc_co_u32_e32 v25, vcc, 0, v29, vcc
	global_load_dwordx4 v[24:27], v[24:25], off nt
	v_add_co_u32_e32 v28, vcc, s26, v28
	v_add_u32_e32 v54, 0x848, v44
	s_nop 0
	v_addc_co_u32_e32 v29, vcc, 0, v29, vcc
	global_load_dwordx4 v[28:31], v[28:29], off nt
	v_add_u32_e32 v56, 0xc60, v44
	v_add_u32_e32 v57, 0xc68, v44
	v_add_u32_e32 v58, 0x1080, v44
	v_add_u32_e32 v60, 0x1088, v44
	v_add_u32_e32 v62, 0x14a0, v44
	v_add_u32_e32 v63, 0x14a8, v44
	v_add_u32_e32 v64, 0x18c0, v44
	v_add_u32_e32 v65, 0x18c8, v44
	v_add_u32_e32 v66, 0x1ce0, v44
	v_add_u32_e32 v67, 0x1ce8, v44
	s_lshl_b32 s6, s6, 1
	v_add_u32_e32 v68, s8, v45
	v_lshl_add_u64 v[52:53], v[40:41], 0, s[6:7]
	s_waitcnt vmcnt(0)
	ds_write2_b32 v44, v0, v1 offset1:1
	ds_write2_b32 v44, v2, v3 offset0:2 offset1:3
	ds_write2_b32 v46, v4, v5 offset1:1
	ds_write2_b32 v48, v6, v7 offset1:1
	ds_write2_b32 v50, v8, v9 offset1:1
	ds_write2_b32 v54, v10, v11 offset1:1
	ds_write2_b32 v56, v12, v13 offset1:1
	ds_write2_b32 v57, v14, v15 offset1:1
	ds_write2_b32 v58, v16, v17 offset1:1
	ds_write2_b32 v60, v18, v19 offset1:1
	ds_write2_b32 v62, v20, v21 offset1:1
	ds_write2_b32 v63, v22, v23 offset1:1
	ds_write2_b32 v64, v24, v25 offset1:1
	ds_write2_b32 v65, v26, v27 offset1:1
	ds_write2_b32 v66, v28, v29 offset1:1
	ds_write2_b32 v67, v30, v31 offset1:1
	s_waitcnt lgkmcnt(0)
	ds_read2_b32 v[4:5], v61 offset0:33 offset1:41
	ds_read2_b32 v[6:7], v61 offset1:8
	ds_read2_b32 v[8:9], v61 offset0:66 offset1:74
	ds_read2_b32 v[10:11], v61 offset0:99 offset1:107
	ds_read2_b32 v[12:13], v61 offset0:132 offset1:140
	ds_read2_b32 v[14:15], v61 offset0:165 offset1:173
	ds_read2_b32 v[16:17], v61 offset0:198 offset1:206
	ds_read2_b32 v[18:19], v61 offset0:231 offset1:239
	v_mad_i64_i32 v[20:21], s[2:3], v68, s28, v[52:53]
	s_waitcnt lgkmcnt(6)
	v_cvt_pk_bf16_f32 v0, v6, v4
	s_waitcnt lgkmcnt(4)
	v_cvt_pk_bf16_f32 v1, v8, v10
	s_waitcnt lgkmcnt(2)
	v_cvt_pk_bf16_f32 v2, v12, v14
	s_waitcnt lgkmcnt(0)
	v_cvt_pk_bf16_f32 v3, v16, v18
	global_store_dwordx4 v[20:21], v[0:3], off sc1
	v_add_u32_e32 v4, s8, v51
	s_nop 0
	v_cvt_pk_bf16_f32 v0, v7, v5
	v_cvt_pk_bf16_f32 v1, v9, v11
	v_cvt_pk_bf16_f32 v2, v13, v15
	v_cvt_pk_bf16_f32 v3, v17, v19
	ds_read2_b32 v[6:7], v61 offset0:49 offset1:57
	ds_read2_b32 v[8:9], v61 offset0:16 offset1:24
	ds_read2_b32 v[10:11], v61 offset0:82 offset1:90
	ds_read2_b32 v[12:13], v61 offset0:115 offset1:123
	ds_read2_b32 v[14:15], v61 offset0:148 offset1:156
	ds_read2_b32 v[16:17], v61 offset0:181 offset1:189
	ds_read2_b32 v[18:19], v61 offset0:214 offset1:222
	ds_read2_b32 v[20:21], v61 offset0:247 offset1:255
	v_mad_i64_i32 v[4:5], s[2:3], v4, s28, v[52:53]
	global_store_dwordx4 v[4:5], v[0:3], off sc1
	v_add_u32_e32 v4, s8, v55
	v_mad_i64_i32 v[4:5], s[2:3], v4, s28, v[52:53]
	s_waitcnt lgkmcnt(6)
	v_cvt_pk_bf16_f32 v0, v8, v6
	s_waitcnt lgkmcnt(4)
	v_cvt_pk_bf16_f32 v1, v10, v12
	s_waitcnt lgkmcnt(2)
	v_cvt_pk_bf16_f32 v2, v14, v16
	s_waitcnt lgkmcnt(0)
	v_cvt_pk_bf16_f32 v3, v18, v20
	global_store_dwordx4 v[4:5], v[0:3], off sc1
	v_add_u32_e32 v4, s8, v59
	v_mad_i64_i32 v[4:5], s[2:3], v4, s28, v[52:53]
	v_cvt_pk_bf16_f32 v0, v9, v7
	v_cvt_pk_bf16_f32 v1, v11, v13
	v_cvt_pk_bf16_f32 v2, v15, v17
	v_cvt_pk_bf16_f32 v3, v19, v21
	global_store_dwordx4 v[4:5], v[0:3], off sc1
	s_waitcnt lgkmcnt(0)

; #define LAS __attribute__((address_space(3)))
; __device__ __forceinline__ void transpose_tile(const float* W, const float* gain, int K, int N, int k0, int n0, bf16* WT, int drow0, LAS float* scr, int lane) {
;     f32x4 v[8]; float gv[8];
;     const int r0 = lane >> 3, c4 = lane & 7;
; #pragma unroll
;     for (int i = 0; i < 8; ++i) { v[i] = *(const f32x4*)(W + (size_t)(k0 + r0 + 8 * i) * N + n0 + 4 * c4); gv[i] = gain ? gain[k0 + r0 + 8 * i] : 1.0f; }
; template <bool SWIGLU> __device__ __forceinline__ void transpose_item(const float* W, const float* gain, int K, int N, bf16* WT, LAS float* scr, int item, int lane) {
;     const int nblk = N / 32, kb = item / nblk, nb = item % nblk, n0 = 32 * nb;
;     int drow0 = n0;
;     if (SWIGLU) { const int up = n0 >= FF, f = up ? n0 - FF : n0; drow0 = 256 * (f >> 7) + (up ? 128 : 0) + (f & 127); }
.LBB0_165:
	s_andn2_b64 vcc, exec, s[2:3]
	s_cbranch_vccnz .LBB0_118
	s_mov_b32 s2, 2
	s_ashr_i32 s3, s2, 31
	s_lshl_b64 s[2:3], s[2:3], 3
	s_add_u32 s2, s0, s2
	s_addc_u32 s3, s1, s3
	s_mov_b32 s8, 1
	s_load_dwordx2 s[2:3], s[2:3], 0x0
	s_ashr_i32 s9, s8, 31
	s_lshl_b64 s[8:9], s[8:9], 3
	s_add_u32 s12, s0, s8
	s_mul_hi_i32 s6, s14, 0x2e8ba2e9
	s_addc_u32 s13, s1, s9
	s_lshr_b32 s8, s6, 31
	s_ashr_i32 s6, s6, 5
	s_add_i32 s6, s6, s8
	s_mul_i32 s8, s6, 0xffffea00
	s_add_i32 s10, s15, s8
	s_ashr_i32 s11, s10, 31
	s_lshl_b32 s8, s6, 6
	s_lshl_b64 s[30:31], s[10:11], 2
	s_waitcnt lgkmcnt(0)
	s_add_u32 s2, s2, s30
	s_addc_u32 s3, s3, s31
	v_add_u32_e32 v28, s8, v45
	v_lshl_add_u64 v[30:31], s[2:3], 0, v[32:33]
	v_mad_i64_i32 v[0:1], s[2:3], v28, s19, v[30:31]
	global_load_dwordx4 v[0:3], v[0:1], off nt
	s_load_dwordx2 s[2:3], s[12:13], 0x0
	v_ashrrev_i32_e32 v29, 31, v28
	v_mov_b32_e32 v44, 1.0
	v_mov_b32_e32 v46, 1.0
	s_waitcnt lgkmcnt(0)
	s_cmp_lg_u64 s[2:3], 0
	s_cselect_b64 s[12:13], -1, 0
	s_cmp_eq_u64 s[2:3], 0
	v_lshl_add_u64 v[56:57], v[28:29], 2, s[2:3]
	s_cbranch_scc1 .LBB0_168
	global_load_dword v46, v[56:57], off nt
.LBB0_168:
	v_add_u32_e32 v4, 8, v28
	v_mad_i64_i32 v[4:5], s[2:3], v4, s19, v[30:31]
	global_load_dwordx4 v[4:7], v[4:5], off nt
	v_cndmask_b32_e64 v8, 0, 1, s[12:13]
	v_cmp_ne_u32_e64 s[2:3], 1, v8
	s_andn2_b64 vcc, exec, s[12:13]
	s_cbranch_vccnz .LBB0_170
	global_load_dword v44, v[56:57], off offset:32 nt
.LBB0_170:
	v_add_u32_e32 v8, 16, v28
	v_mad_i64_i32 v[8:9], s[12:13], v8, s19, v[30:31]
	global_load_dwordx4 v[8:11], v[8:9], off nt
	v_mov_b32_e32 v48, 1.0
	s_and_b64 vcc, exec, s[2:3]
	v_mov_b32_e32 v52, 1.0
	s_cbranch_vccnz .LBB0_172
	global_load_dword v52, v[56:57], off offset:64 nt
.LBB0_172:
	v_add_u32_e32 v12, 24, v28
	v_mad_i64_i32 v[12:13], s[12:13], v12, s19, v[30:31]
	global_load_dwordx4 v[12:15], v[12:13], off nt
	s_and_b64 vcc, exec, s[2:3]
	s_cbranch_vccnz .LBB0_174
	global_load_dword v48, v[56:57], off offset:96 nt
.LBB0_174:
	v_add_u32_e32 v16, 32, v28
	v_mad_i64_i32 v[16:17], s[12:13], v16, s19, v[30:31]
	global_load_dwordx4 v[16:19], v[16:17], off nt
	v_mov_b32_e32 v50, 1.0
	s_and_b64 vcc, exec, s[2:3]
	v_mov_b32_e32 v58, 1.0
	s_cbranch_vccnz .LBB0_176
	global_load_dword v58, v[56:57], off offset:128 nt
.LBB0_176:
	v_add_u32_e32 v20, 40, v28
	v_mad_i64_i32 v[20:21], s[12:13], v20, s19, v[30:31]
	global_load_dwordx4 v[20:23], v[20:21], off nt
	s_and_b64 vcc, exec, s[2:3]
	s_cbranch_vccnz .LBB0_178
	global_load_dword v50, v[56:57], off offset:160 nt
.LBB0_178:
	v_add_u32_e32 v24, 48, v28
	v_mad_i64_i32 v[24:25], s[12:13], v24, s19, v[30:31]
	global_load_dwordx4 v[24:27], v[24:25], off nt
	v_mov_b32_e32 v54, 1.0
	s_and_b64 vcc, exec, s[2:3]
	v_mov_b32_e32 v60, 1.0
	s_cbranch_vccnz .LBB0_180
	global_load_dword v60, v[56:57], off offset:192 nt
.LBB0_180:
	v_add_u32_e32 v28, 56, v28
	v_mad_i64_i32 v[28:29], s[12:13], v28, s19, v[30:31]
	global_load_dwordx4 v[28:31], v[28:29], off nt
	s_and_b64 vcc, exec, s[2:3]
	s_cbranch_vccnz .LBB0_117
	global_load_dword v54, v[56:57], off offset:224 nt
	s_branch .LBB0_117

; __device__ __forceinline__ void transpose_tile(const float* W, const float* gain, int K, int N, int k0, int n0, bf16* WT, int drow0, LAS float* scr, int lane) {
;     ...
; #pragma unroll
;     for (int i = 0; i < 8; ++i) { v[i] = *(const f32x4*)(W + (size_t)(k0 + r0 + 8 * i) * N + n0 + 4 * c4); gv[i] = gain ? gain[k0 + r0 + 8 * i] : 1.0f; }
.LBB0_189:
	s_cmpk_gt_i32 s14, 0xaff
	s_mov_b64 s[2:3], -1
	s_cbranch_scc0 .LBB0_235
	s_cmpk_gt_u32 s14, 0x107f
	s_cbranch_scc0 .LBB0_232
	s_cmpk_gt_u32 s14, 0x167f
	s_cbranch_scc0 .LBB0_213
	s_cmpk_gt_u32 s14, 0x187f
	s_cbranch_scc0 .LBB0_210
	s_mov_b32 s2, 10
	s_ashr_i32 s3, s2, 31
	s_lshl_b64 s[2:3], s[2:3], 3
	s_add_u32 s2, s0, s2
	s_addc_u32 s3, s1, s3
	s_mov_b32 s8, 9
	s_load_dwordx2 s[2:3], s[2:3], 0x0
	s_ashr_i32 s9, s8, 31
	s_lshl_b64 s[8:9], s[8:9], 3
	s_add_u32 s8, s0, s8
	s_addc_u32 s9, s1, s9
	s_add_i32 s6, s14, 0xe780
	s_and_b32 s10, s6, 0xffff
	s_mul_i32 s10, s10, 0xba2f
	s_lshr_b32 s11, s10, 23
	s_mul_i32 s10, s11, 0xb0
	s_sub_i32 s10, s6, s10
	s_lshl_b32 s6, s11, 6
	s_lshl_b32 s11, s10, 7
	s_and_b32 s11, s11, 0x3ff80
	s_waitcnt lgkmcnt(0)
	s_add_u32 s2, s2, s11
	s_addc_u32 s3, s3, 0
	v_add_u32_e32 v28, s6, v45
	v_lshl_add_u64 v[30:31], s[2:3], 0, v[32:33]
	v_mad_i64_i32 v[0:1], s[2:3], v28, s20, v[30:31]
	global_load_dwordx4 v[0:3], v[0:1], off nt
	s_load_dwordx2 s[2:3], s[8:9], 0x0
	v_ashrrev_i32_e32 v29, 31, v28
	v_mov_b32_e32 v44, 1.0
	v_mov_b32_e32 v46, 1.0
	s_waitcnt lgkmcnt(0)
	s_cmp_lg_u64 s[2:3], 0
	s_cselect_b64 s[8:9], -1, 0
	s_cmp_eq_u64 s[2:3], 0
	v_lshl_add_u64 v[56:57], v[28:29], 2, s[2:3]
	s_cbranch_scc1 .LBB0_195
	global_load_dword v46, v[56:57], off nt
.LBB0_195:
	v_add_u32_e32 v4, 8, v28
	v_mad_i64_i32 v[4:5], s[2:3], v4, s20, v[30:31]
	global_load_dwordx4 v[4:7], v[4:5], off nt
	v_cndmask_b32_e64 v8, 0, 1, s[8:9]
	v_cmp_ne_u32_e64 s[2:3], 1, v8
	s_andn2_b64 vcc, exec, s[8:9]
	s_cbranch_vccnz .LBB0_197
	global_load_dword v44, v[56:57], off offset:32 nt
.LBB0_197:
	v_add_u32_e32 v8, 16, v28
	v_mad_i64_i32 v[8:9], s[8:9], v8, s20, v[30:31]
	global_load_dwordx4 v[8:11], v[8:9], off nt
	v_mov_b32_e32 v48, 1.0
	s_and_b64 vcc, exec, s[2:3]
	v_mov_b32_e32 v52, 1.0
	s_cbranch_vccnz .LBB0_199
	global_load_dword v52, v[56:57], off offset:64 nt
.LBB0_199:
	v_add_u32_e32 v12, 24, v28
	v_mad_i64_i32 v[12:13], s[8:9], v12, s20, v[30:31]
	global_load_dwordx4 v[12:15], v[12:13], off nt
	s_and_b64 vcc, exec, s[2:3]
	s_cbranch_vccnz .LBB0_201
	global_load_dword v48, v[56:57], off offset:96 nt
.LBB0_201:
	v_add_u32_e32 v16, 32, v28
	v_mad_i64_i32 v[16:17], s[8:9], v16, s20, v[30:31]
	global_load_dwordx4 v[16:19], v[16:17], off nt
	v_mov_b32_e32 v50, 1.0
	s_and_b64 vcc, exec, s[2:3]
	v_mov_b32_e32 v58, 1.0
	s_cbranch_vccnz .LBB0_203
	global_load_dword v58, v[56:57], off offset:128 nt
.LBB0_203:
	v_add_u32_e32 v20, 40, v28
	v_mad_i64_i32 v[20:21], s[8:9], v20, s20, v[30:31]
	global_load_dwordx4 v[20:23], v[20:21], off nt
	s_and_b64 vcc, exec, s[2:3]
	s_cbranch_vccnz .LBB0_205
	global_load_dword v50, v[56:57], off offset:160 nt
.LBB0_205:
	v_add_u32_e32 v24, 48, v28
	v_mad_i64_i32 v[24:25], s[8:9], v24, s20, v[30:31]
	global_load_dwordx4 v[24:27], v[24:25], off nt
	v_mov_b32_e32 v54, 1.0
	s_and_b64 vcc, exec, s[2:3]
	v_mov_b32_e32 v60, 1.0
	s_cbranch_vccnz .LBB0_207
	global_load_dword v60, v[56:57], off offset:192 nt
.LBB0_207:
	v_add_u32_e32 v28, 56, v28
	v_mad_i64_i32 v[28:29], s[8:9], v28, s20, v[30:31]
	global_load_dwordx4 v[28:31], v[28:29], off nt
	s_and_b64 vcc, exec, s[2:3]
	s_lshl_b32 s2, s10, 5
	s_cbranch_vccnz .LBB0_209
	global_load_dword v54, v[56:57], off offset:224 nt

; __device__ __forceinline__ unsigned pk_bf16(float lo, float hi) { typedef __bf16 b2_t __attribute__((ext_vector_type(2))); f32x2 v = {lo, hi}; b2_t b = __builtin_convertvector(v, b2_t); return __builtin_bit_cast(unsigned, b); }
; #define LAS __attribute__((address_space(3)))
; __device__ __forceinline__ void transpose_tile(const float* W, const float* gain, int K, int N, int k0, int n0, bf16* WT, int drow0, LAS float* scr, int lane) {
;     f32x4 v[8]; float gv[8];
;     const int r0 = lane >> 3, c4 = lane & 7;
; #pragma unroll
;     for (int i = 0; i < 8; ++i) { v[i] = *(const f32x4*)(W + (size_t)(k0 + r0 + 8 * i) * N + n0 + 4 * c4); gv[i] = gain ? gain[k0 + r0 + 8 * i] : 1.0f; }
; #pragma unroll
;     for (int i = 0; i < 8; ++i) { LAS float* d = scr + (r0 + 8 * i) * 33 + 4 * c4; d[0] = v[i][0] * gv[i]; d[1] = v[i][1] * gv[i]; d[2] = v[i][2] * gv[i]; d[3] = v[i][3] * gv[i]; }
;     asm volatile("s_waitcnt lgkmcnt(0)" ::: "memory");
;     const int c = lane & 7;
; #pragma unroll
;     for (int j = 0; j < 4; ++j) { const int n = (lane >> 3) + 8 * j; const LAS float* s = scr + (8 * c) * 33 + n;
;         v4u o; o.x = pk_bf16(s[0 * 33], s[1 * 33]); o.y = pk_bf16(s[2 * 33], s[3 * 33]); o.z = pk_bf16(s[4 * 33], s[5 * 33]); o.w = pk_bf16(s[6 * 33], s[7 * 33]);
;         *(v4u*)(WT + (size_t)(drow0 + n) * K + k0 + 8 * c) = o; }
;     asm volatile("s_waitcnt lgkmcnt(0)" ::: "memory");
; }
.LBB0_210:
	s_and_b64 vcc, exec, s[2:3]
	s_cbranch_vccz .LBB0_212
	s_mov_b32 s2, 8
	s_ashr_i32 s3, s2, 31
	s_lshl_b64 s[2:3], s[2:3], 3
	s_add_u32 s2, s0, s2
	s_addc_u32 s3, s1, s3
	s_load_dwordx2 s[2:3], s[2:3], 0x0
	s_lshl_b32 s6, s14, 5
	s_and_b32 s8, s6, 0x3e0
	s_and_b32 s6, s18, 0x1ffc0
	s_lshl_b32 s9, s8, 2
	v_add_u32_e32 v0, s6, v45
	s_waitcnt lgkmcnt(0)
	s_add_u32 s2, s2, s9
	s_addc_u32 s3, s3, 0
	v_ashrrev_i32_e32 v1, 31, v0
	v_lshl_add_u64 v[2:3], s[2:3], 0, v[32:33]
	v_lshlrev_b64 v[0:1], 12, v[0:1]
	v_lshl_add_u64 v[28:29], v[2:3], 0, v[0:1]
	v_add_co_u32_e32 v4, vcc, s21, v28
	v_add_u32_e32 v44, v47, v49
	s_nop 0
	v_addc_co_u32_e32 v5, vcc, 0, v29, vcc
	v_add_co_u32_e32 v8, vcc, s22, v28
	global_load_dwordx4 v[0:3], v[28:29], off nt
	s_nop 0
	global_load_dwordx4 v[4:7], v[4:5], off nt
	v_addc_co_u32_e32 v9, vcc, 0, v29, vcc
	v_add_co_u32_e32 v12, vcc, s23, v28
	v_add_u32_e32 v46, 0x420, v44
	s_nop 0
	v_addc_co_u32_e32 v13, vcc, 0, v29, vcc
	v_add_co_u32_e32 v16, vcc, s24, v28
	global_load_dwordx4 v[8:11], v[8:9], off nt
	s_nop 0
	global_load_dwordx4 v[12:15], v[12:13], off nt
	v_addc_co_u32_e32 v17, vcc, 0, v29, vcc
	v_add_co_u32_e32 v20, vcc, s25, v28
	v_add_u32_e32 v48, 0x428, v44
	s_nop 0
	v_addc_co_u32_e32 v21, vcc, 0, v29, vcc
	global_load_dwordx4 v[16:19], v[16:17], off nt
	s_nop 0
	global_load_dwordx4 v[20:23], v[20:21], off nt
	v_add_co_u32_e32 v24, vcc, s26, v28
	v_add_u32_e32 v50, 0x840, v44
	s_nop 0
	v_addc_co_u32_e32 v25, vcc, 0, v29, vcc
	global_load_dwordx4 v[24:27], v[24:25], off nt
	v_add_co_u32_e32 v28, vcc, s27, v28
	v_add_u32_e32 v54, 0x848, v44
	s_nop 0
	v_addc_co_u32_e32 v29, vcc, 0, v29, vcc
	global_load_dwordx4 v[28:31], v[28:29], off nt
	v_add_u32_e32 v58, 0xc60, v44
	v_add_u32_e32 v60, 0xc68, v44
	v_add_u32_e32 v62, 0x1080, v44
	v_add_u32_e32 v63, 0x1088, v44
	v_add_u32_e32 v64, 0x14a0, v44
	v_add_u32_e32 v65, 0x14a8, v44
	v_add_u32_e32 v66, 0x18c0, v44
	v_add_u32_e32 v67, 0x18c8, v44
	v_add_u32_e32 v68, 0x1ce0, v44
	v_add_u32_e32 v69, 0x1ce8, v44
	v_add_u32_e32 v52, s8, v45
	v_ashrrev_i32_e32 v53, 31, v52
	s_lshl_b32 s6, s6, 1
	v_lshlrev_b64 v[52:53], 11, v[52:53]
	v_lshl_add_u64 v[56:57], v[36:37], 0, s[6:7]
	s_waitcnt vmcnt(0)
	ds_write2_b32 v44, v0, v1 offset1:1
	ds_write2_b32 v44, v2, v3 offset0:2 offset1:3
	ds_write2_b32 v46, v4, v5 offset1:1
	ds_write2_b32 v48, v6, v7 offset1:1
	ds_write2_b32 v50, v8, v9 offset1:1
	ds_write2_b32 v54, v10, v11 offset1:1
	ds_write2_b32 v58, v12, v13 offset1:1
	ds_write2_b32 v60, v14, v15 offset1:1
	ds_write2_b32 v62, v16, v17 offset1:1
	ds_write2_b32 v63, v18, v19 offset1:1
	ds_write2_b32 v64, v20, v21 offset1:1
	ds_write2_b32 v65, v22, v23 offset1:1
	ds_write2_b32 v66, v24, v25 offset1:1
	ds_write2_b32 v67, v26, v27 offset1:1
	ds_write2_b32 v68, v28, v29 offset1:1
	ds_write2_b32 v69, v30, v31 offset1:1
	s_waitcnt lgkmcnt(0)
	ds_read2_b32 v[4:5], v61 offset0:33 offset1:41
	ds_read2_b32 v[6:7], v61 offset1:8
	ds_read2_b32 v[8:9], v61 offset0:66 offset1:74
	ds_read2_b32 v[10:11], v61 offset0:99 offset1:107
	ds_read2_b32 v[12:13], v61 offset0:132 offset1:140
	ds_read2_b32 v[14:15], v61 offset0:165 offset1:173
	ds_read2_b32 v[16:17], v61 offset0:198 offset1:206
	ds_read2_b32 v[18:19], v61 offset0:231 offset1:239
	v_lshl_add_u64 v[20:21], v[56:57], 0, v[52:53]
	s_waitcnt lgkmcnt(6)
	v_cvt_pk_bf16_f32 v0, v6, v4
	s_waitcnt lgkmcnt(4)
	v_cvt_pk_bf16_f32 v1, v8, v10
	s_waitcnt lgkmcnt(2)
	v_cvt_pk_bf16_f32 v2, v12, v14
	s_waitcnt lgkmcnt(0)
	v_cvt_pk_bf16_f32 v3, v16, v18
	v_add_u32_e32 v4, s8, v51
	global_store_dwordx4 v[20:21], v[0:3], off sc1
	s_nop 1
	v_cvt_pk_bf16_f32 v0, v7, v5
	v_ashrrev_i32_e32 v5, 31, v4
	v_cvt_pk_bf16_f32 v1, v9, v11
	v_cvt_pk_bf16_f32 v2, v13, v15
	v_cvt_pk_bf16_f32 v3, v17, v19
	v_lshlrev_b64 v[4:5], 11, v[4:5]
	ds_read2_b32 v[6:7], v61 offset0:49 offset1:57
	ds_read2_b32 v[8:9], v61 offset0:16 offset1:24
	ds_read2_b32 v[10:11], v61 offset0:82 offset1:90
	ds_read2_b32 v[12:13], v61 offset0:115 offset1:123
	ds_read2_b32 v[14:15], v61 offset0:148 offset1:156
	ds_read2_b32 v[16:17], v61 offset0:181 offset1:189
	ds_read2_b32 v[18:19], v61 offset0:214 offset1:222
	ds_read2_b32 v[20:21], v61 offset0:247 offset1:255
	v_lshl_add_u64 v[4:5], v[56:57], 0, v[4:5]
	global_store_dwordx4 v[4:5], v[0:3], off sc1
	v_add_u32_e32 v4, s8, v55
	v_ashrrev_i32_e32 v5, 31, v4
	v_lshlrev_b64 v[4:5], 11, v[4:5]
	s_waitcnt lgkmcnt(6)
	v_cvt_pk_bf16_f32 v0, v8, v6
	s_waitcnt lgkmcnt(4)
	v_cvt_pk_bf16_f32 v1, v10, v12
	s_waitcnt lgkmcnt(2)
	v_cvt_pk_bf16_f32 v2, v14, v16
	s_waitcnt lgkmcnt(0)
	v_cvt_pk_bf16_f32 v3, v18, v20
	v_lshl_add_u64 v[4:5], v[56:57], 0, v[4:5]
	global_store_dwordx4 v[4:5], v[0:3], off sc1
	v_add_u32_e32 v4, s8, v59
	v_ashrrev_i32_e32 v5, 31, v4
	v_lshlrev_b64 v[4:5], 11, v[4:5]
	v_cvt_pk_bf16_f32 v0, v9, v7
	v_cvt_pk_bf16_f32 v1, v11, v13
	v_cvt_pk_bf16_f32 v2, v15, v17
	v_cvt_pk_bf16_f32 v3, v19, v21
	v_lshl_add_u64 v[4:5], v[56:57], 0, v[4:5]
	global_store_dwordx4 v[4:5], v[0:3], off sc1
	s_waitcnt lgkmcnt(0)

; #define LAS __attribute__((address_space(3)))
; __device__ __forceinline__ void transpose_tile(const float* W, const float* gain, int K, int N, int k0, int n0, bf16* WT, int drow0, LAS float* scr, int lane) {
;     f32x4 v[8]; float gv[8];
;     const int r0 = lane >> 3, c4 = lane & 7;
; #pragma unroll
;     for (int i = 0; i < 8; ++i) { v[i] = *(const f32x4*)(W + (size_t)(k0 + r0 + 8 * i) * N + n0 + 4 * c4); gv[i] = gain ? gain[k0 + r0 + 8 * i] : 1.0f; }
; template <bool SWIGLU> __device__ __forceinline__ void transpose_item(const float* W, const float* gain, int K, int N, bf16* WT, LAS float* scr, int item, int lane) {
;     const int nblk = N / 32, kb = item / nblk, nb = item % nblk, n0 = 32 * nb;
;     int drow0 = n0;
;     if (SWIGLU) { const int up = n0 >= FF, f = up ? n0 - FF : n0; drow0 = 256 * (f >> 7) + (up ? 128 : 0) + (f & 127); }
.LBB0_213:
	s_andn2_b64 vcc, exec, s[2:3]
	s_cbranch_vccnz .LBB0_231
	s_mov_b32 s2, 5
	s_ashr_i32 s3, s2, 31
	s_lshl_b64 s[2:3], s[2:3], 3
	s_add_u32 s2, s0, s2
	s_addc_u32 s3, s1, s3
	s_mov_b32 s8, 4
	s_load_dwordx2 s[2:3], s[2:3], 0x0
	s_ashr_i32 s9, s8, 31
	s_lshl_b64 s[8:9], s[8:9], 3
	s_add_u32 s8, s0, s8
	s_addc_u32 s9, s1, s9
	s_add_i32 s6, s14, 0xef80
	s_and_b32 s10, s6, 0xffff
	s_mul_i32 s10, s10, 0xaaab
	s_lshr_b32 s11, s10, 16
	s_lshr_b32 s10, s10, 22
	s_mulk_i32 s10, 0x60
	s_sub_i32 s10, s6, s10
	s_and_b32 s6, s11, 0xffc0
	s_lshl_b32 s11, s10, 7
	s_and_b32 s11, s11, 0x3ff80
	s_waitcnt lgkmcnt(0)
	s_add_u32 s2, s2, s11
	s_addc_u32 s3, s3, 0
	v_add_u32_e32 v28, s6, v45
	v_lshl_add_u64 v[30:31], s[2:3], 0, v[32:33]
	v_mad_i64_i32 v[0:1], s[2:3], v28, s28, v[30:31]
	global_load_dwordx4 v[0:3], v[0:1], off nt
	s_load_dwordx2 s[2:3], s[8:9], 0x0
	v_ashrrev_i32_e32 v29, 31, v28
	v_mov_b32_e32 v44, 1.0
	v_mov_b32_e32 v46, 1.0
	s_waitcnt lgkmcnt(0)
	s_cmp_lg_u64 s[2:3], 0
	s_cselect_b64 s[8:9], -1, 0
	s_cmp_eq_u64 s[2:3], 0
	v_lshl_add_u64 v[52:53], v[28:29], 2, s[2:3]
	s_cbranch_scc1 .LBB0_216
	global_load_dword v46, v[52:53], off nt
.LBB0_216:
	v_add_u32_e32 v4, 8, v28
	v_mad_i64_i32 v[4:5], s[2:3], v4, s28, v[30:31]
	global_load_dwordx4 v[4:7], v[4:5], off nt
	v_cndmask_b32_e64 v8, 0, 1, s[8:9]
	v_cmp_ne_u32_e64 s[2:3], 1, v8
	s_andn2_b64 vcc, exec, s[8:9]
	s_cbranch_vccnz .LBB0_218
	global_load_dword v44, v[52:53], off offset:32 nt
.LBB0_218:
	v_add_u32_e32 v8, 16, v28
	v_mad_i64_i32 v[8:9], s[8:9], v8, s28, v[30:31]
	global_load_dwordx4 v[8:11], v[8:9], off nt
	v_mov_b32_e32 v48, 1.0
	s_and_b64 vcc, exec, s[2:3]
	v_mov_b32_e32 v54, 1.0
	s_cbranch_vccnz .LBB0_220
	global_load_dword v54, v[52:53], off offset:64 nt
.LBB0_220:
	v_add_u32_e32 v12, 24, v28
	v_mad_i64_i32 v[12:13], s[8:9], v12, s28, v[30:31]
	global_load_dwordx4 v[12:15], v[12:13], off nt
	s_and_b64 vcc, exec, s[2:3]
	s_cbranch_vccnz .LBB0_222
	global_load_dword v48, v[52:53], off offset:96 nt
.LBB0_222:
	v_add_u32_e32 v16, 32, v28
	v_mad_i64_i32 v[16:17], s[8:9], v16, s28, v[30:31]
	global_load_dwordx4 v[16:19], v[16:17], off nt
	v_mov_b32_e32 v50, 1.0
	s_and_b64 vcc, exec, s[2:3]
	v_mov_b32_e32 v58, 1.0
	s_cbranch_vccnz .LBB0_224
	global_load_dword v58, v[52:53], off offset:128 nt
.LBB0_224:
	v_add_u32_e32 v20, 40, v28
	v_mad_i64_i32 v[20:21], s[8:9], v20, s28, v[30:31]
	global_load_dwordx4 v[20:23], v[20:21], off nt
	s_and_b64 vcc, exec, s[2:3]
	s_cbranch_vccnz .LBB0_226
	global_load_dword v50, v[52:53], off offset:160 nt
.LBB0_226:
	v_add_u32_e32 v24, 48, v28
	v_mad_i64_i32 v[24:25], s[8:9], v24, s28, v[30:31]
	global_load_dwordx4 v[24:27], v[24:25], off nt
	v_mov_b32_e32 v56, 1.0
	s_and_b64 vcc, exec, s[2:3]
	v_mov_b32_e32 v60, 1.0
	s_cbranch_vccnz .LBB0_228
	global_load_dword v60, v[52:53], off offset:192 nt
.LBB0_228:
	v_add_u32_e32 v28, 56, v28
	v_mad_i64_i32 v[28:29], s[8:9], v28, s28, v[30:31]
	global_load_dwordx4 v[28:31], v[28:29], off nt
	s_and_b64 vcc, exec, s[2:3]
	s_cbranch_vccnz .LBB0_230
	global_load_dword v56, v[52:53], off offset:224 nt

; __device__ __forceinline__ unsigned pk_bf16(float lo, float hi) { typedef __bf16 b2_t __attribute__((ext_vector_type(2))); f32x2 v = {lo, hi}; b2_t b = __builtin_convertvector(v, b2_t); return __builtin_bit_cast(unsigned, b); }
; #define LAS __attribute__((address_space(3)))
; __device__ __forceinline__ void transpose_tile(const float* W, const float* gain, int K, int N, int k0, int n0, bf16* WT, int drow0, LAS float* scr, int lane) {
;     f32x4 v[8]; float gv[8];
;     const int r0 = lane >> 3, c4 = lane & 7;
; #pragma unroll
;     for (int i = 0; i < 8; ++i) { v[i] = *(const f32x4*)(W + (size_t)(k0 + r0 + 8 * i) * N + n0 + 4 * c4); gv[i] = gain ? gain[k0 + r0 + 8 * i] : 1.0f; }
; #pragma unroll
;     for (int i = 0; i < 8; ++i) { LAS float* d = scr + (r0 + 8 * i) * 33 + 4 * c4; d[0] = v[i][0] * gv[i]; d[1] = v[i][1] * gv[i]; d[2] = v[i][2] * gv[i]; d[3] = v[i][3] * gv[i]; }
;     asm volatile("s_waitcnt lgkmcnt(0)" ::: "memory");
;     const int c = lane & 7;
; #pragma unroll
;     for (int j = 0; j < 4; ++j) { const int n = (lane >> 3) + 8 * j; const LAS float* s = scr + (8 * c) * 33 + n;
;         v4u o; o.x = pk_bf16(s[0 * 33], s[1 * 33]); o.y = pk_bf16(s[2 * 33], s[3 * 33]); o.z = pk_bf16(s[4 * 33], s[5 * 33]); o.w = pk_bf16(s[6 * 33], s[7 * 33]);
;         *(v4u*)(WT + (size_t)(drow0 + n) * K + k0 + 8 * c) = o; }
;     asm volatile("s_waitcnt lgkmcnt(0)" ::: "memory");
; }
.LBB0_232:
	s_andn2_b64 vcc, exec, s[2:3]
	s_cbranch_vccnz .LBB0_234
	s_mov_b32 s2, 3
	s_ashr_i32 s3, s2, 31
	s_lshl_b64 s[2:3], s[2:3], 3
	s_add_u32 s2, s0, s2
	s_addc_u32 s3, s1, s3
	s_load_dwordx2 s[2:3], s[2:3], 0x0
	s_lshl_b32 s6, s14, 5
	s_and_b32 s8, s6, 0x3e0
	s_add_i32 s6, s18, 0x1700
	s_and_b32 s6, s6, 0x1ffc0
	s_lshl_b32 s9, s8, 2
	v_add_u32_e32 v0, s6, v45
	s_waitcnt lgkmcnt(0)
	s_add_u32 s2, s2, s9
	s_addc_u32 s3, s3, 0
	v_ashrrev_i32_e32 v1, 31, v0
	v_lshl_add_u64 v[2:3], s[2:3], 0, v[32:33]
	v_lshlrev_b64 v[0:1], 12, v[0:1]
	v_lshl_add_u64 v[28:29], v[2:3], 0, v[0:1]
	v_add_co_u32_e32 v4, vcc, s21, v28
	v_add_u32_e32 v44, v47, v49
	s_nop 0
	v_addc_co_u32_e32 v5, vcc, 0, v29, vcc
	v_add_co_u32_e32 v8, vcc, s22, v28
	global_load_dwordx4 v[0:3], v[28:29], off nt
	s_nop 0
	global_load_dwordx4 v[4:7], v[4:5], off nt
	v_addc_co_u32_e32 v9, vcc, 0, v29, vcc
	v_add_co_u32_e32 v12, vcc, s23, v28
	v_add_u32_e32 v46, 0x420, v44
	s_nop 0
	v_addc_co_u32_e32 v13, vcc, 0, v29, vcc
	v_add_co_u32_e32 v16, vcc, s24, v28
	global_load_dwordx4 v[8:11], v[8:9], off nt
	s_nop 0
	global_load_dwordx4 v[12:15], v[12:13], off nt
	v_addc_co_u32_e32 v17, vcc, 0, v29, vcc
	v_add_co_u32_e32 v20, vcc, s25, v28
	v_add_u32_e32 v48, 0x428, v44
	s_nop 0
	v_addc_co_u32_e32 v21, vcc, 0, v29, vcc
	global_load_dwordx4 v[16:19], v[16:17], off nt
	s_nop 0
	global_load_dwordx4 v[20:23], v[20:21], off nt
	v_add_co_u32_e32 v24, vcc, s26, v28
	v_add_u32_e32 v50, 0x840, v44
	s_nop 0
	v_addc_co_u32_e32 v25, vcc, 0, v29, vcc
	global_load_dwordx4 v[24:27], v[24:25], off nt
	v_add_co_u32_e32 v28, vcc, s27, v28
	v_add_u32_e32 v54, 0x848, v44
	s_nop 0
	v_addc_co_u32_e32 v29, vcc, 0, v29, vcc
	global_load_dwordx4 v[28:31], v[28:29], off nt
	v_add_u32_e32 v56, 0xc60, v44
	v_add_u32_e32 v57, 0xc68, v44
	v_add_u32_e32 v58, 0x1080, v44
	v_add_u32_e32 v60, 0x1088, v44
	v_add_u32_e32 v62, 0x14a0, v44
	v_add_u32_e32 v63, 0x14a8, v44
	v_add_u32_e32 v64, 0x18c0, v44
	v_add_u32_e32 v65, 0x18c8, v44
	v_add_u32_e32 v66, 0x1ce0, v44
	v_add_u32_e32 v67, 0x1ce8, v44
	s_lshl_b32 s6, s6, 1
	v_add_u32_e32 v68, s8, v45
	v_lshl_add_u64 v[52:53], v[40:41], 0, s[6:7]
	s_waitcnt vmcnt(0)
	ds_write2_b32 v44, v0, v1 offset1:1
	ds_write2_b32 v44, v2, v3 offset0:2 offset1:3
	ds_write2_b32 v46, v4, v5 offset1:1
	ds_write2_b32 v48, v6, v7 offset1:1
	ds_write2_b32 v50, v8, v9 offset1:1
	ds_write2_b32 v54, v10, v11 offset1:1
	ds_write2_b32 v56, v12, v13 offset1:1
	ds_write2_b32 v57, v14, v15 offset1:1
	ds_write2_b32 v58, v16, v17 offset1:1
	ds_write2_b32 v60, v18, v19 offset1:1
	ds_write2_b32 v62, v20, v21 offset1:1
	ds_write2_b32 v63, v22, v23 offset1:1
	ds_write2_b32 v64, v24, v25 offset1:1
	ds_write2_b32 v65, v26, v27 offset1:1
	ds_write2_b32 v66, v28, v29 offset1:1
	ds_write2_b32 v67, v30, v31 offset1:1
	s_waitcnt lgkmcnt(0)
	ds_read2_b32 v[4:5], v61 offset0:33 offset1:41
	ds_read2_b32 v[6:7], v61 offset1:8
	ds_read2_b32 v[8:9], v61 offset0:66 offset1:74
	ds_read2_b32 v[10:11], v61 offset0:99 offset1:107
	ds_read2_b32 v[12:13], v61 offset0:132 offset1:140
	ds_read2_b32 v[14:15], v61 offset0:165 offset1:173
	ds_read2_b32 v[16:17], v61 offset0:198 offset1:206
	ds_read2_b32 v[18:19], v61 offset0:231 offset1:239
	v_mad_i64_i32 v[20:21], s[2:3], v68, s29, v[52:53]
	s_waitcnt lgkmcnt(6)
	v_cvt_pk_bf16_f32 v0, v6, v4
	s_waitcnt lgkmcnt(4)
	v_cvt_pk_bf16_f32 v1, v8, v10
	s_waitcnt lgkmcnt(2)
	v_cvt_pk_bf16_f32 v2, v12, v14
	s_waitcnt lgkmcnt(0)
	v_cvt_pk_bf16_f32 v3, v16, v18
	global_store_dwordx4 v[20:21], v[0:3], off sc1
	v_add_u32_e32 v4, s8, v51
	s_nop 0
	v_cvt_pk_bf16_f32 v0, v7, v5
	v_cvt_pk_bf16_f32 v1, v9, v11
	v_cvt_pk_bf16_f32 v2, v13, v15
	v_cvt_pk_bf16_f32 v3, v17, v19
	ds_read2_b32 v[6:7], v61 offset0:49 offset1:57
	ds_read2_b32 v[8:9], v61 offset0:16 offset1:24
	ds_read2_b32 v[10:11], v61 offset0:82 offset1:90
	ds_read2_b32 v[12:13], v61 offset0:115 offset1:123
	ds_read2_b32 v[14:15], v61 offset0:148 offset1:156
	ds_read2_b32 v[16:17], v61 offset0:181 offset1:189
	ds_read2_b32 v[18:19], v61 offset0:214 offset1:222
	ds_read2_b32 v[20:21], v61 offset0:247 offset1:255
	v_mad_i64_i32 v[4:5], s[2:3], v4, s29, v[52:53]
	global_store_dwordx4 v[4:5], v[0:3], off sc1
	v_add_u32_e32 v4, s8, v55
	v_mad_i64_i32 v[4:5], s[2:3], v4, s29, v[52:53]
	s_waitcnt lgkmcnt(6)
	v_cvt_pk_bf16_f32 v0, v8, v6
	s_waitcnt lgkmcnt(4)
	v_cvt_pk_bf16_f32 v1, v10, v12
	s_waitcnt lgkmcnt(2)
	v_cvt_pk_bf16_f32 v2, v14, v16
	s_waitcnt lgkmcnt(0)
	v_cvt_pk_bf16_f32 v3, v18, v20
	global_store_dwordx4 v[4:5], v[0:3], off sc1
	v_add_u32_e32 v4, s8, v59
	v_mad_i64_i32 v[4:5], s[2:3], v4, s29, v[52:53]
	v_cvt_pk_bf16_f32 v0, v9, v7
	v_cvt_pk_bf16_f32 v1, v11, v13
	v_cvt_pk_bf16_f32 v2, v15, v17
	v_cvt_pk_bf16_f32 v3, v19, v21
	global_store_dwordx4 v[4:5], v[0:3], off sc1
	s_waitcnt lgkmcnt(0)

; #define LAS __attribute__((address_space(3)))
; __device__ __forceinline__ void transpose_tile(const float* W, const float* gain, int K, int N, int k0, int n0, bf16* WT, int drow0, LAS float* scr, int lane) {
;     f32x4 v[8]; float gv[8];
;     const int r0 = lane >> 3, c4 = lane & 7;
; #pragma unroll
;     for (int i = 0; i < 8; ++i) { v[i] = *(const f32x4*)(W + (size_t)(k0 + r0 + 8 * i) * N + n0 + 4 * c4); gv[i] = gain ? gain[k0 + r0 + 8 * i] : 1.0f; }
; template <bool SWIGLU> __device__ __forceinline__ void transpose_item(const float* W, const float* gain, int K, int N, bf16* WT, LAS float* scr, int item, int lane) {
;     const int nblk = N / 32, kb = item / nblk, nb = item % nblk, n0 = 32 * nb;
;     int drow0 = n0;
;     if (SWIGLU) { const int up = n0 >= FF, f = up ? n0 - FF : n0; drow0 = 256 * (f >> 7) + (up ? 128 : 0) + (f & 127); }
.LBB0_235:
	s_andn2_b64 vcc, exec, s[2:3]
	s_cbranch_vccnz .LBB0_188
	s_mov_b32 s2, 2
	s_ashr_i32 s3, s2, 31
	s_lshl_b64 s[2:3], s[2:3], 3
	s_add_u32 s2, s0, s2
	s_addc_u32 s3, s1, s3
	s_mov_b32 s8, 1
	s_load_dwordx2 s[2:3], s[2:3], 0x0
	s_ashr_i32 s9, s8, 31
	s_lshl_b64 s[8:9], s[8:9], 3
	s_add_u32 s12, s0, s8
	s_mul_hi_i32 s6, s14, 0x2e8ba2e9
	s_addc_u32 s13, s1, s9
	s_lshr_b32 s8, s6, 31
	s_ashr_i32 s6, s6, 5
	s_add_i32 s6, s6, s8
	s_mul_i32 s8, s6, 0xffffea00
	s_add_i32 s10, s16, s8
	s_ashr_i32 s11, s10, 31
	s_lshl_b32 s8, s6, 6
	s_lshl_b64 s[30:31], s[10:11], 2
	s_waitcnt lgkmcnt(0)
	s_add_u32 s2, s2, s30
	s_addc_u32 s3, s3, s31
	v_add_u32_e32 v28, s8, v45
	v_lshl_add_u64 v[30:31], s[2:3], 0, v[32:33]
	v_mad_i64_i32 v[0:1], s[2:3], v28, s20, v[30:31]
	global_load_dwordx4 v[0:3], v[0:1], off nt
	s_load_dwordx2 s[2:3], s[12:13], 0x0
	v_ashrrev_i32_e32 v29, 31, v28
	v_mov_b32_e32 v44, 1.0
	v_mov_b32_e32 v46, 1.0
	s_waitcnt lgkmcnt(0)
	s_cmp_lg_u64 s[2:3], 0
	s_cselect_b64 s[12:13], -1, 0
	s_cmp_eq_u64 s[2:3], 0
	v_lshl_add_u64 v[56:57], v[28:29], 2, s[2:3]
	s_cbranch_scc1 .LBB0_238
	global_load_dword v46, v[56:57], off nt
.LBB0_238:
	v_add_u32_e32 v4, 8, v28
	v_mad_i64_i32 v[4:5], s[2:3], v4, s20, v[30:31]
	global_load_dwordx4 v[4:7], v[4:5], off nt
	v_cndmask_b32_e64 v8, 0, 1, s[12:13]
	v_cmp_ne_u32_e64 s[2:3], 1, v8
	s_andn2_b64 vcc, exec, s[12:13]
	s_cbranch_vccnz .LBB0_240
	global_load_dword v44, v[56:57], off offset:32 nt
.LBB0_240:
	v_add_u32_e32 v8, 16, v28
	v_mad_i64_i32 v[8:9], s[12:13], v8, s20, v[30:31]
	global_load_dwordx4 v[8:11], v[8:9], off nt
	v_mov_b32_e32 v48, 1.0
	s_and_b64 vcc, exec, s[2:3]
	v_mov_b32_e32 v52, 1.0
	s_cbranch_vccnz .LBB0_242
	global_load_dword v52, v[56:57], off offset:64 nt
.LBB0_242:
	v_add_u32_e32 v12, 24, v28
	v_mad_i64_i32 v[12:13], s[12:13], v12, s20, v[30:31]
	global_load_dwordx4 v[12:15], v[12:13], off nt
	s_and_b64 vcc, exec, s[2:3]
	s_cbranch_vccnz .LBB0_244
	global_load_dword v48, v[56:57], off offset:96 nt
.LBB0_244:
	v_add_u32_e32 v16, 32, v28
	v_mad_i64_i32 v[16:17], s[12:13], v16, s20, v[30:31]
	global_load_dwordx4 v[16:19], v[16:17], off nt
	v_mov_b32_e32 v50, 1.0
	s_and_b64 vcc, exec, s[2:3]
	v_mov_b32_e32 v58, 1.0
	s_cbranch_vccnz .LBB0_246
	global_load_dword v58, v[56:57], off offset:128 nt
.LBB0_246:
	v_add_u32_e32 v20, 40, v28
	v_mad_i64_i32 v[20:21], s[12:13], v20, s20, v[30:31]
	global_load_dwordx4 v[20:23], v[20:21], off nt
	s_and_b64 vcc, exec, s[2:3]
	s_cbranch_vccnz .LBB0_248
	global_load_dword v50, v[56:57], off offset:160 nt
.LBB0_248:
	v_add_u32_e32 v24, 48, v28
	v_mad_i64_i32 v[24:25], s[12:13], v24, s20, v[30:31]
	global_load_dwordx4 v[24:27], v[24:25], off nt
	v_mov_b32_e32 v54, 1.0
	s_and_b64 vcc, exec, s[2:3]
	v_mov_b32_e32 v60, 1.0
	s_cbranch_vccnz .LBB0_250
	global_load_dword v60, v[56:57], off offset:192 nt
.LBB0_250:
	v_add_u32_e32 v28, 56, v28
	v_mad_i64_i32 v[28:29], s[12:13], v28, s20, v[30:31]
	global_load_dwordx4 v[28:31], v[28:29], off nt
	s_and_b64 vcc, exec, s[2:3]
	s_cbranch_vccnz .LBB0_187
	global_load_dword v54, v[56:57], off offset:224 nt
	s_branch .LBB0_187

; __device__ __forceinline__ unsigned pk_bf16(float lo, float hi) { typedef __bf16 b2_t __attribute__((ext_vector_type(2))); f32x2 v = {lo, hi}; b2_t b = __builtin_convertvector(v, b2_t); return __builtin_bit_cast(unsigned, b); }
; #define LAS __attribute__((address_space(3)))
; __device__ __forceinline__ void transpose_tile(const float* W, const float* gain, int K, int N, int k0, int n0, bf16* WT, int drow0, LAS float* scr, int lane) {
;     f32x4 v[8]; float gv[8];
;     const int r0 = lane >> 3, c4 = lane & 7;
; #pragma unroll
;     for (int i = 0; i < 8; ++i) { v[i] = *(const f32x4*)(W + (size_t)(k0 + r0 + 8 * i) * N + n0 + 4 * c4); gv[i] = gain ? gain[k0 + r0 + 8 * i] : 1.0f; }
; #pragma unroll
;     for (int i = 0; i < 8; ++i) { LAS float* d = scr + (r0 + 8 * i) * 33 + 4 * c4; d[0] = v[i][0] * gv[i]; d[1] = v[i][1] * gv[i]; d[2] = v[i][2] * gv[i]; d[3] = v[i][3] * gv[i]; }
;     asm volatile("s_waitcnt lgkmcnt(0)" ::: "memory");
;     const int c = lane & 7;
; #pragma unroll
;     for (int j = 0; j < 4; ++j) { const int n = (lane >> 3) + 8 * j; const LAS float* s = scr + (8 * c) * 33 + n;
;         v4u o; o.x = pk_bf16(s[0 * 33], s[1 * 33]); o.y = pk_bf16(s[2 * 33], s[3 * 33]); o.z = pk_bf16(s[4 * 33], s[5 * 33]); o.w = pk_bf16(s[6 * 33], s[7 * 33]);
;         *(v4u*)(WT + (size_t)(drow0 + n) * K + k0 + 8 * c) = o; }
;     asm volatile("s_waitcnt lgkmcnt(0)" ::: "memory");
; }
.LBB0_923:
	s_cmpk_gt_i32 s22, 0xaff
	s_mov_b64 s[8:9], -1
	s_cbranch_scc0 .LBB0_997
	s_cmpk_gt_u32 s22, 0x107f
	s_cbranch_scc0 .LBB0_994
	s_cmpk_gt_u32 s22, 0x167f
	s_cbranch_scc0 .LBB0_975
	s_cmpk_gt_u32 s22, 0x187f
	s_cbranch_scc0 .LBB0_972
	s_cmpk_gt_u32 s22, 0x237f
	s_cbranch_scc0 .LBB0_953
	s_cmpk_gt_u32 s22, 0x28ff
	s_cbranch_scc0 .LBB0_950
	s_cmpk_gt_u32 s22, 0x33ff
	s_cbranch_scc0 .LBB0_931
	s_mov_b32 s6, 14
	s_ashr_i32 s7, s6, 31
	s_lshl_b64 s[6:7], s[6:7], 3
	s_add_u32 s6, s0, s6
	s_addc_u32 s7, s1, s7
	s_load_dwordx2 s[6:7], s[6:7], 0x0
	s_lshl_b32 s8, s22, 5
	s_and_b32 s8, s8, 0x3e0
	s_and_b32 s9, s25, 0x1ffc0
	s_lshl_b32 s10, s8, 2
	v_add_u32_e32 v0, s9, v51
	s_waitcnt lgkmcnt(0)
	s_add_u32 s6, s6, s10
	s_addc_u32 s7, s7, 0
	v_ashrrev_i32_e32 v1, 31, v0
	v_lshl_add_u64 v[2:3], s[6:7], 0, v[32:33]
	v_lshlrev_b64 v[0:1], 12, v[0:1]
	v_lshl_add_u64 v[28:29], v[2:3], 0, v[0:1]
	v_add_co_u32_e32 v4, vcc, s27, v28
	s_lshl_b32 s10, s9, 1
	s_nop 0
	v_addc_co_u32_e32 v5, vcc, 0, v29, vcc
	v_add_co_u32_e32 v8, vcc, s28, v28
	global_load_dwordx4 v[0:3], v[28:29], off nt
	s_nop 0
	global_load_dwordx4 v[4:7], v[4:5], off nt
	v_addc_co_u32_e32 v9, vcc, 0, v29, vcc
	v_add_co_u32_e32 v12, vcc, s29, v28
	v_add_u32_e32 v50, s8, v51
	s_nop 0
	v_addc_co_u32_e32 v13, vcc, 0, v29, vcc
	v_add_co_u32_e32 v16, vcc, s30, v28
	global_load_dwordx4 v[8:11], v[8:9], off nt
	s_nop 0
	global_load_dwordx4 v[12:15], v[12:13], off nt
	v_addc_co_u32_e32 v17, vcc, 0, v29, vcc
	v_add_co_u32_e32 v20, vcc, s31, v28
	v_lshl_add_u64 v[56:57], v[34:35], 0, s[10:11]
	s_nop 0
	v_addc_co_u32_e32 v21, vcc, 0, v29, vcc
	global_load_dwordx4 v[16:19], v[16:17], off nt
	s_nop 0
	global_load_dwordx4 v[20:23], v[20:21], off nt
	v_add_co_u32_e32 v24, vcc, s34, v28
	v_add_u32_e32 v52, s8, v53
	s_nop 0
	v_addc_co_u32_e32 v25, vcc, 0, v29, vcc
	global_load_dwordx4 v[24:27], v[24:25], off nt
	v_add_co_u32_e32 v28, vcc, s35, v28
	v_mad_i64_i32 v[60:61], s[6:7], v50, s36, v[56:57]
	s_nop 0
	v_addc_co_u32_e32 v29, vcc, 0, v29, vcc
	global_load_dwordx4 v[28:31], v[28:29], off nt
	v_mad_i64_i32 v[82:83], s[6:7], v52, s36, v[56:57]
	s_waitcnt vmcnt(0)
	ds_write2_b32 v65, v0, v1 offset1:1
	ds_write2_b32 v65, v2, v3 offset0:2 offset1:3
	ds_write2_b32 v67, v4, v5 offset1:1
	ds_write2_b32 v68, v6, v7 offset1:1
	ds_write2_b32 v69, v8, v9 offset1:1
	ds_write2_b32 v70, v10, v11 offset1:1
	ds_write2_b32 v71, v12, v13 offset1:1
	ds_write2_b32 v72, v14, v15 offset1:1
	ds_write2_b32 v73, v16, v17 offset1:1
	ds_write2_b32 v74, v18, v19 offset1:1
	ds_write2_b32 v75, v20, v21 offset1:1
	ds_write2_b32 v76, v22, v23 offset1:1
	ds_write2_b32 v77, v24, v25 offset1:1
	ds_write2_b32 v78, v26, v27 offset1:1
	ds_write2_b32 v79, v28, v29 offset1:1
	ds_write2_b32 v80, v30, v31 offset1:1
	s_waitcnt lgkmcnt(0)
	ds_read2_b32 v[4:5], v63 offset0:33 offset1:41
	ds_read2_b32 v[6:7], v63 offset1:8
	ds_read2_b32 v[8:9], v63 offset0:66 offset1:74
	ds_read2_b32 v[10:11], v63 offset0:99 offset1:107
	ds_read2_b32 v[12:13], v63 offset0:132 offset1:140
	ds_read2_b32 v[14:15], v63 offset0:165 offset1:173
	ds_read2_b32 v[16:17], v63 offset0:198 offset1:206
	ds_read2_b32 v[18:19], v63 offset0:231 offset1:239
	ds_read2_b32 v[20:21], v63 offset0:49 offset1:57
	ds_read2_b32 v[22:23], v63 offset0:16 offset1:24
	ds_read2_b32 v[24:25], v63 offset0:82 offset1:90
	ds_read2_b32 v[26:27], v63 offset0:115 offset1:123
	ds_read2_b32 v[28:29], v63 offset0:148 offset1:156
	ds_read2_b32 v[30:31], v63 offset0:181 offset1:189
	ds_read2_b32 v[84:85], v63 offset0:214 offset1:222
	ds_read2_b32 v[86:87], v63 offset0:247 offset1:255
	s_waitcnt lgkmcnt(14)
	v_cvt_pk_bf16_f32 v0, v6, v4
	s_waitcnt lgkmcnt(12)
	v_cvt_pk_bf16_f32 v1, v8, v10
	s_waitcnt lgkmcnt(10)
	v_cvt_pk_bf16_f32 v2, v12, v14
	s_waitcnt lgkmcnt(8)
	v_cvt_pk_bf16_f32 v3, v16, v18
	v_cvt_pk_bf16_f32 v4, v7, v5
	v_cvt_pk_bf16_f32 v5, v9, v11
	v_cvt_pk_bf16_f32 v6, v13, v15
	v_cvt_pk_bf16_f32 v7, v17, v19
	global_store_dwordx4 v[60:61], v[0:3], off sc1
	global_store_dwordx4 v[82:83], v[4:7], off sc1
	s_waitcnt lgkmcnt(6)
	v_cvt_pk_bf16_f32 v0, v22, v20
	v_add_u32_e32 v4, s8, v55
	s_waitcnt lgkmcnt(4)
	v_cvt_pk_bf16_f32 v1, v24, v26
	s_waitcnt lgkmcnt(2)
	v_cvt_pk_bf16_f32 v2, v28, v30
	s_waitcnt lgkmcnt(0)
	v_cvt_pk_bf16_f32 v3, v84, v86
	v_mad_i64_i32 v[4:5], s[6:7], v4, s36, v[56:57]
	global_store_dwordx4 v[4:5], v[0:3], off sc1
	v_add_u32_e32 v4, s8, v59
	v_mad_i64_i32 v[4:5], s[6:7], v4, s36, v[56:57]
	v_cvt_pk_bf16_f32 v0, v23, v21
	v_cvt_pk_bf16_f32 v1, v25, v27
	v_cvt_pk_bf16_f32 v2, v29, v31
	v_cvt_pk_bf16_f32 v3, v85, v87
	global_store_dwordx4 v[4:5], v[0:3], off sc1
	s_waitcnt lgkmcnt(0)
	s_mov_b64 s[8:9], 0
; #define LAS __attribute__((address_space(3)))
; __device__ __forceinline__ void transpose_tile(const float* W, const float* gain, int K, int N, int k0, int n0, bf16* WT, int drow0, LAS float* scr, int lane) {
;     f32x4 v[8]; float gv[8];
;     const int r0 = lane >> 3, c4 = lane & 7;
; #pragma unroll
;     for (int i = 0; i < 8; ++i) { v[i] = *(const f32x4*)(W + (size_t)(k0 + r0 + 8 * i) * N + n0 + 4 * c4); gv[i] = gain ? gain[k0 + r0 + 8 * i] : 1.0f; }
; template <bool SWIGLU> __device__ __forceinline__ void transpose_item(const float* W, const float* gain, int K, int N, bf16* WT, LAS float* scr, int item, int lane) {
;     const int nblk = N / 32, kb = item / nblk, nb = item % nblk, n0 = 32 * nb;
;     int drow0 = n0;
;     if (SWIGLU) { const int up = n0 >= FF, f = up ? n0 - FF : n0; drow0 = 256 * (f >> 7) + (up ? 128 : 0) + (f & 127); }
.LBB0_931:
	s_andn2_b64 vcc, exec, s[8:9]
	s_cbranch_vccnz .LBB0_949
	s_mov_b32 s6, 13
	s_ashr_i32 s7, s6, 31
	s_lshl_b64 s[6:7], s[6:7], 3
	s_add_u32 s6, s0, s6
	s_addc_u32 s7, s1, s7
	s_load_dwordx2 s[8:9], s[6:7], 0x0
	s_mov_b32 s6, 12
	s_ashr_i32 s7, s6, 31
	s_lshl_b64 s[6:7], s[6:7], 3
	s_add_u32 s12, s0, s6
	s_addc_u32 s13, s1, s7
	s_add_i32 s6, s22, 0xd700
	s_and_b32 s7, s6, 0xffff
	s_mul_i32 s7, s7, 0xba2f
	s_lshr_b32 s10, s7, 23
	s_mul_i32 s7, s10, 0xb0
	s_sub_i32 s7, s6, s7
	s_lshl_b32 s6, s10, 6
	s_lshl_b32 s10, s7, 7
	s_and_b32 s10, s10, 0x3ff80
	s_waitcnt lgkmcnt(0)
	s_add_u32 s8, s8, s10
	s_addc_u32 s9, s9, 0
	v_add_u32_e32 v28, s6, v51
	v_lshl_add_u64 v[30:31], s[8:9], 0, v[32:33]
	v_mad_i64_i32 v[0:1], s[8:9], v28, s37, v[30:31]
	global_load_dwordx4 v[0:3], v[0:1], off nt
	s_load_dwordx2 s[8:9], s[12:13], 0x0
	v_ashrrev_i32_e32 v29, 31, v28
	v_mov_b32_e32 v50, 1.0
	v_mov_b32_e32 v52, 1.0
	s_waitcnt lgkmcnt(0)
	s_cmp_lg_u64 s[8:9], 0
	s_cselect_b64 s[12:13], -1, 0
	s_cmp_eq_u64 s[8:9], 0
	v_lshl_add_u64 v[60:61], v[28:29], 2, s[8:9]
	s_cbranch_scc1 .LBB0_934
	global_load_dword v52, v[60:61], off nt
.LBB0_934:
	v_add_u32_e32 v4, 8, v28
	v_mad_i64_i32 v[4:5], s[8:9], v4, s37, v[30:31]
	global_load_dwordx4 v[4:7], v[4:5], off nt
	v_cndmask_b32_e64 v8, 0, 1, s[12:13]
	v_cmp_ne_u32_e64 s[8:9], 1, v8
	s_andn2_b64 vcc, exec, s[12:13]
	s_cbranch_vccnz .LBB0_936
	global_load_dword v50, v[60:61], off offset:32 nt
.LBB0_936:
	v_add_u32_e32 v8, 16, v28
	v_mad_i64_i32 v[8:9], s[12:13], v8, s37, v[30:31]
	global_load_dwordx4 v[8:11], v[8:9], off nt
	v_mov_b32_e32 v54, 1.0
	s_and_b64 vcc, exec, s[8:9]
	v_mov_b32_e32 v56, 1.0
	s_cbranch_vccnz .LBB0_938
	global_load_dword v56, v[60:61], off offset:64 nt
.LBB0_938:
	v_add_u32_e32 v12, 24, v28
	v_mad_i64_i32 v[12:13], s[12:13], v12, s37, v[30:31]
	global_load_dwordx4 v[12:15], v[12:13], off nt
	s_and_b64 vcc, exec, s[8:9]
	s_cbranch_vccnz .LBB0_940
	global_load_dword v54, v[60:61], off offset:96 nt
.LBB0_940:
	v_add_u32_e32 v16, 32, v28
	v_mad_i64_i32 v[16:17], s[12:13], v16, s37, v[30:31]
	global_load_dwordx4 v[16:19], v[16:17], off nt
	v_mov_b32_e32 v58, 1.0
	s_and_b64 vcc, exec, s[8:9]
	v_mov_b32_e32 v62, 1.0
	s_cbranch_vccnz .LBB0_942
	global_load_dword v62, v[60:61], off offset:128 nt
.LBB0_942:
	v_add_u32_e32 v20, 40, v28
	v_mad_i64_i32 v[20:21], s[12:13], v20, s37, v[30:31]
	global_load_dwordx4 v[20:23], v[20:21], off nt
	s_and_b64 vcc, exec, s[8:9]
	s_cbranch_vccnz .LBB0_944
	global_load_dword v58, v[60:61], off offset:160 nt
.LBB0_944:
	v_add_u32_e32 v24, 48, v28
	v_mad_i64_i32 v[24:25], s[12:13], v24, s37, v[30:31]
	global_load_dwordx4 v[24:27], v[24:25], off nt
	v_mov_b32_e32 v64, 1.0
	s_and_b64 vcc, exec, s[8:9]
	v_mov_b32_e32 v66, 1.0
	s_cbranch_vccnz .LBB0_946
	global_load_dword v66, v[60:61], off offset:192 nt
.LBB0_946:
	v_add_u32_e32 v28, 56, v28
	v_mad_i64_i32 v[28:29], s[12:13], v28, s37, v[30:31]
	global_load_dwordx4 v[28:31], v[28:29], off nt
	s_and_b64 vcc, exec, s[8:9]
	s_cbranch_vccnz .LBB0_948
	global_load_dword v64, v[60:61], off offset:224 nt

; __device__ __forceinline__ unsigned pk_bf16(float lo, float hi) { typedef __bf16 b2_t __attribute__((ext_vector_type(2))); f32x2 v = {lo, hi}; b2_t b = __builtin_convertvector(v, b2_t); return __builtin_bit_cast(unsigned, b); }
; #define LAS __attribute__((address_space(3)))
; __device__ __forceinline__ void transpose_tile(const float* W, const float* gain, int K, int N, int k0, int n0, bf16* WT, int drow0, LAS float* scr, int lane) {
;     f32x4 v[8]; float gv[8];
;     const int r0 = lane >> 3, c4 = lane & 7;
; #pragma unroll
;     for (int i = 0; i < 8; ++i) { v[i] = *(const f32x4*)(W + (size_t)(k0 + r0 + 8 * i) * N + n0 + 4 * c4); gv[i] = gain ? gain[k0 + r0 + 8 * i] : 1.0f; }
; #pragma unroll
;     for (int i = 0; i < 8; ++i) { LAS float* d = scr + (r0 + 8 * i) * 33 + 4 * c4; d[0] = v[i][0] * gv[i]; d[1] = v[i][1] * gv[i]; d[2] = v[i][2] * gv[i]; d[3] = v[i][3] * gv[i]; }
;     asm volatile("s_waitcnt lgkmcnt(0)" ::: "memory");
;     const int c = lane & 7;
; #pragma unroll
;     for (int j = 0; j < 4; ++j) { const int n = (lane >> 3) + 8 * j; const LAS float* s = scr + (8 * c) * 33 + n;
;         v4u o; o.x = pk_bf16(s[0 * 33], s[1 * 33]); o.y = pk_bf16(s[2 * 33], s[3 * 33]); o.z = pk_bf16(s[4 * 33], s[5 * 33]); o.w = pk_bf16(s[6 * 33], s[7 * 33]);
;         *(v4u*)(WT + (size_t)(drow0 + n) * K + k0 + 8 * c) = o; }
;     asm volatile("s_waitcnt lgkmcnt(0)" ::: "memory");
; }
.LBB0_950:
	s_andn2_b64 vcc, exec, s[8:9]
	s_cbranch_vccnz .LBB0_952
	s_mov_b32 s6, 11
	s_ashr_i32 s7, s6, 31
	s_lshl_b64 s[6:7], s[6:7], 3
	s_add_u32 s6, s0, s6
	s_addc_u32 s7, s1, s7
	s_load_dwordx2 s[6:7], s[6:7], 0x0
	s_lshl_b32 s8, s22, 5
	s_and_b32 s8, s8, 0x3e0
	s_add_i32 s9, s25, 0x2100
	s_and_b32 s9, s9, 0x1ffc0
	s_lshl_b32 s10, s8, 2
	v_add_u32_e32 v0, s9, v51
	s_waitcnt lgkmcnt(0)
	s_add_u32 s6, s6, s10
	s_addc_u32 s7, s7, 0
	v_ashrrev_i32_e32 v1, 31, v0
	v_lshl_add_u64 v[2:3], s[6:7], 0, v[32:33]
	v_lshlrev_b64 v[0:1], 12, v[0:1]
	v_lshl_add_u64 v[28:29], v[2:3], 0, v[0:1]
	v_add_co_u32_e32 v4, vcc, s27, v28
	s_lshl_b32 s10, s9, 1
	s_nop 0
	v_addc_co_u32_e32 v5, vcc, 0, v29, vcc
	v_add_co_u32_e32 v8, vcc, s28, v28
	global_load_dwordx4 v[0:3], v[28:29], off nt
	s_nop 0
	global_load_dwordx4 v[4:7], v[4:5], off nt
	v_addc_co_u32_e32 v9, vcc, 0, v29, vcc
	v_add_co_u32_e32 v12, vcc, s29, v28
	v_add_u32_e32 v50, s8, v51
	s_nop 0
	v_addc_co_u32_e32 v13, vcc, 0, v29, vcc
	v_add_co_u32_e32 v16, vcc, s30, v28
	global_load_dwordx4 v[8:11], v[8:9], off nt
	s_nop 0
	global_load_dwordx4 v[12:15], v[12:13], off nt
	v_addc_co_u32_e32 v17, vcc, 0, v29, vcc
	v_add_co_u32_e32 v20, vcc, s31, v28
	v_lshl_add_u64 v[56:57], v[38:39], 0, s[10:11]
	s_nop 0
	v_addc_co_u32_e32 v21, vcc, 0, v29, vcc
	global_load_dwordx4 v[16:19], v[16:17], off nt
	s_nop 0
	global_load_dwordx4 v[20:23], v[20:21], off nt
	v_add_co_u32_e32 v24, vcc, s34, v28
	v_add_u32_e32 v52, s8, v53
	s_nop 0
	v_addc_co_u32_e32 v25, vcc, 0, v29, vcc
	global_load_dwordx4 v[24:27], v[24:25], off nt
	v_add_co_u32_e32 v28, vcc, s35, v28
	v_mad_i64_i32 v[60:61], s[6:7], v50, s36, v[56:57]
	s_nop 0
	v_addc_co_u32_e32 v29, vcc, 0, v29, vcc
	global_load_dwordx4 v[28:31], v[28:29], off nt
	v_mad_i64_i32 v[82:83], s[6:7], v52, s36, v[56:57]
	s_waitcnt vmcnt(0)
	ds_write2_b32 v65, v0, v1 offset1:1
	ds_write2_b32 v65, v2, v3 offset0:2 offset1:3
	ds_write2_b32 v67, v4, v5 offset1:1
	ds_write2_b32 v68, v6, v7 offset1:1
	ds_write2_b32 v69, v8, v9 offset1:1
	ds_write2_b32 v70, v10, v11 offset1:1
	ds_write2_b32 v71, v12, v13 offset1:1
	ds_write2_b32 v72, v14, v15 offset1:1
	ds_write2_b32 v73, v16, v17 offset1:1
	ds_write2_b32 v74, v18, v19 offset1:1
	ds_write2_b32 v75, v20, v21 offset1:1
	ds_write2_b32 v76, v22, v23 offset1:1
	ds_write2_b32 v77, v24, v25 offset1:1
	ds_write2_b32 v78, v26, v27 offset1:1
	ds_write2_b32 v79, v28, v29 offset1:1
	ds_write2_b32 v80, v30, v31 offset1:1
	s_waitcnt lgkmcnt(0)
	ds_read2_b32 v[4:5], v63 offset0:33 offset1:41
	ds_read2_b32 v[6:7], v63 offset1:8
	ds_read2_b32 v[8:9], v63 offset0:66 offset1:74
	ds_read2_b32 v[10:11], v63 offset0:99 offset1:107
	ds_read2_b32 v[12:13], v63 offset0:132 offset1:140
	ds_read2_b32 v[14:15], v63 offset0:165 offset1:173
	ds_read2_b32 v[16:17], v63 offset0:198 offset1:206
	ds_read2_b32 v[18:19], v63 offset0:231 offset1:239
	ds_read2_b32 v[20:21], v63 offset0:49 offset1:57
	ds_read2_b32 v[22:23], v63 offset0:16 offset1:24
	ds_read2_b32 v[24:25], v63 offset0:82 offset1:90
	ds_read2_b32 v[26:27], v63 offset0:115 offset1:123
	ds_read2_b32 v[28:29], v63 offset0:148 offset1:156
	ds_read2_b32 v[30:31], v63 offset0:181 offset1:189
	ds_read2_b32 v[84:85], v63 offset0:214 offset1:222
	ds_read2_b32 v[86:87], v63 offset0:247 offset1:255
	s_waitcnt lgkmcnt(14)
	v_cvt_pk_bf16_f32 v0, v6, v4
	s_waitcnt lgkmcnt(12)
	v_cvt_pk_bf16_f32 v1, v8, v10
	s_waitcnt lgkmcnt(10)
	v_cvt_pk_bf16_f32 v2, v12, v14
	s_waitcnt lgkmcnt(8)
	v_cvt_pk_bf16_f32 v3, v16, v18
	v_cvt_pk_bf16_f32 v4, v7, v5
	v_cvt_pk_bf16_f32 v5, v9, v11
	v_cvt_pk_bf16_f32 v6, v13, v15
	v_cvt_pk_bf16_f32 v7, v17, v19
	global_store_dwordx4 v[60:61], v[0:3], off sc1
	global_store_dwordx4 v[82:83], v[4:7], off sc1
	s_waitcnt lgkmcnt(6)
	v_cvt_pk_bf16_f32 v0, v22, v20
	v_add_u32_e32 v4, s8, v55
	s_waitcnt lgkmcnt(4)
	v_cvt_pk_bf16_f32 v1, v24, v26
	s_waitcnt lgkmcnt(2)
	v_cvt_pk_bf16_f32 v2, v28, v30
	s_waitcnt lgkmcnt(0)
	v_cvt_pk_bf16_f32 v3, v84, v86
	v_mad_i64_i32 v[4:5], s[6:7], v4, s36, v[56:57]
	global_store_dwordx4 v[4:5], v[0:3], off sc1
	v_add_u32_e32 v4, s8, v59
	v_mad_i64_i32 v[4:5], s[6:7], v4, s36, v[56:57]
	v_cvt_pk_bf16_f32 v0, v23, v21
	v_cvt_pk_bf16_f32 v1, v25, v27
	v_cvt_pk_bf16_f32 v2, v29, v31
	v_cvt_pk_bf16_f32 v3, v85, v87
	global_store_dwordx4 v[4:5], v[0:3], off sc1
	s_waitcnt lgkmcnt(0)

; __device__ __forceinline__ void transpose_tile(const float* W, const float* gain, int K, int N, int k0, int n0, bf16* WT, int drow0, LAS float* scr, int lane) {
;     ...
; #pragma unroll
;     for (int i = 0; i < 8; ++i) { v[i] = *(const f32x4*)(W + (size_t)(k0 + r0 + 8 * i) * N + n0 + 4 * c4); gv[i] = gain ? gain[k0 + r0 + 8 * i] : 1.0f; }
; template <bool SWIGLU> __device__ __forceinline__ void transpose_item(const float* W, const float* gain, int K, int N, bf16* WT, LAS float* scr, int item, int lane) {
;     const int nblk = N / 32, kb = item / nblk, nb = item % nblk, n0 = 32 * nb;
;     int drow0 = n0;
;     if (SWIGLU) { const int up = n0 >= FF, f = up ? n0 - FF : n0; drow0 = 256 * (f >> 7) + (up ? 128 : 0) + (f & 127); }
.LBB0_953:
	s_andn2_b64 vcc, exec, s[8:9]
	s_cbranch_vccnz .LBB0_971
	s_mov_b32 s6, 10
	s_ashr_i32 s7, s6, 31
	s_lshl_b64 s[6:7], s[6:7], 3
	s_add_u32 s6, s0, s6
	s_addc_u32 s7, s1, s7
	s_load_dwordx2 s[8:9], s[6:7], 0x0
	s_mov_b32 s6, 9
	s_ashr_i32 s7, s6, 31
	s_lshl_b64 s[6:7], s[6:7], 3
	s_add_u32 s12, s0, s6
	s_addc_u32 s13, s1, s7
	s_add_i32 s6, s22, 0xe780
	s_and_b32 s7, s6, 0xffff
	s_mul_i32 s7, s7, 0xba2f
	s_lshr_b32 s10, s7, 23
	s_mul_i32 s7, s10, 0xb0
	s_sub_i32 s7, s6, s7
	s_lshl_b32 s6, s10, 6
	s_lshl_b32 s10, s7, 7
	s_and_b32 s10, s10, 0x3ff80
	s_waitcnt lgkmcnt(0)
	s_add_u32 s8, s8, s10
	s_addc_u32 s9, s9, 0
	v_add_u32_e32 v28, s6, v51
	v_lshl_add_u64 v[30:31], s[8:9], 0, v[32:33]
	v_mad_i64_i32 v[0:1], s[8:9], v28, s37, v[30:31]
	global_load_dwordx4 v[0:3], v[0:1], off nt
	s_load_dwordx2 s[8:9], s[12:13], 0x0
	v_ashrrev_i32_e32 v29, 31, v28
	v_mov_b32_e32 v50, 1.0
	v_mov_b32_e32 v52, 1.0
	s_waitcnt lgkmcnt(0)
	s_cmp_lg_u64 s[8:9], 0
	s_cselect_b64 s[12:13], -1, 0
	s_cmp_eq_u64 s[8:9], 0
	v_lshl_add_u64 v[60:61], v[28:29], 2, s[8:9]
	s_cbranch_scc1 .LBB0_956
	global_load_dword v52, v[60:61], off nt

; __device__ __forceinline__ unsigned pk_bf16(float lo, float hi) { typedef __bf16 b2_t __attribute__((ext_vector_type(2))); f32x2 v = {lo, hi}; b2_t b = __builtin_convertvector(v, b2_t); return __builtin_bit_cast(unsigned, b); }
; #define LAS __attribute__((address_space(3)))
; __device__ __forceinline__ void transpose_tile(const float* W, const float* gain, int K, int N, int k0, int n0, bf16* WT, int drow0, LAS float* scr, int lane) {
;     f32x4 v[8]; float gv[8];
;     const int r0 = lane >> 3, c4 = lane & 7;
; #pragma unroll
;     for (int i = 0; i < 8; ++i) { v[i] = *(const f32x4*)(W + (size_t)(k0 + r0 + 8 * i) * N + n0 + 4 * c4); gv[i] = gain ? gain[k0 + r0 + 8 * i] : 1.0f; }
; #pragma unroll
;     for (int i = 0; i < 8; ++i) { LAS float* d = scr + (r0 + 8 * i) * 33 + 4 * c4; d[0] = v[i][0] * gv[i]; d[1] = v[i][1] * gv[i]; d[2] = v[i][2] * gv[i]; d[3] = v[i][3] * gv[i]; }
;     asm volatile("s_waitcnt lgkmcnt(0)" ::: "memory");
;     const int c = lane & 7;
; #pragma unroll
;     for (int j = 0; j < 4; ++j) { const int n = (lane >> 3) + 8 * j; const LAS float* s = scr + (8 * c) * 33 + n;
;         v4u o; o.x = pk_bf16(s[0 * 33], s[1 * 33]); o.y = pk_bf16(s[2 * 33], s[3 * 33]); o.z = pk_bf16(s[4 * 33], s[5 * 33]); o.w = pk_bf16(s[6 * 33], s[7 * 33]);
;         *(v4u*)(WT + (size_t)(drow0 + n) * K + k0 + 8 * c) = o; }
;     asm volatile("s_waitcnt lgkmcnt(0)" ::: "memory");
; }
.LBB0_972:
	s_andn2_b64 vcc, exec, s[8:9]
	s_cbranch_vccnz .LBB0_974
	s_mov_b32 s6, 8
	s_ashr_i32 s7, s6, 31
	s_lshl_b64 s[6:7], s[6:7], 3
	s_add_u32 s6, s0, s6
	s_addc_u32 s7, s1, s7
	s_load_dwordx2 s[6:7], s[6:7], 0x0
	s_lshl_b32 s8, s22, 5
	s_and_b32 s8, s8, 0x3e0
	s_add_i32 s9, s25, 0x3b00
	s_and_b32 s9, s9, 0x1ffc0
	s_lshl_b32 s10, s8, 2
	v_add_u32_e32 v0, s9, v51
	s_waitcnt lgkmcnt(0)
	s_add_u32 s6, s6, s10
	s_addc_u32 s7, s7, 0
	v_ashrrev_i32_e32 v1, 31, v0
	v_lshl_add_u64 v[2:3], s[6:7], 0, v[32:33]
	v_lshlrev_b64 v[0:1], 12, v[0:1]
	v_lshl_add_u64 v[28:29], v[2:3], 0, v[0:1]
	v_add_co_u32_e32 v4, vcc, s27, v28
	v_add_u32_e32 v56, s8, v51
	s_nop 0
	v_addc_co_u32_e32 v5, vcc, 0, v29, vcc
	v_add_co_u32_e32 v8, vcc, s28, v28
	global_load_dwordx4 v[0:3], v[28:29], off nt
	s_nop 0
	global_load_dwordx4 v[4:7], v[4:5], off nt
	v_addc_co_u32_e32 v9, vcc, 0, v29, vcc
	v_add_co_u32_e32 v12, vcc, s29, v28
	v_ashrrev_i32_e32 v57, 31, v56
	s_nop 0
	v_addc_co_u32_e32 v13, vcc, 0, v29, vcc
	v_add_co_u32_e32 v16, vcc, s30, v28
	global_load_dwordx4 v[8:11], v[8:9], off nt
	s_nop 0
	global_load_dwordx4 v[12:15], v[12:13], off nt
	v_addc_co_u32_e32 v17, vcc, 0, v29, vcc
	v_add_co_u32_e32 v20, vcc, s31, v28
	s_lshl_b32 s10, s9, 1
	s_nop 0
	v_addc_co_u32_e32 v21, vcc, 0, v29, vcc
	global_load_dwordx4 v[16:19], v[16:17], off nt
	s_nop 0
	global_load_dwordx4 v[20:23], v[20:21], off nt
	v_add_co_u32_e32 v24, vcc, s34, v28
	v_lshlrev_b64 v[56:57], 11, v[56:57]
	s_nop 0
	v_addc_co_u32_e32 v25, vcc, 0, v29, vcc
	global_load_dwordx4 v[24:27], v[24:25], off nt
	v_add_co_u32_e32 v28, vcc, s35, v28
	v_lshl_add_u64 v[82:83], v[42:43], 0, s[10:11]
	s_nop 0
	v_addc_co_u32_e32 v29, vcc, 0, v29, vcc
	global_load_dwordx4 v[28:31], v[28:29], off nt
	v_add_u32_e32 v60, s8, v53
	v_lshl_add_u64 v[56:57], v[82:83], 0, v[56:57]
	v_ashrrev_i32_e32 v61, 31, v60
	v_lshlrev_b64 v[60:61], 11, v[60:61]
	v_lshl_add_u64 v[60:61], v[82:83], 0, v[60:61]
	s_waitcnt vmcnt(0)
	ds_write2_b32 v65, v0, v1 offset1:1
	ds_write2_b32 v65, v2, v3 offset0:2 offset1:3
	ds_write2_b32 v67, v4, v5 offset1:1
	ds_write2_b32 v68, v6, v7 offset1:1
	ds_write2_b32 v69, v8, v9 offset1:1
	ds_write2_b32 v70, v10, v11 offset1:1
	ds_write2_b32 v71, v12, v13 offset1:1
	ds_write2_b32 v72, v14, v15 offset1:1
	ds_write2_b32 v73, v16, v17 offset1:1
	ds_write2_b32 v74, v18, v19 offset1:1
	ds_write2_b32 v75, v20, v21 offset1:1
	ds_write2_b32 v76, v22, v23 offset1:1
	ds_write2_b32 v77, v24, v25 offset1:1
	ds_write2_b32 v78, v26, v27 offset1:1
	ds_write2_b32 v79, v28, v29 offset1:1
	ds_write2_b32 v80, v30, v31 offset1:1
	s_waitcnt lgkmcnt(0)
	ds_read2_b32 v[4:5], v63 offset0:33 offset1:41
	ds_read2_b32 v[6:7], v63 offset1:8
	ds_read2_b32 v[8:9], v63 offset0:66 offset1:74
	ds_read2_b32 v[10:11], v63 offset0:99 offset1:107
	ds_read2_b32 v[12:13], v63 offset0:132 offset1:140
	ds_read2_b32 v[14:15], v63 offset0:165 offset1:173
	ds_read2_b32 v[16:17], v63 offset0:198 offset1:206
	ds_read2_b32 v[18:19], v63 offset0:231 offset1:239
	ds_read2_b32 v[20:21], v63 offset0:49 offset1:57
	ds_read2_b32 v[22:23], v63 offset0:16 offset1:24
	ds_read2_b32 v[24:25], v63 offset0:82 offset1:90
	ds_read2_b32 v[26:27], v63 offset0:115 offset1:123
	ds_read2_b32 v[28:29], v63 offset0:148 offset1:156
	ds_read2_b32 v[30:31], v63 offset0:181 offset1:189
	s_waitcnt lgkmcnt(12)
	v_cvt_pk_bf16_f32 v0, v6, v4
	s_waitcnt lgkmcnt(10)
	v_cvt_pk_bf16_f32 v1, v8, v10
	s_waitcnt lgkmcnt(8)
	v_cvt_pk_bf16_f32 v2, v12, v14
	s_waitcnt lgkmcnt(6)
	v_cvt_pk_bf16_f32 v3, v16, v18
	global_store_dwordx4 v[56:57], v[0:3], off sc1
	v_cvt_pk_bf16_f32 v4, v7, v5
	v_cvt_pk_bf16_f32 v5, v9, v11
	ds_read2_b32 v[8:9], v63 offset0:214 offset1:222
	ds_read2_b32 v[10:11], v63 offset0:247 offset1:255
	v_cvt_pk_bf16_f32 v6, v13, v15
	v_cvt_pk_bf16_f32 v7, v17, v19
	global_store_dwordx4 v[60:61], v[4:7], off sc1
	s_waitcnt lgkmcnt(6)
	v_cvt_pk_bf16_f32 v0, v22, v20
	s_waitcnt lgkmcnt(4)
	v_cvt_pk_bf16_f32 v1, v24, v26
	v_add_u32_e32 v4, s8, v55
	v_ashrrev_i32_e32 v5, 31, v4
	v_lshlrev_b64 v[4:5], 11, v[4:5]
	s_waitcnt lgkmcnt(2)
	v_cvt_pk_bf16_f32 v2, v28, v30
	s_waitcnt lgkmcnt(0)
	v_cvt_pk_bf16_f32 v3, v8, v10
	v_lshl_add_u64 v[4:5], v[82:83], 0, v[4:5]
	global_store_dwordx4 v[4:5], v[0:3], off sc1
	v_add_u32_e32 v4, s8, v59
	v_ashrrev_i32_e32 v5, 31, v4
	v_lshlrev_b64 v[4:5], 11, v[4:5]
	v_cvt_pk_bf16_f32 v0, v23, v21
	v_cvt_pk_bf16_f32 v1, v25, v27
	v_cvt_pk_bf16_f32 v2, v29, v31
	v_cvt_pk_bf16_f32 v3, v9, v11
	v_lshl_add_u64 v[4:5], v[82:83], 0, v[4:5]
	global_store_dwordx4 v[4:5], v[0:3], off sc1
	s_waitcnt lgkmcnt(0)

; #define LAS __attribute__((address_space(3)))
; __device__ __forceinline__ void transpose_tile(const float* W, const float* gain, int K, int N, int k0, int n0, bf16* WT, int drow0, LAS float* scr, int lane) {
;     f32x4 v[8]; float gv[8];
;     const int r0 = lane >> 3, c4 = lane & 7;
; #pragma unroll
;     for (int i = 0; i < 8; ++i) { v[i] = *(const f32x4*)(W + (size_t)(k0 + r0 + 8 * i) * N + n0 + 4 * c4); gv[i] = gain ? gain[k0 + r0 + 8 * i] : 1.0f; }
; template <bool SWIGLU> __device__ __forceinline__ void transpose_item(const float* W, const float* gain, int K, int N, bf16* WT, LAS float* scr, int item, int lane) {
;     const int nblk = N / 32, kb = item / nblk, nb = item % nblk, n0 = 32 * nb;
;     int drow0 = n0;
;     if (SWIGLU) { const int up = n0 >= FF, f = up ? n0 - FF : n0; drow0 = 256 * (f >> 7) + (up ? 128 : 0) + (f & 127); }
.LBB0_975:
	s_andn2_b64 vcc, exec, s[8:9]
	s_cbranch_vccnz .LBB0_993
	s_mov_b32 s6, 5
	s_ashr_i32 s7, s6, 31
	s_lshl_b64 s[6:7], s[6:7], 3
	s_add_u32 s6, s0, s6
	s_addc_u32 s7, s1, s7
	s_load_dwordx2 s[8:9], s[6:7], 0x0
	s_mov_b32 s6, 4
	s_ashr_i32 s7, s6, 31
	s_lshl_b64 s[6:7], s[6:7], 3
	s_add_u32 s12, s0, s6
	s_addc_u32 s13, s1, s7
	s_add_i32 s6, s22, 0xef80
	s_and_b32 s7, s6, 0xffff
	s_mul_i32 s7, s7, 0xaaab
	s_lshr_b32 s10, s7, 16
	s_lshr_b32 s7, s7, 22
	s_mulk_i32 s7, 0x60
	s_sub_i32 s7, s6, s7
	s_and_b32 s6, s10, 0xffc0
	s_lshl_b32 s10, s7, 7
	s_and_b32 s10, s10, 0x3ff80
	s_waitcnt lgkmcnt(0)
	s_add_u32 s8, s8, s10
	s_addc_u32 s9, s9, 0
	v_add_u32_e32 v28, s6, v51
	v_lshl_add_u64 v[30:31], s[8:9], 0, v[32:33]
	v_mad_i64_i32 v[0:1], s[8:9], v28, s38, v[30:31]
	global_load_dwordx4 v[0:3], v[0:1], off nt
	s_load_dwordx2 s[8:9], s[12:13], 0x0
	v_ashrrev_i32_e32 v29, 31, v28
	v_mov_b32_e32 v50, 1.0
	v_mov_b32_e32 v52, 1.0
	s_waitcnt lgkmcnt(0)
	s_cmp_lg_u64 s[8:9], 0
	s_cselect_b64 s[12:13], -1, 0
	s_cmp_eq_u64 s[8:9], 0
	v_lshl_add_u64 v[56:57], v[28:29], 2, s[8:9]
	s_cbranch_scc1 .LBB0_978
	global_load_dword v52, v[56:57], off nt
.LBB0_978:
	v_add_u32_e32 v4, 8, v28
	v_mad_i64_i32 v[4:5], s[8:9], v4, s38, v[30:31]
	global_load_dwordx4 v[4:7], v[4:5], off nt
	v_cndmask_b32_e64 v8, 0, 1, s[12:13]
	v_cmp_ne_u32_e64 s[8:9], 1, v8
	s_andn2_b64 vcc, exec, s[12:13]
	s_cbranch_vccnz .LBB0_980
	global_load_dword v50, v[56:57], off offset:32 nt
.LBB0_980:
	v_add_u32_e32 v8, 16, v28
	v_mad_i64_i32 v[8:9], s[12:13], v8, s38, v[30:31]
	global_load_dwordx4 v[8:11], v[8:9], off nt
	v_mov_b32_e32 v54, 1.0
	s_and_b64 vcc, exec, s[8:9]
	v_mov_b32_e32 v58, 1.0
	s_cbranch_vccnz .LBB0_982
	global_load_dword v58, v[56:57], off offset:64 nt
.LBB0_982:
	v_add_u32_e32 v12, 24, v28
	v_mad_i64_i32 v[12:13], s[12:13], v12, s38, v[30:31]
	global_load_dwordx4 v[12:15], v[12:13], off nt
	s_and_b64 vcc, exec, s[8:9]
	s_cbranch_vccnz .LBB0_984
	global_load_dword v54, v[56:57], off offset:96 nt
.LBB0_984:
	v_add_u32_e32 v16, 32, v28
	v_mad_i64_i32 v[16:17], s[12:13], v16, s38, v[30:31]
	global_load_dwordx4 v[16:19], v[16:17], off nt
	v_mov_b32_e32 v60, 1.0
	s_and_b64 vcc, exec, s[8:9]
	v_mov_b32_e32 v62, 1.0
	s_cbranch_vccnz .LBB0_986
	global_load_dword v62, v[56:57], off offset:128 nt
.LBB0_986:
	v_add_u32_e32 v20, 40, v28
	v_mad_i64_i32 v[20:21], s[12:13], v20, s38, v[30:31]
	global_load_dwordx4 v[20:23], v[20:21], off nt
	s_and_b64 vcc, exec, s[8:9]
	s_cbranch_vccnz .LBB0_988
	global_load_dword v60, v[56:57], off offset:160 nt
.LBB0_988:
	v_add_u32_e32 v24, 48, v28
	v_mad_i64_i32 v[24:25], s[12:13], v24, s38, v[30:31]
	global_load_dwordx4 v[24:27], v[24:25], off nt
	v_mov_b32_e32 v64, 1.0
	s_and_b64 vcc, exec, s[8:9]
	v_mov_b32_e32 v66, 1.0
	s_cbranch_vccnz .LBB0_990
	global_load_dword v66, v[56:57], off offset:192 nt
.LBB0_990:
	v_add_u32_e32 v28, 56, v28
	v_mad_i64_i32 v[28:29], s[12:13], v28, s38, v[30:31]
	global_load_dwordx4 v[28:31], v[28:29], off nt
	s_and_b64 vcc, exec, s[8:9]
	s_cbranch_vccnz .LBB0_992
	global_load_dword v64, v[56:57], off offset:224 nt

; __device__ __forceinline__ unsigned pk_bf16(float lo, float hi) { typedef __bf16 b2_t __attribute__((ext_vector_type(2))); f32x2 v = {lo, hi}; b2_t b = __builtin_convertvector(v, b2_t); return __builtin_bit_cast(unsigned, b); }
; #define LAS __attribute__((address_space(3)))
; __device__ __forceinline__ void transpose_tile(const float* W, const float* gain, int K, int N, int k0, int n0, bf16* WT, int drow0, LAS float* scr, int lane) {
;     f32x4 v[8]; float gv[8];
;     const int r0 = lane >> 3, c4 = lane & 7;
; #pragma unroll
;     for (int i = 0; i < 8; ++i) { v[i] = *(const f32x4*)(W + (size_t)(k0 + r0 + 8 * i) * N + n0 + 4 * c4); gv[i] = gain ? gain[k0 + r0 + 8 * i] : 1.0f; }
; #pragma unroll
;     for (int i = 0; i < 8; ++i) { LAS float* d = scr + (r0 + 8 * i) * 33 + 4 * c4; d[0] = v[i][0] * gv[i]; d[1] = v[i][1] * gv[i]; d[2] = v[i][2] * gv[i]; d[3] = v[i][3] * gv[i]; }
;     asm volatile("s_waitcnt lgkmcnt(0)" ::: "memory");
;     const int c = lane & 7;
; #pragma unroll
;     for (int j = 0; j < 4; ++j) { const int n = (lane >> 3) + 8 * j; const LAS float* s = scr + (8 * c) * 33 + n;
;         v4u o; o.x = pk_bf16(s[0 * 33], s[1 * 33]); o.y = pk_bf16(s[2 * 33], s[3 * 33]); o.z = pk_bf16(s[4 * 33], s[5 * 33]); o.w = pk_bf16(s[6 * 33], s[7 * 33]);
;         *(v4u*)(WT + (size_t)(drow0 + n) * K + k0 + 8 * c) = o; }
;     asm volatile("s_waitcnt lgkmcnt(0)" ::: "memory");
; }
.LBB0_994:
	s_andn2_b64 vcc, exec, s[8:9]
	s_cbranch_vccnz .LBB0_996
	s_mov_b32 s6, 3
	s_ashr_i32 s7, s6, 31
	s_lshl_b64 s[6:7], s[6:7], 3
	s_add_u32 s6, s0, s6
	s_addc_u32 s7, s1, s7
	s_load_dwordx2 s[6:7], s[6:7], 0x0
	s_lshl_b32 s8, s22, 5
	s_and_b32 s8, s8, 0x3e0
	s_add_i32 s9, s25, 0x5200
	s_and_b32 s9, s9, 0x1ffc0
	s_lshl_b32 s10, s8, 2
	v_add_u32_e32 v0, s9, v51
	s_waitcnt lgkmcnt(0)
	s_add_u32 s6, s6, s10
	s_addc_u32 s7, s7, 0
	v_ashrrev_i32_e32 v1, 31, v0
	v_lshl_add_u64 v[2:3], s[6:7], 0, v[32:33]
	v_lshlrev_b64 v[0:1], 12, v[0:1]
	v_lshl_add_u64 v[28:29], v[2:3], 0, v[0:1]
	v_add_co_u32_e32 v4, vcc, s27, v28
	s_lshl_b32 s10, s9, 1
	s_nop 0
	v_addc_co_u32_e32 v5, vcc, 0, v29, vcc
	v_add_co_u32_e32 v8, vcc, s28, v28
	global_load_dwordx4 v[0:3], v[28:29], off nt
	s_nop 0
	global_load_dwordx4 v[4:7], v[4:5], off nt
	v_addc_co_u32_e32 v9, vcc, 0, v29, vcc
	v_add_co_u32_e32 v12, vcc, s29, v28
	v_add_u32_e32 v50, s8, v51
	s_nop 0
	v_addc_co_u32_e32 v13, vcc, 0, v29, vcc
	v_add_co_u32_e32 v16, vcc, s30, v28
	global_load_dwordx4 v[8:11], v[8:9], off nt
	s_nop 0
	global_load_dwordx4 v[12:15], v[12:13], off nt
	v_addc_co_u32_e32 v17, vcc, 0, v29, vcc
	v_add_co_u32_e32 v20, vcc, s31, v28
	v_lshl_add_u64 v[56:57], v[46:47], 0, s[10:11]
	s_nop 0
	v_addc_co_u32_e32 v21, vcc, 0, v29, vcc
	global_load_dwordx4 v[16:19], v[16:17], off nt
	s_nop 0
	global_load_dwordx4 v[20:23], v[20:21], off nt
	v_add_co_u32_e32 v24, vcc, s34, v28
	v_add_u32_e32 v52, s8, v53
	s_nop 0
	v_addc_co_u32_e32 v25, vcc, 0, v29, vcc
	global_load_dwordx4 v[24:27], v[24:25], off nt
	v_add_co_u32_e32 v28, vcc, s35, v28
	v_mad_i64_i32 v[60:61], s[6:7], v50, s36, v[56:57]
	s_nop 0
	v_addc_co_u32_e32 v29, vcc, 0, v29, vcc
	global_load_dwordx4 v[28:31], v[28:29], off nt
	v_mad_i64_i32 v[82:83], s[6:7], v52, s36, v[56:57]
	s_waitcnt vmcnt(0)
	ds_write2_b32 v65, v0, v1 offset1:1
	ds_write2_b32 v65, v2, v3 offset0:2 offset1:3
	ds_write2_b32 v67, v4, v5 offset1:1
	ds_write2_b32 v68, v6, v7 offset1:1
	ds_write2_b32 v69, v8, v9 offset1:1
	ds_write2_b32 v70, v10, v11 offset1:1
	ds_write2_b32 v71, v12, v13 offset1:1
	ds_write2_b32 v72, v14, v15 offset1:1
	ds_write2_b32 v73, v16, v17 offset1:1
	ds_write2_b32 v74, v18, v19 offset1:1
	ds_write2_b32 v75, v20, v21 offset1:1
	ds_write2_b32 v76, v22, v23 offset1:1
	ds_write2_b32 v77, v24, v25 offset1:1
	ds_write2_b32 v78, v26, v27 offset1:1
	ds_write2_b32 v79, v28, v29 offset1:1
	ds_write2_b32 v80, v30, v31 offset1:1
	s_waitcnt lgkmcnt(0)
	ds_read2_b32 v[4:5], v63 offset0:33 offset1:41
	ds_read2_b32 v[6:7], v63 offset1:8
	ds_read2_b32 v[8:9], v63 offset0:66 offset1:74
	ds_read2_b32 v[10:11], v63 offset0:99 offset1:107
	ds_read2_b32 v[12:13], v63 offset0:132 offset1:140
	ds_read2_b32 v[14:15], v63 offset0:165 offset1:173
	ds_read2_b32 v[16:17], v63 offset0:198 offset1:206
	ds_read2_b32 v[18:19], v63 offset0:231 offset1:239
	ds_read2_b32 v[20:21], v63 offset0:49 offset1:57
	ds_read2_b32 v[22:23], v63 offset0:16 offset1:24
	ds_read2_b32 v[24:25], v63 offset0:82 offset1:90
	ds_read2_b32 v[26:27], v63 offset0:115 offset1:123
	ds_read2_b32 v[28:29], v63 offset0:148 offset1:156
	ds_read2_b32 v[30:31], v63 offset0:181 offset1:189
	ds_read2_b32 v[84:85], v63 offset0:214 offset1:222
	ds_read2_b32 v[86:87], v63 offset0:247 offset1:255
	s_waitcnt lgkmcnt(14)
	v_cvt_pk_bf16_f32 v0, v6, v4
	s_waitcnt lgkmcnt(12)
	v_cvt_pk_bf16_f32 v1, v8, v10
	s_waitcnt lgkmcnt(10)
	v_cvt_pk_bf16_f32 v2, v12, v14
	s_waitcnt lgkmcnt(8)
	v_cvt_pk_bf16_f32 v3, v16, v18
	v_cvt_pk_bf16_f32 v4, v7, v5
	v_cvt_pk_bf16_f32 v5, v9, v11
	v_cvt_pk_bf16_f32 v6, v13, v15
	v_cvt_pk_bf16_f32 v7, v17, v19
	global_store_dwordx4 v[60:61], v[0:3], off sc1
	global_store_dwordx4 v[82:83], v[4:7], off sc1
	s_waitcnt lgkmcnt(6)
	v_cvt_pk_bf16_f32 v0, v22, v20
	v_add_u32_e32 v4, s8, v55
	s_waitcnt lgkmcnt(4)
	v_cvt_pk_bf16_f32 v1, v24, v26
	s_waitcnt lgkmcnt(2)
	v_cvt_pk_bf16_f32 v2, v28, v30
	s_waitcnt lgkmcnt(0)
	v_cvt_pk_bf16_f32 v3, v84, v86
	v_mad_i64_i32 v[4:5], s[6:7], v4, s36, v[56:57]
	global_store_dwordx4 v[4:5], v[0:3], off sc1
	v_add_u32_e32 v4, s8, v59
	v_mad_i64_i32 v[4:5], s[6:7], v4, s36, v[56:57]
	v_cvt_pk_bf16_f32 v0, v23, v21
	v_cvt_pk_bf16_f32 v1, v25, v27
	v_cvt_pk_bf16_f32 v2, v29, v31
	v_cvt_pk_bf16_f32 v3, v85, v87
	global_store_dwordx4 v[4:5], v[0:3], off sc1
	s_waitcnt lgkmcnt(0)

; #define LAS __attribute__((address_space(3)))
; __device__ __forceinline__ void transpose_tile(const float* W, const float* gain, int K, int N, int k0, int n0, bf16* WT, int drow0, LAS float* scr, int lane) {
;     f32x4 v[8]; float gv[8];
;     const int r0 = lane >> 3, c4 = lane & 7;
; #pragma unroll
;     for (int i = 0; i < 8; ++i) { v[i] = *(const f32x4*)(W + (size_t)(k0 + r0 + 8 * i) * N + n0 + 4 * c4); gv[i] = gain ? gain[k0 + r0 + 8 * i] : 1.0f; }
; template <bool SWIGLU> __device__ __forceinline__ void transpose_item(const float* W, const float* gain, int K, int N, bf16* WT, LAS float* scr, int item, int lane) {
;     const int nblk = N / 32, kb = item / nblk, nb = item % nblk, n0 = 32 * nb;
;     int drow0 = n0;
;     if (SWIGLU) { const int up = n0 >= FF, f = up ? n0 - FF : n0; drow0 = 256 * (f >> 7) + (up ? 128 : 0) + (f & 127); }
.LBB0_997:
	s_andn2_b64 vcc, exec, s[8:9]
	s_cbranch_vccnz .LBB0_922
	s_mov_b32 s6, 2
	s_ashr_i32 s7, s6, 31
	s_lshl_b64 s[6:7], s[6:7], 3
	s_add_u32 s6, s0, s6
	s_addc_u32 s7, s1, s7
	s_load_dwordx2 s[8:9], s[6:7], 0x0
	s_mov_b32 s6, 1
	s_ashr_i32 s7, s6, 31
	s_lshl_b64 s[6:7], s[6:7], 3
	s_add_u32 s20, s0, s6
	s_mul_hi_i32 s6, s22, 0x2e8ba2e9
	s_addc_u32 s21, s1, s7
	s_lshr_b32 s7, s6, 31
	s_ashr_i32 s6, s6, 5
	s_add_i32 s6, s6, s7
	s_mul_i32 s7, s6, 0xffffea00
	s_add_i32 s18, s23, s7
	s_ashr_i32 s19, s18, 31
	s_lshl_b32 s12, s6, 6
	s_lshl_b64 s[40:41], s[18:19], 2
	s_waitcnt lgkmcnt(0)
	s_add_u32 s8, s8, s40
	s_addc_u32 s9, s9, s41
	v_add_u32_e32 v28, s12, v51
	v_lshl_add_u64 v[30:31], s[8:9], 0, v[32:33]
	v_mad_i64_i32 v[0:1], s[8:9], v28, s37, v[30:31]
	global_load_dwordx4 v[0:3], v[0:1], off nt
	s_load_dwordx2 s[8:9], s[20:21], 0x0
	v_ashrrev_i32_e32 v29, 31, v28
	v_mov_b32_e32 v50, 1.0
	v_mov_b32_e32 v52, 1.0
	s_waitcnt lgkmcnt(0)
	s_cmp_lg_u64 s[8:9], 0
	s_cselect_b64 s[20:21], -1, 0
	s_cmp_eq_u64 s[8:9], 0
	v_lshl_add_u64 v[60:61], v[28:29], 2, s[8:9]
	s_cbranch_scc1 .LBB0_1000
	global_load_dword v52, v[60:61], off nt
.LBB0_1000:
	v_add_u32_e32 v4, 8, v28
	v_mad_i64_i32 v[4:5], s[8:9], v4, s37, v[30:31]
	global_load_dwordx4 v[4:7], v[4:5], off nt
	v_cndmask_b32_e64 v8, 0, 1, s[20:21]
	v_cmp_ne_u32_e64 s[8:9], 1, v8
	s_andn2_b64 vcc, exec, s[20:21]
	s_cbranch_vccnz .LBB0_1002
	global_load_dword v50, v[60:61], off offset:32 nt
.LBB0_1002:
	v_add_u32_e32 v8, 16, v28
	v_mad_i64_i32 v[8:9], s[20:21], v8, s37, v[30:31]
	global_load_dwordx4 v[8:11], v[8:9], off nt
	v_mov_b32_e32 v54, 1.0
	s_and_b64 vcc, exec, s[8:9]
	v_mov_b32_e32 v56, 1.0
	s_cbranch_vccnz .LBB0_1004
	global_load_dword v56, v[60:61], off offset:64 nt
.LBB0_1004:
	v_add_u32_e32 v12, 24, v28
	v_mad_i64_i32 v[12:13], s[20:21], v12, s37, v[30:31]
	global_load_dwordx4 v[12:15], v[12:13], off nt
	s_and_b64 vcc, exec, s[8:9]
	s_cbranch_vccnz .LBB0_1006
	global_load_dword v54, v[60:61], off offset:96 nt
.LBB0_1006:
	v_add_u32_e32 v16, 32, v28
	v_mad_i64_i32 v[16:17], s[20:21], v16, s37, v[30:31]
	global_load_dwordx4 v[16:19], v[16:17], off nt
	v_mov_b32_e32 v58, 1.0
	s_and_b64 vcc, exec, s[8:9]
	v_mov_b32_e32 v62, 1.0
	s_cbranch_vccnz .LBB0_1008
	global_load_dword v62, v[60:61], off offset:128 nt
.LBB0_1008:
	v_add_u32_e32 v20, 40, v28
	v_mad_i64_i32 v[20:21], s[20:21], v20, s37, v[30:31]
	global_load_dwordx4 v[20:23], v[20:21], off nt
	s_and_b64 vcc, exec, s[8:9]
	s_cbranch_vccnz .LBB0_1010
	global_load_dword v58, v[60:61], off offset:160 nt
.LBB0_1010:
	v_add_u32_e32 v24, 48, v28
	v_mad_i64_i32 v[24:25], s[20:21], v24, s37, v[30:31]
	global_load_dwordx4 v[24:27], v[24:25], off nt
	v_mov_b32_e32 v64, 1.0
	s_and_b64 vcc, exec, s[8:9]
	v_mov_b32_e32 v66, 1.0
	s_cbranch_vccnz .LBB0_1012
	global_load_dword v66, v[60:61], off offset:192 nt
.LBB0_1012:
	v_add_u32_e32 v28, 56, v28
	v_mad_i64_i32 v[28:29], s[20:21], v28, s37, v[30:31]
	global_load_dwordx4 v[28:31], v[28:29], off nt
	s_and_b64 vcc, exec, s[8:9]
	s_cbranch_vccnz .LBB0_921
	global_load_dword v64, v[60:61], off offset:224 nt
	s_branch .LBB0_921

; __device__ __forceinline__ unsigned pk_bf16(float lo, float hi) { typedef __bf16 b2_t __attribute__((ext_vector_type(2))); f32x2 v = {lo, hi}; b2_t b = __builtin_convertvector(v, b2_t); return __builtin_bit_cast(unsigned, b); }
; #define LAS __attribute__((address_space(3)))
; __device__ __forceinline__ void transpose_tile(const float* W, const float* gain, int K, int N, int k0, int n0, bf16* WT, int drow0, LAS float* scr, int lane) {
;     f32x4 v[8]; float gv[8];
;     const int r0 = lane >> 3, c4 = lane & 7;
; #pragma unroll
;     for (int i = 0; i < 8; ++i) { v[i] = *(const f32x4*)(W + (size_t)(k0 + r0 + 8 * i) * N + n0 + 4 * c4); gv[i] = gain ? gain[k0 + r0 + 8 * i] : 1.0f; }
; #pragma unroll
;     for (int i = 0; i < 8; ++i) { LAS float* d = scr + (r0 + 8 * i) * 33 + 4 * c4; d[0] = v[i][0] * gv[i]; d[1] = v[i][1] * gv[i]; d[2] = v[i][2] * gv[i]; d[3] = v[i][3] * gv[i]; }
;     asm volatile("s_waitcnt lgkmcnt(0)" ::: "memory");
;     const int c = lane & 7;
; #pragma unroll
;     for (int j = 0; j < 4; ++j) { const int n = (lane >> 3) + 8 * j; const LAS float* s = scr + (8 * c) * 33 + n;
;         v4u o; o.x = pk_bf16(s[0 * 33], s[1 * 33]); o.y = pk_bf16(s[2 * 33], s[3 * 33]); o.z = pk_bf16(s[4 * 33], s[5 * 33]); o.w = pk_bf16(s[6 * 33], s[7 * 33]);
;         *(v4u*)(WT + (size_t)(drow0 + n) * K + k0 + 8 * c) = o; }
;     asm volatile("s_waitcnt lgkmcnt(0)" ::: "memory");
; }
.LBB0_1020:
	s_cmpk_gt_i32 s22, 0xaff
	s_mov_b64 s[8:9], -1
	s_cbranch_scc0 .LBB0_1094
	s_cmpk_gt_u32 s22, 0x107f
	s_cbranch_scc0 .LBB0_1091
	s_cmpk_gt_u32 s22, 0x167f
	s_cbranch_scc0 .LBB0_1072
	s_cmpk_gt_u32 s22, 0x187f
	s_cbranch_scc0 .LBB0_1069
	s_cmpk_gt_u32 s22, 0x237f
	s_cbranch_scc0 .LBB0_1050
	s_cmpk_gt_u32 s22, 0x28ff
	s_cbranch_scc0 .LBB0_1047
	s_cmpk_gt_u32 s22, 0x33ff
	s_cbranch_scc0 .LBB0_1028
	s_mov_b32 s6, 14
	s_ashr_i32 s7, s6, 31
	s_lshl_b64 s[6:7], s[6:7], 3
	s_add_u32 s6, s0, s6
	s_addc_u32 s7, s1, s7
	s_load_dwordx2 s[6:7], s[6:7], 0x0
	s_lshl_b32 s8, s22, 5
	s_and_b32 s8, s8, 0x3e0
	s_and_b32 s9, s26, 0x1ffc0
	s_lshl_b32 s10, s8, 2
	v_add_u32_e32 v0, s9, v51
	s_waitcnt lgkmcnt(0)
	s_add_u32 s6, s6, s10
	s_addc_u32 s7, s7, 0
	v_ashrrev_i32_e32 v1, 31, v0
	v_lshl_add_u64 v[2:3], s[6:7], 0, v[32:33]
	v_lshlrev_b64 v[0:1], 12, v[0:1]
	v_lshl_add_u64 v[28:29], v[2:3], 0, v[0:1]
	v_add_co_u32_e32 v4, vcc, s28, v28
	s_lshl_b32 s10, s9, 1
	s_nop 0
	v_addc_co_u32_e32 v5, vcc, 0, v29, vcc
	v_add_co_u32_e32 v8, vcc, s29, v28
	global_load_dwordx4 v[0:3], v[28:29], off nt
	s_nop 0
	global_load_dwordx4 v[4:7], v[4:5], off nt
	v_addc_co_u32_e32 v9, vcc, 0, v29, vcc
	v_add_co_u32_e32 v12, vcc, s30, v28
	v_add_u32_e32 v50, s8, v51
	s_nop 0
	v_addc_co_u32_e32 v13, vcc, 0, v29, vcc
	v_add_co_u32_e32 v16, vcc, s31, v28
	global_load_dwordx4 v[8:11], v[8:9], off nt
	s_nop 0
	global_load_dwordx4 v[12:15], v[12:13], off nt
	v_addc_co_u32_e32 v17, vcc, 0, v29, vcc
	v_add_co_u32_e32 v20, vcc, s34, v28
	v_lshl_add_u64 v[56:57], v[34:35], 0, s[10:11]
	s_nop 0
	v_addc_co_u32_e32 v21, vcc, 0, v29, vcc
	global_load_dwordx4 v[16:19], v[16:17], off nt
	s_nop 0
	global_load_dwordx4 v[20:23], v[20:21], off nt
	v_add_co_u32_e32 v24, vcc, s35, v28
	v_add_u32_e32 v52, s8, v53
	s_nop 0
	v_addc_co_u32_e32 v25, vcc, 0, v29, vcc
	global_load_dwordx4 v[24:27], v[24:25], off nt
	v_add_co_u32_e32 v28, vcc, s36, v28
	v_mad_i64_i32 v[60:61], s[6:7], v50, s37, v[56:57]
	s_nop 0
	v_addc_co_u32_e32 v29, vcc, 0, v29, vcc
	global_load_dwordx4 v[28:31], v[28:29], off nt
	v_mad_i64_i32 v[82:83], s[6:7], v52, s37, v[56:57]
	s_waitcnt vmcnt(0)
	ds_write2_b32 v65, v0, v1 offset1:1
	ds_write2_b32 v65, v2, v3 offset0:2 offset1:3
	ds_write2_b32 v67, v4, v5 offset1:1
	ds_write2_b32 v68, v6, v7 offset1:1
	ds_write2_b32 v69, v8, v9 offset1:1
	ds_write2_b32 v70, v10, v11 offset1:1
	ds_write2_b32 v71, v12, v13 offset1:1
	ds_write2_b32 v72, v14, v15 offset1:1
	ds_write2_b32 v73, v16, v17 offset1:1
	ds_write2_b32 v74, v18, v19 offset1:1
	ds_write2_b32 v75, v20, v21 offset1:1
	ds_write2_b32 v76, v22, v23 offset1:1
	ds_write2_b32 v77, v24, v25 offset1:1
	ds_write2_b32 v78, v26, v27 offset1:1
	ds_write2_b32 v79, v28, v29 offset1:1
	ds_write2_b32 v80, v30, v31 offset1:1
	s_waitcnt lgkmcnt(0)
	ds_read2_b32 v[4:5], v63 offset0:33 offset1:41
	ds_read2_b32 v[6:7], v63 offset1:8
	ds_read2_b32 v[8:9], v63 offset0:66 offset1:74
	ds_read2_b32 v[10:11], v63 offset0:99 offset1:107
	ds_read2_b32 v[12:13], v63 offset0:132 offset1:140
	ds_read2_b32 v[14:15], v63 offset0:165 offset1:173
	ds_read2_b32 v[16:17], v63 offset0:198 offset1:206
	ds_read2_b32 v[18:19], v63 offset0:231 offset1:239
	ds_read2_b32 v[20:21], v63 offset0:49 offset1:57
	ds_read2_b32 v[22:23], v63 offset0:16 offset1:24
	ds_read2_b32 v[24:25], v63 offset0:82 offset1:90
	ds_read2_b32 v[26:27], v63 offset0:115 offset1:123
	ds_read2_b32 v[28:29], v63 offset0:148 offset1:156
	ds_read2_b32 v[30:31], v63 offset0:181 offset1:189
	ds_read2_b32 v[84:85], v63 offset0:214 offset1:222
	ds_read2_b32 v[86:87], v63 offset0:247 offset1:255
	s_waitcnt lgkmcnt(14)
	v_cvt_pk_bf16_f32 v0, v6, v4
	s_waitcnt lgkmcnt(12)
	v_cvt_pk_bf16_f32 v1, v8, v10
	s_waitcnt lgkmcnt(10)
	v_cvt_pk_bf16_f32 v2, v12, v14
	s_waitcnt lgkmcnt(8)
	v_cvt_pk_bf16_f32 v3, v16, v18
	v_cvt_pk_bf16_f32 v4, v7, v5
	v_cvt_pk_bf16_f32 v5, v9, v11
	v_cvt_pk_bf16_f32 v6, v13, v15
	v_cvt_pk_bf16_f32 v7, v17, v19
	global_store_dwordx4 v[60:61], v[0:3], off sc1
	global_store_dwordx4 v[82:83], v[4:7], off sc1
	s_waitcnt lgkmcnt(6)
	v_cvt_pk_bf16_f32 v0, v22, v20
	v_add_u32_e32 v4, s8, v55
	s_waitcnt lgkmcnt(4)
	v_cvt_pk_bf16_f32 v1, v24, v26
	s_waitcnt lgkmcnt(2)
	v_cvt_pk_bf16_f32 v2, v28, v30
	s_waitcnt lgkmcnt(0)
	v_cvt_pk_bf16_f32 v3, v84, v86
	v_mad_i64_i32 v[4:5], s[6:7], v4, s37, v[56:57]
	global_store_dwordx4 v[4:5], v[0:3], off sc1
	v_add_u32_e32 v4, s8, v59
	v_mad_i64_i32 v[4:5], s[6:7], v4, s37, v[56:57]
	v_cvt_pk_bf16_f32 v0, v23, v21
	v_cvt_pk_bf16_f32 v1, v25, v27
	v_cvt_pk_bf16_f32 v2, v29, v31
	v_cvt_pk_bf16_f32 v3, v85, v87
	global_store_dwordx4 v[4:5], v[0:3], off sc1
	s_waitcnt lgkmcnt(0)
	s_mov_b64 s[8:9], 0
; #define LAS __attribute__((address_space(3)))
; __device__ __forceinline__ void transpose_tile(const float* W, const float* gain, int K, int N, int k0, int n0, bf16* WT, int drow0, LAS float* scr, int lane) {
;     f32x4 v[8]; float gv[8];
;     const int r0 = lane >> 3, c4 = lane & 7;
; #pragma unroll
;     for (int i = 0; i < 8; ++i) { v[i] = *(const f32x4*)(W + (size_t)(k0 + r0 + 8 * i) * N + n0 + 4 * c4); gv[i] = gain ? gain[k0 + r0 + 8 * i] : 1.0f; }
; template <bool SWIGLU> __device__ __forceinline__ void transpose_item(const float* W, const float* gain, int K, int N, bf16* WT, LAS float* scr, int item, int lane) {
;     const int nblk = N / 32, kb = item / nblk, nb = item % nblk, n0 = 32 * nb;
;     int drow0 = n0;
;     if (SWIGLU) { const int up = n0 >= FF, f = up ? n0 - FF : n0; drow0 = 256 * (f >> 7) + (up ? 128 : 0) + (f & 127); }
.LBB0_1028:
	s_andn2_b64 vcc, exec, s[8:9]
	s_cbranch_vccnz .LBB0_1046
	s_mov_b32 s6, 13
	s_ashr_i32 s7, s6, 31
	s_lshl_b64 s[6:7], s[6:7], 3
	s_add_u32 s6, s0, s6
	s_addc_u32 s7, s1, s7
	s_load_dwordx2 s[8:9], s[6:7], 0x0
	s_mov_b32 s6, 12
	s_ashr_i32 s7, s6, 31
	s_lshl_b64 s[6:7], s[6:7], 3
	s_add_u32 s12, s0, s6
	s_addc_u32 s13, s1, s7
	s_add_i32 s6, s22, 0xd700
	s_and_b32 s7, s6, 0xffff
	s_mul_i32 s7, s7, 0xba2f
	s_lshr_b32 s10, s7, 23
	s_mul_i32 s7, s10, 0xb0
	s_sub_i32 s7, s6, s7
	s_lshl_b32 s6, s10, 6
	s_lshl_b32 s10, s7, 7
	s_and_b32 s10, s10, 0x3ff80
	s_waitcnt lgkmcnt(0)
	s_add_u32 s8, s8, s10
	s_addc_u32 s9, s9, 0
	v_add_u32_e32 v28, s6, v51
	v_lshl_add_u64 v[30:31], s[8:9], 0, v[32:33]
	v_mad_i64_i32 v[0:1], s[8:9], v28, s38, v[30:31]
	global_load_dwordx4 v[0:3], v[0:1], off nt
	s_load_dwordx2 s[8:9], s[12:13], 0x0
	v_ashrrev_i32_e32 v29, 31, v28
	v_mov_b32_e32 v50, 1.0
	v_mov_b32_e32 v52, 1.0
	s_waitcnt lgkmcnt(0)
	s_cmp_lg_u64 s[8:9], 0
	s_cselect_b64 s[12:13], -1, 0
	s_cmp_eq_u64 s[8:9], 0
	v_lshl_add_u64 v[60:61], v[28:29], 2, s[8:9]
	s_cbranch_scc1 .LBB0_1031
	global_load_dword v52, v[60:61], off nt
.LBB0_1031:
	v_add_u32_e32 v4, 8, v28
	v_mad_i64_i32 v[4:5], s[8:9], v4, s38, v[30:31]
	global_load_dwordx4 v[4:7], v[4:5], off nt
	v_cndmask_b32_e64 v8, 0, 1, s[12:13]
	v_cmp_ne_u32_e64 s[8:9], 1, v8
	s_andn2_b64 vcc, exec, s[12:13]
	s_cbranch_vccnz .LBB0_1033
	global_load_dword v50, v[60:61], off offset:32 nt
.LBB0_1033:
	v_add_u32_e32 v8, 16, v28
	v_mad_i64_i32 v[8:9], s[12:13], v8, s38, v[30:31]
	global_load_dwordx4 v[8:11], v[8:9], off nt
	v_mov_b32_e32 v54, 1.0
	s_and_b64 vcc, exec, s[8:9]
	v_mov_b32_e32 v56, 1.0
	s_cbranch_vccnz .LBB0_1035
	global_load_dword v56, v[60:61], off offset:64 nt
.LBB0_1035:
	v_add_u32_e32 v12, 24, v28
	v_mad_i64_i32 v[12:13], s[12:13], v12, s38, v[30:31]
	global_load_dwordx4 v[12:15], v[12:13], off nt
	s_and_b64 vcc, exec, s[8:9]
	s_cbranch_vccnz .LBB0_1037
	global_load_dword v54, v[60:61], off offset:96 nt
.LBB0_1037:
	v_add_u32_e32 v16, 32, v28
	v_mad_i64_i32 v[16:17], s[12:13], v16, s38, v[30:31]
	global_load_dwordx4 v[16:19], v[16:17], off nt
	v_mov_b32_e32 v58, 1.0
	s_and_b64 vcc, exec, s[8:9]
	v_mov_b32_e32 v62, 1.0
	s_cbranch_vccnz .LBB0_1039
	global_load_dword v62, v[60:61], off offset:128 nt
.LBB0_1039:
	v_add_u32_e32 v20, 40, v28
	v_mad_i64_i32 v[20:21], s[12:13], v20, s38, v[30:31]
	global_load_dwordx4 v[20:23], v[20:21], off nt
	s_and_b64 vcc, exec, s[8:9]
	s_cbranch_vccnz .LBB0_1041
	global_load_dword v58, v[60:61], off offset:160 nt
.LBB0_1041:
	v_add_u32_e32 v24, 48, v28
	v_mad_i64_i32 v[24:25], s[12:13], v24, s38, v[30:31]
	global_load_dwordx4 v[24:27], v[24:25], off nt
	v_mov_b32_e32 v64, 1.0
	s_and_b64 vcc, exec, s[8:9]
	v_mov_b32_e32 v66, 1.0
	s_cbranch_vccnz .LBB0_1043
	global_load_dword v66, v[60:61], off offset:192 nt
.LBB0_1043:
	v_add_u32_e32 v28, 56, v28
	v_mad_i64_i32 v[28:29], s[12:13], v28, s38, v[30:31]
	global_load_dwordx4 v[28:31], v[28:29], off nt
	s_and_b64 vcc, exec, s[8:9]
	s_cbranch_vccnz .LBB0_1045
	global_load_dword v64, v[60:61], off offset:224 nt

; __device__ __forceinline__ unsigned pk_bf16(float lo, float hi) { typedef __bf16 b2_t __attribute__((ext_vector_type(2))); f32x2 v = {lo, hi}; b2_t b = __builtin_convertvector(v, b2_t); return __builtin_bit_cast(unsigned, b); }
; #define LAS __attribute__((address_space(3)))
; __device__ __forceinline__ void transpose_tile(const float* W, const float* gain, int K, int N, int k0, int n0, bf16* WT, int drow0, LAS float* scr, int lane) {
;     f32x4 v[8]; float gv[8];
;     const int r0 = lane >> 3, c4 = lane & 7;
; #pragma unroll
;     for (int i = 0; i < 8; ++i) { v[i] = *(const f32x4*)(W + (size_t)(k0 + r0 + 8 * i) * N + n0 + 4 * c4); gv[i] = gain ? gain[k0 + r0 + 8 * i] : 1.0f; }
; #pragma unroll
;     for (int i = 0; i < 8; ++i) { LAS float* d = scr + (r0 + 8 * i) * 33 + 4 * c4; d[0] = v[i][0] * gv[i]; d[1] = v[i][1] * gv[i]; d[2] = v[i][2] * gv[i]; d[3] = v[i][3] * gv[i]; }
;     asm volatile("s_waitcnt lgkmcnt(0)" ::: "memory");
;     const int c = lane & 7;
; #pragma unroll
;     for (int j = 0; j < 4; ++j) { const int n = (lane >> 3) + 8 * j; const LAS float* s = scr + (8 * c) * 33 + n;
;         v4u o; o.x = pk_bf16(s[0 * 33], s[1 * 33]); o.y = pk_bf16(s[2 * 33], s[3 * 33]); o.z = pk_bf16(s[4 * 33], s[5 * 33]); o.w = pk_bf16(s[6 * 33], s[7 * 33]);
;         *(v4u*)(WT + (size_t)(drow0 + n) * K + k0 + 8 * c) = o; }
;     asm volatile("s_waitcnt lgkmcnt(0)" ::: "memory");
; }
.LBB0_1047:
	s_andn2_b64 vcc, exec, s[8:9]
	s_cbranch_vccnz .LBB0_1049
	s_mov_b32 s6, 11
	s_ashr_i32 s7, s6, 31
	s_lshl_b64 s[6:7], s[6:7], 3
	s_add_u32 s6, s0, s6
	s_addc_u32 s7, s1, s7
	s_load_dwordx2 s[6:7], s[6:7], 0x0
	s_lshl_b32 s8, s22, 5
	s_and_b32 s8, s8, 0x3e0
	s_add_i32 s9, s26, 0x2100
	s_and_b32 s9, s9, 0x1ffc0
	s_lshl_b32 s10, s8, 2
	v_add_u32_e32 v0, s9, v51
	s_waitcnt lgkmcnt(0)
	s_add_u32 s6, s6, s10
	s_addc_u32 s7, s7, 0
	v_ashrrev_i32_e32 v1, 31, v0
	v_lshl_add_u64 v[2:3], s[6:7], 0, v[32:33]
	v_lshlrev_b64 v[0:1], 12, v[0:1]
	v_lshl_add_u64 v[28:29], v[2:3], 0, v[0:1]
	v_add_co_u32_e32 v4, vcc, s28, v28
	s_lshl_b32 s10, s9, 1
	s_nop 0
	v_addc_co_u32_e32 v5, vcc, 0, v29, vcc
	v_add_co_u32_e32 v8, vcc, s29, v28
	global_load_dwordx4 v[0:3], v[28:29], off nt
	s_nop 0
	global_load_dwordx4 v[4:7], v[4:5], off nt
	v_addc_co_u32_e32 v9, vcc, 0, v29, vcc
	v_add_co_u32_e32 v12, vcc, s30, v28
	v_add_u32_e32 v50, s8, v51
	s_nop 0
	v_addc_co_u32_e32 v13, vcc, 0, v29, vcc
	v_add_co_u32_e32 v16, vcc, s31, v28
	global_load_dwordx4 v[8:11], v[8:9], off nt
	s_nop 0
	global_load_dwordx4 v[12:15], v[12:13], off nt
	v_addc_co_u32_e32 v17, vcc, 0, v29, vcc
	v_add_co_u32_e32 v20, vcc, s34, v28
	v_lshl_add_u64 v[56:57], v[38:39], 0, s[10:11]
	s_nop 0
	v_addc_co_u32_e32 v21, vcc, 0, v29, vcc
	global_load_dwordx4 v[16:19], v[16:17], off nt
	s_nop 0
	global_load_dwordx4 v[20:23], v[20:21], off nt
	v_add_co_u32_e32 v24, vcc, s35, v28
	v_add_u32_e32 v52, s8, v53
	s_nop 0
	v_addc_co_u32_e32 v25, vcc, 0, v29, vcc
	global_load_dwordx4 v[24:27], v[24:25], off nt
	v_add_co_u32_e32 v28, vcc, s36, v28
	v_mad_i64_i32 v[60:61], s[6:7], v50, s37, v[56:57]
	s_nop 0
	v_addc_co_u32_e32 v29, vcc, 0, v29, vcc
	global_load_dwordx4 v[28:31], v[28:29], off nt
	v_mad_i64_i32 v[82:83], s[6:7], v52, s37, v[56:57]
	s_waitcnt vmcnt(0)
	ds_write2_b32 v65, v0, v1 offset1:1
	ds_write2_b32 v65, v2, v3 offset0:2 offset1:3
	ds_write2_b32 v67, v4, v5 offset1:1
	ds_write2_b32 v68, v6, v7 offset1:1
	ds_write2_b32 v69, v8, v9 offset1:1
	ds_write2_b32 v70, v10, v11 offset1:1
	ds_write2_b32 v71, v12, v13 offset1:1
	ds_write2_b32 v72, v14, v15 offset1:1
	ds_write2_b32 v73, v16, v17 offset1:1
	ds_write2_b32 v74, v18, v19 offset1:1
	ds_write2_b32 v75, v20, v21 offset1:1
	ds_write2_b32 v76, v22, v23 offset1:1
	ds_write2_b32 v77, v24, v25 offset1:1
	ds_write2_b32 v78, v26, v27 offset1:1
	ds_write2_b32 v79, v28, v29 offset1:1
	ds_write2_b32 v80, v30, v31 offset1:1
	s_waitcnt lgkmcnt(0)
	ds_read2_b32 v[4:5], v63 offset0:33 offset1:41
	ds_read2_b32 v[6:7], v63 offset1:8
	ds_read2_b32 v[8:9], v63 offset0:66 offset1:74
	ds_read2_b32 v[10:11], v63 offset0:99 offset1:107
	ds_read2_b32 v[12:13], v63 offset0:132 offset1:140
	ds_read2_b32 v[14:15], v63 offset0:165 offset1:173
	ds_read2_b32 v[16:17], v63 offset0:198 offset1:206
	ds_read2_b32 v[18:19], v63 offset0:231 offset1:239
	ds_read2_b32 v[20:21], v63 offset0:49 offset1:57
	ds_read2_b32 v[22:23], v63 offset0:16 offset1:24
	ds_read2_b32 v[24:25], v63 offset0:82 offset1:90
	ds_read2_b32 v[26:27], v63 offset0:115 offset1:123
	ds_read2_b32 v[28:29], v63 offset0:148 offset1:156
	ds_read2_b32 v[30:31], v63 offset0:181 offset1:189
	ds_read2_b32 v[84:85], v63 offset0:214 offset1:222
	ds_read2_b32 v[86:87], v63 offset0:247 offset1:255
	s_waitcnt lgkmcnt(14)
	v_cvt_pk_bf16_f32 v0, v6, v4
	s_waitcnt lgkmcnt(12)
	v_cvt_pk_bf16_f32 v1, v8, v10
	s_waitcnt lgkmcnt(10)
	v_cvt_pk_bf16_f32 v2, v12, v14
	s_waitcnt lgkmcnt(8)
	v_cvt_pk_bf16_f32 v3, v16, v18
	v_cvt_pk_bf16_f32 v4, v7, v5
	v_cvt_pk_bf16_f32 v5, v9, v11
	v_cvt_pk_bf16_f32 v6, v13, v15
	v_cvt_pk_bf16_f32 v7, v17, v19
	global_store_dwordx4 v[60:61], v[0:3], off sc1
	global_store_dwordx4 v[82:83], v[4:7], off sc1
	s_waitcnt lgkmcnt(6)
	v_cvt_pk_bf16_f32 v0, v22, v20
	v_add_u32_e32 v4, s8, v55
	s_waitcnt lgkmcnt(4)
	v_cvt_pk_bf16_f32 v1, v24, v26
	s_waitcnt lgkmcnt(2)
	v_cvt_pk_bf16_f32 v2, v28, v30
	s_waitcnt lgkmcnt(0)
	v_cvt_pk_bf16_f32 v3, v84, v86
	v_mad_i64_i32 v[4:5], s[6:7], v4, s37, v[56:57]
	global_store_dwordx4 v[4:5], v[0:3], off sc1
	v_add_u32_e32 v4, s8, v59
	v_mad_i64_i32 v[4:5], s[6:7], v4, s37, v[56:57]
	v_cvt_pk_bf16_f32 v0, v23, v21
	v_cvt_pk_bf16_f32 v1, v25, v27
	v_cvt_pk_bf16_f32 v2, v29, v31
	v_cvt_pk_bf16_f32 v3, v85, v87
	global_store_dwordx4 v[4:5], v[0:3], off sc1
	s_waitcnt lgkmcnt(0)

; __device__ __forceinline__ void transpose_tile(const float* W, const float* gain, int K, int N, int k0, int n0, bf16* WT, int drow0, LAS float* scr, int lane) {
;     ...
; #pragma unroll
;     for (int i = 0; i < 8; ++i) { v[i] = *(const f32x4*)(W + (size_t)(k0 + r0 + 8 * i) * N + n0 + 4 * c4); gv[i] = gain ? gain[k0 + r0 + 8 * i] : 1.0f; }
; template <bool SWIGLU> __device__ __forceinline__ void transpose_item(const float* W, const float* gain, int K, int N, bf16* WT, LAS float* scr, int item, int lane) {
;     const int nblk = N / 32, kb = item / nblk, nb = item % nblk, n0 = 32 * nb;
;     int drow0 = n0;
;     if (SWIGLU) { const int up = n0 >= FF, f = up ? n0 - FF : n0; drow0 = 256 * (f >> 7) + (up ? 128 : 0) + (f & 127); }
.LBB0_1050:
	s_andn2_b64 vcc, exec, s[8:9]
	s_cbranch_vccnz .LBB0_1068
	s_mov_b32 s6, 10
	s_ashr_i32 s7, s6, 31
	s_lshl_b64 s[6:7], s[6:7], 3
	s_add_u32 s6, s0, s6
	s_addc_u32 s7, s1, s7
	s_load_dwordx2 s[8:9], s[6:7], 0x0
	s_mov_b32 s6, 9
	s_ashr_i32 s7, s6, 31
	s_lshl_b64 s[6:7], s[6:7], 3
	s_add_u32 s12, s0, s6
	s_addc_u32 s13, s1, s7
	s_add_i32 s6, s22, 0xe780
	s_and_b32 s7, s6, 0xffff
	s_mul_i32 s7, s7, 0xba2f
	s_lshr_b32 s10, s7, 23
	s_mul_i32 s7, s10, 0xb0
	s_sub_i32 s7, s6, s7
	s_lshl_b32 s6, s10, 6
	s_lshl_b32 s10, s7, 7
	s_and_b32 s10, s10, 0x3ff80
	s_waitcnt lgkmcnt(0)
	s_add_u32 s8, s8, s10
	s_addc_u32 s9, s9, 0
	v_add_u32_e32 v28, s6, v51
	v_lshl_add_u64 v[30:31], s[8:9], 0, v[32:33]
	v_mad_i64_i32 v[0:1], s[8:9], v28, s38, v[30:31]
	global_load_dwordx4 v[0:3], v[0:1], off nt
	s_load_dwordx2 s[8:9], s[12:13], 0x0
	v_ashrrev_i32_e32 v29, 31, v28
	v_mov_b32_e32 v50, 1.0
	v_mov_b32_e32 v52, 1.0
	s_waitcnt lgkmcnt(0)
	s_cmp_lg_u64 s[8:9], 0
	s_cselect_b64 s[12:13], -1, 0
	s_cmp_eq_u64 s[8:9], 0
	v_lshl_add_u64 v[60:61], v[28:29], 2, s[8:9]
	s_cbranch_scc1 .LBB0_1053
	global_load_dword v52, v[60:61], off nt

; __device__ __forceinline__ unsigned pk_bf16(float lo, float hi) { typedef __bf16 b2_t __attribute__((ext_vector_type(2))); f32x2 v = {lo, hi}; b2_t b = __builtin_convertvector(v, b2_t); return __builtin_bit_cast(unsigned, b); }
; #define LAS __attribute__((address_space(3)))
; __device__ __forceinline__ void transpose_tile(const float* W, const float* gain, int K, int N, int k0, int n0, bf16* WT, int drow0, LAS float* scr, int lane) {
;     f32x4 v[8]; float gv[8];
;     const int r0 = lane >> 3, c4 = lane & 7;
; #pragma unroll
;     for (int i = 0; i < 8; ++i) { v[i] = *(const f32x4*)(W + (size_t)(k0 + r0 + 8 * i) * N + n0 + 4 * c4); gv[i] = gain ? gain[k0 + r0 + 8 * i] : 1.0f; }
; #pragma unroll
;     for (int i = 0; i < 8; ++i) { LAS float* d = scr + (r0 + 8 * i) * 33 + 4 * c4; d[0] = v[i][0] * gv[i]; d[1] = v[i][1] * gv[i]; d[2] = v[i][2] * gv[i]; d[3] = v[i][3] * gv[i]; }
;     asm volatile("s_waitcnt lgkmcnt(0)" ::: "memory");
;     const int c = lane & 7;
; #pragma unroll
;     for (int j = 0; j < 4; ++j) { const int n = (lane >> 3) + 8 * j; const LAS float* s = scr + (8 * c) * 33 + n;
;         v4u o; o.x = pk_bf16(s[0 * 33], s[1 * 33]); o.y = pk_bf16(s[2 * 33], s[3 * 33]); o.z = pk_bf16(s[4 * 33], s[5 * 33]); o.w = pk_bf16(s[6 * 33], s[7 * 33]);
;         *(v4u*)(WT + (size_t)(drow0 + n) * K + k0 + 8 * c) = o; }
;     asm volatile("s_waitcnt lgkmcnt(0)" ::: "memory");
; }
.LBB0_1069:
	s_andn2_b64 vcc, exec, s[8:9]
	s_cbranch_vccnz .LBB0_1071
	s_mov_b32 s6, 8
	s_ashr_i32 s7, s6, 31
	s_lshl_b64 s[6:7], s[6:7], 3
	s_add_u32 s6, s0, s6
	s_addc_u32 s7, s1, s7
	s_load_dwordx2 s[6:7], s[6:7], 0x0
	s_lshl_b32 s8, s22, 5
	s_and_b32 s8, s8, 0x3e0
	s_add_i32 s9, s26, 0x3b00
	s_and_b32 s9, s9, 0x1ffc0
	s_lshl_b32 s10, s8, 2
	v_add_u32_e32 v0, s9, v51
	s_waitcnt lgkmcnt(0)
	s_add_u32 s6, s6, s10
	s_addc_u32 s7, s7, 0
	v_ashrrev_i32_e32 v1, 31, v0
	v_lshl_add_u64 v[2:3], s[6:7], 0, v[32:33]
	v_lshlrev_b64 v[0:1], 12, v[0:1]
	v_lshl_add_u64 v[28:29], v[2:3], 0, v[0:1]
	v_add_co_u32_e32 v4, vcc, s28, v28
	v_add_u32_e32 v56, s8, v51
	s_nop 0
	v_addc_co_u32_e32 v5, vcc, 0, v29, vcc
	v_add_co_u32_e32 v8, vcc, s29, v28
	global_load_dwordx4 v[0:3], v[28:29], off nt
	s_nop 0
	global_load_dwordx4 v[4:7], v[4:5], off nt
	v_addc_co_u32_e32 v9, vcc, 0, v29, vcc
	v_add_co_u32_e32 v12, vcc, s30, v28
	v_ashrrev_i32_e32 v57, 31, v56
	s_nop 0
	v_addc_co_u32_e32 v13, vcc, 0, v29, vcc
	v_add_co_u32_e32 v16, vcc, s31, v28
	global_load_dwordx4 v[8:11], v[8:9], off nt
	s_nop 0
	global_load_dwordx4 v[12:15], v[12:13], off nt
	v_addc_co_u32_e32 v17, vcc, 0, v29, vcc
	v_add_co_u32_e32 v20, vcc, s34, v28
	s_lshl_b32 s10, s9, 1
	s_nop 0
	v_addc_co_u32_e32 v21, vcc, 0, v29, vcc
	global_load_dwordx4 v[16:19], v[16:17], off nt
	s_nop 0
	global_load_dwordx4 v[20:23], v[20:21], off nt
	v_add_co_u32_e32 v24, vcc, s35, v28
	v_lshlrev_b64 v[56:57], 11, v[56:57]
	s_nop 0
	v_addc_co_u32_e32 v25, vcc, 0, v29, vcc
	global_load_dwordx4 v[24:27], v[24:25], off nt
	v_add_co_u32_e32 v28, vcc, s36, v28
	v_lshl_add_u64 v[82:83], v[42:43], 0, s[10:11]
	s_nop 0
	v_addc_co_u32_e32 v29, vcc, 0, v29, vcc
	global_load_dwordx4 v[28:31], v[28:29], off nt
	v_add_u32_e32 v60, s8, v53
	v_lshl_add_u64 v[56:57], v[82:83], 0, v[56:57]
	v_ashrrev_i32_e32 v61, 31, v60
	v_lshlrev_b64 v[60:61], 11, v[60:61]
	v_lshl_add_u64 v[60:61], v[82:83], 0, v[60:61]
	s_waitcnt vmcnt(0)
	ds_write2_b32 v65, v0, v1 offset1:1
	ds_write2_b32 v65, v2, v3 offset0:2 offset1:3
	ds_write2_b32 v67, v4, v5 offset1:1
	ds_write2_b32 v68, v6, v7 offset1:1
	ds_write2_b32 v69, v8, v9 offset1:1
	ds_write2_b32 v70, v10, v11 offset1:1
	ds_write2_b32 v71, v12, v13 offset1:1
	ds_write2_b32 v72, v14, v15 offset1:1
	ds_write2_b32 v73, v16, v17 offset1:1
	ds_write2_b32 v74, v18, v19 offset1:1
	ds_write2_b32 v75, v20, v21 offset1:1
	ds_write2_b32 v76, v22, v23 offset1:1
	ds_write2_b32 v77, v24, v25 offset1:1
	ds_write2_b32 v78, v26, v27 offset1:1
	ds_write2_b32 v79, v28, v29 offset1:1
	ds_write2_b32 v80, v30, v31 offset1:1
	s_waitcnt lgkmcnt(0)
	ds_read2_b32 v[4:5], v63 offset0:33 offset1:41
	ds_read2_b32 v[6:7], v63 offset1:8
	ds_read2_b32 v[8:9], v63 offset0:66 offset1:74
	ds_read2_b32 v[10:11], v63 offset0:99 offset1:107
	ds_read2_b32 v[12:13], v63 offset0:132 offset1:140
	ds_read2_b32 v[14:15], v63 offset0:165 offset1:173
	ds_read2_b32 v[16:17], v63 offset0:198 offset1:206
	ds_read2_b32 v[18:19], v63 offset0:231 offset1:239
	ds_read2_b32 v[20:21], v63 offset0:49 offset1:57
	ds_read2_b32 v[22:23], v63 offset0:16 offset1:24
	ds_read2_b32 v[24:25], v63 offset0:82 offset1:90
	ds_read2_b32 v[26:27], v63 offset0:115 offset1:123
	ds_read2_b32 v[28:29], v63 offset0:148 offset1:156
	ds_read2_b32 v[30:31], v63 offset0:181 offset1:189
	s_waitcnt lgkmcnt(12)
	v_cvt_pk_bf16_f32 v0, v6, v4
	s_waitcnt lgkmcnt(10)
	v_cvt_pk_bf16_f32 v1, v8, v10
	s_waitcnt lgkmcnt(8)
	v_cvt_pk_bf16_f32 v2, v12, v14
	s_waitcnt lgkmcnt(6)
	v_cvt_pk_bf16_f32 v3, v16, v18
	global_store_dwordx4 v[56:57], v[0:3], off sc1
	v_cvt_pk_bf16_f32 v4, v7, v5
	v_cvt_pk_bf16_f32 v5, v9, v11
	ds_read2_b32 v[8:9], v63 offset0:214 offset1:222
	ds_read2_b32 v[10:11], v63 offset0:247 offset1:255
	v_cvt_pk_bf16_f32 v6, v13, v15
	v_cvt_pk_bf16_f32 v7, v17, v19
	global_store_dwordx4 v[60:61], v[4:7], off sc1
	s_waitcnt lgkmcnt(6)
	v_cvt_pk_bf16_f32 v0, v22, v20
	s_waitcnt lgkmcnt(4)
	v_cvt_pk_bf16_f32 v1, v24, v26
	v_add_u32_e32 v4, s8, v55
	v_ashrrev_i32_e32 v5, 31, v4
	v_lshlrev_b64 v[4:5], 11, v[4:5]
	s_waitcnt lgkmcnt(2)
	v_cvt_pk_bf16_f32 v2, v28, v30
	s_waitcnt lgkmcnt(0)
	v_cvt_pk_bf16_f32 v3, v8, v10
	v_lshl_add_u64 v[4:5], v[82:83], 0, v[4:5]
	global_store_dwordx4 v[4:5], v[0:3], off sc1
	v_add_u32_e32 v4, s8, v59
	v_ashrrev_i32_e32 v5, 31, v4
	v_lshlrev_b64 v[4:5], 11, v[4:5]
	v_cvt_pk_bf16_f32 v0, v23, v21
	v_cvt_pk_bf16_f32 v1, v25, v27
	v_cvt_pk_bf16_f32 v2, v29, v31
	v_cvt_pk_bf16_f32 v3, v9, v11
	v_lshl_add_u64 v[4:5], v[82:83], 0, v[4:5]
	global_store_dwordx4 v[4:5], v[0:3], off sc1
	s_waitcnt lgkmcnt(0)

; #define LAS __attribute__((address_space(3)))
; __device__ __forceinline__ void transpose_tile(const float* W, const float* gain, int K, int N, int k0, int n0, bf16* WT, int drow0, LAS float* scr, int lane) {
;     f32x4 v[8]; float gv[8];
;     const int r0 = lane >> 3, c4 = lane & 7;
; #pragma unroll
;     for (int i = 0; i < 8; ++i) { v[i] = *(const f32x4*)(W + (size_t)(k0 + r0 + 8 * i) * N + n0 + 4 * c4); gv[i] = gain ? gain[k0 + r0 + 8 * i] : 1.0f; }
; template <bool SWIGLU> __device__ __forceinline__ void transpose_item(const float* W, const float* gain, int K, int N, bf16* WT, LAS float* scr, int item, int lane) {
;     const int nblk = N / 32, kb = item / nblk, nb = item % nblk, n0 = 32 * nb;
;     int drow0 = n0;
;     if (SWIGLU) { const int up = n0 >= FF, f = up ? n0 - FF : n0; drow0 = 256 * (f >> 7) + (up ? 128 : 0) + (f & 127); }
.LBB0_1072:
	s_andn2_b64 vcc, exec, s[8:9]
	s_cbranch_vccnz .LBB0_1090
	s_mov_b32 s6, 5
	s_ashr_i32 s7, s6, 31
	s_lshl_b64 s[6:7], s[6:7], 3
	s_add_u32 s6, s0, s6
	s_addc_u32 s7, s1, s7
	s_load_dwordx2 s[8:9], s[6:7], 0x0
	s_mov_b32 s6, 4
	s_ashr_i32 s7, s6, 31
	s_lshl_b64 s[6:7], s[6:7], 3
	s_add_u32 s12, s0, s6
	s_addc_u32 s13, s1, s7
	s_add_i32 s6, s22, 0xef80
	s_and_b32 s7, s6, 0xffff
	s_mul_i32 s7, s7, 0xaaab
	s_lshr_b32 s10, s7, 16
	s_lshr_b32 s7, s7, 22
	s_mulk_i32 s7, 0x60
	s_sub_i32 s7, s6, s7
	s_and_b32 s6, s10, 0xffc0
	s_lshl_b32 s10, s7, 7
	s_and_b32 s10, s10, 0x3ff80
	s_waitcnt lgkmcnt(0)
	s_add_u32 s8, s8, s10
	s_addc_u32 s9, s9, 0
	v_add_u32_e32 v28, s6, v51
	v_lshl_add_u64 v[30:31], s[8:9], 0, v[32:33]
	v_mad_i64_i32 v[0:1], s[8:9], v28, s39, v[30:31]
	global_load_dwordx4 v[0:3], v[0:1], off nt
	s_load_dwordx2 s[8:9], s[12:13], 0x0
	v_ashrrev_i32_e32 v29, 31, v28
	v_mov_b32_e32 v50, 1.0
	v_mov_b32_e32 v52, 1.0
	s_waitcnt lgkmcnt(0)
	s_cmp_lg_u64 s[8:9], 0
	s_cselect_b64 s[12:13], -1, 0
	s_cmp_eq_u64 s[8:9], 0
	v_lshl_add_u64 v[56:57], v[28:29], 2, s[8:9]
	s_cbranch_scc1 .LBB0_1075
	global_load_dword v52, v[56:57], off nt
.LBB0_1075:
	v_add_u32_e32 v4, 8, v28
	v_mad_i64_i32 v[4:5], s[8:9], v4, s39, v[30:31]
	global_load_dwordx4 v[4:7], v[4:5], off nt
	v_cndmask_b32_e64 v8, 0, 1, s[12:13]
	v_cmp_ne_u32_e64 s[8:9], 1, v8
	s_andn2_b64 vcc, exec, s[12:13]
	s_cbranch_vccnz .LBB0_1077
	global_load_dword v50, v[56:57], off offset:32 nt
.LBB0_1077:
	v_add_u32_e32 v8, 16, v28
	v_mad_i64_i32 v[8:9], s[12:13], v8, s39, v[30:31]
	global_load_dwordx4 v[8:11], v[8:9], off nt
	v_mov_b32_e32 v54, 1.0
	s_and_b64 vcc, exec, s[8:9]
	v_mov_b32_e32 v58, 1.0
	s_cbranch_vccnz .LBB0_1079
	global_load_dword v58, v[56:57], off offset:64 nt
.LBB0_1079:
	v_add_u32_e32 v12, 24, v28
	v_mad_i64_i32 v[12:13], s[12:13], v12, s39, v[30:31]
	global_load_dwordx4 v[12:15], v[12:13], off nt
	s_and_b64 vcc, exec, s[8:9]
	s_cbranch_vccnz .LBB0_1081
	global_load_dword v54, v[56:57], off offset:96 nt
.LBB0_1081:
	v_add_u32_e32 v16, 32, v28
	v_mad_i64_i32 v[16:17], s[12:13], v16, s39, v[30:31]
	global_load_dwordx4 v[16:19], v[16:17], off nt
	v_mov_b32_e32 v60, 1.0
	s_and_b64 vcc, exec, s[8:9]
	v_mov_b32_e32 v62, 1.0
	s_cbranch_vccnz .LBB0_1083
	global_load_dword v62, v[56:57], off offset:128 nt
.LBB0_1083:
	v_add_u32_e32 v20, 40, v28
	v_mad_i64_i32 v[20:21], s[12:13], v20, s39, v[30:31]
	global_load_dwordx4 v[20:23], v[20:21], off nt
	s_and_b64 vcc, exec, s[8:9]
	s_cbranch_vccnz .LBB0_1085
	global_load_dword v60, v[56:57], off offset:160 nt
.LBB0_1085:
	v_add_u32_e32 v24, 48, v28
	v_mad_i64_i32 v[24:25], s[12:13], v24, s39, v[30:31]
	global_load_dwordx4 v[24:27], v[24:25], off nt
	v_mov_b32_e32 v64, 1.0
	s_and_b64 vcc, exec, s[8:9]
	v_mov_b32_e32 v66, 1.0
	s_cbranch_vccnz .LBB0_1087
	global_load_dword v66, v[56:57], off offset:192 nt
.LBB0_1087:
	v_add_u32_e32 v28, 56, v28
	v_mad_i64_i32 v[28:29], s[12:13], v28, s39, v[30:31]
	global_load_dwordx4 v[28:31], v[28:29], off nt
	s_and_b64 vcc, exec, s[8:9]
	s_cbranch_vccnz .LBB0_1089
	global_load_dword v64, v[56:57], off offset:224 nt

; __device__ __forceinline__ unsigned pk_bf16(float lo, float hi) { typedef __bf16 b2_t __attribute__((ext_vector_type(2))); f32x2 v = {lo, hi}; b2_t b = __builtin_convertvector(v, b2_t); return __builtin_bit_cast(unsigned, b); }
; #define LAS __attribute__((address_space(3)))
; __device__ __forceinline__ void transpose_tile(const float* W, const float* gain, int K, int N, int k0, int n0, bf16* WT, int drow0, LAS float* scr, int lane) {
;     f32x4 v[8]; float gv[8];
;     const int r0 = lane >> 3, c4 = lane & 7;
; #pragma unroll
;     for (int i = 0; i < 8; ++i) { v[i] = *(const f32x4*)(W + (size_t)(k0 + r0 + 8 * i) * N + n0 + 4 * c4); gv[i] = gain ? gain[k0 + r0 + 8 * i] : 1.0f; }
; #pragma unroll
;     for (int i = 0; i < 8; ++i) { LAS float* d = scr + (r0 + 8 * i) * 33 + 4 * c4; d[0] = v[i][0] * gv[i]; d[1] = v[i][1] * gv[i]; d[2] = v[i][2] * gv[i]; d[3] = v[i][3] * gv[i]; }
;     asm volatile("s_waitcnt lgkmcnt(0)" ::: "memory");
;     const int c = lane & 7;
; #pragma unroll
;     for (int j = 0; j < 4; ++j) { const int n = (lane >> 3) + 8 * j; const LAS float* s = scr + (8 * c) * 33 + n;
;         v4u o; o.x = pk_bf16(s[0 * 33], s[1 * 33]); o.y = pk_bf16(s[2 * 33], s[3 * 33]); o.z = pk_bf16(s[4 * 33], s[5 * 33]); o.w = pk_bf16(s[6 * 33], s[7 * 33]);
;         *(v4u*)(WT + (size_t)(drow0 + n) * K + k0 + 8 * c) = o; }
;     asm volatile("s_waitcnt lgkmcnt(0)" ::: "memory");
; }
.LBB0_1091:
	s_andn2_b64 vcc, exec, s[8:9]
	s_cbranch_vccnz .LBB0_1093
	s_mov_b32 s6, 3
	s_ashr_i32 s7, s6, 31
	s_lshl_b64 s[6:7], s[6:7], 3
	s_add_u32 s6, s0, s6
	s_addc_u32 s7, s1, s7
	s_load_dwordx2 s[6:7], s[6:7], 0x0
	s_lshl_b32 s8, s22, 5
	s_and_b32 s8, s8, 0x3e0
	s_add_i32 s9, s26, 0x5200
	s_and_b32 s9, s9, 0x1ffc0
	s_lshl_b32 s10, s8, 2
	v_add_u32_e32 v0, s9, v51
	s_waitcnt lgkmcnt(0)
	s_add_u32 s6, s6, s10
	s_addc_u32 s7, s7, 0
	v_ashrrev_i32_e32 v1, 31, v0
	v_lshl_add_u64 v[2:3], s[6:7], 0, v[32:33]
	v_lshlrev_b64 v[0:1], 12, v[0:1]
	v_lshl_add_u64 v[28:29], v[2:3], 0, v[0:1]
	v_add_co_u32_e32 v4, vcc, s28, v28
	s_lshl_b32 s10, s9, 1
	s_nop 0
	v_addc_co_u32_e32 v5, vcc, 0, v29, vcc
	v_add_co_u32_e32 v8, vcc, s29, v28
	global_load_dwordx4 v[0:3], v[28:29], off nt
	s_nop 0
	global_load_dwordx4 v[4:7], v[4:5], off nt
	v_addc_co_u32_e32 v9, vcc, 0, v29, vcc
	v_add_co_u32_e32 v12, vcc, s30, v28
	v_add_u32_e32 v50, s8, v51
	s_nop 0
	v_addc_co_u32_e32 v13, vcc, 0, v29, vcc
	v_add_co_u32_e32 v16, vcc, s31, v28
	global_load_dwordx4 v[8:11], v[8:9], off nt
	s_nop 0
	global_load_dwordx4 v[12:15], v[12:13], off nt
	v_addc_co_u32_e32 v17, vcc, 0, v29, vcc
	v_add_co_u32_e32 v20, vcc, s34, v28
	v_lshl_add_u64 v[56:57], v[46:47], 0, s[10:11]
	s_nop 0
	v_addc_co_u32_e32 v21, vcc, 0, v29, vcc
	global_load_dwordx4 v[16:19], v[16:17], off nt
	s_nop 0
	global_load_dwordx4 v[20:23], v[20:21], off nt
	v_add_co_u32_e32 v24, vcc, s35, v28
	v_add_u32_e32 v52, s8, v53
	s_nop 0
	v_addc_co_u32_e32 v25, vcc, 0, v29, vcc
	global_load_dwordx4 v[24:27], v[24:25], off nt
	v_add_co_u32_e32 v28, vcc, s36, v28
	v_mad_i64_i32 v[60:61], s[6:7], v50, s37, v[56:57]
	s_nop 0
	v_addc_co_u32_e32 v29, vcc, 0, v29, vcc
	global_load_dwordx4 v[28:31], v[28:29], off nt
	v_mad_i64_i32 v[82:83], s[6:7], v52, s37, v[56:57]
	s_waitcnt vmcnt(0)
	ds_write2_b32 v65, v0, v1 offset1:1
	ds_write2_b32 v65, v2, v3 offset0:2 offset1:3
	ds_write2_b32 v67, v4, v5 offset1:1
	ds_write2_b32 v68, v6, v7 offset1:1
	ds_write2_b32 v69, v8, v9 offset1:1
	ds_write2_b32 v70, v10, v11 offset1:1
	ds_write2_b32 v71, v12, v13 offset1:1
	ds_write2_b32 v72, v14, v15 offset1:1
	ds_write2_b32 v73, v16, v17 offset1:1
	ds_write2_b32 v74, v18, v19 offset1:1
	ds_write2_b32 v75, v20, v21 offset1:1
	ds_write2_b32 v76, v22, v23 offset1:1
	ds_write2_b32 v77, v24, v25 offset1:1
	ds_write2_b32 v78, v26, v27 offset1:1
	ds_write2_b32 v79, v28, v29 offset1:1
	ds_write2_b32 v80, v30, v31 offset1:1
	s_waitcnt lgkmcnt(0)
	ds_read2_b32 v[4:5], v63 offset0:33 offset1:41
	ds_read2_b32 v[6:7], v63 offset1:8
	ds_read2_b32 v[8:9], v63 offset0:66 offset1:74
	ds_read2_b32 v[10:11], v63 offset0:99 offset1:107
	ds_read2_b32 v[12:13], v63 offset0:132 offset1:140
	ds_read2_b32 v[14:15], v63 offset0:165 offset1:173
	ds_read2_b32 v[16:17], v63 offset0:198 offset1:206
	ds_read2_b32 v[18:19], v63 offset0:231 offset1:239
	ds_read2_b32 v[20:21], v63 offset0:49 offset1:57
	ds_read2_b32 v[22:23], v63 offset0:16 offset1:24
	ds_read2_b32 v[24:25], v63 offset0:82 offset1:90
	ds_read2_b32 v[26:27], v63 offset0:115 offset1:123
	ds_read2_b32 v[28:29], v63 offset0:148 offset1:156
	ds_read2_b32 v[30:31], v63 offset0:181 offset1:189
	ds_read2_b32 v[84:85], v63 offset0:214 offset1:222
	ds_read2_b32 v[86:87], v63 offset0:247 offset1:255
	s_waitcnt lgkmcnt(14)
	v_cvt_pk_bf16_f32 v0, v6, v4
	s_waitcnt lgkmcnt(12)
	v_cvt_pk_bf16_f32 v1, v8, v10
	s_waitcnt lgkmcnt(10)
	v_cvt_pk_bf16_f32 v2, v12, v14
	s_waitcnt lgkmcnt(8)
	v_cvt_pk_bf16_f32 v3, v16, v18
	v_cvt_pk_bf16_f32 v4, v7, v5
	v_cvt_pk_bf16_f32 v5, v9, v11
	v_cvt_pk_bf16_f32 v6, v13, v15
	v_cvt_pk_bf16_f32 v7, v17, v19
	global_store_dwordx4 v[60:61], v[0:3], off sc1
	global_store_dwordx4 v[82:83], v[4:7], off sc1
	s_waitcnt lgkmcnt(6)
	v_cvt_pk_bf16_f32 v0, v22, v20
	v_add_u32_e32 v4, s8, v55
	s_waitcnt lgkmcnt(4)
	v_cvt_pk_bf16_f32 v1, v24, v26
	s_waitcnt lgkmcnt(2)
	v_cvt_pk_bf16_f32 v2, v28, v30
	s_waitcnt lgkmcnt(0)
	v_cvt_pk_bf16_f32 v3, v84, v86
	v_mad_i64_i32 v[4:5], s[6:7], v4, s37, v[56:57]
	global_store_dwordx4 v[4:5], v[0:3], off sc1
	v_add_u32_e32 v4, s8, v59
	v_mad_i64_i32 v[4:5], s[6:7], v4, s37, v[56:57]
	v_cvt_pk_bf16_f32 v0, v23, v21
	v_cvt_pk_bf16_f32 v1, v25, v27
	v_cvt_pk_bf16_f32 v2, v29, v31
	v_cvt_pk_bf16_f32 v3, v85, v87
	global_store_dwordx4 v[4:5], v[0:3], off sc1
	s_waitcnt lgkmcnt(0)

; #define LAS __attribute__((address_space(3)))
; __device__ __forceinline__ void transpose_tile(const float* W, const float* gain, int K, int N, int k0, int n0, bf16* WT, int drow0, LAS float* scr, int lane) {
;     f32x4 v[8]; float gv[8];
;     const int r0 = lane >> 3, c4 = lane & 7;
; #pragma unroll
;     for (int i = 0; i < 8; ++i) { v[i] = *(const f32x4*)(W + (size_t)(k0 + r0 + 8 * i) * N + n0 + 4 * c4); gv[i] = gain ? gain[k0 + r0 + 8 * i] : 1.0f; }
; template <bool SWIGLU> __device__ __forceinline__ void transpose_item(const float* W, const float* gain, int K, int N, bf16* WT, LAS float* scr, int item, int lane) {
;     const int nblk = N / 32, kb = item / nblk, nb = item % nblk, n0 = 32 * nb;
;     int drow0 = n0;
;     if (SWIGLU) { const int up = n0 >= FF, f = up ? n0 - FF : n0; drow0 = 256 * (f >> 7) + (up ? 128 : 0) + (f & 127); }
.LBB0_1094:
	s_andn2_b64 vcc, exec, s[8:9]
	s_cbranch_vccnz .LBB0_1019
	s_mov_b32 s6, 2
	s_ashr_i32 s7, s6, 31
	s_lshl_b64 s[6:7], s[6:7], 3
	s_add_u32 s6, s0, s6
	s_addc_u32 s7, s1, s7
	s_load_dwordx2 s[8:9], s[6:7], 0x0
	s_mov_b32 s6, 1
	s_ashr_i32 s7, s6, 31
	s_lshl_b64 s[6:7], s[6:7], 3
	s_add_u32 s20, s0, s6
	s_mul_hi_i32 s6, s22, 0x2e8ba2e9
	s_addc_u32 s21, s1, s7
	s_lshr_b32 s7, s6, 31
	s_ashr_i32 s6, s6, 5
	s_add_i32 s6, s6, s7
	s_mul_i32 s7, s6, 0xffffea00
	s_add_i32 s18, s24, s7
	s_ashr_i32 s19, s18, 31
	s_lshl_b32 s12, s6, 6
	s_lshl_b64 s[40:41], s[18:19], 2
	s_waitcnt lgkmcnt(0)
	s_add_u32 s8, s8, s40
	s_addc_u32 s9, s9, s41
	v_add_u32_e32 v28, s12, v51
	v_lshl_add_u64 v[30:31], s[8:9], 0, v[32:33]
	v_mad_i64_i32 v[0:1], s[8:9], v28, s38, v[30:31]
	global_load_dwordx4 v[0:3], v[0:1], off nt
	s_load_dwordx2 s[8:9], s[20:21], 0x0
	v_ashrrev_i32_e32 v29, 31, v28
	v_mov_b32_e32 v50, 1.0
	v_mov_b32_e32 v52, 1.0
	s_waitcnt lgkmcnt(0)
	s_cmp_lg_u64 s[8:9], 0
	s_cselect_b64 s[20:21], -1, 0
	s_cmp_eq_u64 s[8:9], 0
	v_lshl_add_u64 v[60:61], v[28:29], 2, s[8:9]
	s_cbranch_scc1 .LBB0_1097
	global_load_dword v52, v[60:61], off nt
.LBB0_1097:
	v_add_u32_e32 v4, 8, v28
	v_mad_i64_i32 v[4:5], s[8:9], v4, s38, v[30:31]
	global_load_dwordx4 v[4:7], v[4:5], off nt
	v_cndmask_b32_e64 v8, 0, 1, s[20:21]
	v_cmp_ne_u32_e64 s[8:9], 1, v8
	s_andn2_b64 vcc, exec, s[20:21]
	s_cbranch_vccnz .LBB0_1099
	global_load_dword v50, v[60:61], off offset:32 nt
.LBB0_1099:
	v_add_u32_e32 v8, 16, v28
	v_mad_i64_i32 v[8:9], s[20:21], v8, s38, v[30:31]
	global_load_dwordx4 v[8:11], v[8:9], off nt
	v_mov_b32_e32 v54, 1.0
	s_and_b64 vcc, exec, s[8:9]
	v_mov_b32_e32 v56, 1.0
	s_cbranch_vccnz .LBB0_1101
	global_load_dword v56, v[60:61], off offset:64 nt
.LBB0_1101:
	v_add_u32_e32 v12, 24, v28
	v_mad_i64_i32 v[12:13], s[20:21], v12, s38, v[30:31]
	global_load_dwordx4 v[12:15], v[12:13], off nt
	s_and_b64 vcc, exec, s[8:9]
	s_cbranch_vccnz .LBB0_1103
	global_load_dword v54, v[60:61], off offset:96 nt
.LBB0_1103:
	v_add_u32_e32 v16, 32, v28
	v_mad_i64_i32 v[16:17], s[20:21], v16, s38, v[30:31]
	global_load_dwordx4 v[16:19], v[16:17], off nt
	v_mov_b32_e32 v58, 1.0
	s_and_b64 vcc, exec, s[8:9]
	v_mov_b32_e32 v62, 1.0
	s_cbranch_vccnz .LBB0_1105
	global_load_dword v62, v[60:61], off offset:128 nt
.LBB0_1105:
	v_add_u32_e32 v20, 40, v28
	v_mad_i64_i32 v[20:21], s[20:21], v20, s38, v[30:31]
	global_load_dwordx4 v[20:23], v[20:21], off nt
	s_and_b64 vcc, exec, s[8:9]
	s_cbranch_vccnz .LBB0_1107
	global_load_dword v58, v[60:61], off offset:160 nt
.LBB0_1107:
	v_add_u32_e32 v24, 48, v28
	v_mad_i64_i32 v[24:25], s[20:21], v24, s38, v[30:31]
	global_load_dwordx4 v[24:27], v[24:25], off nt
	v_mov_b32_e32 v64, 1.0
	s_and_b64 vcc, exec, s[8:9]
	v_mov_b32_e32 v66, 1.0
	s_cbranch_vccnz .LBB0_1109
	global_load_dword v66, v[60:61], off offset:192 nt
.LBB0_1109:
	v_add_u32_e32 v28, 56, v28
	v_mad_i64_i32 v[28:29], s[20:21], v28, s38, v[30:31]
	global_load_dwordx4 v[28:31], v[28:29], off nt
	s_and_b64 vcc, exec, s[8:9]
	s_cbranch_vccnz .LBB0_1018
	global_load_dword v64, v[60:61], off offset:224 nt
	s_branch .LBB0_1018

; __device__ __forceinline__ unsigned pk_bf16(float lo, float hi) { typedef __bf16 b2_t __attribute__((ext_vector_type(2))); f32x2 v = {lo, hi}; b2_t b = __builtin_convertvector(v, b2_t); return __builtin_bit_cast(unsigned, b); }
; #define LAS __attribute__((address_space(3)))
; __device__ __forceinline__ void transpose_tile(const float* W, const float* gain, int K, int N, int k0, int n0, bf16* WT, int drow0, LAS float* scr, int lane) {
;     f32x4 v[8]; float gv[8];
;     const int r0 = lane >> 3, c4 = lane & 7;
; #pragma unroll
;     for (int i = 0; i < 8; ++i) { v[i] = *(const f32x4*)(W + (size_t)(k0 + r0 + 8 * i) * N + n0 + 4 * c4); gv[i] = gain ? gain[k0 + r0 + 8 * i] : 1.0f; }
; #pragma unroll
;     for (int i = 0; i < 8; ++i) { LAS float* d = scr + (r0 + 8 * i) * 33 + 4 * c4; d[0] = v[i][0] * gv[i]; d[1] = v[i][1] * gv[i]; d[2] = v[i][2] * gv[i]; d[3] = v[i][3] * gv[i]; }
;     asm volatile("s_waitcnt lgkmcnt(0)" ::: "memory");
;     const int c = lane & 7;
; #pragma unroll
;     for (int j = 0; j < 4; ++j) { const int n = (lane >> 3) + 8 * j; const LAS float* s = scr + (8 * c) * 33 + n;
;         v4u o; o.x = pk_bf16(s[0 * 33], s[1 * 33]); o.y = pk_bf16(s[2 * 33], s[3 * 33]); o.z = pk_bf16(s[4 * 33], s[5 * 33]); o.w = pk_bf16(s[6 * 33], s[7 * 33]);
;         *(v4u*)(WT + (size_t)(drow0 + n) * K + k0 + 8 * c) = o; }
;     asm volatile("s_waitcnt lgkmcnt(0)" ::: "memory");
; }
.LBB0_1289:
	s_cmpk_gt_i32 s26, 0xaff
	s_mov_b64 s[8:9], -1
	s_cbranch_scc0 .LBB0_1419
	s_cmpk_gt_u32 s26, 0x107f
	s_cbranch_scc0 .LBB0_1416
	s_cmpk_gt_u32 s26, 0x167f
	s_cbranch_scc0 .LBB0_1397
	s_cmpk_gt_u32 s26, 0x187f
	s_cbranch_scc0 .LBB0_1394
	s_cmpk_gt_u32 s26, 0x237f
	s_cbranch_scc0 .LBB0_1375
	s_cmpk_gt_u32 s26, 0x28ff
	s_cbranch_scc0 .LBB0_1372
	s_cmpk_gt_u32 s26, 0x33ff
	s_cbranch_scc0 .LBB0_1353
	s_cmpk_gt_u32 s26, 0x397f
	s_cbranch_scc0 .LBB0_1350
	s_cmpk_gt_u32 s26, 0x3d7f
	s_cbranch_scc0 .LBB0_1331
	s_cmpk_gt_u32 s26, 0x3f7f
	s_cbranch_scc0 .LBB0_1328
	s_cmpk_gt_u32 s26, 0x3f9f
	s_cbranch_scc0 .LBB0_1325
	s_cmpk_gt_u32 s26, 0x3fbf
	s_cbranch_scc0 .LBB0_1322
	s_cmpk_gt_u32 s26, 0x4abf
	s_cbranch_scc0 .LBB0_1303
	s_mov_b32 s6, 27
	s_ashr_i32 s7, s6, 31
	s_lshl_b64 s[6:7], s[6:7], 3
	s_add_u32 s6, s0, s6
	s_addc_u32 s7, s1, s7
	s_load_dwordx2 s[6:7], s[6:7], 0x0
	s_lshl_b32 s8, s26, 5
	s_and_b32 s8, s8, 0x3e0
	s_and_b32 s9, s29, 0x1ffc0
	s_lshl_b32 s12, s8, 2
	v_add_u32_e32 v0, s9, v32
	s_waitcnt lgkmcnt(0)
	s_add_u32 s6, s6, s12
	s_addc_u32 s7, s7, 0
	v_lshlrev_b32_e32 v36, 2, v34
	v_ashrrev_i32_e32 v1, 31, v0
	v_lshl_add_u64 v[2:3], s[6:7], 0, v[36:37]
	v_lshlrev_b64 v[0:1], 12, v[0:1]
	v_lshl_add_u64 v[28:29], v[2:3], 0, v[0:1]
	v_add_co_u32_e32 v4, vcc, s31, v28
	v_add_u32_e32 v33, v35, v89
	s_nop 0
	v_addc_co_u32_e32 v5, vcc, 0, v29, vcc
	v_add_co_u32_e32 v8, vcc, s34, v28
	global_load_dwordx4 v[0:3], v[28:29], off nt
	s_nop 0
	global_load_dwordx4 v[4:7], v[4:5], off nt
	v_addc_co_u32_e32 v9, vcc, 0, v29, vcc
	v_add_co_u32_e32 v12, vcc, s35, v28
	v_add_u32_e32 v36, 0x420, v33
	s_nop 0
	v_addc_co_u32_e32 v13, vcc, 0, v29, vcc
	v_add_co_u32_e32 v16, vcc, s36, v28
	global_load_dwordx4 v[8:11], v[8:9], off nt
	s_nop 0
	global_load_dwordx4 v[12:15], v[12:13], off nt
	v_addc_co_u32_e32 v17, vcc, 0, v29, vcc
	v_add_co_u32_e32 v20, vcc, s37, v28
	v_add_u32_e32 v39, 0x428, v33
	s_nop 0
	v_addc_co_u32_e32 v21, vcc, 0, v29, vcc
	global_load_dwordx4 v[16:19], v[16:17], off nt
	s_nop 0
	global_load_dwordx4 v[20:23], v[20:21], off nt
	v_add_co_u32_e32 v24, vcc, s38, v28
	v_add_u32_e32 v41, 0x840, v33
	s_nop 0
	v_addc_co_u32_e32 v25, vcc, 0, v29, vcc
	global_load_dwordx4 v[24:27], v[24:25], off nt
	v_add_co_u32_e32 v28, vcc, s39, v28
	v_add_u32_e32 v43, 0x848, v33
	s_nop 0
	v_addc_co_u32_e32 v29, vcc, 0, v29, vcc
	global_load_dwordx4 v[28:31], v[28:29], off nt
	v_add_u32_e32 v88, 0xc60, v33
	v_add_u32_e32 v92, 0xc68, v33
	v_add_u32_e32 v94, 0x1080, v33
	v_add_u32_e32 v95, 0x1088, v33
	v_add_u32_e32 v96, 0x14a0, v33
	v_add_u32_e32 v97, 0x14a8, v33
	v_add_u32_e32 v98, 0x18c0, v33
	v_add_u32_e32 v99, 0x18c8, v33
	v_add_u32_e32 v100, 0x1ce0, v33
	v_add_u32_e32 v101, 0x1ce8, v33
	s_lshl_b32 s12, s9, 1
	v_add_u32_e32 v102, s8, v32
	v_lshl_add_u64 v[90:91], v[44:45], 0, s[12:13]
	s_waitcnt vmcnt(0)
	ds_write2_b32 v33, v0, v1 offset1:1
	ds_write2_b32 v33, v2, v3 offset0:2 offset1:3
	ds_write2_b32 v36, v4, v5 offset1:1
	ds_write2_b32 v39, v6, v7 offset1:1
	ds_write2_b32 v41, v8, v9 offset1:1
	ds_write2_b32 v43, v10, v11 offset1:1
	ds_write2_b32 v88, v12, v13 offset1:1
	ds_write2_b32 v92, v14, v15 offset1:1
	ds_write2_b32 v94, v16, v17 offset1:1
	ds_write2_b32 v95, v18, v19 offset1:1
	ds_write2_b32 v96, v20, v21 offset1:1
	ds_write2_b32 v97, v22, v23 offset1:1
	ds_write2_b32 v98, v24, v25 offset1:1
	ds_write2_b32 v99, v26, v27 offset1:1
	ds_write2_b32 v100, v28, v29 offset1:1
	ds_write2_b32 v101, v30, v31 offset1:1
	s_waitcnt lgkmcnt(0)
	ds_read2_b32 v[4:5], v93 offset0:33 offset1:41
	ds_read2_b32 v[6:7], v93 offset1:8
	ds_read2_b32 v[8:9], v93 offset0:66 offset1:74
	ds_read2_b32 v[10:11], v93 offset0:99 offset1:107
	ds_read2_b32 v[12:13], v93 offset0:132 offset1:140
	ds_read2_b32 v[14:15], v93 offset0:165 offset1:173
	ds_read2_b32 v[16:17], v93 offset0:198 offset1:206
	ds_read2_b32 v[18:19], v93 offset0:231 offset1:239
	v_mad_i64_i32 v[20:21], s[6:7], v102, s40, v[90:91]
	s_waitcnt lgkmcnt(6)
	v_cvt_pk_bf16_f32 v0, v6, v4
	s_waitcnt lgkmcnt(4)
	v_cvt_pk_bf16_f32 v1, v8, v10
	s_waitcnt lgkmcnt(2)
	v_cvt_pk_bf16_f32 v2, v12, v14
	s_waitcnt lgkmcnt(0)
	v_cvt_pk_bf16_f32 v3, v16, v18
	global_store_dwordx4 v[20:21], v[0:3], off sc1
	v_add_u32_e32 v4, s8, v38
	s_nop 0
	v_cvt_pk_bf16_f32 v0, v7, v5
	v_cvt_pk_bf16_f32 v1, v9, v11
	v_cvt_pk_bf16_f32 v2, v13, v15
	v_cvt_pk_bf16_f32 v3, v17, v19
	ds_read2_b32 v[6:7], v93 offset0:49 offset1:57
	ds_read2_b32 v[8:9], v93 offset0:16 offset1:24
	ds_read2_b32 v[10:11], v93 offset0:82 offset1:90
	ds_read2_b32 v[12:13], v93 offset0:115 offset1:123
	ds_read2_b32 v[14:15], v93 offset0:148 offset1:156
	ds_read2_b32 v[16:17], v93 offset0:181 offset1:189
	ds_read2_b32 v[18:19], v93 offset0:214 offset1:222
	ds_read2_b32 v[20:21], v93 offset0:247 offset1:255
	v_mad_i64_i32 v[4:5], s[6:7], v4, s40, v[90:91]
	global_store_dwordx4 v[4:5], v[0:3], off sc1
	v_add_u32_e32 v4, s8, v40
	v_mad_i64_i32 v[4:5], s[6:7], v4, s40, v[90:91]
	s_waitcnt lgkmcnt(6)
	v_cvt_pk_bf16_f32 v0, v8, v6
	s_waitcnt lgkmcnt(4)
	v_cvt_pk_bf16_f32 v1, v10, v12
	s_waitcnt lgkmcnt(2)
	v_cvt_pk_bf16_f32 v2, v14, v16
	s_waitcnt lgkmcnt(0)
	v_cvt_pk_bf16_f32 v3, v18, v20
	global_store_dwordx4 v[4:5], v[0:3], off sc1
	v_add_u32_e32 v4, s8, v42
	v_mad_i64_i32 v[4:5], s[6:7], v4, s40, v[90:91]
	v_cvt_pk_bf16_f32 v0, v9, v7
	v_cvt_pk_bf16_f32 v1, v11, v13
	v_cvt_pk_bf16_f32 v2, v15, v17
	v_cvt_pk_bf16_f32 v3, v19, v21
	global_store_dwordx4 v[4:5], v[0:3], off sc1
	s_waitcnt lgkmcnt(0)
	s_mov_b64 s[8:9], 0
; #define LAS __attribute__((address_space(3)))
; __device__ __forceinline__ void transpose_tile(const float* W, const float* gain, int K, int N, int k0, int n0, bf16* WT, int drow0, LAS float* scr, int lane) {
;     f32x4 v[8]; float gv[8];
;     const int r0 = lane >> 3, c4 = lane & 7;
; #pragma unroll
;     for (int i = 0; i < 8; ++i) { v[i] = *(const f32x4*)(W + (size_t)(k0 + r0 + 8 * i) * N + n0 + 4 * c4); gv[i] = gain ? gain[k0 + r0 + 8 * i] : 1.0f; }
; template <bool SWIGLU> __device__ __forceinline__ void transpose_item(const float* W, const float* gain, int K, int N, bf16* WT, LAS float* scr, int item, int lane) {
;     const int nblk = N / 32, kb = item / nblk, nb = item % nblk, n0 = 32 * nb;
;     int drow0 = n0;
;     if (SWIGLU) { const int up = n0 >= FF, f = up ? n0 - FF : n0; drow0 = 256 * (f >> 7) + (up ? 128 : 0) + (f & 127); }
.LBB0_1303:
	s_andn2_b64 vcc, exec, s[8:9]
	s_cbranch_vccnz .LBB0_1321
	s_mov_b32 s6, 26
	s_ashr_i32 s7, s6, 31
	s_lshl_b64 s[6:7], s[6:7], 3
	s_add_u32 s6, s0, s6
	s_addc_u32 s7, s1, s7
	s_load_dwordx2 s[8:9], s[6:7], 0x0
	s_mov_b32 s6, 25
	s_ashr_i32 s7, s6, 31
	s_lshl_b64 s[6:7], s[6:7], 3
	s_add_u32 s20, s0, s6
	s_addc_u32 s21, s1, s7
	s_add_i32 s6, s26, 0xc040
	s_and_b32 s7, s6, 0xffff
	s_mul_i32 s7, s7, 0xba2f
	s_lshr_b32 s12, s7, 23
	s_mul_i32 s7, s12, 0xb0
	s_sub_i32 s7, s6, s7
	s_lshl_b32 s6, s12, 6
	s_lshl_b32 s12, s7, 7
	s_and_b32 s12, s12, 0x3ff80
	s_waitcnt lgkmcnt(0)
	s_add_u32 s8, s8, s12
	s_addc_u32 s9, s9, 0
	v_lshlrev_b32_e32 v36, 2, v34
	v_add_u32_e32 v28, s6, v32
	v_lshl_add_u64 v[30:31], s[8:9], 0, v[36:37]
	v_mad_i64_i32 v[0:1], s[8:9], v28, s41, v[30:31]
	global_load_dwordx4 v[0:3], v[0:1], off nt
	s_load_dwordx2 s[8:9], s[20:21], 0x0
	v_ashrrev_i32_e32 v29, 31, v28
	v_mov_b32_e32 v36, 1.0
	v_mov_b32_e32 v88, 1.0
	s_waitcnt lgkmcnt(0)
	s_cmp_lg_u64 s[8:9], 0
	s_cselect_b64 s[20:21], -1, 0
	s_cmp_eq_u64 s[8:9], 0
	v_lshl_add_u64 v[98:99], v[28:29], 2, s[8:9]
	s_cbranch_scc1 .LBB0_1306
	global_load_dword v88, v[98:99], off nt
.LBB0_1306:
	v_add_u32_e32 v4, 8, v28
	v_mad_i64_i32 v[4:5], s[8:9], v4, s41, v[30:31]
	global_load_dwordx4 v[4:7], v[4:5], off nt
	v_cndmask_b32_e64 v8, 0, 1, s[20:21]
	v_cmp_ne_u32_e64 s[8:9], 1, v8
	s_andn2_b64 vcc, exec, s[20:21]
	s_cbranch_vccnz .LBB0_1308
	global_load_dword v36, v[98:99], off offset:32 nt
.LBB0_1308:
	v_add_u32_e32 v8, 16, v28
	v_mad_i64_i32 v[8:9], s[20:21], v8, s41, v[30:31]
	global_load_dwordx4 v[8:11], v[8:9], off nt
	v_mov_b32_e32 v90, 1.0
	s_and_b64 vcc, exec, s[8:9]
	v_mov_b32_e32 v94, 1.0
	s_cbranch_vccnz .LBB0_1310
	global_load_dword v94, v[98:99], off offset:64 nt
.LBB0_1310:
	v_add_u32_e32 v12, 24, v28
	v_mad_i64_i32 v[12:13], s[20:21], v12, s41, v[30:31]
	global_load_dwordx4 v[12:15], v[12:13], off nt
	s_and_b64 vcc, exec, s[8:9]
	s_cbranch_vccnz .LBB0_1312
	global_load_dword v90, v[98:99], off offset:96 nt
.LBB0_1312:
	v_add_u32_e32 v16, 32, v28
	v_mad_i64_i32 v[16:17], s[20:21], v16, s41, v[30:31]
	global_load_dwordx4 v[16:19], v[16:17], off nt
	v_mov_b32_e32 v92, 1.0
	s_and_b64 vcc, exec, s[8:9]
	v_mov_b32_e32 v100, 1.0
	s_cbranch_vccnz .LBB0_1314
	global_load_dword v100, v[98:99], off offset:128 nt
.LBB0_1314:
	v_add_u32_e32 v20, 40, v28
	v_mad_i64_i32 v[20:21], s[20:21], v20, s41, v[30:31]
	global_load_dwordx4 v[20:23], v[20:21], off nt
	s_and_b64 vcc, exec, s[8:9]
	s_cbranch_vccnz .LBB0_1316
	global_load_dword v92, v[98:99], off offset:160 nt
.LBB0_1316:
	v_add_u32_e32 v24, 48, v28
	v_mad_i64_i32 v[24:25], s[20:21], v24, s41, v[30:31]
	global_load_dwordx4 v[24:27], v[24:25], off nt
	v_mov_b32_e32 v96, 1.0
	s_and_b64 vcc, exec, s[8:9]
	v_mov_b32_e32 v102, 1.0
	s_cbranch_vccnz .LBB0_1318
	global_load_dword v102, v[98:99], off offset:192 nt
.LBB0_1318:
	v_add_u32_e32 v28, 56, v28
	v_mad_i64_i32 v[28:29], s[20:21], v28, s41, v[30:31]
	global_load_dwordx4 v[28:31], v[28:29], off nt
	s_and_b64 vcc, exec, s[8:9]
	s_lshl_b32 s8, s7, 5
	s_cbranch_vccnz .LBB0_1320
	global_load_dword v96, v[98:99], off offset:224 nt

; __device__ __forceinline__ unsigned pk_bf16(float lo, float hi) { typedef __bf16 b2_t __attribute__((ext_vector_type(2))); f32x2 v = {lo, hi}; b2_t b = __builtin_convertvector(v, b2_t); return __builtin_bit_cast(unsigned, b); }
; #define LAS __attribute__((address_space(3)))
; __device__ __forceinline__ void transpose_tile(const float* W, const float* gain, int K, int N, int k0, int n0, bf16* WT, int drow0, LAS float* scr, int lane) {
;     f32x4 v[8]; float gv[8];
;     const int r0 = lane >> 3, c4 = lane & 7;
; #pragma unroll
;     for (int i = 0; i < 8; ++i) { v[i] = *(const f32x4*)(W + (size_t)(k0 + r0 + 8 * i) * N + n0 + 4 * c4); gv[i] = gain ? gain[k0 + r0 + 8 * i] : 1.0f; }
; #pragma unroll
;     for (int i = 0; i < 8; ++i) { LAS float* d = scr + (r0 + 8 * i) * 33 + 4 * c4; d[0] = v[i][0] * gv[i]; d[1] = v[i][1] * gv[i]; d[2] = v[i][2] * gv[i]; d[3] = v[i][3] * gv[i]; }
;     asm volatile("s_waitcnt lgkmcnt(0)" ::: "memory");
;     const int c = lane & 7;
; #pragma unroll
;     for (int j = 0; j < 4; ++j) { const int n = (lane >> 3) + 8 * j; const LAS float* s = scr + (8 * c) * 33 + n;
;         v4u o; o.x = pk_bf16(s[0 * 33], s[1 * 33]); o.y = pk_bf16(s[2 * 33], s[3 * 33]); o.z = pk_bf16(s[4 * 33], s[5 * 33]); o.w = pk_bf16(s[6 * 33], s[7 * 33]);
;         *(v4u*)(WT + (size_t)(drow0 + n) * K + k0 + 8 * c) = o; }
;     asm volatile("s_waitcnt lgkmcnt(0)" ::: "memory");
; }
.LBB0_1322:
	s_andn2_b64 vcc, exec, s[8:9]
	s_cbranch_vccnz .LBB0_1324
	s_mov_b32 s6, 21
	s_ashr_i32 s7, s6, 31
	s_add_i32 s8, s26, 0xffffc060
	s_lshl_b64 s[6:7], s[6:7], 3
	s_add_u32 s6, s0, s6
	s_addc_u32 s7, s1, s7
	s_load_dwordx2 s[6:7], s[6:7], 0x0
	s_lshr_b32 s12, s8, 1
	s_lshl_b64 s[8:9], s[12:13], 14
	v_lshlrev_b32_e32 v36, 2, v34
	v_add_u32_e32 v33, v35, v89
	s_waitcnt lgkmcnt(0)
	s_add_u32 s6, s6, s8
	s_addc_u32 s7, s7, s9
	s_lshl_b32 s8, s26, 5
	s_and_b32 s8, s8, 32
	s_lshl_b32 s9, s8, 2
	s_add_u32 s6, s6, s9
	s_addc_u32 s7, s7, 0
	v_lshl_add_u64 v[28:29], s[6:7], 0, v[36:37]
	v_lshl_add_u64 v[0:1], v[28:29], 0, v[48:49]
	global_load_dwordx4 v[0:3], v[0:1], off nt
	v_lshl_add_u64 v[4:5], v[28:29], 0, v[50:51]
	global_load_dwordx4 v[4:7], v[4:5], off nt
	v_lshl_add_u64 v[8:9], v[28:29], 0, v[52:53]
	global_load_dwordx4 v[8:11], v[8:9], off nt
	v_lshl_add_u64 v[12:13], v[28:29], 0, v[54:55]
	global_load_dwordx4 v[12:15], v[12:13], off nt
	v_lshl_add_u64 v[16:17], v[28:29], 0, v[56:57]
	global_load_dwordx4 v[16:19], v[16:17], off nt
	v_lshl_add_u64 v[20:21], v[28:29], 0, v[58:59]
	global_load_dwordx4 v[20:23], v[20:21], off nt
	v_lshl_add_u64 v[24:25], v[28:29], 0, v[60:61]
	global_load_dwordx4 v[24:27], v[24:25], off nt
	v_lshl_add_u64 v[28:29], v[28:29], 0, v[62:63]
	global_load_dwordx4 v[28:31], v[28:29], off nt
	v_add_u32_e32 v36, 0x420, v33
	v_add_u32_e32 v39, 0x428, v33
	v_add_u32_e32 v41, 0x840, v33
	v_add_u32_e32 v43, 0x848, v33
	v_add_u32_e32 v88, 0xc60, v33
	v_add_u32_e32 v92, 0xc68, v33
	v_add_u32_e32 v97, 0x1080, v33
	v_add_u32_e32 v100, 0x1088, v33
	v_add_u32_e32 v101, 0x14a0, v33
	v_add_u32_e32 v102, 0x14a8, v33
	v_add_u32_e32 v103, 0x18c0, v33
	v_add_u32_e32 v104, 0x18c8, v33
	v_add_u32_e32 v105, 0x1ce0, v33
	v_add_u32_e32 v106, 0x1ce8, v33
	v_add_u32_e32 v90, s8, v32
	v_add_u32_e32 v94, s8, v38
	v_ashrrev_i32_e32 v91, 31, v90
	s_lshl_b64 s[6:7], s[12:13], 13
	v_ashrrev_i32_e32 v95, 31, v94
	v_lshlrev_b64 v[90:91], 7, v[90:91]
	v_lshl_add_u64 v[98:99], v[64:65], 0, s[6:7]
	v_add_u32_e32 v96, s8, v40
	v_lshlrev_b64 v[94:95], 7, v[94:95]
	v_lshl_add_u64 v[90:91], v[98:99], 0, v[90:91]
	v_lshl_add_u64 v[94:95], v[98:99], 0, v[94:95]
	s_waitcnt vmcnt(0)
	ds_write2_b32 v33, v0, v1 offset1:1
	ds_write2_b32 v33, v2, v3 offset0:2 offset1:3
	ds_write2_b32 v36, v4, v5 offset1:1
	ds_write2_b32 v39, v6, v7 offset1:1
	ds_write2_b32 v41, v8, v9 offset1:1
	ds_write2_b32 v43, v10, v11 offset1:1
	ds_write2_b32 v88, v12, v13 offset1:1
	ds_write2_b32 v92, v14, v15 offset1:1
	ds_write2_b32 v97, v16, v17 offset1:1
	ds_write2_b32 v100, v18, v19 offset1:1
	ds_write2_b32 v101, v20, v21 offset1:1
	ds_write2_b32 v102, v22, v23 offset1:1
	ds_write2_b32 v103, v24, v25 offset1:1
	ds_write2_b32 v104, v26, v27 offset1:1
	ds_write2_b32 v105, v28, v29 offset1:1
	ds_write2_b32 v106, v30, v31 offset1:1
	s_waitcnt lgkmcnt(0)
	ds_read2_b32 v[4:5], v93 offset0:33 offset1:41
	ds_read2_b32 v[6:7], v93 offset1:8
	ds_read2_b32 v[8:9], v93 offset0:66 offset1:74
	ds_read2_b32 v[10:11], v93 offset0:99 offset1:107
	ds_read2_b32 v[12:13], v93 offset0:132 offset1:140
	ds_read2_b32 v[14:15], v93 offset0:165 offset1:173
	ds_read2_b32 v[16:17], v93 offset0:198 offset1:206
	ds_read2_b32 v[18:19], v93 offset0:231 offset1:239
	ds_read2_b32 v[20:21], v93 offset0:49 offset1:57
	ds_read2_b32 v[22:23], v93 offset0:16 offset1:24
	ds_read2_b32 v[24:25], v93 offset0:82 offset1:90
	ds_read2_b32 v[26:27], v93 offset0:115 offset1:123
	ds_read2_b32 v[28:29], v93 offset0:148 offset1:156
	ds_read2_b32 v[30:31], v93 offset0:181 offset1:189
	ds_read2_b32 v[100:101], v93 offset0:214 offset1:222
	ds_read2_b32 v[102:103], v93 offset0:247 offset1:255
	s_waitcnt lgkmcnt(14)
	v_cvt_pk_bf16_f32 v0, v6, v4
	s_waitcnt lgkmcnt(12)
	v_cvt_pk_bf16_f32 v1, v8, v10
	s_waitcnt lgkmcnt(10)
	v_cvt_pk_bf16_f32 v2, v12, v14
	s_waitcnt lgkmcnt(8)
	v_cvt_pk_bf16_f32 v3, v16, v18
	v_cvt_pk_bf16_f32 v4, v7, v5
	v_cvt_pk_bf16_f32 v5, v9, v11
	v_cvt_pk_bf16_f32 v6, v13, v15
	v_cvt_pk_bf16_f32 v7, v17, v19
	global_store_dwordx4 v[90:91], v[0:3], off sc1
	global_store_dwordx4 v[94:95], v[4:7], off sc1
	v_ashrrev_i32_e32 v97, 31, v96
	v_lshlrev_b64 v[0:1], 7, v[96:97]
	v_add_u32_e32 v4, s8, v42
	v_ashrrev_i32_e32 v5, 31, v4
	s_waitcnt lgkmcnt(6)
	v_cvt_pk_bf16_f32 v8, v22, v20
	s_waitcnt lgkmcnt(4)
	v_cvt_pk_bf16_f32 v9, v24, v26
	s_waitcnt lgkmcnt(2)
	v_cvt_pk_bf16_f32 v10, v28, v30
	s_waitcnt lgkmcnt(0)
	v_cvt_pk_bf16_f32 v11, v100, v102
	v_lshl_add_u64 v[0:1], v[98:99], 0, v[0:1]
	v_lshlrev_b64 v[4:5], 7, v[4:5]
	global_store_dwordx4 v[0:1], v[8:11], off sc1
	v_cvt_pk_bf16_f32 v0, v23, v21
	v_cvt_pk_bf16_f32 v1, v25, v27
	v_cvt_pk_bf16_f32 v2, v29, v31
	v_cvt_pk_bf16_f32 v3, v101, v103
	v_lshl_add_u64 v[4:5], v[98:99], 0, v[4:5]
	global_store_dwordx4 v[4:5], v[0:3], off sc1
	s_waitcnt lgkmcnt(0)

; __device__ __forceinline__ unsigned pk_bf16(float lo, float hi) { typedef __bf16 b2_t __attribute__((ext_vector_type(2))); f32x2 v = {lo, hi}; b2_t b = __builtin_convertvector(v, b2_t); return __builtin_bit_cast(unsigned, b); }
; #define LAS __attribute__((address_space(3)))
; __device__ __forceinline__ void transpose_tile(const float* W, const float* gain, int K, int N, int k0, int n0, bf16* WT, int drow0, LAS float* scr, int lane) {
;     f32x4 v[8]; float gv[8];
;     const int r0 = lane >> 3, c4 = lane & 7;
; #pragma unroll
;     for (int i = 0; i < 8; ++i) { v[i] = *(const f32x4*)(W + (size_t)(k0 + r0 + 8 * i) * N + n0 + 4 * c4); gv[i] = gain ? gain[k0 + r0 + 8 * i] : 1.0f; }
; #pragma unroll
;     for (int i = 0; i < 8; ++i) { LAS float* d = scr + (r0 + 8 * i) * 33 + 4 * c4; d[0] = v[i][0] * gv[i]; d[1] = v[i][1] * gv[i]; d[2] = v[i][2] * gv[i]; d[3] = v[i][3] * gv[i]; }
;     asm volatile("s_waitcnt lgkmcnt(0)" ::: "memory");
;     const int c = lane & 7;
; #pragma unroll
;     for (int j = 0; j < 4; ++j) { const int n = (lane >> 3) + 8 * j; const LAS float* s = scr + (8 * c) * 33 + n;
;         v4u o; o.x = pk_bf16(s[0 * 33], s[1 * 33]); o.y = pk_bf16(s[2 * 33], s[3 * 33]); o.z = pk_bf16(s[4 * 33], s[5 * 33]); o.w = pk_bf16(s[6 * 33], s[7 * 33]);
;         *(v4u*)(WT + (size_t)(drow0 + n) * K + k0 + 8 * c) = o; }
;     asm volatile("s_waitcnt lgkmcnt(0)" ::: "memory");
; }
.LBB0_1325:
	s_andn2_b64 vcc, exec, s[8:9]
	s_cbranch_vccnz .LBB0_1327
	s_mov_b32 s6, 19
	s_ashr_i32 s7, s6, 31
	s_add_i32 s8, s26, 0xffffc080
	s_lshl_b64 s[6:7], s[6:7], 3
	s_add_u32 s6, s0, s6
	s_addc_u32 s7, s1, s7
	s_load_dwordx2 s[6:7], s[6:7], 0x0
	s_lshr_b32 s12, s8, 1
	s_lshl_b64 s[8:9], s[12:13], 14
	v_lshlrev_b32_e32 v36, 2, v34
	v_add_u32_e32 v33, v35, v89
	s_waitcnt lgkmcnt(0)
	s_add_u32 s6, s6, s8
	s_addc_u32 s7, s7, s9
	s_lshl_b32 s8, s26, 5
	s_and_b32 s8, s8, 32
	s_lshl_b32 s9, s8, 2
	s_add_u32 s6, s6, s9
	s_addc_u32 s7, s7, 0
	v_lshl_add_u64 v[28:29], s[6:7], 0, v[36:37]
	v_lshl_add_u64 v[0:1], v[28:29], 0, v[48:49]
	global_load_dwordx4 v[0:3], v[0:1], off nt
	v_lshl_add_u64 v[4:5], v[28:29], 0, v[50:51]
	global_load_dwordx4 v[4:7], v[4:5], off nt
	v_lshl_add_u64 v[8:9], v[28:29], 0, v[52:53]
	global_load_dwordx4 v[8:11], v[8:9], off nt
	v_lshl_add_u64 v[12:13], v[28:29], 0, v[54:55]
	global_load_dwordx4 v[12:15], v[12:13], off nt
	v_lshl_add_u64 v[16:17], v[28:29], 0, v[56:57]
	global_load_dwordx4 v[16:19], v[16:17], off nt
	v_lshl_add_u64 v[20:21], v[28:29], 0, v[58:59]
	global_load_dwordx4 v[20:23], v[20:21], off nt
	v_lshl_add_u64 v[24:25], v[28:29], 0, v[60:61]
	global_load_dwordx4 v[24:27], v[24:25], off nt
	v_lshl_add_u64 v[28:29], v[28:29], 0, v[62:63]
	global_load_dwordx4 v[28:31], v[28:29], off nt
	v_add_u32_e32 v36, 0x420, v33
	v_add_u32_e32 v39, 0x428, v33
	v_add_u32_e32 v41, 0x840, v33
	v_add_u32_e32 v43, 0x848, v33
	v_add_u32_e32 v88, 0xc60, v33
	v_add_u32_e32 v92, 0xc68, v33
	v_add_u32_e32 v97, 0x1080, v33
	v_add_u32_e32 v100, 0x1088, v33
	v_add_u32_e32 v101, 0x14a0, v33
	v_add_u32_e32 v102, 0x14a8, v33
	v_add_u32_e32 v103, 0x18c0, v33
	v_add_u32_e32 v104, 0x18c8, v33
	v_add_u32_e32 v105, 0x1ce0, v33
	v_add_u32_e32 v106, 0x1ce8, v33
	v_add_u32_e32 v90, s8, v32
	v_add_u32_e32 v94, s8, v38
	v_ashrrev_i32_e32 v91, 31, v90
	s_lshl_b64 s[6:7], s[12:13], 13
	v_ashrrev_i32_e32 v95, 31, v94
	v_lshlrev_b64 v[90:91], 7, v[90:91]
	v_lshl_add_u64 v[98:99], v[66:67], 0, s[6:7]
	v_add_u32_e32 v96, s8, v40
	v_lshlrev_b64 v[94:95], 7, v[94:95]
	v_lshl_add_u64 v[90:91], v[98:99], 0, v[90:91]
	v_lshl_add_u64 v[94:95], v[98:99], 0, v[94:95]
	s_waitcnt vmcnt(0)
	ds_write2_b32 v33, v0, v1 offset1:1
	ds_write2_b32 v33, v2, v3 offset0:2 offset1:3
	ds_write2_b32 v36, v4, v5 offset1:1
	ds_write2_b32 v39, v6, v7 offset1:1
	ds_write2_b32 v41, v8, v9 offset1:1
	ds_write2_b32 v43, v10, v11 offset1:1
	ds_write2_b32 v88, v12, v13 offset1:1
	ds_write2_b32 v92, v14, v15 offset1:1
	ds_write2_b32 v97, v16, v17 offset1:1
	ds_write2_b32 v100, v18, v19 offset1:1
	ds_write2_b32 v101, v20, v21 offset1:1
	ds_write2_b32 v102, v22, v23 offset1:1
	ds_write2_b32 v103, v24, v25 offset1:1
	ds_write2_b32 v104, v26, v27 offset1:1
	ds_write2_b32 v105, v28, v29 offset1:1
	ds_write2_b32 v106, v30, v31 offset1:1
	s_waitcnt lgkmcnt(0)
	ds_read2_b32 v[4:5], v93 offset0:33 offset1:41
	ds_read2_b32 v[6:7], v93 offset1:8
	ds_read2_b32 v[8:9], v93 offset0:66 offset1:74
	ds_read2_b32 v[10:11], v93 offset0:99 offset1:107
	ds_read2_b32 v[12:13], v93 offset0:132 offset1:140
	ds_read2_b32 v[14:15], v93 offset0:165 offset1:173
	ds_read2_b32 v[16:17], v93 offset0:198 offset1:206
	ds_read2_b32 v[18:19], v93 offset0:231 offset1:239
	ds_read2_b32 v[20:21], v93 offset0:49 offset1:57
	ds_read2_b32 v[22:23], v93 offset0:16 offset1:24
	ds_read2_b32 v[24:25], v93 offset0:82 offset1:90
	ds_read2_b32 v[26:27], v93 offset0:115 offset1:123
	ds_read2_b32 v[28:29], v93 offset0:148 offset1:156
	ds_read2_b32 v[30:31], v93 offset0:181 offset1:189
	ds_read2_b32 v[100:101], v93 offset0:214 offset1:222
	ds_read2_b32 v[102:103], v93 offset0:247 offset1:255
	s_waitcnt lgkmcnt(14)
	v_cvt_pk_bf16_f32 v0, v6, v4
	s_waitcnt lgkmcnt(12)
	v_cvt_pk_bf16_f32 v1, v8, v10
	s_waitcnt lgkmcnt(10)
	v_cvt_pk_bf16_f32 v2, v12, v14
	s_waitcnt lgkmcnt(8)
	v_cvt_pk_bf16_f32 v3, v16, v18
	v_cvt_pk_bf16_f32 v4, v7, v5
	v_cvt_pk_bf16_f32 v5, v9, v11
	v_cvt_pk_bf16_f32 v6, v13, v15
	v_cvt_pk_bf16_f32 v7, v17, v19
	global_store_dwordx4 v[90:91], v[0:3], off sc1
	global_store_dwordx4 v[94:95], v[4:7], off sc1
	v_ashrrev_i32_e32 v97, 31, v96
	v_lshlrev_b64 v[0:1], 7, v[96:97]
	v_add_u32_e32 v4, s8, v42
	v_ashrrev_i32_e32 v5, 31, v4
	s_waitcnt lgkmcnt(6)
	v_cvt_pk_bf16_f32 v8, v22, v20
	s_waitcnt lgkmcnt(4)
	v_cvt_pk_bf16_f32 v9, v24, v26
	s_waitcnt lgkmcnt(2)
	v_cvt_pk_bf16_f32 v10, v28, v30
	s_waitcnt lgkmcnt(0)
	v_cvt_pk_bf16_f32 v11, v100, v102
	v_lshl_add_u64 v[0:1], v[98:99], 0, v[0:1]
	v_lshlrev_b64 v[4:5], 7, v[4:5]
	global_store_dwordx4 v[0:1], v[8:11], off sc1
	v_cvt_pk_bf16_f32 v0, v23, v21
	v_cvt_pk_bf16_f32 v1, v25, v27
	v_cvt_pk_bf16_f32 v2, v29, v31
	v_cvt_pk_bf16_f32 v3, v101, v103
	v_lshl_add_u64 v[4:5], v[98:99], 0, v[4:5]
	global_store_dwordx4 v[4:5], v[0:3], off sc1
	s_waitcnt lgkmcnt(0)

; __device__ __forceinline__ unsigned pk_bf16(float lo, float hi) { typedef __bf16 b2_t __attribute__((ext_vector_type(2))); f32x2 v = {lo, hi}; b2_t b = __builtin_convertvector(v, b2_t); return __builtin_bit_cast(unsigned, b); }
; #define LAS __attribute__((address_space(3)))
; __device__ __forceinline__ void transpose_tile(const float* W, const float* gain, int K, int N, int k0, int n0, bf16* WT, int drow0, LAS float* scr, int lane) {
;     f32x4 v[8]; float gv[8];
;     const int r0 = lane >> 3, c4 = lane & 7;
; #pragma unroll
;     for (int i = 0; i < 8; ++i) { v[i] = *(const f32x4*)(W + (size_t)(k0 + r0 + 8 * i) * N + n0 + 4 * c4); gv[i] = gain ? gain[k0 + r0 + 8 * i] : 1.0f; }
; #pragma unroll
;     for (int i = 0; i < 8; ++i) { LAS float* d = scr + (r0 + 8 * i) * 33 + 4 * c4; d[0] = v[i][0] * gv[i]; d[1] = v[i][1] * gv[i]; d[2] = v[i][2] * gv[i]; d[3] = v[i][3] * gv[i]; }
;     asm volatile("s_waitcnt lgkmcnt(0)" ::: "memory");
;     const int c = lane & 7;
; #pragma unroll
;     for (int j = 0; j < 4; ++j) { const int n = (lane >> 3) + 8 * j; const LAS float* s = scr + (8 * c) * 33 + n;
;         v4u o; o.x = pk_bf16(s[0 * 33], s[1 * 33]); o.y = pk_bf16(s[2 * 33], s[3 * 33]); o.z = pk_bf16(s[4 * 33], s[5 * 33]); o.w = pk_bf16(s[6 * 33], s[7 * 33]);
;         *(v4u*)(WT + (size_t)(drow0 + n) * K + k0 + 8 * c) = o; }
;     asm volatile("s_waitcnt lgkmcnt(0)" ::: "memory");
; }
.LBB0_1328:
	s_andn2_b64 vcc, exec, s[8:9]
	s_cbranch_vccnz .LBB0_1330
	s_mov_b32 s6, 24
	s_ashr_i32 s7, s6, 31
	s_lshl_b64 s[6:7], s[6:7], 3
	s_add_u32 s6, s0, s6
	s_addc_u32 s7, s1, s7
	s_load_dwordx2 s[6:7], s[6:7], 0x0
	s_lshl_b32 s8, s26, 5
	s_and_b32 s8, s8, 0x3e0
	s_add_i32 s9, s29, 0x1a80
	s_and_b32 s9, s9, 0x1ffc0
	s_lshl_b32 s12, s8, 2
	v_add_u32_e32 v0, s9, v32
	s_waitcnt lgkmcnt(0)
	s_add_u32 s6, s6, s12
	s_addc_u32 s7, s7, 0
	v_lshlrev_b32_e32 v36, 2, v34
	v_ashrrev_i32_e32 v1, 31, v0
	v_lshl_add_u64 v[2:3], s[6:7], 0, v[36:37]
	v_lshlrev_b64 v[0:1], 12, v[0:1]
	v_lshl_add_u64 v[28:29], v[2:3], 0, v[0:1]
	v_add_co_u32_e32 v4, vcc, s31, v28
	v_add_u32_e32 v33, v35, v89
	s_nop 0
	v_addc_co_u32_e32 v5, vcc, 0, v29, vcc
	v_add_co_u32_e32 v8, vcc, s34, v28
	global_load_dwordx4 v[0:3], v[28:29], off nt
	s_nop 0
	global_load_dwordx4 v[4:7], v[4:5], off nt
	v_addc_co_u32_e32 v9, vcc, 0, v29, vcc
	v_add_co_u32_e32 v12, vcc, s35, v28
	v_add_u32_e32 v36, 0x420, v33
	s_nop 0
	v_addc_co_u32_e32 v13, vcc, 0, v29, vcc
	v_add_co_u32_e32 v16, vcc, s36, v28
	global_load_dwordx4 v[8:11], v[8:9], off nt
	s_nop 0
	global_load_dwordx4 v[12:15], v[12:13], off nt
	v_addc_co_u32_e32 v17, vcc, 0, v29, vcc
	v_add_co_u32_e32 v20, vcc, s37, v28
	v_add_u32_e32 v39, 0x428, v33
	s_nop 0
	v_addc_co_u32_e32 v21, vcc, 0, v29, vcc
	global_load_dwordx4 v[16:19], v[16:17], off nt
	s_nop 0
	global_load_dwordx4 v[20:23], v[20:21], off nt
	v_add_co_u32_e32 v24, vcc, s38, v28
	v_add_u32_e32 v41, 0x840, v33
	s_nop 0
	v_addc_co_u32_e32 v25, vcc, 0, v29, vcc
	global_load_dwordx4 v[24:27], v[24:25], off nt
	v_add_co_u32_e32 v28, vcc, s39, v28
	v_add_u32_e32 v43, 0x848, v33
	s_nop 0
	v_addc_co_u32_e32 v29, vcc, 0, v29, vcc
	global_load_dwordx4 v[28:31], v[28:29], off nt
	v_add_u32_e32 v88, 0xc60, v33
	v_add_u32_e32 v92, 0xc68, v33
	v_add_u32_e32 v94, 0x1080, v33
	v_add_u32_e32 v95, 0x1088, v33
	v_add_u32_e32 v96, 0x14a0, v33
	v_add_u32_e32 v97, 0x14a8, v33
	v_add_u32_e32 v98, 0x18c0, v33
	v_add_u32_e32 v99, 0x18c8, v33
	v_add_u32_e32 v100, 0x1ce0, v33
	v_add_u32_e32 v101, 0x1ce8, v33
	v_add_u32_e32 v90, s8, v32
	v_ashrrev_i32_e32 v91, 31, v90
	s_lshl_b32 s12, s9, 1
	s_waitcnt vmcnt(0)
	ds_write2_b32 v33, v0, v1 offset1:1
	ds_write2_b32 v33, v2, v3 offset0:2 offset1:3
	ds_write2_b32 v36, v4, v5 offset1:1
	ds_write2_b32 v39, v6, v7 offset1:1
	ds_write2_b32 v41, v8, v9 offset1:1
	ds_write2_b32 v43, v10, v11 offset1:1
	ds_write2_b32 v88, v12, v13 offset1:1
	ds_write2_b32 v92, v14, v15 offset1:1
	ds_write2_b32 v94, v16, v17 offset1:1
	ds_write2_b32 v95, v18, v19 offset1:1
	ds_write2_b32 v96, v20, v21 offset1:1
	ds_write2_b32 v97, v22, v23 offset1:1
	ds_write2_b32 v98, v24, v25 offset1:1
	ds_write2_b32 v99, v26, v27 offset1:1
	ds_write2_b32 v100, v28, v29 offset1:1
	ds_write2_b32 v101, v30, v31 offset1:1
	s_waitcnt lgkmcnt(0)
	ds_read2_b32 v[4:5], v93 offset0:33 offset1:41
	ds_read2_b32 v[6:7], v93 offset1:8
	ds_read2_b32 v[8:9], v93 offset0:66 offset1:74
	ds_read2_b32 v[10:11], v93 offset0:99 offset1:107
	ds_read2_b32 v[12:13], v93 offset0:132 offset1:140
	ds_read2_b32 v[14:15], v93 offset0:165 offset1:173
	ds_read2_b32 v[16:17], v93 offset0:198 offset1:206
	ds_read2_b32 v[18:19], v93 offset0:231 offset1:239
	v_lshl_add_u64 v[20:21], v[68:69], 0, s[12:13]
	v_lshlrev_b64 v[22:23], 11, v[90:91]
	s_waitcnt lgkmcnt(6)
	v_cvt_pk_bf16_f32 v0, v6, v4
	s_waitcnt lgkmcnt(4)
	v_cvt_pk_bf16_f32 v1, v8, v10
	s_waitcnt lgkmcnt(2)
	v_cvt_pk_bf16_f32 v2, v12, v14
	s_waitcnt lgkmcnt(0)
	v_cvt_pk_bf16_f32 v3, v16, v18
	v_lshl_add_u64 v[22:23], v[20:21], 0, v[22:23]
	v_add_u32_e32 v4, s8, v38
	global_store_dwordx4 v[22:23], v[0:3], off sc1
	s_nop 1
	v_cvt_pk_bf16_f32 v0, v7, v5
	v_ashrrev_i32_e32 v5, 31, v4
	v_cvt_pk_bf16_f32 v1, v9, v11
	v_cvt_pk_bf16_f32 v2, v13, v15
	v_cvt_pk_bf16_f32 v3, v17, v19
	v_lshlrev_b64 v[4:5], 11, v[4:5]
	ds_read2_b32 v[6:7], v93 offset0:49 offset1:57
	ds_read2_b32 v[8:9], v93 offset0:16 offset1:24
	ds_read2_b32 v[10:11], v93 offset0:82 offset1:90
	ds_read2_b32 v[12:13], v93 offset0:115 offset1:123
	ds_read2_b32 v[14:15], v93 offset0:148 offset1:156
	ds_read2_b32 v[16:17], v93 offset0:181 offset1:189
	ds_read2_b32 v[18:19], v93 offset0:214 offset1:222
	ds_read2_b32 v[22:23], v93 offset0:247 offset1:255
	v_lshl_add_u64 v[4:5], v[20:21], 0, v[4:5]
	global_store_dwordx4 v[4:5], v[0:3], off sc1
	v_add_u32_e32 v4, s8, v40
	v_ashrrev_i32_e32 v5, 31, v4
	v_lshlrev_b64 v[4:5], 11, v[4:5]
	s_waitcnt lgkmcnt(6)
	v_cvt_pk_bf16_f32 v0, v8, v6
	s_waitcnt lgkmcnt(4)
	v_cvt_pk_bf16_f32 v1, v10, v12
	s_waitcnt lgkmcnt(2)
	v_cvt_pk_bf16_f32 v2, v14, v16
	s_waitcnt lgkmcnt(0)
	v_cvt_pk_bf16_f32 v3, v18, v22
	v_lshl_add_u64 v[4:5], v[20:21], 0, v[4:5]
	global_store_dwordx4 v[4:5], v[0:3], off sc1
	v_add_u32_e32 v4, s8, v42
	v_ashrrev_i32_e32 v5, 31, v4
	v_lshlrev_b64 v[4:5], 11, v[4:5]
	v_cvt_pk_bf16_f32 v0, v9, v7
	v_cvt_pk_bf16_f32 v1, v11, v13
	v_cvt_pk_bf16_f32 v2, v15, v17
	v_cvt_pk_bf16_f32 v3, v19, v23
	v_lshl_add_u64 v[4:5], v[20:21], 0, v[4:5]
	global_store_dwordx4 v[4:5], v[0:3], off sc1
	s_waitcnt lgkmcnt(0)

; #define LAS __attribute__((address_space(3)))
; __device__ __forceinline__ void transpose_tile(const float* W, const float* gain, int K, int N, int k0, int n0, bf16* WT, int drow0, LAS float* scr, int lane) {
;     f32x4 v[8]; float gv[8];
;     const int r0 = lane >> 3, c4 = lane & 7;
; #pragma unroll
;     for (int i = 0; i < 8; ++i) { v[i] = *(const f32x4*)(W + (size_t)(k0 + r0 + 8 * i) * N + n0 + 4 * c4); gv[i] = gain ? gain[k0 + r0 + 8 * i] : 1.0f; }
.LBB0_1331:
	s_andn2_b64 vcc, exec, s[8:9]
	s_cbranch_vccnz .LBB0_1349
	s_mov_b32 s6, 16
	s_ashr_i32 s7, s6, 31
	s_lshl_b64 s[6:7], s[6:7], 3
	s_add_u32 s6, s0, s6
	s_addc_u32 s7, s1, s7
	s_load_dwordx2 s[8:9], s[6:7], 0x0
	s_mov_b32 s6, 15
	s_ashr_i32 s7, s6, 31
	s_lshl_b64 s[6:7], s[6:7], 3
	s_add_u32 s20, s0, s6
	s_addc_u32 s21, s1, s7
	s_lshl_b32 s7, s26, 5
	s_add_i32 s6, s26, 0xc680
	s_and_b32 s7, s7, 0x7e0
	s_and_b32 s6, s6, 0xffc0
	s_lshl_b32 s12, s7, 2
	v_add_u32_e32 v4, s6, v32
	s_waitcnt lgkmcnt(0)
	s_add_u32 s8, s8, s12
	s_addc_u32 s9, s9, 0
	v_lshlrev_b32_e32 v36, 2, v34
	v_ashrrev_i32_e32 v5, 31, v4
	v_lshl_add_u64 v[0:1], s[8:9], 0, v[36:37]
	v_lshlrev_b64 v[2:3], 13, v[4:5]
	v_lshl_add_u64 v[28:29], v[0:1], 0, v[2:3]
	global_load_dwordx4 v[0:3], v[28:29], off nt
	s_load_dwordx2 s[8:9], s[20:21], 0x0
	v_mov_b32_e32 v36, 1.0
	v_mov_b32_e32 v88, 1.0
	s_waitcnt lgkmcnt(0)
	s_cmp_lg_u64 s[8:9], 0
	s_cselect_b64 s[20:21], -1, 0
	s_cmp_eq_u64 s[8:9], 0
	v_lshl_add_u64 v[90:91], v[4:5], 2, s[8:9]
	s_cbranch_scc1 .LBB0_1334
	global_load_dword v88, v[90:91], off nt
.LBB0_1334:
	v_add_co_u32_e32 v4, vcc, 0x10000, v28
	v_cndmask_b32_e64 v8, 0, 1, s[20:21]
	s_nop 0
	v_addc_co_u32_e32 v5, vcc, 0, v29, vcc
	global_load_dwordx4 v[4:7], v[4:5], off nt
	v_cmp_ne_u32_e64 s[8:9], 1, v8
	s_andn2_b64 vcc, exec, s[20:21]
	s_cbranch_vccnz .LBB0_1336
	global_load_dword v36, v[90:91], off offset:32 nt
.LBB0_1336:
	v_add_co_u32_e32 v8, vcc, 0x20000, v28
	v_mov_b32_e32 v92, 1.0
	s_nop 0
	v_addc_co_u32_e32 v9, vcc, 0, v29, vcc
	global_load_dwordx4 v[8:11], v[8:9], off nt
	s_and_b64 vcc, exec, s[8:9]
	v_mov_b32_e32 v94, 1.0
	s_cbranch_vccnz .LBB0_1338
	global_load_dword v94, v[90:91], off offset:64 nt
.LBB0_1338:
	v_add_co_u32_e32 v12, vcc, 0x30000, v28
	s_nop 1
	v_addc_co_u32_e32 v13, vcc, 0, v29, vcc
	global_load_dwordx4 v[12:15], v[12:13], off nt
	s_and_b64 vcc, exec, s[8:9]
	s_cbranch_vccnz .LBB0_1340
	global_load_dword v92, v[90:91], off offset:96 nt
.LBB0_1340:
	v_add_co_u32_e32 v16, vcc, 0x40000, v28
	v_mov_b32_e32 v96, 1.0
	s_nop 0
	v_addc_co_u32_e32 v17, vcc, 0, v29, vcc
	global_load_dwordx4 v[16:19], v[16:17], off nt
	s_and_b64 vcc, exec, s[8:9]
	v_mov_b32_e32 v98, 1.0
	s_cbranch_vccnz .LBB0_1342
	global_load_dword v98, v[90:91], off offset:128 nt
.LBB0_1342:
	v_add_co_u32_e32 v20, vcc, 0x50000, v28
	s_nop 1
	v_addc_co_u32_e32 v21, vcc, 0, v29, vcc
	global_load_dwordx4 v[20:23], v[20:21], off nt
	s_and_b64 vcc, exec, s[8:9]
	s_cbranch_vccnz .LBB0_1344
	global_load_dword v96, v[90:91], off offset:160 nt
.LBB0_1344:
	v_add_co_u32_e32 v24, vcc, 0x60000, v28
	v_mov_b32_e32 v100, 1.0
	s_nop 0
	v_addc_co_u32_e32 v25, vcc, 0, v29, vcc
	global_load_dwordx4 v[24:27], v[24:25], off nt
	s_and_b64 vcc, exec, s[8:9]
	v_mov_b32_e32 v102, 1.0
	s_cbranch_vccnz .LBB0_1346
	global_load_dword v102, v[90:91], off offset:192 nt
.LBB0_1346:
	v_add_co_u32_e32 v28, vcc, 0x70000, v28
	s_nop 1
	v_addc_co_u32_e32 v29, vcc, 0, v29, vcc
	global_load_dwordx4 v[28:31], v[28:29], off nt
	s_and_b64 vcc, exec, s[8:9]
	s_cbranch_vccnz .LBB0_1348
	global_load_dword v100, v[90:91], off offset:224 nt

; __device__ __forceinline__ unsigned pk_bf16(float lo, float hi) { typedef __bf16 b2_t __attribute__((ext_vector_type(2))); f32x2 v = {lo, hi}; b2_t b = __builtin_convertvector(v, b2_t); return __builtin_bit_cast(unsigned, b); }
; #define LAS __attribute__((address_space(3)))
; __device__ __forceinline__ void transpose_tile(const float* W, const float* gain, int K, int N, int k0, int n0, bf16* WT, int drow0, LAS float* scr, int lane) {
;     f32x4 v[8]; float gv[8];
;     const int r0 = lane >> 3, c4 = lane & 7;
; #pragma unroll
;     for (int i = 0; i < 8; ++i) { v[i] = *(const f32x4*)(W + (size_t)(k0 + r0 + 8 * i) * N + n0 + 4 * c4); gv[i] = gain ? gain[k0 + r0 + 8 * i] : 1.0f; }
; #pragma unroll
;     for (int i = 0; i < 8; ++i) { LAS float* d = scr + (r0 + 8 * i) * 33 + 4 * c4; d[0] = v[i][0] * gv[i]; d[1] = v[i][1] * gv[i]; d[2] = v[i][2] * gv[i]; d[3] = v[i][3] * gv[i]; }
;     asm volatile("s_waitcnt lgkmcnt(0)" ::: "memory");
;     const int c = lane & 7;
; #pragma unroll
;     for (int j = 0; j < 4; ++j) { const int n = (lane >> 3) + 8 * j; const LAS float* s = scr + (8 * c) * 33 + n;
;         v4u o; o.x = pk_bf16(s[0 * 33], s[1 * 33]); o.y = pk_bf16(s[2 * 33], s[3 * 33]); o.z = pk_bf16(s[4 * 33], s[5 * 33]); o.w = pk_bf16(s[6 * 33], s[7 * 33]);
;         *(v4u*)(WT + (size_t)(drow0 + n) * K + k0 + 8 * c) = o; }
;     asm volatile("s_waitcnt lgkmcnt(0)" ::: "memory");
; }
.LBB0_1350:
	s_andn2_b64 vcc, exec, s[8:9]
	s_cbranch_vccnz .LBB0_1352
	s_mov_b32 s6, 14
	s_ashr_i32 s7, s6, 31
	s_lshl_b64 s[6:7], s[6:7], 3
	s_add_u32 s6, s0, s6
	s_addc_u32 s7, s1, s7
	s_load_dwordx2 s[6:7], s[6:7], 0x0
	s_lshl_b32 s8, s26, 5
	s_and_b32 s8, s8, 0x3e0
	s_add_i32 s9, s29, 0x2d80
	s_and_b32 s9, s9, 0x1ffc0
	s_lshl_b32 s12, s8, 2
	v_add_u32_e32 v0, s9, v32
	s_waitcnt lgkmcnt(0)
	s_add_u32 s6, s6, s12
	s_addc_u32 s7, s7, 0
	v_lshlrev_b32_e32 v36, 2, v34
	v_ashrrev_i32_e32 v1, 31, v0
	v_lshl_add_u64 v[2:3], s[6:7], 0, v[36:37]
	v_lshlrev_b64 v[0:1], 12, v[0:1]
	v_lshl_add_u64 v[28:29], v[2:3], 0, v[0:1]
	v_add_co_u32_e32 v4, vcc, s31, v28
	v_add_u32_e32 v33, v35, v89
	s_nop 0
	v_addc_co_u32_e32 v5, vcc, 0, v29, vcc
	v_add_co_u32_e32 v8, vcc, s34, v28
	global_load_dwordx4 v[0:3], v[28:29], off nt
	s_nop 0
	global_load_dwordx4 v[4:7], v[4:5], off nt
	v_addc_co_u32_e32 v9, vcc, 0, v29, vcc
	v_add_co_u32_e32 v12, vcc, s35, v28
	v_add_u32_e32 v36, 0x420, v33
	s_nop 0
	v_addc_co_u32_e32 v13, vcc, 0, v29, vcc
	v_add_co_u32_e32 v16, vcc, s36, v28
	global_load_dwordx4 v[8:11], v[8:9], off nt
	s_nop 0
	global_load_dwordx4 v[12:15], v[12:13], off nt
	v_addc_co_u32_e32 v17, vcc, 0, v29, vcc
	v_add_co_u32_e32 v20, vcc, s37, v28
	v_add_u32_e32 v39, 0x428, v33
	s_nop 0
	v_addc_co_u32_e32 v21, vcc, 0, v29, vcc
	global_load_dwordx4 v[16:19], v[16:17], off nt
	s_nop 0
	global_load_dwordx4 v[20:23], v[20:21], off nt
	v_add_co_u32_e32 v24, vcc, s38, v28
	v_add_u32_e32 v41, 0x840, v33
	s_nop 0
	v_addc_co_u32_e32 v25, vcc, 0, v29, vcc
	global_load_dwordx4 v[24:27], v[24:25], off nt
	v_add_co_u32_e32 v28, vcc, s39, v28
	v_add_u32_e32 v43, 0x848, v33
	s_nop 0
	v_addc_co_u32_e32 v29, vcc, 0, v29, vcc
	global_load_dwordx4 v[28:31], v[28:29], off nt
	v_add_u32_e32 v88, 0xc60, v33
	v_add_u32_e32 v90, 0xc68, v33
	v_add_u32_e32 v91, 0x1080, v33
	v_add_u32_e32 v92, 0x1088, v33
	v_add_u32_e32 v94, 0x14a0, v33
	v_add_u32_e32 v95, 0x14a8, v33
	v_add_u32_e32 v96, 0x18c0, v33
	v_add_u32_e32 v97, 0x18c8, v33
	v_add_u32_e32 v98, 0x1ce0, v33
	v_add_u32_e32 v99, 0x1ce8, v33
	s_lshl_b32 s12, s9, 1
	v_add_u32_e32 v100, s8, v32
	s_waitcnt vmcnt(0)
	ds_write2_b32 v33, v0, v1 offset1:1
	ds_write2_b32 v33, v2, v3 offset0:2 offset1:3
	ds_write2_b32 v36, v4, v5 offset1:1
	ds_write2_b32 v39, v6, v7 offset1:1
	ds_write2_b32 v41, v8, v9 offset1:1
	ds_write2_b32 v43, v10, v11 offset1:1
	ds_write2_b32 v88, v12, v13 offset1:1
	ds_write2_b32 v90, v14, v15 offset1:1
	ds_write2_b32 v91, v16, v17 offset1:1
	ds_write2_b32 v92, v18, v19 offset1:1
	ds_write2_b32 v94, v20, v21 offset1:1
	ds_write2_b32 v95, v22, v23 offset1:1
	ds_write2_b32 v96, v24, v25 offset1:1
	ds_write2_b32 v97, v26, v27 offset1:1
	ds_write2_b32 v98, v28, v29 offset1:1
	ds_write2_b32 v99, v30, v31 offset1:1
	s_waitcnt lgkmcnt(0)
	ds_read2_b32 v[4:5], v93 offset0:33 offset1:41
	ds_read2_b32 v[6:7], v93 offset1:8
	ds_read2_b32 v[8:9], v93 offset0:66 offset1:74
	ds_read2_b32 v[10:11], v93 offset0:99 offset1:107
	ds_read2_b32 v[12:13], v93 offset0:132 offset1:140
	ds_read2_b32 v[14:15], v93 offset0:165 offset1:173
	ds_read2_b32 v[16:17], v93 offset0:198 offset1:206
	ds_read2_b32 v[18:19], v93 offset0:231 offset1:239
	v_lshl_add_u64 v[20:21], v[72:73], 0, s[12:13]
	s_waitcnt lgkmcnt(6)
	v_cvt_pk_bf16_f32 v0, v6, v4
	s_waitcnt lgkmcnt(4)
	v_cvt_pk_bf16_f32 v1, v8, v10
	s_waitcnt lgkmcnt(2)
	v_cvt_pk_bf16_f32 v2, v12, v14
	s_waitcnt lgkmcnt(0)
	v_cvt_pk_bf16_f32 v3, v16, v18
	v_mad_i64_i32 v[22:23], s[6:7], v100, s40, v[20:21]
	global_store_dwordx4 v[22:23], v[0:3], off sc1
	v_add_u32_e32 v4, s8, v38
	s_nop 0
	v_cvt_pk_bf16_f32 v0, v7, v5
	v_cvt_pk_bf16_f32 v1, v9, v11
	v_cvt_pk_bf16_f32 v2, v13, v15
	v_cvt_pk_bf16_f32 v3, v17, v19
	ds_read2_b32 v[6:7], v93 offset0:49 offset1:57
	ds_read2_b32 v[8:9], v93 offset0:16 offset1:24
	ds_read2_b32 v[10:11], v93 offset0:82 offset1:90
	ds_read2_b32 v[12:13], v93 offset0:115 offset1:123
	ds_read2_b32 v[14:15], v93 offset0:148 offset1:156
	ds_read2_b32 v[16:17], v93 offset0:181 offset1:189
	ds_read2_b32 v[18:19], v93 offset0:214 offset1:222
	ds_read2_b32 v[22:23], v93 offset0:247 offset1:255
	v_mad_i64_i32 v[4:5], s[6:7], v4, s40, v[20:21]
	global_store_dwordx4 v[4:5], v[0:3], off sc1
	v_add_u32_e32 v4, s8, v40
	v_mad_i64_i32 v[4:5], s[6:7], v4, s40, v[20:21]
	s_waitcnt lgkmcnt(6)
	v_cvt_pk_bf16_f32 v0, v8, v6
	s_waitcnt lgkmcnt(4)
	v_cvt_pk_bf16_f32 v1, v10, v12
	s_waitcnt lgkmcnt(2)
	v_cvt_pk_bf16_f32 v2, v14, v16
	s_waitcnt lgkmcnt(0)
	v_cvt_pk_bf16_f32 v3, v18, v22
	global_store_dwordx4 v[4:5], v[0:3], off sc1
	v_add_u32_e32 v4, s8, v42
	v_mad_i64_i32 v[4:5], s[6:7], v4, s40, v[20:21]
	v_cvt_pk_bf16_f32 v0, v9, v7
	v_cvt_pk_bf16_f32 v1, v11, v13
	v_cvt_pk_bf16_f32 v2, v15, v17
	v_cvt_pk_bf16_f32 v3, v19, v23
	global_store_dwordx4 v[4:5], v[0:3], off sc1
	s_waitcnt lgkmcnt(0)

; __device__ __forceinline__ void transpose_tile(const float* W, const float* gain, int K, int N, int k0, int n0, bf16* WT, int drow0, LAS float* scr, int lane) {
;     ...
; #pragma unroll
;     for (int i = 0; i < 8; ++i) { v[i] = *(const f32x4*)(W + (size_t)(k0 + r0 + 8 * i) * N + n0 + 4 * c4); gv[i] = gain ? gain[k0 + r0 + 8 * i] : 1.0f; }
; template <bool SWIGLU> __device__ __forceinline__ void transpose_item(const float* W, const float* gain, int K, int N, bf16* WT, LAS float* scr, int item, int lane) {
;     ...
;     if (SWIGLU) { const int up = n0 >= FF, f = up ? n0 - FF : n0; drow0 = 256 * (f >> 7) + (up ? 128 : 0) + (f & 127); }
.LBB0_1353:
	s_andn2_b64 vcc, exec, s[8:9]
	s_cbranch_vccnz .LBB0_1371
	s_mov_b32 s6, 13
	s_ashr_i32 s7, s6, 31
	s_lshl_b64 s[6:7], s[6:7], 3
	s_add_u32 s6, s0, s6
	s_addc_u32 s7, s1, s7
	s_load_dwordx2 s[8:9], s[6:7], 0x0
	s_mov_b32 s6, 12
	s_ashr_i32 s7, s6, 31
	s_lshl_b64 s[6:7], s[6:7], 3
	s_add_u32 s20, s0, s6
	s_addc_u32 s21, s1, s7
	s_add_i32 s6, s26, 0xd700
	s_and_b32 s7, s6, 0xffff
	s_mul_i32 s7, s7, 0xba2f
	s_lshr_b32 s12, s7, 23
	s_mul_i32 s7, s12, 0xb0
	s_sub_i32 s7, s6, s7
	s_lshl_b32 s6, s12, 6
	s_lshl_b32 s12, s7, 7
	s_and_b32 s12, s12, 0x3ff80
	s_waitcnt lgkmcnt(0)
	s_add_u32 s8, s8, s12
	s_addc_u32 s9, s9, 0
	v_lshlrev_b32_e32 v36, 2, v34
	v_add_u32_e32 v28, s6, v32
	v_lshl_add_u64 v[30:31], s[8:9], 0, v[36:37]
	v_mad_i64_i32 v[0:1], s[8:9], v28, s41, v[30:31]
	global_load_dwordx4 v[0:3], v[0:1], off nt
	s_load_dwordx2 s[8:9], s[20:21], 0x0
	v_ashrrev_i32_e32 v29, 31, v28
	v_mov_b32_e32 v36, 1.0
	v_mov_b32_e32 v88, 1.0
	s_waitcnt lgkmcnt(0)
	s_cmp_lg_u64 s[8:9], 0
	s_cselect_b64 s[20:21], -1, 0
	s_cmp_eq_u64 s[8:9], 0
	v_lshl_add_u64 v[98:99], v[28:29], 2, s[8:9]
	s_cbranch_scc1 .LBB0_1356
	global_load_dword v88, v[98:99], off nt

; __device__ __forceinline__ unsigned pk_bf16(float lo, float hi) { typedef __bf16 b2_t __attribute__((ext_vector_type(2))); f32x2 v = {lo, hi}; b2_t b = __builtin_convertvector(v, b2_t); return __builtin_bit_cast(unsigned, b); }
; #define LAS __attribute__((address_space(3)))
; __device__ __forceinline__ void transpose_tile(const float* W, const float* gain, int K, int N, int k0, int n0, bf16* WT, int drow0, LAS float* scr, int lane) {
;     f32x4 v[8]; float gv[8];
;     const int r0 = lane >> 3, c4 = lane & 7;
; #pragma unroll
;     for (int i = 0; i < 8; ++i) { v[i] = *(const f32x4*)(W + (size_t)(k0 + r0 + 8 * i) * N + n0 + 4 * c4); gv[i] = gain ? gain[k0 + r0 + 8 * i] : 1.0f; }
; #pragma unroll
;     for (int i = 0; i < 8; ++i) { LAS float* d = scr + (r0 + 8 * i) * 33 + 4 * c4; d[0] = v[i][0] * gv[i]; d[1] = v[i][1] * gv[i]; d[2] = v[i][2] * gv[i]; d[3] = v[i][3] * gv[i]; }
;     asm volatile("s_waitcnt lgkmcnt(0)" ::: "memory");
;     const int c = lane & 7;
; #pragma unroll
;     for (int j = 0; j < 4; ++j) { const int n = (lane >> 3) + 8 * j; const LAS float* s = scr + (8 * c) * 33 + n;
;         v4u o; o.x = pk_bf16(s[0 * 33], s[1 * 33]); o.y = pk_bf16(s[2 * 33], s[3 * 33]); o.z = pk_bf16(s[4 * 33], s[5 * 33]); o.w = pk_bf16(s[6 * 33], s[7 * 33]);
;         *(v4u*)(WT + (size_t)(drow0 + n) * K + k0 + 8 * c) = o; }
;     asm volatile("s_waitcnt lgkmcnt(0)" ::: "memory");
; }
.LBB0_1372:
	s_andn2_b64 vcc, exec, s[8:9]
	s_cbranch_vccnz .LBB0_1374
	s_mov_b32 s6, 11
	s_ashr_i32 s7, s6, 31
	s_lshl_b64 s[6:7], s[6:7], 3
	s_add_u32 s6, s0, s6
	s_addc_u32 s7, s1, s7
	s_load_dwordx2 s[6:7], s[6:7], 0x0
	s_lshl_b32 s8, s26, 5
	s_and_b32 s8, s8, 0x3e0
	s_add_i32 s9, s29, 0x4e80
	s_and_b32 s9, s9, 0x1ffc0
	s_lshl_b32 s12, s8, 2
	v_add_u32_e32 v0, s9, v32
	s_waitcnt lgkmcnt(0)
	s_add_u32 s6, s6, s12
	s_addc_u32 s7, s7, 0
	v_lshlrev_b32_e32 v36, 2, v34
	v_ashrrev_i32_e32 v1, 31, v0
	v_lshl_add_u64 v[2:3], s[6:7], 0, v[36:37]
	v_lshlrev_b64 v[0:1], 12, v[0:1]
	v_lshl_add_u64 v[28:29], v[2:3], 0, v[0:1]
	v_add_co_u32_e32 v4, vcc, s31, v28
	v_add_u32_e32 v33, v35, v89
	s_nop 0
	v_addc_co_u32_e32 v5, vcc, 0, v29, vcc
	v_add_co_u32_e32 v8, vcc, s34, v28
	global_load_dwordx4 v[0:3], v[28:29], off nt
	s_nop 0
	global_load_dwordx4 v[4:7], v[4:5], off nt
	v_addc_co_u32_e32 v9, vcc, 0, v29, vcc
	v_add_co_u32_e32 v12, vcc, s35, v28
	v_add_u32_e32 v36, 0x420, v33
	s_nop 0
	v_addc_co_u32_e32 v13, vcc, 0, v29, vcc
	v_add_co_u32_e32 v16, vcc, s36, v28
	global_load_dwordx4 v[8:11], v[8:9], off nt
	s_nop 0
	global_load_dwordx4 v[12:15], v[12:13], off nt
	v_addc_co_u32_e32 v17, vcc, 0, v29, vcc
	v_add_co_u32_e32 v20, vcc, s37, v28
	v_add_u32_e32 v39, 0x428, v33
	s_nop 0
	v_addc_co_u32_e32 v21, vcc, 0, v29, vcc
	global_load_dwordx4 v[16:19], v[16:17], off nt
	s_nop 0
	global_load_dwordx4 v[20:23], v[20:21], off nt
	v_add_co_u32_e32 v24, vcc, s38, v28
	v_add_u32_e32 v41, 0x840, v33
	s_nop 0
	v_addc_co_u32_e32 v25, vcc, 0, v29, vcc
	global_load_dwordx4 v[24:27], v[24:25], off nt
	v_add_co_u32_e32 v28, vcc, s39, v28
	v_add_u32_e32 v43, 0x848, v33
	s_nop 0
	v_addc_co_u32_e32 v29, vcc, 0, v29, vcc
	global_load_dwordx4 v[28:31], v[28:29], off nt
	v_add_u32_e32 v88, 0xc60, v33
	v_add_u32_e32 v90, 0xc68, v33
	v_add_u32_e32 v91, 0x1080, v33
	v_add_u32_e32 v92, 0x1088, v33
	v_add_u32_e32 v94, 0x14a0, v33
	v_add_u32_e32 v95, 0x14a8, v33
	v_add_u32_e32 v96, 0x18c0, v33
	v_add_u32_e32 v97, 0x18c8, v33
	v_add_u32_e32 v98, 0x1ce0, v33
	v_add_u32_e32 v99, 0x1ce8, v33
	s_lshl_b32 s12, s9, 1
	v_add_u32_e32 v100, s8, v32
	s_waitcnt vmcnt(0)
	ds_write2_b32 v33, v0, v1 offset1:1
	ds_write2_b32 v33, v2, v3 offset0:2 offset1:3
	ds_write2_b32 v36, v4, v5 offset1:1
	ds_write2_b32 v39, v6, v7 offset1:1
	ds_write2_b32 v41, v8, v9 offset1:1
	ds_write2_b32 v43, v10, v11 offset1:1
	ds_write2_b32 v88, v12, v13 offset1:1
	ds_write2_b32 v90, v14, v15 offset1:1
	ds_write2_b32 v91, v16, v17 offset1:1
	ds_write2_b32 v92, v18, v19 offset1:1
	ds_write2_b32 v94, v20, v21 offset1:1
	ds_write2_b32 v95, v22, v23 offset1:1
	ds_write2_b32 v96, v24, v25 offset1:1
	ds_write2_b32 v97, v26, v27 offset1:1
	ds_write2_b32 v98, v28, v29 offset1:1
	ds_write2_b32 v99, v30, v31 offset1:1
	s_waitcnt lgkmcnt(0)
	ds_read2_b32 v[4:5], v93 offset0:33 offset1:41
	ds_read2_b32 v[6:7], v93 offset1:8
	ds_read2_b32 v[8:9], v93 offset0:66 offset1:74
	ds_read2_b32 v[10:11], v93 offset0:99 offset1:107
	ds_read2_b32 v[12:13], v93 offset0:132 offset1:140
	ds_read2_b32 v[14:15], v93 offset0:165 offset1:173
	ds_read2_b32 v[16:17], v93 offset0:198 offset1:206
	ds_read2_b32 v[18:19], v93 offset0:231 offset1:239
	v_lshl_add_u64 v[20:21], v[76:77], 0, s[12:13]
	s_waitcnt lgkmcnt(6)
	v_cvt_pk_bf16_f32 v0, v6, v4
	s_waitcnt lgkmcnt(4)
	v_cvt_pk_bf16_f32 v1, v8, v10
	s_waitcnt lgkmcnt(2)
	v_cvt_pk_bf16_f32 v2, v12, v14
	s_waitcnt lgkmcnt(0)
	v_cvt_pk_bf16_f32 v3, v16, v18
	v_mad_i64_i32 v[22:23], s[6:7], v100, s40, v[20:21]
	global_store_dwordx4 v[22:23], v[0:3], off sc1
	v_add_u32_e32 v4, s8, v38
	s_nop 0
	v_cvt_pk_bf16_f32 v0, v7, v5
	v_cvt_pk_bf16_f32 v1, v9, v11
	v_cvt_pk_bf16_f32 v2, v13, v15
	v_cvt_pk_bf16_f32 v3, v17, v19
	ds_read2_b32 v[6:7], v93 offset0:49 offset1:57
	ds_read2_b32 v[8:9], v93 offset0:16 offset1:24
	ds_read2_b32 v[10:11], v93 offset0:82 offset1:90
	ds_read2_b32 v[12:13], v93 offset0:115 offset1:123
	ds_read2_b32 v[14:15], v93 offset0:148 offset1:156
	ds_read2_b32 v[16:17], v93 offset0:181 offset1:189
	ds_read2_b32 v[18:19], v93 offset0:214 offset1:222
	ds_read2_b32 v[22:23], v93 offset0:247 offset1:255
	v_mad_i64_i32 v[4:5], s[6:7], v4, s40, v[20:21]
	global_store_dwordx4 v[4:5], v[0:3], off sc1
	v_add_u32_e32 v4, s8, v40
	v_mad_i64_i32 v[4:5], s[6:7], v4, s40, v[20:21]
	s_waitcnt lgkmcnt(6)
	v_cvt_pk_bf16_f32 v0, v8, v6
	s_waitcnt lgkmcnt(4)
	v_cvt_pk_bf16_f32 v1, v10, v12
	s_waitcnt lgkmcnt(2)
	v_cvt_pk_bf16_f32 v2, v14, v16
	s_waitcnt lgkmcnt(0)
	v_cvt_pk_bf16_f32 v3, v18, v22
	global_store_dwordx4 v[4:5], v[0:3], off sc1
	v_add_u32_e32 v4, s8, v42
	v_mad_i64_i32 v[4:5], s[6:7], v4, s40, v[20:21]
	v_cvt_pk_bf16_f32 v0, v9, v7
	v_cvt_pk_bf16_f32 v1, v11, v13
	v_cvt_pk_bf16_f32 v2, v15, v17
	v_cvt_pk_bf16_f32 v3, v19, v23
	global_store_dwordx4 v[4:5], v[0:3], off sc1
	s_waitcnt lgkmcnt(0)

; __device__ __forceinline__ void transpose_tile(const float* W, const float* gain, int K, int N, int k0, int n0, bf16* WT, int drow0, LAS float* scr, int lane) {
;     ...
; #pragma unroll
;     for (int i = 0; i < 8; ++i) { v[i] = *(const f32x4*)(W + (size_t)(k0 + r0 + 8 * i) * N + n0 + 4 * c4); gv[i] = gain ? gain[k0 + r0 + 8 * i] : 1.0f; }
; template <bool SWIGLU> __device__ __forceinline__ void transpose_item(const float* W, const float* gain, int K, int N, bf16* WT, LAS float* scr, int item, int lane) {
;     ...
;     if (SWIGLU) { const int up = n0 >= FF, f = up ? n0 - FF : n0; drow0 = 256 * (f >> 7) + (up ? 128 : 0) + (f & 127); }
.LBB0_1375:
	s_andn2_b64 vcc, exec, s[8:9]
	s_cbranch_vccnz .LBB0_1393
	s_mov_b32 s6, 10
	s_ashr_i32 s7, s6, 31
	s_lshl_b64 s[6:7], s[6:7], 3
	s_add_u32 s6, s0, s6
	s_addc_u32 s7, s1, s7
	s_load_dwordx2 s[8:9], s[6:7], 0x0
	s_mov_b32 s6, 9
	s_ashr_i32 s7, s6, 31
	s_lshl_b64 s[6:7], s[6:7], 3
	s_add_u32 s20, s0, s6
	s_addc_u32 s21, s1, s7
	s_add_i32 s6, s26, 0xe780
	s_and_b32 s7, s6, 0xffff
	s_mul_i32 s7, s7, 0xba2f
	s_lshr_b32 s12, s7, 23
	s_mul_i32 s7, s12, 0xb0
	s_sub_i32 s7, s6, s7
	s_lshl_b32 s6, s12, 6
	s_lshl_b32 s12, s7, 7
	s_and_b32 s12, s12, 0x3ff80
	s_waitcnt lgkmcnt(0)
	s_add_u32 s8, s8, s12
	s_addc_u32 s9, s9, 0
	v_lshlrev_b32_e32 v36, 2, v34
	v_add_u32_e32 v28, s6, v32
	v_lshl_add_u64 v[30:31], s[8:9], 0, v[36:37]
	v_mad_i64_i32 v[0:1], s[8:9], v28, s41, v[30:31]
	global_load_dwordx4 v[0:3], v[0:1], off nt
	s_load_dwordx2 s[8:9], s[20:21], 0x0
	v_ashrrev_i32_e32 v29, 31, v28
	v_mov_b32_e32 v36, 1.0
	v_mov_b32_e32 v88, 1.0
	s_waitcnt lgkmcnt(0)
	s_cmp_lg_u64 s[8:9], 0
	s_cselect_b64 s[20:21], -1, 0
	s_cmp_eq_u64 s[8:9], 0
	v_lshl_add_u64 v[98:99], v[28:29], 2, s[8:9]
	s_cbranch_scc1 .LBB0_1378
	global_load_dword v88, v[98:99], off nt

; __device__ __forceinline__ unsigned pk_bf16(float lo, float hi) { typedef __bf16 b2_t __attribute__((ext_vector_type(2))); f32x2 v = {lo, hi}; b2_t b = __builtin_convertvector(v, b2_t); return __builtin_bit_cast(unsigned, b); }
; #define LAS __attribute__((address_space(3)))
; __device__ __forceinline__ void transpose_tile(const float* W, const float* gain, int K, int N, int k0, int n0, bf16* WT, int drow0, LAS float* scr, int lane) {
;     f32x4 v[8]; float gv[8];
;     const int r0 = lane >> 3, c4 = lane & 7;
; #pragma unroll
;     for (int i = 0; i < 8; ++i) { v[i] = *(const f32x4*)(W + (size_t)(k0 + r0 + 8 * i) * N + n0 + 4 * c4); gv[i] = gain ? gain[k0 + r0 + 8 * i] : 1.0f; }
; #pragma unroll
;     for (int i = 0; i < 8; ++i) { LAS float* d = scr + (r0 + 8 * i) * 33 + 4 * c4; d[0] = v[i][0] * gv[i]; d[1] = v[i][1] * gv[i]; d[2] = v[i][2] * gv[i]; d[3] = v[i][3] * gv[i]; }
;     asm volatile("s_waitcnt lgkmcnt(0)" ::: "memory");
;     const int c = lane & 7;
; #pragma unroll
;     for (int j = 0; j < 4; ++j) { const int n = (lane >> 3) + 8 * j; const LAS float* s = scr + (8 * c) * 33 + n;
;         v4u o; o.x = pk_bf16(s[0 * 33], s[1 * 33]); o.y = pk_bf16(s[2 * 33], s[3 * 33]); o.z = pk_bf16(s[4 * 33], s[5 * 33]); o.w = pk_bf16(s[6 * 33], s[7 * 33]);
;         *(v4u*)(WT + (size_t)(drow0 + n) * K + k0 + 8 * c) = o; }
;     asm volatile("s_waitcnt lgkmcnt(0)" ::: "memory");
; }
.LBB0_1394:
	s_andn2_b64 vcc, exec, s[8:9]
	s_cbranch_vccnz .LBB0_1396
	s_mov_b32 s6, 8
	s_ashr_i32 s7, s6, 31
	s_lshl_b64 s[6:7], s[6:7], 3
	s_add_u32 s6, s0, s6
	s_addc_u32 s7, s1, s7
	s_load_dwordx2 s[6:7], s[6:7], 0x0
	s_lshl_b32 s8, s26, 5
	s_and_b32 s8, s8, 0x3e0
	s_add_i32 s9, s29, 0x6880
	s_and_b32 s9, s9, 0x1ffc0
	s_lshl_b32 s12, s8, 2
	v_add_u32_e32 v0, s9, v32
	s_waitcnt lgkmcnt(0)
	s_add_u32 s6, s6, s12
	s_addc_u32 s7, s7, 0
	v_lshlrev_b32_e32 v36, 2, v34
	v_ashrrev_i32_e32 v1, 31, v0
	v_lshl_add_u64 v[2:3], s[6:7], 0, v[36:37]
	v_lshlrev_b64 v[0:1], 12, v[0:1]
	v_lshl_add_u64 v[28:29], v[2:3], 0, v[0:1]
	v_add_co_u32_e32 v4, vcc, s31, v28
	v_add_u32_e32 v33, v35, v89
	s_nop 0
	v_addc_co_u32_e32 v5, vcc, 0, v29, vcc
	v_add_co_u32_e32 v8, vcc, s34, v28
	global_load_dwordx4 v[0:3], v[28:29], off nt
	s_nop 0
	global_load_dwordx4 v[4:7], v[4:5], off nt
	v_addc_co_u32_e32 v9, vcc, 0, v29, vcc
	v_add_co_u32_e32 v12, vcc, s35, v28
	v_add_u32_e32 v36, 0x420, v33
	s_nop 0
	v_addc_co_u32_e32 v13, vcc, 0, v29, vcc
	v_add_co_u32_e32 v16, vcc, s36, v28
	global_load_dwordx4 v[8:11], v[8:9], off nt
	s_nop 0
	global_load_dwordx4 v[12:15], v[12:13], off nt
	v_addc_co_u32_e32 v17, vcc, 0, v29, vcc
	v_add_co_u32_e32 v20, vcc, s37, v28
	v_add_u32_e32 v39, 0x428, v33
	s_nop 0
	v_addc_co_u32_e32 v21, vcc, 0, v29, vcc
	global_load_dwordx4 v[16:19], v[16:17], off nt
	s_nop 0
	global_load_dwordx4 v[20:23], v[20:21], off nt
	v_add_co_u32_e32 v24, vcc, s38, v28
	v_add_u32_e32 v41, 0x840, v33
	s_nop 0
	v_addc_co_u32_e32 v25, vcc, 0, v29, vcc
	global_load_dwordx4 v[24:27], v[24:25], off nt
	v_add_co_u32_e32 v28, vcc, s39, v28
	v_add_u32_e32 v43, 0x848, v33
	s_nop 0
	v_addc_co_u32_e32 v29, vcc, 0, v29, vcc
	global_load_dwordx4 v[28:31], v[28:29], off nt
	v_add_u32_e32 v88, 0xc60, v33
	v_add_u32_e32 v92, 0xc68, v33
	v_add_u32_e32 v94, 0x1080, v33
	v_add_u32_e32 v95, 0x1088, v33
	v_add_u32_e32 v96, 0x14a0, v33
	v_add_u32_e32 v97, 0x14a8, v33
	v_add_u32_e32 v98, 0x18c0, v33
	v_add_u32_e32 v99, 0x18c8, v33
	v_add_u32_e32 v100, 0x1ce0, v33
	v_add_u32_e32 v101, 0x1ce8, v33
	v_add_u32_e32 v90, s8, v32
	v_ashrrev_i32_e32 v91, 31, v90
	s_lshl_b32 s12, s9, 1
	s_waitcnt vmcnt(0)
	ds_write2_b32 v33, v0, v1 offset1:1
	ds_write2_b32 v33, v2, v3 offset0:2 offset1:3
	ds_write2_b32 v36, v4, v5 offset1:1
	ds_write2_b32 v39, v6, v7 offset1:1
	ds_write2_b32 v41, v8, v9 offset1:1
	ds_write2_b32 v43, v10, v11 offset1:1
	ds_write2_b32 v88, v12, v13 offset1:1
	ds_write2_b32 v92, v14, v15 offset1:1
	ds_write2_b32 v94, v16, v17 offset1:1
	ds_write2_b32 v95, v18, v19 offset1:1
	ds_write2_b32 v96, v20, v21 offset1:1
	ds_write2_b32 v97, v22, v23 offset1:1
	ds_write2_b32 v98, v24, v25 offset1:1
	ds_write2_b32 v99, v26, v27 offset1:1
	ds_write2_b32 v100, v28, v29 offset1:1
	ds_write2_b32 v101, v30, v31 offset1:1
	s_waitcnt lgkmcnt(0)
	ds_read2_b32 v[4:5], v93 offset0:33 offset1:41
	ds_read2_b32 v[6:7], v93 offset1:8
	ds_read2_b32 v[8:9], v93 offset0:66 offset1:74
	ds_read2_b32 v[10:11], v93 offset0:99 offset1:107
	ds_read2_b32 v[12:13], v93 offset0:132 offset1:140
	ds_read2_b32 v[14:15], v93 offset0:165 offset1:173
	ds_read2_b32 v[16:17], v93 offset0:198 offset1:206
	ds_read2_b32 v[18:19], v93 offset0:231 offset1:239
	v_lshl_add_u64 v[20:21], v[80:81], 0, s[12:13]
	v_lshlrev_b64 v[22:23], 11, v[90:91]
	s_waitcnt lgkmcnt(6)
	v_cvt_pk_bf16_f32 v0, v6, v4
	s_waitcnt lgkmcnt(4)
	v_cvt_pk_bf16_f32 v1, v8, v10
	s_waitcnt lgkmcnt(2)
	v_cvt_pk_bf16_f32 v2, v12, v14
	s_waitcnt lgkmcnt(0)
	v_cvt_pk_bf16_f32 v3, v16, v18
	v_lshl_add_u64 v[22:23], v[20:21], 0, v[22:23]
	v_add_u32_e32 v4, s8, v38
	global_store_dwordx4 v[22:23], v[0:3], off sc1
	s_nop 1
	v_cvt_pk_bf16_f32 v0, v7, v5
	v_ashrrev_i32_e32 v5, 31, v4
	v_cvt_pk_bf16_f32 v1, v9, v11
	v_cvt_pk_bf16_f32 v2, v13, v15
	v_cvt_pk_bf16_f32 v3, v17, v19
	v_lshlrev_b64 v[4:5], 11, v[4:5]
	ds_read2_b32 v[6:7], v93 offset0:49 offset1:57
	ds_read2_b32 v[8:9], v93 offset0:16 offset1:24
	ds_read2_b32 v[10:11], v93 offset0:82 offset1:90
	ds_read2_b32 v[12:13], v93 offset0:115 offset1:123
	ds_read2_b32 v[14:15], v93 offset0:148 offset1:156
	ds_read2_b32 v[16:17], v93 offset0:181 offset1:189
	ds_read2_b32 v[18:19], v93 offset0:214 offset1:222
	ds_read2_b32 v[22:23], v93 offset0:247 offset1:255
	v_lshl_add_u64 v[4:5], v[20:21], 0, v[4:5]
	global_store_dwordx4 v[4:5], v[0:3], off sc1
	v_add_u32_e32 v4, s8, v40
	v_ashrrev_i32_e32 v5, 31, v4
	v_lshlrev_b64 v[4:5], 11, v[4:5]
	s_waitcnt lgkmcnt(6)
	v_cvt_pk_bf16_f32 v0, v8, v6
	s_waitcnt lgkmcnt(4)
	v_cvt_pk_bf16_f32 v1, v10, v12
	s_waitcnt lgkmcnt(2)
	v_cvt_pk_bf16_f32 v2, v14, v16
	s_waitcnt lgkmcnt(0)
	v_cvt_pk_bf16_f32 v3, v18, v22
	v_lshl_add_u64 v[4:5], v[20:21], 0, v[4:5]
	global_store_dwordx4 v[4:5], v[0:3], off sc1
	v_add_u32_e32 v4, s8, v42
	v_ashrrev_i32_e32 v5, 31, v4
	v_lshlrev_b64 v[4:5], 11, v[4:5]
	v_cvt_pk_bf16_f32 v0, v9, v7
	v_cvt_pk_bf16_f32 v1, v11, v13
	v_cvt_pk_bf16_f32 v2, v15, v17
	v_cvt_pk_bf16_f32 v3, v19, v23
	v_lshl_add_u64 v[4:5], v[20:21], 0, v[4:5]
	global_store_dwordx4 v[4:5], v[0:3], off sc1
	s_waitcnt lgkmcnt(0)

; #define LAS __attribute__((address_space(3)))
; __device__ __forceinline__ void transpose_tile(const float* W, const float* gain, int K, int N, int k0, int n0, bf16* WT, int drow0, LAS float* scr, int lane) {
;     f32x4 v[8]; float gv[8];
;     const int r0 = lane >> 3, c4 = lane & 7;
; #pragma unroll
;     for (int i = 0; i < 8; ++i) { v[i] = *(const f32x4*)(W + (size_t)(k0 + r0 + 8 * i) * N + n0 + 4 * c4); gv[i] = gain ? gain[k0 + r0 + 8 * i] : 1.0f; }
.LBB0_1397:
	s_andn2_b64 vcc, exec, s[8:9]
	s_cbranch_vccnz .LBB0_1415
	s_mov_b32 s6, 5
	s_ashr_i32 s7, s6, 31
	s_lshl_b64 s[6:7], s[6:7], 3
	s_add_u32 s6, s0, s6
	s_addc_u32 s7, s1, s7
	s_load_dwordx2 s[8:9], s[6:7], 0x0
	s_mov_b32 s6, 4
	s_ashr_i32 s7, s6, 31
	s_lshl_b64 s[6:7], s[6:7], 3
	s_add_u32 s20, s0, s6
	s_addc_u32 s21, s1, s7
	s_add_i32 s6, s26, 0xef80
	s_and_b32 s7, s6, 0xffff
	s_mul_i32 s7, s7, 0xaaab
	s_lshr_b32 s12, s7, 16
	s_lshr_b32 s7, s7, 22
	s_mulk_i32 s7, 0x60
	s_sub_i32 s7, s6, s7
	s_and_b32 s6, s12, 0xffc0
	s_lshl_b32 s12, s7, 7
	s_and_b32 s12, s12, 0x3ff80
	s_waitcnt lgkmcnt(0)
	s_add_u32 s8, s8, s12
	s_addc_u32 s9, s9, 0
	v_lshlrev_b32_e32 v36, 2, v34
	v_add_u32_e32 v28, s6, v32
	v_lshl_add_u64 v[30:31], s[8:9], 0, v[36:37]
	v_mad_i64_i32 v[0:1], s[8:9], v28, s42, v[30:31]
	global_load_dwordx4 v[0:3], v[0:1], off nt
	s_load_dwordx2 s[8:9], s[20:21], 0x0
	v_ashrrev_i32_e32 v29, 31, v28
	v_mov_b32_e32 v36, 1.0
	v_mov_b32_e32 v88, 1.0
	s_waitcnt lgkmcnt(0)
	s_cmp_lg_u64 s[8:9], 0
	s_cselect_b64 s[20:21], -1, 0
	s_cmp_eq_u64 s[8:9], 0
	v_lshl_add_u64 v[94:95], v[28:29], 2, s[8:9]
	s_cbranch_scc1 .LBB0_1400
	global_load_dword v88, v[94:95], off nt
.LBB0_1400:
	v_add_u32_e32 v4, 8, v28
	v_mad_i64_i32 v[4:5], s[8:9], v4, s42, v[30:31]
	global_load_dwordx4 v[4:7], v[4:5], off nt
	v_cndmask_b32_e64 v8, 0, 1, s[20:21]
	v_cmp_ne_u32_e64 s[8:9], 1, v8
	s_andn2_b64 vcc, exec, s[20:21]
	s_cbranch_vccnz .LBB0_1402
	global_load_dword v36, v[94:95], off offset:32 nt
.LBB0_1402:
	v_add_u32_e32 v8, 16, v28
	v_mad_i64_i32 v[8:9], s[20:21], v8, s42, v[30:31]
	global_load_dwordx4 v[8:11], v[8:9], off nt
	v_mov_b32_e32 v90, 1.0
	s_and_b64 vcc, exec, s[8:9]
	v_mov_b32_e32 v96, 1.0
	s_cbranch_vccnz .LBB0_1404
	global_load_dword v96, v[94:95], off offset:64 nt
.LBB0_1404:
	v_add_u32_e32 v12, 24, v28
	v_mad_i64_i32 v[12:13], s[20:21], v12, s42, v[30:31]
	global_load_dwordx4 v[12:15], v[12:13], off nt
	s_and_b64 vcc, exec, s[8:9]
	s_cbranch_vccnz .LBB0_1406
	global_load_dword v90, v[94:95], off offset:96 nt
.LBB0_1406:
	v_add_u32_e32 v16, 32, v28
	v_mad_i64_i32 v[16:17], s[20:21], v16, s42, v[30:31]
	global_load_dwordx4 v[16:19], v[16:17], off nt
	v_mov_b32_e32 v92, 1.0
	s_and_b64 vcc, exec, s[8:9]
	v_mov_b32_e32 v100, 1.0
	s_cbranch_vccnz .LBB0_1408
	global_load_dword v100, v[94:95], off offset:128 nt
.LBB0_1408:
	v_add_u32_e32 v20, 40, v28
	v_mad_i64_i32 v[20:21], s[20:21], v20, s42, v[30:31]
	global_load_dwordx4 v[20:23], v[20:21], off nt
	s_and_b64 vcc, exec, s[8:9]
	s_cbranch_vccnz .LBB0_1410
	global_load_dword v92, v[94:95], off offset:160 nt
.LBB0_1410:
	v_add_u32_e32 v24, 48, v28
	v_mad_i64_i32 v[24:25], s[20:21], v24, s42, v[30:31]
	global_load_dwordx4 v[24:27], v[24:25], off nt
	v_mov_b32_e32 v98, 1.0
	s_and_b64 vcc, exec, s[8:9]
	v_mov_b32_e32 v102, 1.0
	s_cbranch_vccnz .LBB0_1412
	global_load_dword v102, v[94:95], off offset:192 nt
.LBB0_1412:
	v_add_u32_e32 v28, 56, v28
	v_mad_i64_i32 v[28:29], s[20:21], v28, s42, v[30:31]
	global_load_dwordx4 v[28:31], v[28:29], off nt
	s_and_b64 vcc, exec, s[8:9]
	s_cbranch_vccnz .LBB0_1414
	global_load_dword v98, v[94:95], off offset:224 nt

; __device__ __forceinline__ unsigned pk_bf16(float lo, float hi) { typedef __bf16 b2_t __attribute__((ext_vector_type(2))); f32x2 v = {lo, hi}; b2_t b = __builtin_convertvector(v, b2_t); return __builtin_bit_cast(unsigned, b); }
; #define LAS __attribute__((address_space(3)))
; __device__ __forceinline__ void transpose_tile(const float* W, const float* gain, int K, int N, int k0, int n0, bf16* WT, int drow0, LAS float* scr, int lane) {
;     f32x4 v[8]; float gv[8];
;     const int r0 = lane >> 3, c4 = lane & 7;
; #pragma unroll
;     for (int i = 0; i < 8; ++i) { v[i] = *(const f32x4*)(W + (size_t)(k0 + r0 + 8 * i) * N + n0 + 4 * c4); gv[i] = gain ? gain[k0 + r0 + 8 * i] : 1.0f; }
; #pragma unroll
;     for (int i = 0; i < 8; ++i) { LAS float* d = scr + (r0 + 8 * i) * 33 + 4 * c4; d[0] = v[i][0] * gv[i]; d[1] = v[i][1] * gv[i]; d[2] = v[i][2] * gv[i]; d[3] = v[i][3] * gv[i]; }
;     asm volatile("s_waitcnt lgkmcnt(0)" ::: "memory");
;     const int c = lane & 7;
; #pragma unroll
;     for (int j = 0; j < 4; ++j) { const int n = (lane >> 3) + 8 * j; const LAS float* s = scr + (8 * c) * 33 + n;
;         v4u o; o.x = pk_bf16(s[0 * 33], s[1 * 33]); o.y = pk_bf16(s[2 * 33], s[3 * 33]); o.z = pk_bf16(s[4 * 33], s[5 * 33]); o.w = pk_bf16(s[6 * 33], s[7 * 33]);
;         *(v4u*)(WT + (size_t)(drow0 + n) * K + k0 + 8 * c) = o; }
;     asm volatile("s_waitcnt lgkmcnt(0)" ::: "memory");
; }
.LBB0_1416:
	s_andn2_b64 vcc, exec, s[8:9]
	s_cbranch_vccnz .LBB0_1418
	s_mov_b32 s6, 3
	s_ashr_i32 s7, s6, 31
	s_lshl_b64 s[6:7], s[6:7], 3
	s_add_u32 s6, s0, s6
	s_addc_u32 s7, s1, s7
	s_load_dwordx2 s[6:7], s[6:7], 0x0
	s_lshl_b32 s8, s26, 5
	s_and_b32 s8, s8, 0x3e0
	s_add_i32 s9, s29, 0x7f80
	s_and_b32 s9, s9, 0x1ffc0
	s_lshl_b32 s12, s8, 2
	v_add_u32_e32 v0, s9, v32
	s_waitcnt lgkmcnt(0)
	s_add_u32 s6, s6, s12
	s_addc_u32 s7, s7, 0
	v_lshlrev_b32_e32 v36, 2, v34
	v_ashrrev_i32_e32 v1, 31, v0
	v_lshl_add_u64 v[2:3], s[6:7], 0, v[36:37]
	v_lshlrev_b64 v[0:1], 12, v[0:1]
	v_lshl_add_u64 v[28:29], v[2:3], 0, v[0:1]
	v_add_co_u32_e32 v4, vcc, s31, v28
	v_add_u32_e32 v33, v35, v89
	s_nop 0
	v_addc_co_u32_e32 v5, vcc, 0, v29, vcc
	v_add_co_u32_e32 v8, vcc, s34, v28
	global_load_dwordx4 v[0:3], v[28:29], off nt
	s_nop 0
	global_load_dwordx4 v[4:7], v[4:5], off nt
	v_addc_co_u32_e32 v9, vcc, 0, v29, vcc
	v_add_co_u32_e32 v12, vcc, s35, v28
	v_add_u32_e32 v36, 0x420, v33
	s_nop 0
	v_addc_co_u32_e32 v13, vcc, 0, v29, vcc
	v_add_co_u32_e32 v16, vcc, s36, v28
	global_load_dwordx4 v[8:11], v[8:9], off nt
	s_nop 0
	global_load_dwordx4 v[12:15], v[12:13], off nt
	v_addc_co_u32_e32 v17, vcc, 0, v29, vcc
	v_add_co_u32_e32 v20, vcc, s37, v28
	v_add_u32_e32 v39, 0x428, v33
	s_nop 0
	v_addc_co_u32_e32 v21, vcc, 0, v29, vcc
	global_load_dwordx4 v[16:19], v[16:17], off nt
	s_nop 0
	global_load_dwordx4 v[20:23], v[20:21], off nt
	v_add_co_u32_e32 v24, vcc, s38, v28
	v_add_u32_e32 v41, 0x840, v33
	s_nop 0
	v_addc_co_u32_e32 v25, vcc, 0, v29, vcc
	global_load_dwordx4 v[24:27], v[24:25], off nt
	v_add_co_u32_e32 v28, vcc, s39, v28
	v_add_u32_e32 v43, 0x848, v33
	s_nop 0
	v_addc_co_u32_e32 v29, vcc, 0, v29, vcc
	global_load_dwordx4 v[28:31], v[28:29], off nt
	v_add_u32_e32 v88, 0xc60, v33
	v_add_u32_e32 v90, 0xc68, v33
	v_add_u32_e32 v91, 0x1080, v33
	v_add_u32_e32 v92, 0x1088, v33
	v_add_u32_e32 v94, 0x14a0, v33
	v_add_u32_e32 v95, 0x14a8, v33
	v_add_u32_e32 v96, 0x18c0, v33
	v_add_u32_e32 v97, 0x18c8, v33
	v_add_u32_e32 v98, 0x1ce0, v33
	v_add_u32_e32 v99, 0x1ce8, v33
	s_lshl_b32 s12, s9, 1
	v_add_u32_e32 v100, s8, v32
	s_waitcnt vmcnt(0)
	ds_write2_b32 v33, v0, v1 offset1:1
	ds_write2_b32 v33, v2, v3 offset0:2 offset1:3
	ds_write2_b32 v36, v4, v5 offset1:1
	ds_write2_b32 v39, v6, v7 offset1:1
	ds_write2_b32 v41, v8, v9 offset1:1
	ds_write2_b32 v43, v10, v11 offset1:1
	ds_write2_b32 v88, v12, v13 offset1:1
	ds_write2_b32 v90, v14, v15 offset1:1
	ds_write2_b32 v91, v16, v17 offset1:1
	ds_write2_b32 v92, v18, v19 offset1:1
	ds_write2_b32 v94, v20, v21 offset1:1
	ds_write2_b32 v95, v22, v23 offset1:1
	ds_write2_b32 v96, v24, v25 offset1:1
	ds_write2_b32 v97, v26, v27 offset1:1
	ds_write2_b32 v98, v28, v29 offset1:1
	ds_write2_b32 v99, v30, v31 offset1:1
	s_waitcnt lgkmcnt(0)
	ds_read2_b32 v[4:5], v93 offset0:33 offset1:41
	ds_read2_b32 v[6:7], v93 offset1:8
	ds_read2_b32 v[8:9], v93 offset0:66 offset1:74
	ds_read2_b32 v[10:11], v93 offset0:99 offset1:107
	ds_read2_b32 v[12:13], v93 offset0:132 offset1:140
	ds_read2_b32 v[14:15], v93 offset0:165 offset1:173
	ds_read2_b32 v[16:17], v93 offset0:198 offset1:206
	ds_read2_b32 v[18:19], v93 offset0:231 offset1:239
	v_lshl_add_u64 v[20:21], v[84:85], 0, s[12:13]
	s_waitcnt lgkmcnt(6)
	v_cvt_pk_bf16_f32 v0, v6, v4
	s_waitcnt lgkmcnt(4)
	v_cvt_pk_bf16_f32 v1, v8, v10
	s_waitcnt lgkmcnt(2)
	v_cvt_pk_bf16_f32 v2, v12, v14
	s_waitcnt lgkmcnt(0)
	v_cvt_pk_bf16_f32 v3, v16, v18
	v_mad_i64_i32 v[22:23], s[6:7], v100, s40, v[20:21]
	global_store_dwordx4 v[22:23], v[0:3], off sc1
	v_add_u32_e32 v4, s8, v38
	s_nop 0
	v_cvt_pk_bf16_f32 v0, v7, v5
	v_cvt_pk_bf16_f32 v1, v9, v11
	v_cvt_pk_bf16_f32 v2, v13, v15
	v_cvt_pk_bf16_f32 v3, v17, v19
	ds_read2_b32 v[6:7], v93 offset0:49 offset1:57
	ds_read2_b32 v[8:9], v93 offset0:16 offset1:24
	ds_read2_b32 v[10:11], v93 offset0:82 offset1:90
	ds_read2_b32 v[12:13], v93 offset0:115 offset1:123
	ds_read2_b32 v[14:15], v93 offset0:148 offset1:156
	ds_read2_b32 v[16:17], v93 offset0:181 offset1:189
	ds_read2_b32 v[18:19], v93 offset0:214 offset1:222
	ds_read2_b32 v[22:23], v93 offset0:247 offset1:255
	v_mad_i64_i32 v[4:5], s[6:7], v4, s40, v[20:21]
	global_store_dwordx4 v[4:5], v[0:3], off sc1
	v_add_u32_e32 v4, s8, v40
	v_mad_i64_i32 v[4:5], s[6:7], v4, s40, v[20:21]
	s_waitcnt lgkmcnt(6)
	v_cvt_pk_bf16_f32 v0, v8, v6
	s_waitcnt lgkmcnt(4)
	v_cvt_pk_bf16_f32 v1, v10, v12
	s_waitcnt lgkmcnt(2)
	v_cvt_pk_bf16_f32 v2, v14, v16
	s_waitcnt lgkmcnt(0)
	v_cvt_pk_bf16_f32 v3, v18, v22
	global_store_dwordx4 v[4:5], v[0:3], off sc1
	v_add_u32_e32 v4, s8, v42
	v_mad_i64_i32 v[4:5], s[6:7], v4, s40, v[20:21]
	v_cvt_pk_bf16_f32 v0, v9, v7
	v_cvt_pk_bf16_f32 v1, v11, v13
	v_cvt_pk_bf16_f32 v2, v15, v17
	v_cvt_pk_bf16_f32 v3, v19, v23
	global_store_dwordx4 v[4:5], v[0:3], off sc1
	s_waitcnt lgkmcnt(0)

; #define LAS __attribute__((address_space(3)))
; __device__ __forceinline__ void transpose_tile(const float* W, const float* gain, int K, int N, int k0, int n0, bf16* WT, int drow0, LAS float* scr, int lane) {
;     f32x4 v[8]; float gv[8];
;     const int r0 = lane >> 3, c4 = lane & 7;
; #pragma unroll
;     for (int i = 0; i < 8; ++i) { v[i] = *(const f32x4*)(W + (size_t)(k0 + r0 + 8 * i) * N + n0 + 4 * c4); gv[i] = gain ? gain[k0 + r0 + 8 * i] : 1.0f; }
.LBB0_1419:
	s_andn2_b64 vcc, exec, s[8:9]
	s_cbranch_vccnz .LBB0_1288
	s_mov_b32 s6, 2
	s_ashr_i32 s7, s6, 31
	s_lshl_b64 s[6:7], s[6:7], 3
	s_add_u32 s6, s0, s6
	s_addc_u32 s7, s1, s7
	s_load_dwordx2 s[8:9], s[6:7], 0x0
	s_mov_b32 s6, 1
	s_ashr_i32 s7, s6, 31
	s_lshl_b64 s[6:7], s[6:7], 3
	s_add_u32 s24, s0, s6
	s_mul_hi_i32 s6, s26, 0x2e8ba2e9
	s_addc_u32 s25, s1, s7
	s_lshr_b32 s7, s6, 31
	s_ashr_i32 s6, s6, 5
	s_add_i32 s6, s6, s7
	s_mul_i32 s7, s6, 0xffffea00
	s_add_i32 s22, s27, s7
	s_ashr_i32 s23, s22, 31
	s_lshl_b32 s20, s6, 6
	s_lshl_b64 s[60:61], s[22:23], 2
	s_waitcnt lgkmcnt(0)
	s_add_u32 s8, s8, s60
	s_addc_u32 s9, s9, s61
	v_lshlrev_b32_e32 v36, 2, v34
	v_add_u32_e32 v28, s20, v32
	v_lshl_add_u64 v[30:31], s[8:9], 0, v[36:37]
	v_mad_i64_i32 v[0:1], s[8:9], v28, s41, v[30:31]
	global_load_dwordx4 v[0:3], v[0:1], off nt
	s_load_dwordx2 s[8:9], s[24:25], 0x0
	v_ashrrev_i32_e32 v29, 31, v28
	v_mov_b32_e32 v36, 1.0
	v_mov_b32_e32 v88, 1.0
	s_waitcnt lgkmcnt(0)
	s_cmp_lg_u64 s[8:9], 0
	s_cselect_b64 s[24:25], -1, 0
	s_cmp_eq_u64 s[8:9], 0
	v_lshl_add_u64 v[98:99], v[28:29], 2, s[8:9]
	s_cbranch_scc1 .LBB0_1422
	global_load_dword v88, v[98:99], off nt
.LBB0_1422:
	v_add_u32_e32 v4, 8, v28
	v_mad_i64_i32 v[4:5], s[8:9], v4, s41, v[30:31]
	global_load_dwordx4 v[4:7], v[4:5], off nt
	v_cndmask_b32_e64 v8, 0, 1, s[24:25]
	v_cmp_ne_u32_e64 s[8:9], 1, v8
	s_andn2_b64 vcc, exec, s[24:25]
	s_cbranch_vccnz .LBB0_1424
	global_load_dword v36, v[98:99], off offset:32 nt
.LBB0_1424:
	v_add_u32_e32 v8, 16, v28
	v_mad_i64_i32 v[8:9], s[24:25], v8, s41, v[30:31]
	global_load_dwordx4 v[8:11], v[8:9], off nt
	v_mov_b32_e32 v90, 1.0
	s_and_b64 vcc, exec, s[8:9]
	v_mov_b32_e32 v94, 1.0
	s_cbranch_vccnz .LBB0_1426
	global_load_dword v94, v[98:99], off offset:64 nt
.LBB0_1426:
	v_add_u32_e32 v12, 24, v28
	v_mad_i64_i32 v[12:13], s[24:25], v12, s41, v[30:31]
	global_load_dwordx4 v[12:15], v[12:13], off nt
	s_and_b64 vcc, exec, s[8:9]
	s_cbranch_vccnz .LBB0_1428
	global_load_dword v90, v[98:99], off offset:96 nt
.LBB0_1428:
	v_add_u32_e32 v16, 32, v28
	v_mad_i64_i32 v[16:17], s[24:25], v16, s41, v[30:31]
	global_load_dwordx4 v[16:19], v[16:17], off nt
	v_mov_b32_e32 v92, 1.0
	s_and_b64 vcc, exec, s[8:9]
	v_mov_b32_e32 v100, 1.0
	s_cbranch_vccnz .LBB0_1430
	global_load_dword v100, v[98:99], off offset:128 nt
.LBB0_1430:
	v_add_u32_e32 v20, 40, v28
	v_mad_i64_i32 v[20:21], s[24:25], v20, s41, v[30:31]
	global_load_dwordx4 v[20:23], v[20:21], off nt
	s_and_b64 vcc, exec, s[8:9]
	s_cbranch_vccnz .LBB0_1432
	global_load_dword v92, v[98:99], off offset:160 nt
.LBB0_1432:
	v_add_u32_e32 v24, 48, v28
	v_mad_i64_i32 v[24:25], s[24:25], v24, s41, v[30:31]
	global_load_dwordx4 v[24:27], v[24:25], off nt
	v_mov_b32_e32 v96, 1.0
	s_and_b64 vcc, exec, s[8:9]
	v_mov_b32_e32 v102, 1.0
	s_cbranch_vccnz .LBB0_1434
	global_load_dword v102, v[98:99], off offset:192 nt
.LBB0_1434:
	v_add_u32_e32 v28, 56, v28
	v_mad_i64_i32 v[28:29], s[24:25], v28, s41, v[30:31]
	global_load_dwordx4 v[28:31], v[28:29], off nt
	s_and_b64 vcc, exec, s[8:9]
	s_cbranch_vccnz .LBB0_1287
	global_load_dword v96, v[98:99], off offset:224 nt
	s_branch .LBB0_1287

; __device__ __forceinline__ unsigned pk_bf16(float lo, float hi) { typedef __bf16 b2_t __attribute__((ext_vector_type(2))); f32x2 v = {lo, hi}; b2_t b = __builtin_convertvector(v, b2_t); return __builtin_bit_cast(unsigned, b); }
; #define LAS __attribute__((address_space(3)))
; __device__ __forceinline__ void transpose_tile(const float* W, const float* gain, int K, int N, int k0, int n0, bf16* WT, int drow0, LAS float* scr, int lane) {
;     f32x4 v[8]; float gv[8];
;     const int r0 = lane >> 3, c4 = lane & 7;
; #pragma unroll
;     for (int i = 0; i < 8; ++i) { v[i] = *(const f32x4*)(W + (size_t)(k0 + r0 + 8 * i) * N + n0 + 4 * c4); gv[i] = gain ? gain[k0 + r0 + 8 * i] : 1.0f; }
; #pragma unroll
;     for (int i = 0; i < 8; ++i) { LAS float* d = scr + (r0 + 8 * i) * 33 + 4 * c4; d[0] = v[i][0] * gv[i]; d[1] = v[i][1] * gv[i]; d[2] = v[i][2] * gv[i]; d[3] = v[i][3] * gv[i]; }
;     asm volatile("s_waitcnt lgkmcnt(0)" ::: "memory");
;     const int c = lane & 7;
; #pragma unroll
;     for (int j = 0; j < 4; ++j) { const int n = (lane >> 3) + 8 * j; const LAS float* s = scr + (8 * c) * 33 + n;
;         v4u o; o.x = pk_bf16(s[0 * 33], s[1 * 33]); o.y = pk_bf16(s[2 * 33], s[3 * 33]); o.z = pk_bf16(s[4 * 33], s[5 * 33]); o.w = pk_bf16(s[6 * 33], s[7 * 33]);
;         *(v4u*)(WT + (size_t)(drow0 + n) * K + k0 + 8 * c) = o; }
;     asm volatile("s_waitcnt lgkmcnt(0)" ::: "memory");
; }
.LBB0_1442:
	s_cmpk_gt_i32 s20, 0xaff
	s_mov_b64 s[8:9], -1
	s_cbranch_scc0 .LBB0_1572
	s_cmpk_gt_u32 s20, 0x107f
	s_cbranch_scc0 .LBB0_1569
	s_cmpk_gt_u32 s20, 0x167f
	s_cbranch_scc0 .LBB0_1550
	s_cmpk_gt_u32 s20, 0x187f
	s_cbranch_scc0 .LBB0_1547
	s_cmpk_gt_u32 s20, 0x237f
	s_cbranch_scc0 .LBB0_1528
	s_cmpk_gt_u32 s20, 0x28ff
	s_cbranch_scc0 .LBB0_1525
	s_cmpk_gt_u32 s20, 0x33ff
	s_cbranch_scc0 .LBB0_1506
	s_cmpk_gt_u32 s20, 0x397f
	s_cbranch_scc0 .LBB0_1503
	s_cmpk_gt_u32 s20, 0x3d7f
	s_cbranch_scc0 .LBB0_1484
	s_cmpk_gt_u32 s20, 0x3f7f
	s_cbranch_scc0 .LBB0_1481
	s_cmpk_gt_u32 s20, 0x3f9f
	s_cbranch_scc0 .LBB0_1478
	s_cmpk_gt_u32 s20, 0x3fbf
	s_cbranch_scc0 .LBB0_1475
	s_cmpk_gt_u32 s20, 0x4abf
	s_cbranch_scc0 .LBB0_1456
	s_mov_b32 s6, 27
	s_ashr_i32 s7, s6, 31
	s_lshl_b64 s[6:7], s[6:7], 3
	s_add_u32 s6, s0, s6
	s_addc_u32 s7, s1, s7
	s_load_dwordx2 s[6:7], s[6:7], 0x0
	s_lshl_b32 s8, s20, 5
	s_and_b32 s8, s8, 0x3e0
	s_and_b32 s9, s22, 0x1ffc0
	s_lshl_b32 s10, s8, 2
	v_add_u32_e32 v0, s9, v32
	s_waitcnt lgkmcnt(0)
	s_add_u32 s6, s6, s10
	s_addc_u32 s7, s7, 0
	v_lshlrev_b32_e32 v36, 2, v34
	v_ashrrev_i32_e32 v1, 31, v0
	v_lshl_add_u64 v[2:3], s[6:7], 0, v[36:37]
	v_lshlrev_b64 v[0:1], 12, v[0:1]
	v_lshl_add_u64 v[28:29], v[2:3], 0, v[0:1]
	v_add_co_u32_e32 v4, vcc, s24, v28
	v_add_u32_e32 v33, v35, v89
	s_nop 0
	v_addc_co_u32_e32 v5, vcc, 0, v29, vcc
	v_add_co_u32_e32 v8, vcc, s25, v28
	global_load_dwordx4 v[0:3], v[28:29], off nt
	s_nop 0
	global_load_dwordx4 v[4:7], v[4:5], off nt
	v_addc_co_u32_e32 v9, vcc, 0, v29, vcc
	v_add_co_u32_e32 v12, vcc, s26, v28
	v_add_u32_e32 v36, 0x420, v33
	s_nop 0
	v_addc_co_u32_e32 v13, vcc, 0, v29, vcc
	v_add_co_u32_e32 v16, vcc, s27, v28
	global_load_dwordx4 v[8:11], v[8:9], off nt
	s_nop 0
	global_load_dwordx4 v[12:15], v[12:13], off nt
	v_addc_co_u32_e32 v17, vcc, 0, v29, vcc
	v_add_co_u32_e32 v20, vcc, s28, v28
	v_add_u32_e32 v39, 0x428, v33
	s_nop 0
	v_addc_co_u32_e32 v21, vcc, 0, v29, vcc
	global_load_dwordx4 v[16:19], v[16:17], off nt
	s_nop 0
	global_load_dwordx4 v[20:23], v[20:21], off nt
	v_add_co_u32_e32 v24, vcc, s29, v28
	v_add_u32_e32 v41, 0x840, v33
	s_nop 0
	v_addc_co_u32_e32 v25, vcc, 0, v29, vcc
	global_load_dwordx4 v[24:27], v[24:25], off nt
	v_add_co_u32_e32 v28, vcc, s30, v28
	v_add_u32_e32 v43, 0x848, v33
	s_nop 0
	v_addc_co_u32_e32 v29, vcc, 0, v29, vcc
	global_load_dwordx4 v[28:31], v[28:29], off nt
	v_add_u32_e32 v88, 0xc60, v33
	v_add_u32_e32 v92, 0xc68, v33
	v_add_u32_e32 v94, 0x1080, v33
	v_add_u32_e32 v95, 0x1088, v33
	v_add_u32_e32 v96, 0x14a0, v33
	v_add_u32_e32 v97, 0x14a8, v33
	v_add_u32_e32 v98, 0x18c0, v33
	v_add_u32_e32 v99, 0x18c8, v33
	v_add_u32_e32 v100, 0x1ce0, v33
	v_add_u32_e32 v101, 0x1ce8, v33
	s_lshl_b32 s10, s9, 1
	v_add_u32_e32 v102, s8, v32
	v_lshl_add_u64 v[90:91], v[44:45], 0, s[10:11]
	s_waitcnt vmcnt(0)
	ds_write2_b32 v33, v0, v1 offset1:1
	ds_write2_b32 v33, v2, v3 offset0:2 offset1:3
	ds_write2_b32 v36, v4, v5 offset1:1
	ds_write2_b32 v39, v6, v7 offset1:1
	ds_write2_b32 v41, v8, v9 offset1:1
	ds_write2_b32 v43, v10, v11 offset1:1
	ds_write2_b32 v88, v12, v13 offset1:1
	ds_write2_b32 v92, v14, v15 offset1:1
	ds_write2_b32 v94, v16, v17 offset1:1
	ds_write2_b32 v95, v18, v19 offset1:1
	ds_write2_b32 v96, v20, v21 offset1:1
	ds_write2_b32 v97, v22, v23 offset1:1
	ds_write2_b32 v98, v24, v25 offset1:1
	ds_write2_b32 v99, v26, v27 offset1:1
	ds_write2_b32 v100, v28, v29 offset1:1
	ds_write2_b32 v101, v30, v31 offset1:1
	s_waitcnt lgkmcnt(0)
	ds_read2_b32 v[4:5], v93 offset0:33 offset1:41
	ds_read2_b32 v[6:7], v93 offset1:8
	ds_read2_b32 v[8:9], v93 offset0:66 offset1:74
	ds_read2_b32 v[10:11], v93 offset0:99 offset1:107
	ds_read2_b32 v[12:13], v93 offset0:132 offset1:140
	ds_read2_b32 v[14:15], v93 offset0:165 offset1:173
	ds_read2_b32 v[16:17], v93 offset0:198 offset1:206
	ds_read2_b32 v[18:19], v93 offset0:231 offset1:239
	v_mad_i64_i32 v[20:21], s[6:7], v102, s31, v[90:91]
	s_waitcnt lgkmcnt(6)
	v_cvt_pk_bf16_f32 v0, v6, v4
	s_waitcnt lgkmcnt(4)
	v_cvt_pk_bf16_f32 v1, v8, v10
	s_waitcnt lgkmcnt(2)
	v_cvt_pk_bf16_f32 v2, v12, v14
	s_waitcnt lgkmcnt(0)
	v_cvt_pk_bf16_f32 v3, v16, v18
	global_store_dwordx4 v[20:21], v[0:3], off sc1
	v_add_u32_e32 v4, s8, v38
	s_nop 0
	v_cvt_pk_bf16_f32 v0, v7, v5
	v_cvt_pk_bf16_f32 v1, v9, v11
	v_cvt_pk_bf16_f32 v2, v13, v15
	v_cvt_pk_bf16_f32 v3, v17, v19
	ds_read2_b32 v[6:7], v93 offset0:49 offset1:57
	ds_read2_b32 v[8:9], v93 offset0:16 offset1:24
	ds_read2_b32 v[10:11], v93 offset0:82 offset1:90
	ds_read2_b32 v[12:13], v93 offset0:115 offset1:123
	ds_read2_b32 v[14:15], v93 offset0:148 offset1:156
	ds_read2_b32 v[16:17], v93 offset0:181 offset1:189
	ds_read2_b32 v[18:19], v93 offset0:214 offset1:222
	ds_read2_b32 v[20:21], v93 offset0:247 offset1:255
	v_mad_i64_i32 v[4:5], s[6:7], v4, s31, v[90:91]
	global_store_dwordx4 v[4:5], v[0:3], off sc1
	v_add_u32_e32 v4, s8, v40
	v_mad_i64_i32 v[4:5], s[6:7], v4, s31, v[90:91]
	s_waitcnt lgkmcnt(6)
	v_cvt_pk_bf16_f32 v0, v8, v6
	s_waitcnt lgkmcnt(4)
	v_cvt_pk_bf16_f32 v1, v10, v12
	s_waitcnt lgkmcnt(2)
	v_cvt_pk_bf16_f32 v2, v14, v16
	s_waitcnt lgkmcnt(0)
	v_cvt_pk_bf16_f32 v3, v18, v20
	global_store_dwordx4 v[4:5], v[0:3], off sc1
	v_add_u32_e32 v4, s8, v42
	v_mad_i64_i32 v[4:5], s[6:7], v4, s31, v[90:91]
	v_cvt_pk_bf16_f32 v0, v9, v7
	v_cvt_pk_bf16_f32 v1, v11, v13
	v_cvt_pk_bf16_f32 v2, v15, v17
	v_cvt_pk_bf16_f32 v3, v19, v21
	global_store_dwordx4 v[4:5], v[0:3], off sc1
	s_waitcnt lgkmcnt(0)
	s_mov_b64 s[8:9], 0
; #define LAS __attribute__((address_space(3)))
; __device__ __forceinline__ void transpose_tile(const float* W, const float* gain, int K, int N, int k0, int n0, bf16* WT, int drow0, LAS float* scr, int lane) {
;     f32x4 v[8]; float gv[8];
;     const int r0 = lane >> 3, c4 = lane & 7;
; #pragma unroll
;     for (int i = 0; i < 8; ++i) { v[i] = *(const f32x4*)(W + (size_t)(k0 + r0 + 8 * i) * N + n0 + 4 * c4); gv[i] = gain ? gain[k0 + r0 + 8 * i] : 1.0f; }
.LBB0_1456:
	s_andn2_b64 vcc, exec, s[8:9]
	s_cbranch_vccnz .LBB0_1474
	s_mov_b32 s6, 26
	s_ashr_i32 s7, s6, 31
	s_lshl_b64 s[6:7], s[6:7], 3
	s_add_u32 s6, s0, s6
	s_addc_u32 s7, s1, s7
	s_load_dwordx2 s[8:9], s[6:7], 0x0
	s_mov_b32 s6, 25
	s_ashr_i32 s7, s6, 31
	s_lshl_b64 s[6:7], s[6:7], 3
	s_add_u32 s12, s0, s6
	s_addc_u32 s13, s1, s7
	s_add_i32 s6, s20, 0xc040
	s_and_b32 s7, s6, 0xffff
	s_mul_i32 s7, s7, 0xba2f
	s_lshr_b32 s10, s7, 23
	s_mul_i32 s7, s10, 0xb0
	s_sub_i32 s7, s6, s7
	s_lshl_b32 s6, s10, 6
	s_lshl_b32 s10, s7, 7
	s_and_b32 s10, s10, 0x3ff80
	s_waitcnt lgkmcnt(0)
	s_add_u32 s8, s8, s10
	s_addc_u32 s9, s9, 0
	v_lshlrev_b32_e32 v36, 2, v34
	v_add_u32_e32 v28, s6, v32
	v_lshl_add_u64 v[30:31], s[8:9], 0, v[36:37]
	v_mad_i64_i32 v[0:1], s[8:9], v28, s34, v[30:31]
	global_load_dwordx4 v[0:3], v[0:1], off nt
	s_load_dwordx2 s[8:9], s[12:13], 0x0
	v_ashrrev_i32_e32 v29, 31, v28
	v_mov_b32_e32 v36, 1.0
	v_mov_b32_e32 v88, 1.0
	s_waitcnt lgkmcnt(0)
	s_cmp_lg_u64 s[8:9], 0
	s_cselect_b64 s[12:13], -1, 0
	s_cmp_eq_u64 s[8:9], 0
	v_lshl_add_u64 v[98:99], v[28:29], 2, s[8:9]
	s_cbranch_scc1 .LBB0_1459
	global_load_dword v88, v[98:99], off nt
.LBB0_1459:
	v_add_u32_e32 v4, 8, v28
	v_mad_i64_i32 v[4:5], s[8:9], v4, s34, v[30:31]
	global_load_dwordx4 v[4:7], v[4:5], off nt
	v_cndmask_b32_e64 v8, 0, 1, s[12:13]
	v_cmp_ne_u32_e64 s[8:9], 1, v8
	s_andn2_b64 vcc, exec, s[12:13]
	s_cbranch_vccnz .LBB0_1461
	global_load_dword v36, v[98:99], off offset:32 nt
.LBB0_1461:
	v_add_u32_e32 v8, 16, v28
	v_mad_i64_i32 v[8:9], s[12:13], v8, s34, v[30:31]
	global_load_dwordx4 v[8:11], v[8:9], off nt
	v_mov_b32_e32 v90, 1.0
	s_and_b64 vcc, exec, s[8:9]
	v_mov_b32_e32 v94, 1.0
	s_cbranch_vccnz .LBB0_1463
	global_load_dword v94, v[98:99], off offset:64 nt
.LBB0_1463:
	v_add_u32_e32 v12, 24, v28
	v_mad_i64_i32 v[12:13], s[12:13], v12, s34, v[30:31]
	global_load_dwordx4 v[12:15], v[12:13], off nt
	s_and_b64 vcc, exec, s[8:9]
	s_cbranch_vccnz .LBB0_1465
	global_load_dword v90, v[98:99], off offset:96 nt
.LBB0_1465:
	v_add_u32_e32 v16, 32, v28
	v_mad_i64_i32 v[16:17], s[12:13], v16, s34, v[30:31]
	global_load_dwordx4 v[16:19], v[16:17], off nt
	v_mov_b32_e32 v92, 1.0
	s_and_b64 vcc, exec, s[8:9]
	v_mov_b32_e32 v100, 1.0
	s_cbranch_vccnz .LBB0_1467
	global_load_dword v100, v[98:99], off offset:128 nt
.LBB0_1467:
	v_add_u32_e32 v20, 40, v28
	v_mad_i64_i32 v[20:21], s[12:13], v20, s34, v[30:31]
	global_load_dwordx4 v[20:23], v[20:21], off nt
	s_and_b64 vcc, exec, s[8:9]
	s_cbranch_vccnz .LBB0_1469
	global_load_dword v92, v[98:99], off offset:160 nt
.LBB0_1469:
	v_add_u32_e32 v24, 48, v28
	v_mad_i64_i32 v[24:25], s[12:13], v24, s34, v[30:31]
	global_load_dwordx4 v[24:27], v[24:25], off nt
	v_mov_b32_e32 v96, 1.0
	s_and_b64 vcc, exec, s[8:9]
	v_mov_b32_e32 v102, 1.0
	s_cbranch_vccnz .LBB0_1471
	global_load_dword v102, v[98:99], off offset:192 nt
.LBB0_1471:
	v_add_u32_e32 v28, 56, v28
	v_mad_i64_i32 v[28:29], s[12:13], v28, s34, v[30:31]
	global_load_dwordx4 v[28:31], v[28:29], off nt
	s_and_b64 vcc, exec, s[8:9]
	s_lshl_b32 s8, s7, 5
	s_cbranch_vccnz .LBB0_1473
	global_load_dword v96, v[98:99], off offset:224 nt

; __device__ __forceinline__ unsigned pk_bf16(float lo, float hi) { typedef __bf16 b2_t __attribute__((ext_vector_type(2))); f32x2 v = {lo, hi}; b2_t b = __builtin_convertvector(v, b2_t); return __builtin_bit_cast(unsigned, b); }
; #define LAS __attribute__((address_space(3)))
; __device__ __forceinline__ void transpose_tile(const float* W, const float* gain, int K, int N, int k0, int n0, bf16* WT, int drow0, LAS float* scr, int lane) {
;     f32x4 v[8]; float gv[8];
;     const int r0 = lane >> 3, c4 = lane & 7;
; #pragma unroll
;     for (int i = 0; i < 8; ++i) { v[i] = *(const f32x4*)(W + (size_t)(k0 + r0 + 8 * i) * N + n0 + 4 * c4); gv[i] = gain ? gain[k0 + r0 + 8 * i] : 1.0f; }
; #pragma unroll
;     for (int i = 0; i < 8; ++i) { LAS float* d = scr + (r0 + 8 * i) * 33 + 4 * c4; d[0] = v[i][0] * gv[i]; d[1] = v[i][1] * gv[i]; d[2] = v[i][2] * gv[i]; d[3] = v[i][3] * gv[i]; }
;     asm volatile("s_waitcnt lgkmcnt(0)" ::: "memory");
;     const int c = lane & 7;
; #pragma unroll
;     for (int j = 0; j < 4; ++j) { const int n = (lane >> 3) + 8 * j; const LAS float* s = scr + (8 * c) * 33 + n;
;         v4u o; o.x = pk_bf16(s[0 * 33], s[1 * 33]); o.y = pk_bf16(s[2 * 33], s[3 * 33]); o.z = pk_bf16(s[4 * 33], s[5 * 33]); o.w = pk_bf16(s[6 * 33], s[7 * 33]);
;         *(v4u*)(WT + (size_t)(drow0 + n) * K + k0 + 8 * c) = o; }
;     asm volatile("s_waitcnt lgkmcnt(0)" ::: "memory");
; }
.LBB0_1475:
	s_andn2_b64 vcc, exec, s[8:9]
	s_cbranch_vccnz .LBB0_1477
	s_mov_b32 s6, 21
	s_ashr_i32 s7, s6, 31
	s_add_i32 s8, s20, 0xffffc060
	s_lshl_b64 s[6:7], s[6:7], 3
	s_add_u32 s6, s0, s6
	s_addc_u32 s7, s1, s7
	s_load_dwordx2 s[6:7], s[6:7], 0x0
	s_lshr_b32 s10, s8, 1
	s_lshl_b64 s[8:9], s[10:11], 14
	v_lshlrev_b32_e32 v36, 2, v34
	v_add_u32_e32 v33, v35, v89
	s_waitcnt lgkmcnt(0)
	s_add_u32 s6, s6, s8
	s_addc_u32 s7, s7, s9
	s_lshl_b32 s8, s20, 5
	s_and_b32 s8, s8, 32
	s_lshl_b32 s9, s8, 2
	s_add_u32 s6, s6, s9
	s_addc_u32 s7, s7, 0
	v_lshl_add_u64 v[28:29], s[6:7], 0, v[36:37]
	v_lshl_add_u64 v[0:1], v[28:29], 0, v[48:49]
	global_load_dwordx4 v[0:3], v[0:1], off nt
	v_lshl_add_u64 v[4:5], v[28:29], 0, v[50:51]
	global_load_dwordx4 v[4:7], v[4:5], off nt
	v_lshl_add_u64 v[8:9], v[28:29], 0, v[52:53]
	global_load_dwordx4 v[8:11], v[8:9], off nt
	v_lshl_add_u64 v[12:13], v[28:29], 0, v[54:55]
	global_load_dwordx4 v[12:15], v[12:13], off nt
	v_lshl_add_u64 v[16:17], v[28:29], 0, v[56:57]
	global_load_dwordx4 v[16:19], v[16:17], off nt
	v_lshl_add_u64 v[20:21], v[28:29], 0, v[58:59]
	global_load_dwordx4 v[20:23], v[20:21], off nt
	v_lshl_add_u64 v[24:25], v[28:29], 0, v[60:61]
	global_load_dwordx4 v[24:27], v[24:25], off nt
	v_lshl_add_u64 v[28:29], v[28:29], 0, v[62:63]
	global_load_dwordx4 v[28:31], v[28:29], off nt
	v_add_u32_e32 v36, 0x420, v33
	v_add_u32_e32 v39, 0x428, v33
	v_add_u32_e32 v41, 0x840, v33
	v_add_u32_e32 v43, 0x848, v33
	v_add_u32_e32 v88, 0xc60, v33
	v_add_u32_e32 v92, 0xc68, v33
	v_add_u32_e32 v97, 0x1080, v33
	v_add_u32_e32 v100, 0x1088, v33
	v_add_u32_e32 v101, 0x14a0, v33
	v_add_u32_e32 v102, 0x14a8, v33
	v_add_u32_e32 v103, 0x18c0, v33
	v_add_u32_e32 v104, 0x18c8, v33
	v_add_u32_e32 v105, 0x1ce0, v33
	v_add_u32_e32 v106, 0x1ce8, v33
	v_add_u32_e32 v90, s8, v32
	v_add_u32_e32 v94, s8, v38
	v_ashrrev_i32_e32 v91, 31, v90
	s_lshl_b64 s[6:7], s[10:11], 13
	v_ashrrev_i32_e32 v95, 31, v94
	v_lshlrev_b64 v[90:91], 7, v[90:91]
	v_lshl_add_u64 v[98:99], v[64:65], 0, s[6:7]
	v_add_u32_e32 v96, s8, v40
	v_lshlrev_b64 v[94:95], 7, v[94:95]
	v_lshl_add_u64 v[90:91], v[98:99], 0, v[90:91]
	v_lshl_add_u64 v[94:95], v[98:99], 0, v[94:95]
	s_waitcnt vmcnt(0)
	ds_write2_b32 v33, v0, v1 offset1:1
	ds_write2_b32 v33, v2, v3 offset0:2 offset1:3
	ds_write2_b32 v36, v4, v5 offset1:1
	ds_write2_b32 v39, v6, v7 offset1:1
	ds_write2_b32 v41, v8, v9 offset1:1
	ds_write2_b32 v43, v10, v11 offset1:1
	ds_write2_b32 v88, v12, v13 offset1:1
	ds_write2_b32 v92, v14, v15 offset1:1
	ds_write2_b32 v97, v16, v17 offset1:1
	ds_write2_b32 v100, v18, v19 offset1:1
	ds_write2_b32 v101, v20, v21 offset1:1
	ds_write2_b32 v102, v22, v23 offset1:1
	ds_write2_b32 v103, v24, v25 offset1:1
	ds_write2_b32 v104, v26, v27 offset1:1
	ds_write2_b32 v105, v28, v29 offset1:1
	ds_write2_b32 v106, v30, v31 offset1:1
	s_waitcnt lgkmcnt(0)
	ds_read2_b32 v[4:5], v93 offset0:33 offset1:41
	ds_read2_b32 v[6:7], v93 offset1:8
	ds_read2_b32 v[8:9], v93 offset0:66 offset1:74
	ds_read2_b32 v[10:11], v93 offset0:99 offset1:107
	ds_read2_b32 v[12:13], v93 offset0:132 offset1:140
	ds_read2_b32 v[14:15], v93 offset0:165 offset1:173
	ds_read2_b32 v[16:17], v93 offset0:198 offset1:206
	ds_read2_b32 v[18:19], v93 offset0:231 offset1:239
	ds_read2_b32 v[20:21], v93 offset0:49 offset1:57
	ds_read2_b32 v[22:23], v93 offset0:16 offset1:24
	ds_read2_b32 v[24:25], v93 offset0:82 offset1:90
	ds_read2_b32 v[26:27], v93 offset0:115 offset1:123
	ds_read2_b32 v[28:29], v93 offset0:148 offset1:156
	ds_read2_b32 v[30:31], v93 offset0:181 offset1:189
	ds_read2_b32 v[100:101], v93 offset0:214 offset1:222
	ds_read2_b32 v[102:103], v93 offset0:247 offset1:255
	s_waitcnt lgkmcnt(14)
	v_cvt_pk_bf16_f32 v0, v6, v4
	s_waitcnt lgkmcnt(12)
	v_cvt_pk_bf16_f32 v1, v8, v10
	s_waitcnt lgkmcnt(10)
	v_cvt_pk_bf16_f32 v2, v12, v14
	s_waitcnt lgkmcnt(8)
	v_cvt_pk_bf16_f32 v3, v16, v18
	v_cvt_pk_bf16_f32 v4, v7, v5
	v_cvt_pk_bf16_f32 v5, v9, v11
	v_cvt_pk_bf16_f32 v6, v13, v15
	v_cvt_pk_bf16_f32 v7, v17, v19
	global_store_dwordx4 v[90:91], v[0:3], off sc1
	global_store_dwordx4 v[94:95], v[4:7], off sc1
	v_ashrrev_i32_e32 v97, 31, v96
	v_lshlrev_b64 v[0:1], 7, v[96:97]
	v_add_u32_e32 v4, s8, v42
	v_ashrrev_i32_e32 v5, 31, v4
	s_waitcnt lgkmcnt(6)
	v_cvt_pk_bf16_f32 v8, v22, v20
	s_waitcnt lgkmcnt(4)
	v_cvt_pk_bf16_f32 v9, v24, v26
	s_waitcnt lgkmcnt(2)
	v_cvt_pk_bf16_f32 v10, v28, v30
	s_waitcnt lgkmcnt(0)
	v_cvt_pk_bf16_f32 v11, v100, v102
	v_lshl_add_u64 v[0:1], v[98:99], 0, v[0:1]
	v_lshlrev_b64 v[4:5], 7, v[4:5]
	global_store_dwordx4 v[0:1], v[8:11], off sc1
	v_cvt_pk_bf16_f32 v0, v23, v21
	v_cvt_pk_bf16_f32 v1, v25, v27
	v_cvt_pk_bf16_f32 v2, v29, v31
	v_cvt_pk_bf16_f32 v3, v101, v103
	v_lshl_add_u64 v[4:5], v[98:99], 0, v[4:5]
	global_store_dwordx4 v[4:5], v[0:3], off sc1
	s_waitcnt lgkmcnt(0)

; __device__ __forceinline__ unsigned pk_bf16(float lo, float hi) { typedef __bf16 b2_t __attribute__((ext_vector_type(2))); f32x2 v = {lo, hi}; b2_t b = __builtin_convertvector(v, b2_t); return __builtin_bit_cast(unsigned, b); }
; #define LAS __attribute__((address_space(3)))
; __device__ __forceinline__ void transpose_tile(const float* W, const float* gain, int K, int N, int k0, int n0, bf16* WT, int drow0, LAS float* scr, int lane) {
;     f32x4 v[8]; float gv[8];
;     const int r0 = lane >> 3, c4 = lane & 7;
; #pragma unroll
;     for (int i = 0; i < 8; ++i) { v[i] = *(const f32x4*)(W + (size_t)(k0 + r0 + 8 * i) * N + n0 + 4 * c4); gv[i] = gain ? gain[k0 + r0 + 8 * i] : 1.0f; }
; #pragma unroll
;     for (int i = 0; i < 8; ++i) { LAS float* d = scr + (r0 + 8 * i) * 33 + 4 * c4; d[0] = v[i][0] * gv[i]; d[1] = v[i][1] * gv[i]; d[2] = v[i][2] * gv[i]; d[3] = v[i][3] * gv[i]; }
;     asm volatile("s_waitcnt lgkmcnt(0)" ::: "memory");
;     const int c = lane & 7;
; #pragma unroll
;     for (int j = 0; j < 4; ++j) { const int n = (lane >> 3) + 8 * j; const LAS float* s = scr + (8 * c) * 33 + n;
;         v4u o; o.x = pk_bf16(s[0 * 33], s[1 * 33]); o.y = pk_bf16(s[2 * 33], s[3 * 33]); o.z = pk_bf16(s[4 * 33], s[5 * 33]); o.w = pk_bf16(s[6 * 33], s[7 * 33]);
;         *(v4u*)(WT + (size_t)(drow0 + n) * K + k0 + 8 * c) = o; }
;     asm volatile("s_waitcnt lgkmcnt(0)" ::: "memory");
; }
.LBB0_1478:
	s_andn2_b64 vcc, exec, s[8:9]
	s_cbranch_vccnz .LBB0_1480
	s_mov_b32 s6, 19
	s_ashr_i32 s7, s6, 31
	s_add_i32 s8, s20, 0xffffc080
	s_lshl_b64 s[6:7], s[6:7], 3
	s_add_u32 s6, s0, s6
	s_addc_u32 s7, s1, s7
	s_load_dwordx2 s[6:7], s[6:7], 0x0
	s_lshr_b32 s10, s8, 1
	s_lshl_b64 s[8:9], s[10:11], 14
	v_lshlrev_b32_e32 v36, 2, v34
	v_add_u32_e32 v33, v35, v89
	s_waitcnt lgkmcnt(0)
	s_add_u32 s6, s6, s8
	s_addc_u32 s7, s7, s9
	s_lshl_b32 s8, s20, 5
	s_and_b32 s8, s8, 32
	s_lshl_b32 s9, s8, 2
	s_add_u32 s6, s6, s9
	s_addc_u32 s7, s7, 0
	v_lshl_add_u64 v[28:29], s[6:7], 0, v[36:37]
	v_lshl_add_u64 v[0:1], v[28:29], 0, v[48:49]
	global_load_dwordx4 v[0:3], v[0:1], off nt
	v_lshl_add_u64 v[4:5], v[28:29], 0, v[50:51]
	global_load_dwordx4 v[4:7], v[4:5], off nt
	v_lshl_add_u64 v[8:9], v[28:29], 0, v[52:53]
	global_load_dwordx4 v[8:11], v[8:9], off nt
	v_lshl_add_u64 v[12:13], v[28:29], 0, v[54:55]
	global_load_dwordx4 v[12:15], v[12:13], off nt
	v_lshl_add_u64 v[16:17], v[28:29], 0, v[56:57]
	global_load_dwordx4 v[16:19], v[16:17], off nt
	v_lshl_add_u64 v[20:21], v[28:29], 0, v[58:59]
	global_load_dwordx4 v[20:23], v[20:21], off nt
	v_lshl_add_u64 v[24:25], v[28:29], 0, v[60:61]
	global_load_dwordx4 v[24:27], v[24:25], off nt
	v_lshl_add_u64 v[28:29], v[28:29], 0, v[62:63]
	global_load_dwordx4 v[28:31], v[28:29], off nt
	v_add_u32_e32 v36, 0x420, v33
	v_add_u32_e32 v39, 0x428, v33
	v_add_u32_e32 v41, 0x840, v33
	v_add_u32_e32 v43, 0x848, v33
	v_add_u32_e32 v88, 0xc60, v33
	v_add_u32_e32 v92, 0xc68, v33
	v_add_u32_e32 v97, 0x1080, v33
	v_add_u32_e32 v100, 0x1088, v33
	v_add_u32_e32 v101, 0x14a0, v33
	v_add_u32_e32 v102, 0x14a8, v33
	v_add_u32_e32 v103, 0x18c0, v33
	v_add_u32_e32 v104, 0x18c8, v33
	v_add_u32_e32 v105, 0x1ce0, v33
	v_add_u32_e32 v106, 0x1ce8, v33
	v_add_u32_e32 v90, s8, v32
	v_add_u32_e32 v94, s8, v38
	v_ashrrev_i32_e32 v91, 31, v90
	s_lshl_b64 s[6:7], s[10:11], 13
	v_ashrrev_i32_e32 v95, 31, v94
	v_lshlrev_b64 v[90:91], 7, v[90:91]
	v_lshl_add_u64 v[98:99], v[66:67], 0, s[6:7]
	v_add_u32_e32 v96, s8, v40
	v_lshlrev_b64 v[94:95], 7, v[94:95]
	v_lshl_add_u64 v[90:91], v[98:99], 0, v[90:91]
	v_lshl_add_u64 v[94:95], v[98:99], 0, v[94:95]
	s_waitcnt vmcnt(0)
	ds_write2_b32 v33, v0, v1 offset1:1
	ds_write2_b32 v33, v2, v3 offset0:2 offset1:3
	ds_write2_b32 v36, v4, v5 offset1:1
	ds_write2_b32 v39, v6, v7 offset1:1
	ds_write2_b32 v41, v8, v9 offset1:1
	ds_write2_b32 v43, v10, v11 offset1:1
	ds_write2_b32 v88, v12, v13 offset1:1
	ds_write2_b32 v92, v14, v15 offset1:1
	ds_write2_b32 v97, v16, v17 offset1:1
	ds_write2_b32 v100, v18, v19 offset1:1
	ds_write2_b32 v101, v20, v21 offset1:1
	ds_write2_b32 v102, v22, v23 offset1:1
	ds_write2_b32 v103, v24, v25 offset1:1
	ds_write2_b32 v104, v26, v27 offset1:1
	ds_write2_b32 v105, v28, v29 offset1:1
	ds_write2_b32 v106, v30, v31 offset1:1
	s_waitcnt lgkmcnt(0)
	ds_read2_b32 v[4:5], v93 offset0:33 offset1:41
	ds_read2_b32 v[6:7], v93 offset1:8
	ds_read2_b32 v[8:9], v93 offset0:66 offset1:74
	ds_read2_b32 v[10:11], v93 offset0:99 offset1:107
	ds_read2_b32 v[12:13], v93 offset0:132 offset1:140
	ds_read2_b32 v[14:15], v93 offset0:165 offset1:173
	ds_read2_b32 v[16:17], v93 offset0:198 offset1:206
	ds_read2_b32 v[18:19], v93 offset0:231 offset1:239
	ds_read2_b32 v[20:21], v93 offset0:49 offset1:57
	ds_read2_b32 v[22:23], v93 offset0:16 offset1:24
	ds_read2_b32 v[24:25], v93 offset0:82 offset1:90
	ds_read2_b32 v[26:27], v93 offset0:115 offset1:123
	ds_read2_b32 v[28:29], v93 offset0:148 offset1:156
	ds_read2_b32 v[30:31], v93 offset0:181 offset1:189
	ds_read2_b32 v[100:101], v93 offset0:214 offset1:222
	ds_read2_b32 v[102:103], v93 offset0:247 offset1:255
	s_waitcnt lgkmcnt(14)
	v_cvt_pk_bf16_f32 v0, v6, v4
	s_waitcnt lgkmcnt(12)
	v_cvt_pk_bf16_f32 v1, v8, v10
	s_waitcnt lgkmcnt(10)
	v_cvt_pk_bf16_f32 v2, v12, v14
	s_waitcnt lgkmcnt(8)
	v_cvt_pk_bf16_f32 v3, v16, v18
	v_cvt_pk_bf16_f32 v4, v7, v5
	v_cvt_pk_bf16_f32 v5, v9, v11
	v_cvt_pk_bf16_f32 v6, v13, v15
	v_cvt_pk_bf16_f32 v7, v17, v19
	global_store_dwordx4 v[90:91], v[0:3], off sc1
	global_store_dwordx4 v[94:95], v[4:7], off sc1
	v_ashrrev_i32_e32 v97, 31, v96
	v_lshlrev_b64 v[0:1], 7, v[96:97]
	v_add_u32_e32 v4, s8, v42
	v_ashrrev_i32_e32 v5, 31, v4
	s_waitcnt lgkmcnt(6)
	v_cvt_pk_bf16_f32 v8, v22, v20
	s_waitcnt lgkmcnt(4)
	v_cvt_pk_bf16_f32 v9, v24, v26
	s_waitcnt lgkmcnt(2)
	v_cvt_pk_bf16_f32 v10, v28, v30
	s_waitcnt lgkmcnt(0)
	v_cvt_pk_bf16_f32 v11, v100, v102
	v_lshl_add_u64 v[0:1], v[98:99], 0, v[0:1]
	v_lshlrev_b64 v[4:5], 7, v[4:5]
	global_store_dwordx4 v[0:1], v[8:11], off sc1
	v_cvt_pk_bf16_f32 v0, v23, v21
	v_cvt_pk_bf16_f32 v1, v25, v27
	v_cvt_pk_bf16_f32 v2, v29, v31
	v_cvt_pk_bf16_f32 v3, v101, v103
	v_lshl_add_u64 v[4:5], v[98:99], 0, v[4:5]
	global_store_dwordx4 v[4:5], v[0:3], off sc1
	s_waitcnt lgkmcnt(0)

; __device__ __forceinline__ unsigned pk_bf16(float lo, float hi) { typedef __bf16 b2_t __attribute__((ext_vector_type(2))); f32x2 v = {lo, hi}; b2_t b = __builtin_convertvector(v, b2_t); return __builtin_bit_cast(unsigned, b); }
; #define LAS __attribute__((address_space(3)))
; __device__ __forceinline__ void transpose_tile(const float* W, const float* gain, int K, int N, int k0, int n0, bf16* WT, int drow0, LAS float* scr, int lane) {
;     f32x4 v[8]; float gv[8];
;     const int r0 = lane >> 3, c4 = lane & 7;
; #pragma unroll
;     for (int i = 0; i < 8; ++i) { v[i] = *(const f32x4*)(W + (size_t)(k0 + r0 + 8 * i) * N + n0 + 4 * c4); gv[i] = gain ? gain[k0 + r0 + 8 * i] : 1.0f; }
; #pragma unroll
;     for (int i = 0; i < 8; ++i) { LAS float* d = scr + (r0 + 8 * i) * 33 + 4 * c4; d[0] = v[i][0] * gv[i]; d[1] = v[i][1] * gv[i]; d[2] = v[i][2] * gv[i]; d[3] = v[i][3] * gv[i]; }
;     asm volatile("s_waitcnt lgkmcnt(0)" ::: "memory");
;     const int c = lane & 7;
; #pragma unroll
;     for (int j = 0; j < 4; ++j) { const int n = (lane >> 3) + 8 * j; const LAS float* s = scr + (8 * c) * 33 + n;
;         v4u o; o.x = pk_bf16(s[0 * 33], s[1 * 33]); o.y = pk_bf16(s[2 * 33], s[3 * 33]); o.z = pk_bf16(s[4 * 33], s[5 * 33]); o.w = pk_bf16(s[6 * 33], s[7 * 33]);
;         *(v4u*)(WT + (size_t)(drow0 + n) * K + k0 + 8 * c) = o; }
;     asm volatile("s_waitcnt lgkmcnt(0)" ::: "memory");
; }
.LBB0_1481:
	s_andn2_b64 vcc, exec, s[8:9]
	s_cbranch_vccnz .LBB0_1483
	s_mov_b32 s6, 24
	s_ashr_i32 s7, s6, 31
	s_lshl_b64 s[6:7], s[6:7], 3
	s_add_u32 s6, s0, s6
	s_addc_u32 s7, s1, s7
	s_load_dwordx2 s[6:7], s[6:7], 0x0
	s_lshl_b32 s8, s20, 5
	s_and_b32 s8, s8, 0x3e0
	s_add_i32 s9, s22, 0x1a80
	s_and_b32 s9, s9, 0x1ffc0
	s_lshl_b32 s10, s8, 2
	v_add_u32_e32 v0, s9, v32
	s_waitcnt lgkmcnt(0)
	s_add_u32 s6, s6, s10
	s_addc_u32 s7, s7, 0
	v_lshlrev_b32_e32 v36, 2, v34
	v_ashrrev_i32_e32 v1, 31, v0
	v_lshl_add_u64 v[2:3], s[6:7], 0, v[36:37]
	v_lshlrev_b64 v[0:1], 12, v[0:1]
	v_lshl_add_u64 v[28:29], v[2:3], 0, v[0:1]
	v_add_co_u32_e32 v4, vcc, s24, v28
	v_add_u32_e32 v33, v35, v89
	s_nop 0
	v_addc_co_u32_e32 v5, vcc, 0, v29, vcc
	v_add_co_u32_e32 v8, vcc, s25, v28
	global_load_dwordx4 v[0:3], v[28:29], off nt
	s_nop 0
	global_load_dwordx4 v[4:7], v[4:5], off nt
	v_addc_co_u32_e32 v9, vcc, 0, v29, vcc
	v_add_co_u32_e32 v12, vcc, s26, v28
	v_add_u32_e32 v36, 0x420, v33
	s_nop 0
	v_addc_co_u32_e32 v13, vcc, 0, v29, vcc
	v_add_co_u32_e32 v16, vcc, s27, v28
	global_load_dwordx4 v[8:11], v[8:9], off nt
	s_nop 0
	global_load_dwordx4 v[12:15], v[12:13], off nt
	v_addc_co_u32_e32 v17, vcc, 0, v29, vcc
	v_add_co_u32_e32 v20, vcc, s28, v28
	v_add_u32_e32 v39, 0x428, v33
	s_nop 0
	v_addc_co_u32_e32 v21, vcc, 0, v29, vcc
	global_load_dwordx4 v[16:19], v[16:17], off nt
	s_nop 0
	global_load_dwordx4 v[20:23], v[20:21], off nt
	v_add_co_u32_e32 v24, vcc, s29, v28
	v_add_u32_e32 v41, 0x840, v33
	s_nop 0
	v_addc_co_u32_e32 v25, vcc, 0, v29, vcc
	global_load_dwordx4 v[24:27], v[24:25], off nt
	v_add_co_u32_e32 v28, vcc, s30, v28
	v_add_u32_e32 v43, 0x848, v33
	s_nop 0
	v_addc_co_u32_e32 v29, vcc, 0, v29, vcc
	global_load_dwordx4 v[28:31], v[28:29], off nt
	v_add_u32_e32 v88, 0xc60, v33
	v_add_u32_e32 v92, 0xc68, v33
	v_add_u32_e32 v94, 0x1080, v33
	v_add_u32_e32 v95, 0x1088, v33
	v_add_u32_e32 v96, 0x14a0, v33
	v_add_u32_e32 v97, 0x14a8, v33
	v_add_u32_e32 v98, 0x18c0, v33
	v_add_u32_e32 v99, 0x18c8, v33
	v_add_u32_e32 v100, 0x1ce0, v33
	v_add_u32_e32 v101, 0x1ce8, v33
	v_add_u32_e32 v90, s8, v32
	v_ashrrev_i32_e32 v91, 31, v90
	s_lshl_b32 s10, s9, 1
	s_waitcnt vmcnt(0)
	ds_write2_b32 v33, v0, v1 offset1:1
	ds_write2_b32 v33, v2, v3 offset0:2 offset1:3
	ds_write2_b32 v36, v4, v5 offset1:1
	ds_write2_b32 v39, v6, v7 offset1:1
	ds_write2_b32 v41, v8, v9 offset1:1
	ds_write2_b32 v43, v10, v11 offset1:1
	ds_write2_b32 v88, v12, v13 offset1:1
	ds_write2_b32 v92, v14, v15 offset1:1
	ds_write2_b32 v94, v16, v17 offset1:1
	ds_write2_b32 v95, v18, v19 offset1:1
	ds_write2_b32 v96, v20, v21 offset1:1
	ds_write2_b32 v97, v22, v23 offset1:1
	ds_write2_b32 v98, v24, v25 offset1:1
	ds_write2_b32 v99, v26, v27 offset1:1
	ds_write2_b32 v100, v28, v29 offset1:1
	ds_write2_b32 v101, v30, v31 offset1:1
	s_waitcnt lgkmcnt(0)
	ds_read2_b32 v[4:5], v93 offset0:33 offset1:41
	ds_read2_b32 v[6:7], v93 offset1:8
	ds_read2_b32 v[8:9], v93 offset0:66 offset1:74
	ds_read2_b32 v[10:11], v93 offset0:99 offset1:107
	ds_read2_b32 v[12:13], v93 offset0:132 offset1:140
	ds_read2_b32 v[14:15], v93 offset0:165 offset1:173
	ds_read2_b32 v[16:17], v93 offset0:198 offset1:206
	ds_read2_b32 v[18:19], v93 offset0:231 offset1:239
	v_lshl_add_u64 v[20:21], v[68:69], 0, s[10:11]
	v_lshlrev_b64 v[22:23], 11, v[90:91]
	s_waitcnt lgkmcnt(6)
	v_cvt_pk_bf16_f32 v0, v6, v4
	s_waitcnt lgkmcnt(4)
	v_cvt_pk_bf16_f32 v1, v8, v10
	s_waitcnt lgkmcnt(2)
	v_cvt_pk_bf16_f32 v2, v12, v14
	s_waitcnt lgkmcnt(0)
	v_cvt_pk_bf16_f32 v3, v16, v18
	v_lshl_add_u64 v[22:23], v[20:21], 0, v[22:23]
	v_add_u32_e32 v4, s8, v38
	global_store_dwordx4 v[22:23], v[0:3], off sc1
	s_nop 1
	v_cvt_pk_bf16_f32 v0, v7, v5
	v_ashrrev_i32_e32 v5, 31, v4
	v_cvt_pk_bf16_f32 v1, v9, v11
	v_cvt_pk_bf16_f32 v2, v13, v15
	v_cvt_pk_bf16_f32 v3, v17, v19
	v_lshlrev_b64 v[4:5], 11, v[4:5]
	ds_read2_b32 v[6:7], v93 offset0:49 offset1:57
	ds_read2_b32 v[8:9], v93 offset0:16 offset1:24
	ds_read2_b32 v[10:11], v93 offset0:82 offset1:90
	ds_read2_b32 v[12:13], v93 offset0:115 offset1:123
	ds_read2_b32 v[14:15], v93 offset0:148 offset1:156
	ds_read2_b32 v[16:17], v93 offset0:181 offset1:189
	ds_read2_b32 v[18:19], v93 offset0:214 offset1:222
	ds_read2_b32 v[22:23], v93 offset0:247 offset1:255
	v_lshl_add_u64 v[4:5], v[20:21], 0, v[4:5]
	global_store_dwordx4 v[4:5], v[0:3], off sc1
	v_add_u32_e32 v4, s8, v40
	v_ashrrev_i32_e32 v5, 31, v4
	v_lshlrev_b64 v[4:5], 11, v[4:5]
	s_waitcnt lgkmcnt(6)
	v_cvt_pk_bf16_f32 v0, v8, v6
	s_waitcnt lgkmcnt(4)
	v_cvt_pk_bf16_f32 v1, v10, v12
	s_waitcnt lgkmcnt(2)
	v_cvt_pk_bf16_f32 v2, v14, v16
	s_waitcnt lgkmcnt(0)
	v_cvt_pk_bf16_f32 v3, v18, v22
	v_lshl_add_u64 v[4:5], v[20:21], 0, v[4:5]
	global_store_dwordx4 v[4:5], v[0:3], off sc1
	v_add_u32_e32 v4, s8, v42
	v_ashrrev_i32_e32 v5, 31, v4
	v_lshlrev_b64 v[4:5], 11, v[4:5]
	v_cvt_pk_bf16_f32 v0, v9, v7
	v_cvt_pk_bf16_f32 v1, v11, v13
	v_cvt_pk_bf16_f32 v2, v15, v17
	v_cvt_pk_bf16_f32 v3, v19, v23
	v_lshl_add_u64 v[4:5], v[20:21], 0, v[4:5]
	global_store_dwordx4 v[4:5], v[0:3], off sc1
	s_waitcnt lgkmcnt(0)

; #define LAS __attribute__((address_space(3)))
; __device__ __forceinline__ void transpose_tile(const float* W, const float* gain, int K, int N, int k0, int n0, bf16* WT, int drow0, LAS float* scr, int lane) {
;     f32x4 v[8]; float gv[8];
;     const int r0 = lane >> 3, c4 = lane & 7;
; #pragma unroll
;     for (int i = 0; i < 8; ++i) { v[i] = *(const f32x4*)(W + (size_t)(k0 + r0 + 8 * i) * N + n0 + 4 * c4); gv[i] = gain ? gain[k0 + r0 + 8 * i] : 1.0f; }
.LBB0_1484:
	s_andn2_b64 vcc, exec, s[8:9]
	s_cbranch_vccnz .LBB0_1502
	s_mov_b32 s6, 16
	s_ashr_i32 s7, s6, 31
	s_lshl_b64 s[6:7], s[6:7], 3
	s_add_u32 s6, s0, s6
	s_addc_u32 s7, s1, s7
	s_load_dwordx2 s[8:9], s[6:7], 0x0
	s_mov_b32 s6, 15
	s_ashr_i32 s7, s6, 31
	s_lshl_b64 s[6:7], s[6:7], 3
	s_add_u32 s12, s0, s6
	s_addc_u32 s13, s1, s7
	s_lshl_b32 s7, s20, 5
	s_add_i32 s6, s20, 0xc680
	s_and_b32 s7, s7, 0x7e0
	s_and_b32 s6, s6, 0xffc0
	s_lshl_b32 s10, s7, 2
	v_add_u32_e32 v4, s6, v32
	s_waitcnt lgkmcnt(0)
	s_add_u32 s8, s8, s10
	s_addc_u32 s9, s9, 0
	v_lshlrev_b32_e32 v36, 2, v34
	v_ashrrev_i32_e32 v5, 31, v4
	v_lshl_add_u64 v[0:1], s[8:9], 0, v[36:37]
	v_lshlrev_b64 v[2:3], 13, v[4:5]
	v_lshl_add_u64 v[28:29], v[0:1], 0, v[2:3]
	global_load_dwordx4 v[0:3], v[28:29], off nt
	s_load_dwordx2 s[8:9], s[12:13], 0x0
	v_mov_b32_e32 v36, 1.0
	v_mov_b32_e32 v88, 1.0
	s_waitcnt lgkmcnt(0)
	s_cmp_lg_u64 s[8:9], 0
	s_cselect_b64 s[12:13], -1, 0
	s_cmp_eq_u64 s[8:9], 0
	v_lshl_add_u64 v[90:91], v[4:5], 2, s[8:9]
	s_cbranch_scc1 .LBB0_1487
	global_load_dword v88, v[90:91], off nt
.LBB0_1487:
	v_add_co_u32_e32 v4, vcc, 0x10000, v28
	v_cndmask_b32_e64 v8, 0, 1, s[12:13]
	s_nop 0
	v_addc_co_u32_e32 v5, vcc, 0, v29, vcc
	global_load_dwordx4 v[4:7], v[4:5], off nt
	v_cmp_ne_u32_e64 s[8:9], 1, v8
	s_andn2_b64 vcc, exec, s[12:13]
	s_cbranch_vccnz .LBB0_1489
	global_load_dword v36, v[90:91], off offset:32 nt

; __device__ __forceinline__ unsigned pk_bf16(float lo, float hi) { typedef __bf16 b2_t __attribute__((ext_vector_type(2))); f32x2 v = {lo, hi}; b2_t b = __builtin_convertvector(v, b2_t); return __builtin_bit_cast(unsigned, b); }
; #define LAS __attribute__((address_space(3)))
; __device__ __forceinline__ void transpose_tile(const float* W, const float* gain, int K, int N, int k0, int n0, bf16* WT, int drow0, LAS float* scr, int lane) {
;     f32x4 v[8]; float gv[8];
;     const int r0 = lane >> 3, c4 = lane & 7;
; #pragma unroll
;     for (int i = 0; i < 8; ++i) { v[i] = *(const f32x4*)(W + (size_t)(k0 + r0 + 8 * i) * N + n0 + 4 * c4); gv[i] = gain ? gain[k0 + r0 + 8 * i] : 1.0f; }
; #pragma unroll
;     for (int i = 0; i < 8; ++i) { LAS float* d = scr + (r0 + 8 * i) * 33 + 4 * c4; d[0] = v[i][0] * gv[i]; d[1] = v[i][1] * gv[i]; d[2] = v[i][2] * gv[i]; d[3] = v[i][3] * gv[i]; }
;     asm volatile("s_waitcnt lgkmcnt(0)" ::: "memory");
;     const int c = lane & 7;
; #pragma unroll
;     for (int j = 0; j < 4; ++j) { const int n = (lane >> 3) + 8 * j; const LAS float* s = scr + (8 * c) * 33 + n;
;         v4u o; o.x = pk_bf16(s[0 * 33], s[1 * 33]); o.y = pk_bf16(s[2 * 33], s[3 * 33]); o.z = pk_bf16(s[4 * 33], s[5 * 33]); o.w = pk_bf16(s[6 * 33], s[7 * 33]);
;         *(v4u*)(WT + (size_t)(drow0 + n) * K + k0 + 8 * c) = o; }
;     asm volatile("s_waitcnt lgkmcnt(0)" ::: "memory");
; }
.LBB0_1503:
	s_andn2_b64 vcc, exec, s[8:9]
	s_cbranch_vccnz .LBB0_1505
	s_mov_b32 s6, 14
	s_ashr_i32 s7, s6, 31
	s_lshl_b64 s[6:7], s[6:7], 3
	s_add_u32 s6, s0, s6
	s_addc_u32 s7, s1, s7
	s_load_dwordx2 s[6:7], s[6:7], 0x0
	s_lshl_b32 s8, s20, 5
	s_and_b32 s8, s8, 0x3e0
	s_add_i32 s9, s22, 0x2d80
	s_and_b32 s9, s9, 0x1ffc0
	s_lshl_b32 s10, s8, 2
	v_add_u32_e32 v0, s9, v32
	s_waitcnt lgkmcnt(0)
	s_add_u32 s6, s6, s10
	s_addc_u32 s7, s7, 0
	v_lshlrev_b32_e32 v36, 2, v34
	v_ashrrev_i32_e32 v1, 31, v0
	v_lshl_add_u64 v[2:3], s[6:7], 0, v[36:37]
	v_lshlrev_b64 v[0:1], 12, v[0:1]
	v_lshl_add_u64 v[28:29], v[2:3], 0, v[0:1]
	v_add_co_u32_e32 v4, vcc, s24, v28
	v_add_u32_e32 v33, v35, v89
	s_nop 0
	v_addc_co_u32_e32 v5, vcc, 0, v29, vcc
	v_add_co_u32_e32 v8, vcc, s25, v28
	global_load_dwordx4 v[0:3], v[28:29], off nt
	s_nop 0
	global_load_dwordx4 v[4:7], v[4:5], off nt
	v_addc_co_u32_e32 v9, vcc, 0, v29, vcc
	v_add_co_u32_e32 v12, vcc, s26, v28
	v_add_u32_e32 v36, 0x420, v33
	s_nop 0
	v_addc_co_u32_e32 v13, vcc, 0, v29, vcc
	v_add_co_u32_e32 v16, vcc, s27, v28
	global_load_dwordx4 v[8:11], v[8:9], off nt
	s_nop 0
	global_load_dwordx4 v[12:15], v[12:13], off nt
	v_addc_co_u32_e32 v17, vcc, 0, v29, vcc
	v_add_co_u32_e32 v20, vcc, s28, v28
	v_add_u32_e32 v39, 0x428, v33
	s_nop 0
	v_addc_co_u32_e32 v21, vcc, 0, v29, vcc
	global_load_dwordx4 v[16:19], v[16:17], off nt
	s_nop 0
	global_load_dwordx4 v[20:23], v[20:21], off nt
	v_add_co_u32_e32 v24, vcc, s29, v28
	v_add_u32_e32 v41, 0x840, v33
	s_nop 0
	v_addc_co_u32_e32 v25, vcc, 0, v29, vcc
	global_load_dwordx4 v[24:27], v[24:25], off nt
	v_add_co_u32_e32 v28, vcc, s30, v28
	v_add_u32_e32 v43, 0x848, v33
	s_nop 0
	v_addc_co_u32_e32 v29, vcc, 0, v29, vcc
	global_load_dwordx4 v[28:31], v[28:29], off nt
	v_add_u32_e32 v88, 0xc60, v33
	v_add_u32_e32 v90, 0xc68, v33
	v_add_u32_e32 v91, 0x1080, v33
	v_add_u32_e32 v92, 0x1088, v33
	v_add_u32_e32 v94, 0x14a0, v33
	v_add_u32_e32 v95, 0x14a8, v33
	v_add_u32_e32 v96, 0x18c0, v33
	v_add_u32_e32 v97, 0x18c8, v33
	v_add_u32_e32 v98, 0x1ce0, v33
	v_add_u32_e32 v99, 0x1ce8, v33
	s_lshl_b32 s10, s9, 1
	v_add_u32_e32 v100, s8, v32
	s_waitcnt vmcnt(0)
	ds_write2_b32 v33, v0, v1 offset1:1
	ds_write2_b32 v33, v2, v3 offset0:2 offset1:3
	ds_write2_b32 v36, v4, v5 offset1:1
	ds_write2_b32 v39, v6, v7 offset1:1
	ds_write2_b32 v41, v8, v9 offset1:1
	ds_write2_b32 v43, v10, v11 offset1:1
	ds_write2_b32 v88, v12, v13 offset1:1
	ds_write2_b32 v90, v14, v15 offset1:1
	ds_write2_b32 v91, v16, v17 offset1:1
	ds_write2_b32 v92, v18, v19 offset1:1
	ds_write2_b32 v94, v20, v21 offset1:1
	ds_write2_b32 v95, v22, v23 offset1:1
	ds_write2_b32 v96, v24, v25 offset1:1
	ds_write2_b32 v97, v26, v27 offset1:1
	ds_write2_b32 v98, v28, v29 offset1:1
	ds_write2_b32 v99, v30, v31 offset1:1
	s_waitcnt lgkmcnt(0)
	ds_read2_b32 v[4:5], v93 offset0:33 offset1:41
	ds_read2_b32 v[6:7], v93 offset1:8
	ds_read2_b32 v[8:9], v93 offset0:66 offset1:74
	ds_read2_b32 v[10:11], v93 offset0:99 offset1:107
	ds_read2_b32 v[12:13], v93 offset0:132 offset1:140
	ds_read2_b32 v[14:15], v93 offset0:165 offset1:173
	ds_read2_b32 v[16:17], v93 offset0:198 offset1:206
	ds_read2_b32 v[18:19], v93 offset0:231 offset1:239
	v_lshl_add_u64 v[20:21], v[72:73], 0, s[10:11]
	s_waitcnt lgkmcnt(6)
	v_cvt_pk_bf16_f32 v0, v6, v4
	s_waitcnt lgkmcnt(4)
	v_cvt_pk_bf16_f32 v1, v8, v10
	s_waitcnt lgkmcnt(2)
	v_cvt_pk_bf16_f32 v2, v12, v14
	s_waitcnt lgkmcnt(0)
	v_cvt_pk_bf16_f32 v3, v16, v18
	v_mad_i64_i32 v[22:23], s[6:7], v100, s31, v[20:21]
	global_store_dwordx4 v[22:23], v[0:3], off sc1
	v_add_u32_e32 v4, s8, v38
	s_nop 0
	v_cvt_pk_bf16_f32 v0, v7, v5
	v_cvt_pk_bf16_f32 v1, v9, v11
	v_cvt_pk_bf16_f32 v2, v13, v15
	v_cvt_pk_bf16_f32 v3, v17, v19
	ds_read2_b32 v[6:7], v93 offset0:49 offset1:57
	ds_read2_b32 v[8:9], v93 offset0:16 offset1:24
	ds_read2_b32 v[10:11], v93 offset0:82 offset1:90
	ds_read2_b32 v[12:13], v93 offset0:115 offset1:123
	ds_read2_b32 v[14:15], v93 offset0:148 offset1:156
	ds_read2_b32 v[16:17], v93 offset0:181 offset1:189
	ds_read2_b32 v[18:19], v93 offset0:214 offset1:222
	ds_read2_b32 v[22:23], v93 offset0:247 offset1:255
	v_mad_i64_i32 v[4:5], s[6:7], v4, s31, v[20:21]
	global_store_dwordx4 v[4:5], v[0:3], off sc1
	v_add_u32_e32 v4, s8, v40
	v_mad_i64_i32 v[4:5], s[6:7], v4, s31, v[20:21]
	s_waitcnt lgkmcnt(6)
	v_cvt_pk_bf16_f32 v0, v8, v6
	s_waitcnt lgkmcnt(4)
	v_cvt_pk_bf16_f32 v1, v10, v12
	s_waitcnt lgkmcnt(2)
	v_cvt_pk_bf16_f32 v2, v14, v16
	s_waitcnt lgkmcnt(0)
	v_cvt_pk_bf16_f32 v3, v18, v22
	global_store_dwordx4 v[4:5], v[0:3], off sc1
	v_add_u32_e32 v4, s8, v42
	v_mad_i64_i32 v[4:5], s[6:7], v4, s31, v[20:21]
	v_cvt_pk_bf16_f32 v0, v9, v7
	v_cvt_pk_bf16_f32 v1, v11, v13
	v_cvt_pk_bf16_f32 v2, v15, v17
	v_cvt_pk_bf16_f32 v3, v19, v23
	global_store_dwordx4 v[4:5], v[0:3], off sc1
	s_waitcnt lgkmcnt(0)

; __device__ __forceinline__ void transpose_tile(const float* W, const float* gain, int K, int N, int k0, int n0, bf16* WT, int drow0, LAS float* scr, int lane) {
;     ...
; #pragma unroll
;     for (int i = 0; i < 8; ++i) { v[i] = *(const f32x4*)(W + (size_t)(k0 + r0 + 8 * i) * N + n0 + 4 * c4); gv[i] = gain ? gain[k0 + r0 + 8 * i] : 1.0f; }
; template <bool SWIGLU> __device__ __forceinline__ void transpose_item(const float* W, const float* gain, int K, int N, bf16* WT, LAS float* scr, int item, int lane) {
;     ...
;     if (SWIGLU) { const int up = n0 >= FF, f = up ? n0 - FF : n0; drow0 = 256 * (f >> 7) + (up ? 128 : 0) + (f & 127); }
.LBB0_1506:
	s_andn2_b64 vcc, exec, s[8:9]
	s_cbranch_vccnz .LBB0_1524
	s_mov_b32 s6, 13
	s_ashr_i32 s7, s6, 31
	s_lshl_b64 s[6:7], s[6:7], 3
	s_add_u32 s6, s0, s6
	s_addc_u32 s7, s1, s7
	s_load_dwordx2 s[8:9], s[6:7], 0x0
	s_mov_b32 s6, 12
	s_ashr_i32 s7, s6, 31
	s_lshl_b64 s[6:7], s[6:7], 3
	s_add_u32 s12, s0, s6
	s_addc_u32 s13, s1, s7
	s_add_i32 s6, s20, 0xd700
	s_and_b32 s7, s6, 0xffff
	s_mul_i32 s7, s7, 0xba2f
	s_lshr_b32 s10, s7, 23
	s_mul_i32 s7, s10, 0xb0
	s_sub_i32 s7, s6, s7
	s_lshl_b32 s6, s10, 6
	s_lshl_b32 s10, s7, 7
	s_and_b32 s10, s10, 0x3ff80
	s_waitcnt lgkmcnt(0)
	s_add_u32 s8, s8, s10
	s_addc_u32 s9, s9, 0
	v_lshlrev_b32_e32 v36, 2, v34
	v_add_u32_e32 v28, s6, v32
	v_lshl_add_u64 v[30:31], s[8:9], 0, v[36:37]
	v_mad_i64_i32 v[0:1], s[8:9], v28, s34, v[30:31]
	global_load_dwordx4 v[0:3], v[0:1], off nt
	s_load_dwordx2 s[8:9], s[12:13], 0x0
	v_ashrrev_i32_e32 v29, 31, v28
	v_mov_b32_e32 v36, 1.0
	v_mov_b32_e32 v88, 1.0
	s_waitcnt lgkmcnt(0)
	s_cmp_lg_u64 s[8:9], 0
	s_cselect_b64 s[12:13], -1, 0
	s_cmp_eq_u64 s[8:9], 0
	v_lshl_add_u64 v[98:99], v[28:29], 2, s[8:9]
	s_cbranch_scc1 .LBB0_1509
	global_load_dword v88, v[98:99], off nt

; __device__ __forceinline__ unsigned pk_bf16(float lo, float hi) { typedef __bf16 b2_t __attribute__((ext_vector_type(2))); f32x2 v = {lo, hi}; b2_t b = __builtin_convertvector(v, b2_t); return __builtin_bit_cast(unsigned, b); }
; #define LAS __attribute__((address_space(3)))
; __device__ __forceinline__ void transpose_tile(const float* W, const float* gain, int K, int N, int k0, int n0, bf16* WT, int drow0, LAS float* scr, int lane) {
;     f32x4 v[8]; float gv[8];
;     const int r0 = lane >> 3, c4 = lane & 7;
; #pragma unroll
;     for (int i = 0; i < 8; ++i) { v[i] = *(const f32x4*)(W + (size_t)(k0 + r0 + 8 * i) * N + n0 + 4 * c4); gv[i] = gain ? gain[k0 + r0 + 8 * i] : 1.0f; }
; #pragma unroll
;     for (int i = 0; i < 8; ++i) { LAS float* d = scr + (r0 + 8 * i) * 33 + 4 * c4; d[0] = v[i][0] * gv[i]; d[1] = v[i][1] * gv[i]; d[2] = v[i][2] * gv[i]; d[3] = v[i][3] * gv[i]; }
;     asm volatile("s_waitcnt lgkmcnt(0)" ::: "memory");
;     const int c = lane & 7;
; #pragma unroll
;     for (int j = 0; j < 4; ++j) { const int n = (lane >> 3) + 8 * j; const LAS float* s = scr + (8 * c) * 33 + n;
;         v4u o; o.x = pk_bf16(s[0 * 33], s[1 * 33]); o.y = pk_bf16(s[2 * 33], s[3 * 33]); o.z = pk_bf16(s[4 * 33], s[5 * 33]); o.w = pk_bf16(s[6 * 33], s[7 * 33]);
;         *(v4u*)(WT + (size_t)(drow0 + n) * K + k0 + 8 * c) = o; }
;     asm volatile("s_waitcnt lgkmcnt(0)" ::: "memory");
; }
.LBB0_1525:
	s_andn2_b64 vcc, exec, s[8:9]
	s_cbranch_vccnz .LBB0_1527
	s_mov_b32 s6, 11
	s_ashr_i32 s7, s6, 31
	s_lshl_b64 s[6:7], s[6:7], 3
	s_add_u32 s6, s0, s6
	s_addc_u32 s7, s1, s7
	s_load_dwordx2 s[6:7], s[6:7], 0x0
	s_lshl_b32 s8, s20, 5
	s_and_b32 s8, s8, 0x3e0
	s_add_i32 s9, s22, 0x4e80
	s_and_b32 s9, s9, 0x1ffc0
	s_lshl_b32 s10, s8, 2
	v_add_u32_e32 v0, s9, v32
	s_waitcnt lgkmcnt(0)
	s_add_u32 s6, s6, s10
	s_addc_u32 s7, s7, 0
	v_lshlrev_b32_e32 v36, 2, v34
	v_ashrrev_i32_e32 v1, 31, v0
	v_lshl_add_u64 v[2:3], s[6:7], 0, v[36:37]
	v_lshlrev_b64 v[0:1], 12, v[0:1]
	v_lshl_add_u64 v[28:29], v[2:3], 0, v[0:1]
	v_add_co_u32_e32 v4, vcc, s24, v28
	v_add_u32_e32 v33, v35, v89
	s_nop 0
	v_addc_co_u32_e32 v5, vcc, 0, v29, vcc
	v_add_co_u32_e32 v8, vcc, s25, v28
	global_load_dwordx4 v[0:3], v[28:29], off nt
	s_nop 0
	global_load_dwordx4 v[4:7], v[4:5], off nt
	v_addc_co_u32_e32 v9, vcc, 0, v29, vcc
	v_add_co_u32_e32 v12, vcc, s26, v28
	v_add_u32_e32 v36, 0x420, v33
	s_nop 0
	v_addc_co_u32_e32 v13, vcc, 0, v29, vcc
	v_add_co_u32_e32 v16, vcc, s27, v28
	global_load_dwordx4 v[8:11], v[8:9], off nt
	s_nop 0
	global_load_dwordx4 v[12:15], v[12:13], off nt
	v_addc_co_u32_e32 v17, vcc, 0, v29, vcc
	v_add_co_u32_e32 v20, vcc, s28, v28
	v_add_u32_e32 v39, 0x428, v33
	s_nop 0
	v_addc_co_u32_e32 v21, vcc, 0, v29, vcc
	global_load_dwordx4 v[16:19], v[16:17], off nt
	s_nop 0
	global_load_dwordx4 v[20:23], v[20:21], off nt
	v_add_co_u32_e32 v24, vcc, s29, v28
	v_add_u32_e32 v41, 0x840, v33
	s_nop 0
	v_addc_co_u32_e32 v25, vcc, 0, v29, vcc
	global_load_dwordx4 v[24:27], v[24:25], off nt
	v_add_co_u32_e32 v28, vcc, s30, v28
	v_add_u32_e32 v43, 0x848, v33
	s_nop 0
	v_addc_co_u32_e32 v29, vcc, 0, v29, vcc
	global_load_dwordx4 v[28:31], v[28:29], off nt
	v_add_u32_e32 v88, 0xc60, v33
	v_add_u32_e32 v90, 0xc68, v33
	v_add_u32_e32 v91, 0x1080, v33
	v_add_u32_e32 v92, 0x1088, v33
	v_add_u32_e32 v94, 0x14a0, v33
	v_add_u32_e32 v95, 0x14a8, v33
	v_add_u32_e32 v96, 0x18c0, v33
	v_add_u32_e32 v97, 0x18c8, v33
	v_add_u32_e32 v98, 0x1ce0, v33
	v_add_u32_e32 v99, 0x1ce8, v33
	s_lshl_b32 s10, s9, 1
	v_add_u32_e32 v100, s8, v32
	s_waitcnt vmcnt(0)
	ds_write2_b32 v33, v0, v1 offset1:1
	ds_write2_b32 v33, v2, v3 offset0:2 offset1:3
	ds_write2_b32 v36, v4, v5 offset1:1
	ds_write2_b32 v39, v6, v7 offset1:1
	ds_write2_b32 v41, v8, v9 offset1:1
	ds_write2_b32 v43, v10, v11 offset1:1
	ds_write2_b32 v88, v12, v13 offset1:1
	ds_write2_b32 v90, v14, v15 offset1:1
	ds_write2_b32 v91, v16, v17 offset1:1
	ds_write2_b32 v92, v18, v19 offset1:1
	ds_write2_b32 v94, v20, v21 offset1:1
	ds_write2_b32 v95, v22, v23 offset1:1
	ds_write2_b32 v96, v24, v25 offset1:1
	ds_write2_b32 v97, v26, v27 offset1:1
	ds_write2_b32 v98, v28, v29 offset1:1
	ds_write2_b32 v99, v30, v31 offset1:1
	s_waitcnt lgkmcnt(0)
	ds_read2_b32 v[4:5], v93 offset0:33 offset1:41
	ds_read2_b32 v[6:7], v93 offset1:8
	ds_read2_b32 v[8:9], v93 offset0:66 offset1:74
	ds_read2_b32 v[10:11], v93 offset0:99 offset1:107
	ds_read2_b32 v[12:13], v93 offset0:132 offset1:140
	ds_read2_b32 v[14:15], v93 offset0:165 offset1:173
	ds_read2_b32 v[16:17], v93 offset0:198 offset1:206
	ds_read2_b32 v[18:19], v93 offset0:231 offset1:239
	v_lshl_add_u64 v[20:21], v[76:77], 0, s[10:11]
	s_waitcnt lgkmcnt(6)
	v_cvt_pk_bf16_f32 v0, v6, v4
	s_waitcnt lgkmcnt(4)
	v_cvt_pk_bf16_f32 v1, v8, v10
	s_waitcnt lgkmcnt(2)
	v_cvt_pk_bf16_f32 v2, v12, v14
	s_waitcnt lgkmcnt(0)
	v_cvt_pk_bf16_f32 v3, v16, v18
	v_mad_i64_i32 v[22:23], s[6:7], v100, s31, v[20:21]
	global_store_dwordx4 v[22:23], v[0:3], off sc1
	v_add_u32_e32 v4, s8, v38
	s_nop 0
	v_cvt_pk_bf16_f32 v0, v7, v5
	v_cvt_pk_bf16_f32 v1, v9, v11
	v_cvt_pk_bf16_f32 v2, v13, v15
	v_cvt_pk_bf16_f32 v3, v17, v19
	ds_read2_b32 v[6:7], v93 offset0:49 offset1:57
	ds_read2_b32 v[8:9], v93 offset0:16 offset1:24
	ds_read2_b32 v[10:11], v93 offset0:82 offset1:90
	ds_read2_b32 v[12:13], v93 offset0:115 offset1:123
	ds_read2_b32 v[14:15], v93 offset0:148 offset1:156
	ds_read2_b32 v[16:17], v93 offset0:181 offset1:189
	ds_read2_b32 v[18:19], v93 offset0:214 offset1:222
	ds_read2_b32 v[22:23], v93 offset0:247 offset1:255
	v_mad_i64_i32 v[4:5], s[6:7], v4, s31, v[20:21]
	global_store_dwordx4 v[4:5], v[0:3], off sc1
	v_add_u32_e32 v4, s8, v40
	v_mad_i64_i32 v[4:5], s[6:7], v4, s31, v[20:21]
	s_waitcnt lgkmcnt(6)
	v_cvt_pk_bf16_f32 v0, v8, v6
	s_waitcnt lgkmcnt(4)
	v_cvt_pk_bf16_f32 v1, v10, v12
	s_waitcnt lgkmcnt(2)
	v_cvt_pk_bf16_f32 v2, v14, v16
	s_waitcnt lgkmcnt(0)
	v_cvt_pk_bf16_f32 v3, v18, v22
	global_store_dwordx4 v[4:5], v[0:3], off sc1
	v_add_u32_e32 v4, s8, v42
	v_mad_i64_i32 v[4:5], s[6:7], v4, s31, v[20:21]
	v_cvt_pk_bf16_f32 v0, v9, v7
	v_cvt_pk_bf16_f32 v1, v11, v13
	v_cvt_pk_bf16_f32 v2, v15, v17
	v_cvt_pk_bf16_f32 v3, v19, v23
	global_store_dwordx4 v[4:5], v[0:3], off sc1
	s_waitcnt lgkmcnt(0)

; __device__ __forceinline__ void transpose_tile(const float* W, const float* gain, int K, int N, int k0, int n0, bf16* WT, int drow0, LAS float* scr, int lane) {
;     ...
; #pragma unroll
;     for (int i = 0; i < 8; ++i) { v[i] = *(const f32x4*)(W + (size_t)(k0 + r0 + 8 * i) * N + n0 + 4 * c4); gv[i] = gain ? gain[k0 + r0 + 8 * i] : 1.0f; }
; template <bool SWIGLU> __device__ __forceinline__ void transpose_item(const float* W, const float* gain, int K, int N, bf16* WT, LAS float* scr, int item, int lane) {
;     ...
;     if (SWIGLU) { const int up = n0 >= FF, f = up ? n0 - FF : n0; drow0 = 256 * (f >> 7) + (up ? 128 : 0) + (f & 127); }
.LBB0_1528:
	s_andn2_b64 vcc, exec, s[8:9]
	s_cbranch_vccnz .LBB0_1546
	s_mov_b32 s6, 10
	s_ashr_i32 s7, s6, 31
	s_lshl_b64 s[6:7], s[6:7], 3
	s_add_u32 s6, s0, s6
	s_addc_u32 s7, s1, s7
	s_load_dwordx2 s[8:9], s[6:7], 0x0
	s_mov_b32 s6, 9
	s_ashr_i32 s7, s6, 31
	s_lshl_b64 s[6:7], s[6:7], 3
	s_add_u32 s12, s0, s6
	s_addc_u32 s13, s1, s7
	s_add_i32 s6, s20, 0xe780
	s_and_b32 s7, s6, 0xffff
	s_mul_i32 s7, s7, 0xba2f
	s_lshr_b32 s10, s7, 23
	s_mul_i32 s7, s10, 0xb0
	s_sub_i32 s7, s6, s7
	s_lshl_b32 s6, s10, 6
	s_lshl_b32 s10, s7, 7
	s_and_b32 s10, s10, 0x3ff80
	s_waitcnt lgkmcnt(0)
	s_add_u32 s8, s8, s10
	s_addc_u32 s9, s9, 0
	v_lshlrev_b32_e32 v36, 2, v34
	v_add_u32_e32 v28, s6, v32
	v_lshl_add_u64 v[30:31], s[8:9], 0, v[36:37]
	v_mad_i64_i32 v[0:1], s[8:9], v28, s34, v[30:31]
	global_load_dwordx4 v[0:3], v[0:1], off nt
	s_load_dwordx2 s[8:9], s[12:13], 0x0
	v_ashrrev_i32_e32 v29, 31, v28
	v_mov_b32_e32 v36, 1.0
	v_mov_b32_e32 v88, 1.0
	s_waitcnt lgkmcnt(0)
	s_cmp_lg_u64 s[8:9], 0
	s_cselect_b64 s[12:13], -1, 0
	s_cmp_eq_u64 s[8:9], 0
	v_lshl_add_u64 v[98:99], v[28:29], 2, s[8:9]
	s_cbranch_scc1 .LBB0_1531
	global_load_dword v88, v[98:99], off nt

; __device__ __forceinline__ unsigned pk_bf16(float lo, float hi) { typedef __bf16 b2_t __attribute__((ext_vector_type(2))); f32x2 v = {lo, hi}; b2_t b = __builtin_convertvector(v, b2_t); return __builtin_bit_cast(unsigned, b); }
; #define LAS __attribute__((address_space(3)))
; __device__ __forceinline__ void transpose_tile(const float* W, const float* gain, int K, int N, int k0, int n0, bf16* WT, int drow0, LAS float* scr, int lane) {
;     f32x4 v[8]; float gv[8];
;     const int r0 = lane >> 3, c4 = lane & 7;
; #pragma unroll
;     for (int i = 0; i < 8; ++i) { v[i] = *(const f32x4*)(W + (size_t)(k0 + r0 + 8 * i) * N + n0 + 4 * c4); gv[i] = gain ? gain[k0 + r0 + 8 * i] : 1.0f; }
; #pragma unroll
;     for (int i = 0; i < 8; ++i) { LAS float* d = scr + (r0 + 8 * i) * 33 + 4 * c4; d[0] = v[i][0] * gv[i]; d[1] = v[i][1] * gv[i]; d[2] = v[i][2] * gv[i]; d[3] = v[i][3] * gv[i]; }
;     asm volatile("s_waitcnt lgkmcnt(0)" ::: "memory");
;     const int c = lane & 7;
; #pragma unroll
;     for (int j = 0; j < 4; ++j) { const int n = (lane >> 3) + 8 * j; const LAS float* s = scr + (8 * c) * 33 + n;
;         v4u o; o.x = pk_bf16(s[0 * 33], s[1 * 33]); o.y = pk_bf16(s[2 * 33], s[3 * 33]); o.z = pk_bf16(s[4 * 33], s[5 * 33]); o.w = pk_bf16(s[6 * 33], s[7 * 33]);
;         *(v4u*)(WT + (size_t)(drow0 + n) * K + k0 + 8 * c) = o; }
;     asm volatile("s_waitcnt lgkmcnt(0)" ::: "memory");
; }
.LBB0_1547:
	s_andn2_b64 vcc, exec, s[8:9]
	s_cbranch_vccnz .LBB0_1549
	s_mov_b32 s6, 8
	s_ashr_i32 s7, s6, 31
	s_lshl_b64 s[6:7], s[6:7], 3
	s_add_u32 s6, s0, s6
	s_addc_u32 s7, s1, s7
	s_load_dwordx2 s[6:7], s[6:7], 0x0
	s_lshl_b32 s8, s20, 5
	s_and_b32 s8, s8, 0x3e0
	s_add_i32 s9, s22, 0x6880
	s_and_b32 s9, s9, 0x1ffc0
	s_lshl_b32 s10, s8, 2
	v_add_u32_e32 v0, s9, v32
	s_waitcnt lgkmcnt(0)
	s_add_u32 s6, s6, s10
	s_addc_u32 s7, s7, 0
	v_lshlrev_b32_e32 v36, 2, v34
	v_ashrrev_i32_e32 v1, 31, v0
	v_lshl_add_u64 v[2:3], s[6:7], 0, v[36:37]
	v_lshlrev_b64 v[0:1], 12, v[0:1]
	v_lshl_add_u64 v[28:29], v[2:3], 0, v[0:1]
	v_add_co_u32_e32 v4, vcc, s24, v28
	v_add_u32_e32 v33, v35, v89
	s_nop 0
	v_addc_co_u32_e32 v5, vcc, 0, v29, vcc
	v_add_co_u32_e32 v8, vcc, s25, v28
	global_load_dwordx4 v[0:3], v[28:29], off nt
	s_nop 0
	global_load_dwordx4 v[4:7], v[4:5], off nt
	v_addc_co_u32_e32 v9, vcc, 0, v29, vcc
	v_add_co_u32_e32 v12, vcc, s26, v28
	v_add_u32_e32 v36, 0x420, v33
	s_nop 0
	v_addc_co_u32_e32 v13, vcc, 0, v29, vcc
	v_add_co_u32_e32 v16, vcc, s27, v28
	global_load_dwordx4 v[8:11], v[8:9], off nt
	s_nop 0
	global_load_dwordx4 v[12:15], v[12:13], off nt
	v_addc_co_u32_e32 v17, vcc, 0, v29, vcc
	v_add_co_u32_e32 v20, vcc, s28, v28
	v_add_u32_e32 v39, 0x428, v33
	s_nop 0
	v_addc_co_u32_e32 v21, vcc, 0, v29, vcc
	global_load_dwordx4 v[16:19], v[16:17], off nt
	s_nop 0
	global_load_dwordx4 v[20:23], v[20:21], off nt
	v_add_co_u32_e32 v24, vcc, s29, v28
	v_add_u32_e32 v41, 0x840, v33
	s_nop 0
	v_addc_co_u32_e32 v25, vcc, 0, v29, vcc
	global_load_dwordx4 v[24:27], v[24:25], off nt
	v_add_co_u32_e32 v28, vcc, s30, v28
	v_add_u32_e32 v43, 0x848, v33
	s_nop 0
	v_addc_co_u32_e32 v29, vcc, 0, v29, vcc
	global_load_dwordx4 v[28:31], v[28:29], off nt
	v_add_u32_e32 v88, 0xc60, v33
	v_add_u32_e32 v92, 0xc68, v33
	v_add_u32_e32 v94, 0x1080, v33
	v_add_u32_e32 v95, 0x1088, v33
	v_add_u32_e32 v96, 0x14a0, v33
	v_add_u32_e32 v97, 0x14a8, v33
	v_add_u32_e32 v98, 0x18c0, v33
	v_add_u32_e32 v99, 0x18c8, v33
	v_add_u32_e32 v100, 0x1ce0, v33
	v_add_u32_e32 v101, 0x1ce8, v33
	v_add_u32_e32 v90, s8, v32
	v_ashrrev_i32_e32 v91, 31, v90
	s_lshl_b32 s10, s9, 1
	s_waitcnt vmcnt(0)
	ds_write2_b32 v33, v0, v1 offset1:1
	ds_write2_b32 v33, v2, v3 offset0:2 offset1:3
	ds_write2_b32 v36, v4, v5 offset1:1
	ds_write2_b32 v39, v6, v7 offset1:1
	ds_write2_b32 v41, v8, v9 offset1:1
	ds_write2_b32 v43, v10, v11 offset1:1
	ds_write2_b32 v88, v12, v13 offset1:1
	ds_write2_b32 v92, v14, v15 offset1:1
	ds_write2_b32 v94, v16, v17 offset1:1
	ds_write2_b32 v95, v18, v19 offset1:1
	ds_write2_b32 v96, v20, v21 offset1:1
	ds_write2_b32 v97, v22, v23 offset1:1
	ds_write2_b32 v98, v24, v25 offset1:1
	ds_write2_b32 v99, v26, v27 offset1:1
	ds_write2_b32 v100, v28, v29 offset1:1
	ds_write2_b32 v101, v30, v31 offset1:1
	s_waitcnt lgkmcnt(0)
	ds_read2_b32 v[4:5], v93 offset0:33 offset1:41
	ds_read2_b32 v[6:7], v93 offset1:8
	ds_read2_b32 v[8:9], v93 offset0:66 offset1:74
	ds_read2_b32 v[10:11], v93 offset0:99 offset1:107
	ds_read2_b32 v[12:13], v93 offset0:132 offset1:140
	ds_read2_b32 v[14:15], v93 offset0:165 offset1:173
	ds_read2_b32 v[16:17], v93 offset0:198 offset1:206
	ds_read2_b32 v[18:19], v93 offset0:231 offset1:239
	v_lshl_add_u64 v[20:21], v[80:81], 0, s[10:11]
	v_lshlrev_b64 v[22:23], 11, v[90:91]
	s_waitcnt lgkmcnt(6)
	v_cvt_pk_bf16_f32 v0, v6, v4
	s_waitcnt lgkmcnt(4)
	v_cvt_pk_bf16_f32 v1, v8, v10
	s_waitcnt lgkmcnt(2)
	v_cvt_pk_bf16_f32 v2, v12, v14
	s_waitcnt lgkmcnt(0)
	v_cvt_pk_bf16_f32 v3, v16, v18
	v_lshl_add_u64 v[22:23], v[20:21], 0, v[22:23]
	v_add_u32_e32 v4, s8, v38
	global_store_dwordx4 v[22:23], v[0:3], off sc1
	s_nop 1
	v_cvt_pk_bf16_f32 v0, v7, v5
	v_ashrrev_i32_e32 v5, 31, v4
	v_cvt_pk_bf16_f32 v1, v9, v11
	v_cvt_pk_bf16_f32 v2, v13, v15
	v_cvt_pk_bf16_f32 v3, v17, v19
	v_lshlrev_b64 v[4:5], 11, v[4:5]
	ds_read2_b32 v[6:7], v93 offset0:49 offset1:57
	ds_read2_b32 v[8:9], v93 offset0:16 offset1:24
	ds_read2_b32 v[10:11], v93 offset0:82 offset1:90
	ds_read2_b32 v[12:13], v93 offset0:115 offset1:123
	ds_read2_b32 v[14:15], v93 offset0:148 offset1:156
	ds_read2_b32 v[16:17], v93 offset0:181 offset1:189
	ds_read2_b32 v[18:19], v93 offset0:214 offset1:222
	ds_read2_b32 v[22:23], v93 offset0:247 offset1:255
	v_lshl_add_u64 v[4:5], v[20:21], 0, v[4:5]
	global_store_dwordx4 v[4:5], v[0:3], off sc1
	v_add_u32_e32 v4, s8, v40
	v_ashrrev_i32_e32 v5, 31, v4
	v_lshlrev_b64 v[4:5], 11, v[4:5]
	s_waitcnt lgkmcnt(6)
	v_cvt_pk_bf16_f32 v0, v8, v6
	s_waitcnt lgkmcnt(4)
	v_cvt_pk_bf16_f32 v1, v10, v12
	s_waitcnt lgkmcnt(2)
	v_cvt_pk_bf16_f32 v2, v14, v16
	s_waitcnt lgkmcnt(0)
	v_cvt_pk_bf16_f32 v3, v18, v22
	v_lshl_add_u64 v[4:5], v[20:21], 0, v[4:5]
	global_store_dwordx4 v[4:5], v[0:3], off sc1
	v_add_u32_e32 v4, s8, v42
	v_ashrrev_i32_e32 v5, 31, v4
	v_lshlrev_b64 v[4:5], 11, v[4:5]
	v_cvt_pk_bf16_f32 v0, v9, v7
	v_cvt_pk_bf16_f32 v1, v11, v13
	v_cvt_pk_bf16_f32 v2, v15, v17
	v_cvt_pk_bf16_f32 v3, v19, v23
	v_lshl_add_u64 v[4:5], v[20:21], 0, v[4:5]
	global_store_dwordx4 v[4:5], v[0:3], off sc1
	s_waitcnt lgkmcnt(0)

; #define LAS __attribute__((address_space(3)))
; __device__ __forceinline__ void transpose_tile(const float* W, const float* gain, int K, int N, int k0, int n0, bf16* WT, int drow0, LAS float* scr, int lane) {
;     f32x4 v[8]; float gv[8];
;     const int r0 = lane >> 3, c4 = lane & 7;
; #pragma unroll
;     for (int i = 0; i < 8; ++i) { v[i] = *(const f32x4*)(W + (size_t)(k0 + r0 + 8 * i) * N + n0 + 4 * c4); gv[i] = gain ? gain[k0 + r0 + 8 * i] : 1.0f; }
.LBB0_1550:
	s_andn2_b64 vcc, exec, s[8:9]
	s_cbranch_vccnz .LBB0_1568
	s_mov_b32 s6, 5
	s_ashr_i32 s7, s6, 31
	s_lshl_b64 s[6:7], s[6:7], 3
	s_add_u32 s6, s0, s6
	s_addc_u32 s7, s1, s7
	s_load_dwordx2 s[8:9], s[6:7], 0x0
	s_mov_b32 s6, 4
	s_ashr_i32 s7, s6, 31
	s_lshl_b64 s[6:7], s[6:7], 3
	s_add_u32 s12, s0, s6
	s_addc_u32 s13, s1, s7
	s_add_i32 s6, s20, 0xef80
	s_and_b32 s7, s6, 0xffff
	s_mul_i32 s7, s7, 0xaaab
	s_lshr_b32 s10, s7, 16
	s_lshr_b32 s7, s7, 22
	s_mulk_i32 s7, 0x60
	s_sub_i32 s7, s6, s7
	s_and_b32 s6, s10, 0xffc0
	s_lshl_b32 s10, s7, 7
	s_and_b32 s10, s10, 0x3ff80
	s_waitcnt lgkmcnt(0)
	s_add_u32 s8, s8, s10
	s_addc_u32 s9, s9, 0
	v_lshlrev_b32_e32 v36, 2, v34
	v_add_u32_e32 v28, s6, v32
	v_lshl_add_u64 v[30:31], s[8:9], 0, v[36:37]
	v_mad_i64_i32 v[0:1], s[8:9], v28, s35, v[30:31]
	global_load_dwordx4 v[0:3], v[0:1], off nt
	s_load_dwordx2 s[8:9], s[12:13], 0x0
	v_ashrrev_i32_e32 v29, 31, v28
	v_mov_b32_e32 v36, 1.0
	v_mov_b32_e32 v88, 1.0
	s_waitcnt lgkmcnt(0)
	s_cmp_lg_u64 s[8:9], 0
	s_cselect_b64 s[12:13], -1, 0
	s_cmp_eq_u64 s[8:9], 0
	v_lshl_add_u64 v[94:95], v[28:29], 2, s[8:9]
	s_cbranch_scc1 .LBB0_1553
	global_load_dword v88, v[94:95], off nt
.LBB0_1553:
	v_add_u32_e32 v4, 8, v28
	v_mad_i64_i32 v[4:5], s[8:9], v4, s35, v[30:31]
	global_load_dwordx4 v[4:7], v[4:5], off nt
	v_cndmask_b32_e64 v8, 0, 1, s[12:13]
	v_cmp_ne_u32_e64 s[8:9], 1, v8
	s_andn2_b64 vcc, exec, s[12:13]
	s_cbranch_vccnz .LBB0_1555
	global_load_dword v36, v[94:95], off offset:32 nt
.LBB0_1555:
	v_add_u32_e32 v8, 16, v28
	v_mad_i64_i32 v[8:9], s[12:13], v8, s35, v[30:31]
	global_load_dwordx4 v[8:11], v[8:9], off nt
	v_mov_b32_e32 v90, 1.0
	s_and_b64 vcc, exec, s[8:9]
	v_mov_b32_e32 v96, 1.0
	s_cbranch_vccnz .LBB0_1557
	global_load_dword v96, v[94:95], off offset:64 nt
.LBB0_1557:
	v_add_u32_e32 v12, 24, v28
	v_mad_i64_i32 v[12:13], s[12:13], v12, s35, v[30:31]
	global_load_dwordx4 v[12:15], v[12:13], off nt
	s_and_b64 vcc, exec, s[8:9]
	s_cbranch_vccnz .LBB0_1559
	global_load_dword v90, v[94:95], off offset:96 nt
.LBB0_1559:
	v_add_u32_e32 v16, 32, v28
	v_mad_i64_i32 v[16:17], s[12:13], v16, s35, v[30:31]
	global_load_dwordx4 v[16:19], v[16:17], off nt
	v_mov_b32_e32 v92, 1.0
	s_and_b64 vcc, exec, s[8:9]
	v_mov_b32_e32 v100, 1.0
	s_cbranch_vccnz .LBB0_1561
	global_load_dword v100, v[94:95], off offset:128 nt
.LBB0_1561:
	v_add_u32_e32 v20, 40, v28
	v_mad_i64_i32 v[20:21], s[12:13], v20, s35, v[30:31]
	global_load_dwordx4 v[20:23], v[20:21], off nt
	s_and_b64 vcc, exec, s[8:9]
	s_cbranch_vccnz .LBB0_1563
	global_load_dword v92, v[94:95], off offset:160 nt
.LBB0_1563:
	v_add_u32_e32 v24, 48, v28
	v_mad_i64_i32 v[24:25], s[12:13], v24, s35, v[30:31]
	global_load_dwordx4 v[24:27], v[24:25], off nt
	v_mov_b32_e32 v98, 1.0
	s_and_b64 vcc, exec, s[8:9]
	v_mov_b32_e32 v102, 1.0
	s_cbranch_vccnz .LBB0_1565
	global_load_dword v102, v[94:95], off offset:192 nt
.LBB0_1565:
	v_add_u32_e32 v28, 56, v28
	v_mad_i64_i32 v[28:29], s[12:13], v28, s35, v[30:31]
	global_load_dwordx4 v[28:31], v[28:29], off nt
	s_and_b64 vcc, exec, s[8:9]
	s_cbranch_vccnz .LBB0_1567
	global_load_dword v98, v[94:95], off offset:224 nt

; __device__ __forceinline__ unsigned pk_bf16(float lo, float hi) { typedef __bf16 b2_t __attribute__((ext_vector_type(2))); f32x2 v = {lo, hi}; b2_t b = __builtin_convertvector(v, b2_t); return __builtin_bit_cast(unsigned, b); }
; #define LAS __attribute__((address_space(3)))
; __device__ __forceinline__ void transpose_tile(const float* W, const float* gain, int K, int N, int k0, int n0, bf16* WT, int drow0, LAS float* scr, int lane) {
;     f32x4 v[8]; float gv[8];
;     const int r0 = lane >> 3, c4 = lane & 7;
; #pragma unroll
;     for (int i = 0; i < 8; ++i) { v[i] = *(const f32x4*)(W + (size_t)(k0 + r0 + 8 * i) * N + n0 + 4 * c4); gv[i] = gain ? gain[k0 + r0 + 8 * i] : 1.0f; }
; #pragma unroll
;     for (int i = 0; i < 8; ++i) { LAS float* d = scr + (r0 + 8 * i) * 33 + 4 * c4; d[0] = v[i][0] * gv[i]; d[1] = v[i][1] * gv[i]; d[2] = v[i][2] * gv[i]; d[3] = v[i][3] * gv[i]; }
;     asm volatile("s_waitcnt lgkmcnt(0)" ::: "memory");
;     const int c = lane & 7;
; #pragma unroll
;     for (int j = 0; j < 4; ++j) { const int n = (lane >> 3) + 8 * j; const LAS float* s = scr + (8 * c) * 33 + n;
;         v4u o; o.x = pk_bf16(s[0 * 33], s[1 * 33]); o.y = pk_bf16(s[2 * 33], s[3 * 33]); o.z = pk_bf16(s[4 * 33], s[5 * 33]); o.w = pk_bf16(s[6 * 33], s[7 * 33]);
;         *(v4u*)(WT + (size_t)(drow0 + n) * K + k0 + 8 * c) = o; }
;     asm volatile("s_waitcnt lgkmcnt(0)" ::: "memory");
; }
.LBB0_1569:
	s_andn2_b64 vcc, exec, s[8:9]
	s_cbranch_vccnz .LBB0_1571
	s_mov_b32 s6, 3
	s_ashr_i32 s7, s6, 31
	s_lshl_b64 s[6:7], s[6:7], 3
	s_add_u32 s6, s0, s6
	s_addc_u32 s7, s1, s7
	s_load_dwordx2 s[6:7], s[6:7], 0x0
	s_lshl_b32 s8, s20, 5
	s_and_b32 s8, s8, 0x3e0
	s_add_i32 s9, s22, 0x7f80
	s_and_b32 s9, s9, 0x1ffc0
	s_lshl_b32 s10, s8, 2
	v_add_u32_e32 v0, s9, v32
	s_waitcnt lgkmcnt(0)
	s_add_u32 s6, s6, s10
	s_addc_u32 s7, s7, 0
	v_lshlrev_b32_e32 v36, 2, v34
	v_ashrrev_i32_e32 v1, 31, v0
	v_lshl_add_u64 v[2:3], s[6:7], 0, v[36:37]
	v_lshlrev_b64 v[0:1], 12, v[0:1]
	v_lshl_add_u64 v[28:29], v[2:3], 0, v[0:1]
	v_add_co_u32_e32 v4, vcc, s24, v28
	v_add_u32_e32 v33, v35, v89
	s_nop 0
	v_addc_co_u32_e32 v5, vcc, 0, v29, vcc
	v_add_co_u32_e32 v8, vcc, s25, v28
	global_load_dwordx4 v[0:3], v[28:29], off nt
	s_nop 0
	global_load_dwordx4 v[4:7], v[4:5], off nt
	v_addc_co_u32_e32 v9, vcc, 0, v29, vcc
	v_add_co_u32_e32 v12, vcc, s26, v28
	v_add_u32_e32 v36, 0x420, v33
	s_nop 0
	v_addc_co_u32_e32 v13, vcc, 0, v29, vcc
	v_add_co_u32_e32 v16, vcc, s27, v28
	global_load_dwordx4 v[8:11], v[8:9], off nt
	s_nop 0
	global_load_dwordx4 v[12:15], v[12:13], off nt
	v_addc_co_u32_e32 v17, vcc, 0, v29, vcc
	v_add_co_u32_e32 v20, vcc, s28, v28
	v_add_u32_e32 v39, 0x428, v33
	s_nop 0
	v_addc_co_u32_e32 v21, vcc, 0, v29, vcc
	global_load_dwordx4 v[16:19], v[16:17], off nt
	s_nop 0
	global_load_dwordx4 v[20:23], v[20:21], off nt
	v_add_co_u32_e32 v24, vcc, s29, v28
	v_add_u32_e32 v41, 0x840, v33
	s_nop 0
	v_addc_co_u32_e32 v25, vcc, 0, v29, vcc
	global_load_dwordx4 v[24:27], v[24:25], off nt
	v_add_co_u32_e32 v28, vcc, s30, v28
	v_add_u32_e32 v43, 0x848, v33
	s_nop 0
	v_addc_co_u32_e32 v29, vcc, 0, v29, vcc
	global_load_dwordx4 v[28:31], v[28:29], off nt
	v_add_u32_e32 v88, 0xc60, v33
	v_add_u32_e32 v90, 0xc68, v33
	v_add_u32_e32 v91, 0x1080, v33
	v_add_u32_e32 v92, 0x1088, v33
	v_add_u32_e32 v94, 0x14a0, v33
	v_add_u32_e32 v95, 0x14a8, v33
	v_add_u32_e32 v96, 0x18c0, v33
	v_add_u32_e32 v97, 0x18c8, v33
	v_add_u32_e32 v98, 0x1ce0, v33
	v_add_u32_e32 v99, 0x1ce8, v33
	s_lshl_b32 s10, s9, 1
	v_add_u32_e32 v100, s8, v32
	s_waitcnt vmcnt(0)
	ds_write2_b32 v33, v0, v1 offset1:1
	ds_write2_b32 v33, v2, v3 offset0:2 offset1:3
	ds_write2_b32 v36, v4, v5 offset1:1
	ds_write2_b32 v39, v6, v7 offset1:1
	ds_write2_b32 v41, v8, v9 offset1:1
	ds_write2_b32 v43, v10, v11 offset1:1
	ds_write2_b32 v88, v12, v13 offset1:1
	ds_write2_b32 v90, v14, v15 offset1:1
	ds_write2_b32 v91, v16, v17 offset1:1
	ds_write2_b32 v92, v18, v19 offset1:1
	ds_write2_b32 v94, v20, v21 offset1:1
	ds_write2_b32 v95, v22, v23 offset1:1
	ds_write2_b32 v96, v24, v25 offset1:1
	ds_write2_b32 v97, v26, v27 offset1:1
	ds_write2_b32 v98, v28, v29 offset1:1
	ds_write2_b32 v99, v30, v31 offset1:1
	s_waitcnt lgkmcnt(0)
	ds_read2_b32 v[4:5], v93 offset0:33 offset1:41
	ds_read2_b32 v[6:7], v93 offset1:8
	ds_read2_b32 v[8:9], v93 offset0:66 offset1:74
	ds_read2_b32 v[10:11], v93 offset0:99 offset1:107
	ds_read2_b32 v[12:13], v93 offset0:132 offset1:140
	ds_read2_b32 v[14:15], v93 offset0:165 offset1:173
	ds_read2_b32 v[16:17], v93 offset0:198 offset1:206
	ds_read2_b32 v[18:19], v93 offset0:231 offset1:239
	v_lshl_add_u64 v[20:21], v[84:85], 0, s[10:11]
	s_waitcnt lgkmcnt(6)
	v_cvt_pk_bf16_f32 v0, v6, v4
	s_waitcnt lgkmcnt(4)
	v_cvt_pk_bf16_f32 v1, v8, v10
	s_waitcnt lgkmcnt(2)
	v_cvt_pk_bf16_f32 v2, v12, v14
	s_waitcnt lgkmcnt(0)
	v_cvt_pk_bf16_f32 v3, v16, v18
	v_mad_i64_i32 v[22:23], s[6:7], v100, s31, v[20:21]
	global_store_dwordx4 v[22:23], v[0:3], off sc1
	v_add_u32_e32 v4, s8, v38
	s_nop 0
	v_cvt_pk_bf16_f32 v0, v7, v5
	v_cvt_pk_bf16_f32 v1, v9, v11
	v_cvt_pk_bf16_f32 v2, v13, v15
	v_cvt_pk_bf16_f32 v3, v17, v19
	ds_read2_b32 v[6:7], v93 offset0:49 offset1:57
	ds_read2_b32 v[8:9], v93 offset0:16 offset1:24
	ds_read2_b32 v[10:11], v93 offset0:82 offset1:90
	ds_read2_b32 v[12:13], v93 offset0:115 offset1:123
	ds_read2_b32 v[14:15], v93 offset0:148 offset1:156
	ds_read2_b32 v[16:17], v93 offset0:181 offset1:189
	ds_read2_b32 v[18:19], v93 offset0:214 offset1:222
	ds_read2_b32 v[22:23], v93 offset0:247 offset1:255
	v_mad_i64_i32 v[4:5], s[6:7], v4, s31, v[20:21]
	global_store_dwordx4 v[4:5], v[0:3], off sc1
	v_add_u32_e32 v4, s8, v40
	v_mad_i64_i32 v[4:5], s[6:7], v4, s31, v[20:21]
	s_waitcnt lgkmcnt(6)
	v_cvt_pk_bf16_f32 v0, v8, v6
	s_waitcnt lgkmcnt(4)
	v_cvt_pk_bf16_f32 v1, v10, v12
	s_waitcnt lgkmcnt(2)
	v_cvt_pk_bf16_f32 v2, v14, v16
	s_waitcnt lgkmcnt(0)
	v_cvt_pk_bf16_f32 v3, v18, v22
	global_store_dwordx4 v[4:5], v[0:3], off sc1
	v_add_u32_e32 v4, s8, v42
	v_mad_i64_i32 v[4:5], s[6:7], v4, s31, v[20:21]
	v_cvt_pk_bf16_f32 v0, v9, v7
	v_cvt_pk_bf16_f32 v1, v11, v13
	v_cvt_pk_bf16_f32 v2, v15, v17
	v_cvt_pk_bf16_f32 v3, v19, v23
	global_store_dwordx4 v[4:5], v[0:3], off sc1
	s_waitcnt lgkmcnt(0)

; #define LAS __attribute__((address_space(3)))
; __device__ __forceinline__ void transpose_tile(const float* W, const float* gain, int K, int N, int k0, int n0, bf16* WT, int drow0, LAS float* scr, int lane) {
;     f32x4 v[8]; float gv[8];
;     const int r0 = lane >> 3, c4 = lane & 7;
; #pragma unroll
;     for (int i = 0; i < 8; ++i) { v[i] = *(const f32x4*)(W + (size_t)(k0 + r0 + 8 * i) * N + n0 + 4 * c4); gv[i] = gain ? gain[k0 + r0 + 8 * i] : 1.0f; }
.LBB0_1572:
	s_andn2_b64 vcc, exec, s[8:9]
	s_cbranch_vccnz .LBB0_1441
	s_mov_b32 s6, 2
	s_ashr_i32 s7, s6, 31
	s_lshl_b64 s[6:7], s[6:7], 3
	s_add_u32 s6, s0, s6
	s_addc_u32 s7, s1, s7
	s_load_dwordx2 s[8:9], s[6:7], 0x0
	s_mov_b32 s6, 1
	s_ashr_i32 s7, s6, 31
	s_lshl_b64 s[6:7], s[6:7], 3
	s_add_u32 s16, s0, s6
	s_mul_hi_i32 s6, s20, 0x2e8ba2e9
	s_addc_u32 s17, s1, s7
	s_lshr_b32 s7, s6, 31
	s_ashr_i32 s6, s6, 5
	s_add_i32 s6, s6, s7
	s_mul_i32 s7, s6, 0xffffea00
	s_add_i32 s14, s19, s7
	s_ashr_i32 s15, s14, 31
	s_lshl_b32 s12, s6, 6
	s_lshl_b64 s[36:37], s[14:15], 2
	s_waitcnt lgkmcnt(0)
	s_add_u32 s8, s8, s36
	s_addc_u32 s9, s9, s37
	v_lshlrev_b32_e32 v36, 2, v34
	v_add_u32_e32 v28, s12, v32
	v_lshl_add_u64 v[30:31], s[8:9], 0, v[36:37]
	v_mad_i64_i32 v[0:1], s[8:9], v28, s34, v[30:31]
	global_load_dwordx4 v[0:3], v[0:1], off nt
	s_load_dwordx2 s[8:9], s[16:17], 0x0
	v_ashrrev_i32_e32 v29, 31, v28
	v_mov_b32_e32 v36, 1.0
	v_mov_b32_e32 v88, 1.0
	s_waitcnt lgkmcnt(0)
	s_cmp_lg_u64 s[8:9], 0
	s_cselect_b64 s[16:17], -1, 0
	s_cmp_eq_u64 s[8:9], 0
	v_lshl_add_u64 v[98:99], v[28:29], 2, s[8:9]
	s_cbranch_scc1 .LBB0_1575
	global_load_dword v88, v[98:99], off nt
.LBB0_1575:
	v_add_u32_e32 v4, 8, v28
	v_mad_i64_i32 v[4:5], s[8:9], v4, s34, v[30:31]
	global_load_dwordx4 v[4:7], v[4:5], off nt
	v_cndmask_b32_e64 v8, 0, 1, s[16:17]
	v_cmp_ne_u32_e64 s[8:9], 1, v8
	s_andn2_b64 vcc, exec, s[16:17]
	s_cbranch_vccnz .LBB0_1577
	global_load_dword v36, v[98:99], off offset:32 nt
.LBB0_1577:
	v_add_u32_e32 v8, 16, v28
	v_mad_i64_i32 v[8:9], s[16:17], v8, s34, v[30:31]
	global_load_dwordx4 v[8:11], v[8:9], off nt
	v_mov_b32_e32 v90, 1.0
	s_and_b64 vcc, exec, s[8:9]
	v_mov_b32_e32 v94, 1.0
	s_cbranch_vccnz .LBB0_1579
	global_load_dword v94, v[98:99], off offset:64 nt
.LBB0_1579:
	v_add_u32_e32 v12, 24, v28
	v_mad_i64_i32 v[12:13], s[16:17], v12, s34, v[30:31]
	global_load_dwordx4 v[12:15], v[12:13], off nt
	s_and_b64 vcc, exec, s[8:9]
	s_cbranch_vccnz .LBB0_1581
	global_load_dword v90, v[98:99], off offset:96 nt
.LBB0_1581:
	v_add_u32_e32 v16, 32, v28
	v_mad_i64_i32 v[16:17], s[16:17], v16, s34, v[30:31]
	global_load_dwordx4 v[16:19], v[16:17], off nt
	v_mov_b32_e32 v92, 1.0
	s_and_b64 vcc, exec, s[8:9]
	v_mov_b32_e32 v100, 1.0
	s_cbranch_vccnz .LBB0_1583
	global_load_dword v100, v[98:99], off offset:128 nt
.LBB0_1583:
	v_add_u32_e32 v20, 40, v28
	v_mad_i64_i32 v[20:21], s[16:17], v20, s34, v[30:31]
	global_load_dwordx4 v[20:23], v[20:21], off nt
	s_and_b64 vcc, exec, s[8:9]
	s_cbranch_vccnz .LBB0_1585
	global_load_dword v92, v[98:99], off offset:160 nt
.LBB0_1585:
	v_add_u32_e32 v24, 48, v28
	v_mad_i64_i32 v[24:25], s[16:17], v24, s34, v[30:31]
	global_load_dwordx4 v[24:27], v[24:25], off nt
	v_mov_b32_e32 v96, 1.0
	s_and_b64 vcc, exec, s[8:9]
	v_mov_b32_e32 v102, 1.0
	s_cbranch_vccnz .LBB0_1587
	global_load_dword v102, v[98:99], off offset:192 nt
.LBB0_1587:
	v_add_u32_e32 v28, 56, v28
	v_mad_i64_i32 v[28:29], s[16:17], v28, s34, v[30:31]
	global_load_dwordx4 v[28:31], v[28:29], off nt
	s_and_b64 vcc, exec, s[8:9]
	s_cbranch_vccnz .LBB0_1440
	global_load_dword v96, v[98:99], off offset:224 nt
	s_branch .LBB0_1440
